# GEMM_OUT and GEMM_BR on the LDS-DMA mainloop; prep_rwkv edge loads deferred
# speedup vs baseline: 1.2293x; 1.0256x over previous
.LBB0_76:
	v_readlane_b32 s0, v255, 37
	s_cmp_lg_u32 s0, 0
	s_cbranch_scc0 .LBB0_96
	s_add_i32 s0, s0, -1
	s_mul_hi_i32 s1, s0, 0x92492493
	s_add_i32 s1, s1, s0
	s_lshr_b32 s25, s1, 31
	s_ashr_i32 s1, s1, 2
	s_add_i32 s70, s1, s25
	s_mul_i32 s1, s70, 7
	s_sub_i32 s16, s0, s1
	s_mov_b64 s[0:1], -1
	s_cmp_lt_i32 s16, 3
	s_mov_b64 s[18:19], 0
	s_cbranch_scc1 .LBB0_147
	s_cmp_gt_i32 s16, 3
	s_cbranch_scc0 .LBB0_98
	s_cmp_gt_i32 s16, 4
	s_cbranch_scc0 .LBB0_88
	s_cmp_eq_u32 s16, 5
	s_mov_b64 s[18:19], -1
	s_cbranch_scc0 .LBB0_87
	v_readlane_b32 s0, v254, 13
	v_readlane_b32 s1, v254, 14
	v_mov_b32_e32 v219, 0x2040
	v_mov_b32_e32 v129, 0x3a27c5ac
	v_mov_b32_e32 v220, 0x3f4ccccd
	v_mov_b32_e32 v144, 0x3727c5ac
	v_mov_b32_e32 v251, 1
	v_mov_b64_e32 v[212:213], v[208:209]
	s_andn2_b64 vcc, exec, s[0:1]
	s_cbranch_vccnz .LBB0_86
	v_and_b32_e32 v244, 63, v128
	v_lshrrev_b32_e32 v245, 6, v128
	v_lshrrev_b32_e32 v246, 3, v244
	v_readfirstlane_b32 s0, v245
	v_and_b32_e32 v247, 7, v244
	v_xor_b32_e32 v247, v247, v246
	v_lshlrev_b32_e32 v247, 4, v247
	v_lshl_add_u32 v247, v246, 10, v247
	s_lshl_b32 s1, s0, 15
	v_add_u32_e32 v132, s1, v247
	v_add_u32_e32 v133, 0x1c00, v132
	v_add_u32_e32 v134, 0x3800, v132
	v_add_u32_e32 v135, 0x5400, v132
	s_lshl_b32 s1, s0, 12
	s_add_u32 s40, s1, 0
	s_add_u32 s41, s1, 16384
	s_add_u32 s42, s1, 45056
	s_add_u32 s43, s1, 61440
	v_and_b32_e32 v246, 15, v244
	v_lshrrev_b32_e32 v247, 4, v244
	v_and_b32_e32 v248, 7, v246
	v_xor_b32_e32 v248, v248, v247
	v_lshlrev_b32_e32 v248, 4, v248
	v_lshl_add_u32 v248, v246, 7, v248
	s_lshr_b32 s1, s0, 1
	s_lshl_b32 s1, s1, 13
	v_add_u32_e32 v136, s1, v248
	v_xor_b32_e32 v137, 64, v136
	v_add_u32_e32 v138, 0xb000, v136
	v_add_u32_e32 v139, 0xb000, v137
	s_and_b32 s1, s0, 1
	s_lshl_b32 s1, s1, 13
	s_add_u32 s1, s1, 16384
	v_add_u32_e32 v140, s1, v248
	v_xor_b32_e32 v141, 64, v140
	v_add_u32_e32 v142, 0xb000, v140
	v_add_u32_e32 v143, 0xb000, v141
	s_and_b32 s1, s0, 1
	s_lshl_b32 s1, s1, 6
	v_add_u32_e32 v246, s1, v246
	v_lshlrev_b32_e32 v247, 3, v247
	s_lshr_b32 s1, s0, 1
	s_lshl_b32 s1, s1, 7
	v_add_u32_e32 v247, s1, v247
	v_mov_b32_e32 v248, 0x4a00
	v_mul_lo_u32 v248, v246, v248
	v_add_u32_e32 v236, v248, v247
	v_lshl_add_u32 v240, v246, 11, v247
	v_add_u32_e32 v237, 0x4a000, v236
	v_add_u32_e32 v241, 0x8000, v240
	v_add_u32_e32 v238, 0x94000, v236
	v_add_u32_e32 v242, 0x10000, v240
	v_add_u32_e32 v239, 0xde000, v236
	v_add_u32_e32 v243, 0x18000, v240
	v_readlane_b32 s25, v252, 0
.Lgbr_tile:
	s_and_b32 s0, s25, 63
	s_lshr_b32 s1, s25, 6
	s_mul_i32 s4, s70, 0x300000
	s_lshl_b32 s39, s1, 17
	s_add_u32 s4, s4, s39
	s_add_u32 s4, s4, 0x4a00000
	s_add_u32 s26, s96, s4
	s_addc_u32 s27, s97, 0
	s_lshl_b32 s4, s0, 17
	s_add_u32 s4, s4, 0x20fa6100
	s_add_u32 s28, s96, s4
	s_addc_u32 s29, s97, 0
	s_mul_i32 s4, s0, 0x250000
	s_lshl_b32 s39, s1, 8
	s_add_u32 s4, s4, s39
	s_add_u32 s4, s4, 0x92a9300
	s_add_u32 s36, s96, s4
	s_addc_u32 s37, s97, 0
	s_lshl_b32 s4, s0, 18
	s_add_u32 s4, s4, s39
	s_add_u32 s4, s4, 0x82a6100
	s_add_u32 s44, s96, s4
	s_addc_u32 s45, s97, 0
	s_mov_b32 m0, s40
	s_nop 0
	global_load_lds_dwordx4 v132, s[26:27] offset:0
	global_load_lds_dwordx4 v133, s[26:27] offset:1024
	global_load_lds_dwordx4 v134, s[26:27] offset:2048
	global_load_lds_dwordx4 v135, s[26:27] offset:3072
	s_mov_b32 m0, s41
	s_nop 0
	global_load_lds_dwordx4 v132, s[28:29] offset:0
	global_load_lds_dwordx4 v133, s[28:29] offset:1024
	global_load_lds_dwordx4 v134, s[28:29] offset:2048
	global_load_lds_dwordx4 v135, s[28:29] offset:3072
	s_waitcnt vmcnt(0)
	s_barrier
	s_add_u32 s26, s26, 0x80
	s_addc_u32 s27, s27, 0
	s_add_u32 s28, s28, 0x80
	s_addc_u32 s29, s29, 0
	s_mov_b32 m0, s42
	s_nop 0
	global_load_lds_dwordx4 v132, s[26:27] offset:0
	global_load_lds_dwordx4 v133, s[26:27] offset:1024
	global_load_lds_dwordx4 v134, s[26:27] offset:2048
	global_load_lds_dwordx4 v135, s[26:27] offset:3072
	s_mov_b32 m0, s43
	s_nop 0
	global_load_lds_dwordx4 v132, s[28:29] offset:0
	global_load_lds_dwordx4 v133, s[28:29] offset:1024
	global_load_lds_dwordx4 v134, s[28:29] offset:2048
	global_load_lds_dwordx4 v135, s[28:29] offset:3072
	ds_read_b128 v[64:67], v136 offset:0
	ds_read_b128 v[96:99], v140 offset:0
	ds_read_b128 v[100:103], v140 offset:2048
	ds_read_b128 v[104:107], v140 offset:4096
	ds_read_b128 v[108:111], v140 offset:6144
	ds_read_b128 v[68:71], v136 offset:2048
	ds_read_b128 v[72:75], v136 offset:4096
	ds_read_b128 v[76:79], v136 offset:6144
	s_waitcnt lgkmcnt(3)
	v_mfma_f32_16x16x32_bf16 v[0:3], v[64:67], v[96:99], 0
	v_mfma_f32_16x16x32_bf16 v[4:7], v[64:67], v[100:103], 0
	ds_read_b128 v[80:83], v137 offset:0
	v_mfma_f32_16x16x32_bf16 v[8:11], v[64:67], v[104:107], 0
	v_mfma_f32_16x16x32_bf16 v[12:15], v[64:67], v[108:111], 0
	ds_read_b128 v[112:115], v141 offset:0
	s_waitcnt lgkmcnt(4)
	v_mfma_f32_16x16x32_bf16 v[16:19], v[68:71], v[96:99], 0
	v_mfma_f32_16x16x32_bf16 v[20:23], v[68:71], v[100:103], 0
	ds_read_b128 v[116:119], v141 offset:2048
	v_mfma_f32_16x16x32_bf16 v[24:27], v[68:71], v[104:107], 0
	v_mfma_f32_16x16x32_bf16 v[28:31], v[68:71], v[108:111], 0
	ds_read_b128 v[120:123], v141 offset:4096
	s_waitcnt lgkmcnt(5)
	v_mfma_f32_16x16x32_bf16 v[32:35], v[72:75], v[96:99], 0
	v_mfma_f32_16x16x32_bf16 v[36:39], v[72:75], v[100:103], 0
	ds_read_b128 v[124:127], v141 offset:6144
	v_mfma_f32_16x16x32_bf16 v[40:43], v[72:75], v[104:107], 0
	v_mfma_f32_16x16x32_bf16 v[44:47], v[72:75], v[108:111], 0
	ds_read_b128 v[84:87], v137 offset:2048
	s_waitcnt lgkmcnt(6)
	v_mfma_f32_16x16x32_bf16 v[48:51], v[76:79], v[96:99], 0
	v_mfma_f32_16x16x32_bf16 v[52:55], v[76:79], v[100:103], 0
	ds_read_b128 v[88:91], v137 offset:4096
	v_mfma_f32_16x16x32_bf16 v[56:59], v[76:79], v[104:107], 0
	v_mfma_f32_16x16x32_bf16 v[60:63], v[76:79], v[108:111], 0
	ds_read_b128 v[92:95], v137 offset:6144
	s_waitcnt lgkmcnt(3)
	v_mfma_f32_16x16x32_bf16 v[0:3], v[80:83], v[112:115], v[0:3]
	v_mfma_f32_16x16x32_bf16 v[4:7], v[80:83], v[116:119], v[4:7]
	v_mfma_f32_16x16x32_bf16 v[8:11], v[80:83], v[120:123], v[8:11]
	v_mfma_f32_16x16x32_bf16 v[12:15], v[80:83], v[124:127], v[12:15]
	s_waitcnt lgkmcnt(2)
	v_mfma_f32_16x16x32_bf16 v[16:19], v[84:87], v[112:115], v[16:19]
	v_mfma_f32_16x16x32_bf16 v[20:23], v[84:87], v[116:119], v[20:23]
	v_mfma_f32_16x16x32_bf16 v[24:27], v[84:87], v[120:123], v[24:27]
	v_mfma_f32_16x16x32_bf16 v[28:31], v[84:87], v[124:127], v[28:31]
	s_waitcnt lgkmcnt(1)
	v_mfma_f32_16x16x32_bf16 v[32:35], v[88:91], v[112:115], v[32:35]
	v_mfma_f32_16x16x32_bf16 v[36:39], v[88:91], v[116:119], v[36:39]
	v_mfma_f32_16x16x32_bf16 v[40:43], v[88:91], v[120:123], v[40:43]
	v_mfma_f32_16x16x32_bf16 v[44:47], v[88:91], v[124:127], v[44:47]
	s_waitcnt lgkmcnt(0)
	v_mfma_f32_16x16x32_bf16 v[48:51], v[92:95], v[112:115], v[48:51]
	v_mfma_f32_16x16x32_bf16 v[52:55], v[92:95], v[116:119], v[52:55]
	v_mfma_f32_16x16x32_bf16 v[56:59], v[92:95], v[120:123], v[56:59]
	v_mfma_f32_16x16x32_bf16 v[60:63], v[92:95], v[124:127], v[60:63]
	s_waitcnt vmcnt(0)
	s_barrier
	s_add_u32 s26, s26, 0x80
	s_addc_u32 s27, s27, 0
	s_add_u32 s28, s28, 0x80
	s_addc_u32 s29, s29, 0
	s_mov_b32 m0, s40
	s_nop 0
	global_load_lds_dwordx4 v132, s[26:27] offset:0
	global_load_lds_dwordx4 v133, s[26:27] offset:1024
	global_load_lds_dwordx4 v134, s[26:27] offset:2048
	global_load_lds_dwordx4 v135, s[26:27] offset:3072
	s_mov_b32 m0, s41
	s_nop 0
	global_load_lds_dwordx4 v132, s[28:29] offset:0
	global_load_lds_dwordx4 v133, s[28:29] offset:1024
	global_load_lds_dwordx4 v134, s[28:29] offset:2048
	global_load_lds_dwordx4 v135, s[28:29] offset:3072
	ds_read_b128 v[64:67], v138 offset:0
	ds_read_b128 v[96:99], v142 offset:0
	ds_read_b128 v[100:103], v142 offset:2048
	ds_read_b128 v[104:107], v142 offset:4096
	ds_read_b128 v[108:111], v142 offset:6144
	ds_read_b128 v[68:71], v138 offset:2048
	ds_read_b128 v[72:75], v138 offset:4096
	ds_read_b128 v[76:79], v138 offset:6144
	s_waitcnt lgkmcnt(3)
	v_mfma_f32_16x16x32_bf16 v[0:3], v[64:67], v[96:99], v[0:3]
	v_mfma_f32_16x16x32_bf16 v[4:7], v[64:67], v[100:103], v[4:7]
	ds_read_b128 v[80:83], v139 offset:0
	v_mfma_f32_16x16x32_bf16 v[8:11], v[64:67], v[104:107], v[8:11]
	v_mfma_f32_16x16x32_bf16 v[12:15], v[64:67], v[108:111], v[12:15]
	ds_read_b128 v[112:115], v143 offset:0
	s_waitcnt lgkmcnt(4)
	v_mfma_f32_16x16x32_bf16 v[16:19], v[68:71], v[96:99], v[16:19]
	v_mfma_f32_16x16x32_bf16 v[20:23], v[68:71], v[100:103], v[20:23]
	ds_read_b128 v[116:119], v143 offset:2048
	v_mfma_f32_16x16x32_bf16 v[24:27], v[68:71], v[104:107], v[24:27]
	v_mfma_f32_16x16x32_bf16 v[28:31], v[68:71], v[108:111], v[28:31]
	ds_read_b128 v[120:123], v143 offset:4096
	s_waitcnt lgkmcnt(5)
	v_mfma_f32_16x16x32_bf16 v[32:35], v[72:75], v[96:99], v[32:35]
	v_mfma_f32_16x16x32_bf16 v[36:39], v[72:75], v[100:103], v[36:39]
	ds_read_b128 v[124:127], v143 offset:6144
	v_mfma_f32_16x16x32_bf16 v[40:43], v[72:75], v[104:107], v[40:43]
	v_mfma_f32_16x16x32_bf16 v[44:47], v[72:75], v[108:111], v[44:47]
	ds_read_b128 v[84:87], v139 offset:2048
	s_waitcnt lgkmcnt(6)
	v_mfma_f32_16x16x32_bf16 v[48:51], v[76:79], v[96:99], v[48:51]
	v_mfma_f32_16x16x32_bf16 v[52:55], v[76:79], v[100:103], v[52:55]
	ds_read_b128 v[88:91], v139 offset:4096
	v_mfma_f32_16x16x32_bf16 v[56:59], v[76:79], v[104:107], v[56:59]
	v_mfma_f32_16x16x32_bf16 v[60:63], v[76:79], v[108:111], v[60:63]
	ds_read_b128 v[92:95], v139 offset:6144
	s_waitcnt lgkmcnt(3)
	v_mfma_f32_16x16x32_bf16 v[0:3], v[80:83], v[112:115], v[0:3]
	v_mfma_f32_16x16x32_bf16 v[4:7], v[80:83], v[116:119], v[4:7]
	v_mfma_f32_16x16x32_bf16 v[8:11], v[80:83], v[120:123], v[8:11]
	v_mfma_f32_16x16x32_bf16 v[12:15], v[80:83], v[124:127], v[12:15]
	s_waitcnt lgkmcnt(2)
	v_mfma_f32_16x16x32_bf16 v[16:19], v[84:87], v[112:115], v[16:19]
	v_mfma_f32_16x16x32_bf16 v[20:23], v[84:87], v[116:119], v[20:23]
	v_mfma_f32_16x16x32_bf16 v[24:27], v[84:87], v[120:123], v[24:27]
	v_mfma_f32_16x16x32_bf16 v[28:31], v[84:87], v[124:127], v[28:31]
	s_waitcnt lgkmcnt(1)
	v_mfma_f32_16x16x32_bf16 v[32:35], v[88:91], v[112:115], v[32:35]
	v_mfma_f32_16x16x32_bf16 v[36:39], v[88:91], v[116:119], v[36:39]
	v_mfma_f32_16x16x32_bf16 v[40:43], v[88:91], v[120:123], v[40:43]
	v_mfma_f32_16x16x32_bf16 v[44:47], v[88:91], v[124:127], v[44:47]
	s_waitcnt lgkmcnt(0)
	v_mfma_f32_16x16x32_bf16 v[48:51], v[92:95], v[112:115], v[48:51]
	v_mfma_f32_16x16x32_bf16 v[52:55], v[92:95], v[116:119], v[52:55]
	v_mfma_f32_16x16x32_bf16 v[56:59], v[92:95], v[120:123], v[56:59]
	v_mfma_f32_16x16x32_bf16 v[60:63], v[92:95], v[124:127], v[60:63]
	s_waitcnt vmcnt(0)
	s_barrier
	s_add_u32 s26, s26, 0x80
	s_addc_u32 s27, s27, 0
	s_add_u32 s28, s28, 0x80
	s_addc_u32 s29, s29, 0
	s_mov_b32 m0, s42
	s_nop 0
	global_load_lds_dwordx4 v132, s[26:27] offset:0
	global_load_lds_dwordx4 v133, s[26:27] offset:1024
	global_load_lds_dwordx4 v134, s[26:27] offset:2048
	global_load_lds_dwordx4 v135, s[26:27] offset:3072
	s_mov_b32 m0, s43
	s_nop 0
	global_load_lds_dwordx4 v132, s[28:29] offset:0
	global_load_lds_dwordx4 v133, s[28:29] offset:1024
	global_load_lds_dwordx4 v134, s[28:29] offset:2048
	global_load_lds_dwordx4 v135, s[28:29] offset:3072
	ds_read_b128 v[64:67], v136 offset:0
	ds_read_b128 v[96:99], v140 offset:0
	ds_read_b128 v[100:103], v140 offset:2048
	ds_read_b128 v[104:107], v140 offset:4096
	ds_read_b128 v[108:111], v140 offset:6144
	ds_read_b128 v[68:71], v136 offset:2048
	ds_read_b128 v[72:75], v136 offset:4096
	ds_read_b128 v[76:79], v136 offset:6144
	s_waitcnt lgkmcnt(3)
	v_mfma_f32_16x16x32_bf16 v[0:3], v[64:67], v[96:99], v[0:3]
	v_mfma_f32_16x16x32_bf16 v[4:7], v[64:67], v[100:103], v[4:7]
	ds_read_b128 v[80:83], v137 offset:0
	v_mfma_f32_16x16x32_bf16 v[8:11], v[64:67], v[104:107], v[8:11]
	v_mfma_f32_16x16x32_bf16 v[12:15], v[64:67], v[108:111], v[12:15]
	ds_read_b128 v[112:115], v141 offset:0
	s_waitcnt lgkmcnt(4)
	v_mfma_f32_16x16x32_bf16 v[16:19], v[68:71], v[96:99], v[16:19]
	v_mfma_f32_16x16x32_bf16 v[20:23], v[68:71], v[100:103], v[20:23]
	ds_read_b128 v[116:119], v141 offset:2048
	v_mfma_f32_16x16x32_bf16 v[24:27], v[68:71], v[104:107], v[24:27]
	v_mfma_f32_16x16x32_bf16 v[28:31], v[68:71], v[108:111], v[28:31]
	ds_read_b128 v[120:123], v141 offset:4096
	s_waitcnt lgkmcnt(5)
	v_mfma_f32_16x16x32_bf16 v[32:35], v[72:75], v[96:99], v[32:35]
	v_mfma_f32_16x16x32_bf16 v[36:39], v[72:75], v[100:103], v[36:39]
	ds_read_b128 v[124:127], v141 offset:6144
	v_mfma_f32_16x16x32_bf16 v[40:43], v[72:75], v[104:107], v[40:43]
	v_mfma_f32_16x16x32_bf16 v[44:47], v[72:75], v[108:111], v[44:47]
	ds_read_b128 v[84:87], v137 offset:2048
	s_waitcnt lgkmcnt(6)
	v_mfma_f32_16x16x32_bf16 v[48:51], v[76:79], v[96:99], v[48:51]
	v_mfma_f32_16x16x32_bf16 v[52:55], v[76:79], v[100:103], v[52:55]
	ds_read_b128 v[88:91], v137 offset:4096
	v_mfma_f32_16x16x32_bf16 v[56:59], v[76:79], v[104:107], v[56:59]
	v_mfma_f32_16x16x32_bf16 v[60:63], v[76:79], v[108:111], v[60:63]
	ds_read_b128 v[92:95], v137 offset:6144
	s_waitcnt lgkmcnt(3)
	v_mfma_f32_16x16x32_bf16 v[0:3], v[80:83], v[112:115], v[0:3]
	v_mfma_f32_16x16x32_bf16 v[4:7], v[80:83], v[116:119], v[4:7]
	v_mfma_f32_16x16x32_bf16 v[8:11], v[80:83], v[120:123], v[8:11]
	v_mfma_f32_16x16x32_bf16 v[12:15], v[80:83], v[124:127], v[12:15]
	s_waitcnt lgkmcnt(2)
	v_mfma_f32_16x16x32_bf16 v[16:19], v[84:87], v[112:115], v[16:19]
	v_mfma_f32_16x16x32_bf16 v[20:23], v[84:87], v[116:119], v[20:23]
	v_mfma_f32_16x16x32_bf16 v[24:27], v[84:87], v[120:123], v[24:27]
	v_mfma_f32_16x16x32_bf16 v[28:31], v[84:87], v[124:127], v[28:31]
	s_waitcnt lgkmcnt(1)
	v_mfma_f32_16x16x32_bf16 v[32:35], v[88:91], v[112:115], v[32:35]
	v_mfma_f32_16x16x32_bf16 v[36:39], v[88:91], v[116:119], v[36:39]
	v_mfma_f32_16x16x32_bf16 v[40:43], v[88:91], v[120:123], v[40:43]
	v_mfma_f32_16x16x32_bf16 v[44:47], v[88:91], v[124:127], v[44:47]
	s_waitcnt lgkmcnt(0)
	v_mfma_f32_16x16x32_bf16 v[48:51], v[92:95], v[112:115], v[48:51]
	v_mfma_f32_16x16x32_bf16 v[52:55], v[92:95], v[116:119], v[52:55]
	v_mfma_f32_16x16x32_bf16 v[56:59], v[92:95], v[120:123], v[56:59]
	v_mfma_f32_16x16x32_bf16 v[60:63], v[92:95], v[124:127], v[60:63]
	s_waitcnt vmcnt(0)
	s_barrier
	s_add_u32 s26, s26, 0x80
	s_addc_u32 s27, s27, 0
	s_add_u32 s28, s28, 0x80
	s_addc_u32 s29, s29, 0
	s_mov_b32 m0, s40
	s_nop 0
	global_load_lds_dwordx4 v132, s[26:27] offset:0
	global_load_lds_dwordx4 v133, s[26:27] offset:1024
	global_load_lds_dwordx4 v134, s[26:27] offset:2048
	global_load_lds_dwordx4 v135, s[26:27] offset:3072
	s_mov_b32 m0, s41
	s_nop 0
	global_load_lds_dwordx4 v132, s[28:29] offset:0
	global_load_lds_dwordx4 v133, s[28:29] offset:1024
	global_load_lds_dwordx4 v134, s[28:29] offset:2048
	global_load_lds_dwordx4 v135, s[28:29] offset:3072
	ds_read_b128 v[64:67], v138 offset:0
	ds_read_b128 v[96:99], v142 offset:0
	ds_read_b128 v[100:103], v142 offset:2048
	ds_read_b128 v[104:107], v142 offset:4096
	ds_read_b128 v[108:111], v142 offset:6144
	ds_read_b128 v[68:71], v138 offset:2048
	ds_read_b128 v[72:75], v138 offset:4096
	ds_read_b128 v[76:79], v138 offset:6144
	s_waitcnt lgkmcnt(3)
	v_mfma_f32_16x16x32_bf16 v[0:3], v[64:67], v[96:99], v[0:3]
	v_mfma_f32_16x16x32_bf16 v[4:7], v[64:67], v[100:103], v[4:7]
	ds_read_b128 v[80:83], v139 offset:0
	v_mfma_f32_16x16x32_bf16 v[8:11], v[64:67], v[104:107], v[8:11]
	v_mfma_f32_16x16x32_bf16 v[12:15], v[64:67], v[108:111], v[12:15]
	ds_read_b128 v[112:115], v143 offset:0
	s_waitcnt lgkmcnt(4)
	v_mfma_f32_16x16x32_bf16 v[16:19], v[68:71], v[96:99], v[16:19]
	v_mfma_f32_16x16x32_bf16 v[20:23], v[68:71], v[100:103], v[20:23]
	ds_read_b128 v[116:119], v143 offset:2048
	v_mfma_f32_16x16x32_bf16 v[24:27], v[68:71], v[104:107], v[24:27]
	v_mfma_f32_16x16x32_bf16 v[28:31], v[68:71], v[108:111], v[28:31]
	ds_read_b128 v[120:123], v143 offset:4096
	s_waitcnt lgkmcnt(5)
	v_mfma_f32_16x16x32_bf16 v[32:35], v[72:75], v[96:99], v[32:35]
	v_mfma_f32_16x16x32_bf16 v[36:39], v[72:75], v[100:103], v[36:39]
	ds_read_b128 v[124:127], v143 offset:6144
	v_mfma_f32_16x16x32_bf16 v[40:43], v[72:75], v[104:107], v[40:43]
	v_mfma_f32_16x16x32_bf16 v[44:47], v[72:75], v[108:111], v[44:47]
	ds_read_b128 v[84:87], v139 offset:2048
	s_waitcnt lgkmcnt(6)
	v_mfma_f32_16x16x32_bf16 v[48:51], v[76:79], v[96:99], v[48:51]
	v_mfma_f32_16x16x32_bf16 v[52:55], v[76:79], v[100:103], v[52:55]
	ds_read_b128 v[88:91], v139 offset:4096
	v_mfma_f32_16x16x32_bf16 v[56:59], v[76:79], v[104:107], v[56:59]
	v_mfma_f32_16x16x32_bf16 v[60:63], v[76:79], v[108:111], v[60:63]
	ds_read_b128 v[92:95], v139 offset:6144
	s_waitcnt lgkmcnt(3)
	v_mfma_f32_16x16x32_bf16 v[0:3], v[80:83], v[112:115], v[0:3]
	v_mfma_f32_16x16x32_bf16 v[4:7], v[80:83], v[116:119], v[4:7]
	v_mfma_f32_16x16x32_bf16 v[8:11], v[80:83], v[120:123], v[8:11]
	v_mfma_f32_16x16x32_bf16 v[12:15], v[80:83], v[124:127], v[12:15]
	s_waitcnt lgkmcnt(2)
	v_mfma_f32_16x16x32_bf16 v[16:19], v[84:87], v[112:115], v[16:19]
	v_mfma_f32_16x16x32_bf16 v[20:23], v[84:87], v[116:119], v[20:23]
	v_mfma_f32_16x16x32_bf16 v[24:27], v[84:87], v[120:123], v[24:27]
	v_mfma_f32_16x16x32_bf16 v[28:31], v[84:87], v[124:127], v[28:31]
	s_waitcnt lgkmcnt(1)
	v_mfma_f32_16x16x32_bf16 v[32:35], v[88:91], v[112:115], v[32:35]
	v_mfma_f32_16x16x32_bf16 v[36:39], v[88:91], v[116:119], v[36:39]
	v_mfma_f32_16x16x32_bf16 v[40:43], v[88:91], v[120:123], v[40:43]
	v_mfma_f32_16x16x32_bf16 v[44:47], v[88:91], v[124:127], v[44:47]
	s_waitcnt lgkmcnt(0)
	v_mfma_f32_16x16x32_bf16 v[48:51], v[92:95], v[112:115], v[48:51]
	v_mfma_f32_16x16x32_bf16 v[52:55], v[92:95], v[116:119], v[52:55]
	v_mfma_f32_16x16x32_bf16 v[56:59], v[92:95], v[120:123], v[56:59]
	v_mfma_f32_16x16x32_bf16 v[60:63], v[92:95], v[124:127], v[60:63]
	s_waitcnt vmcnt(0)
	s_barrier
	s_add_u32 s26, s26, 0x80
	s_addc_u32 s27, s27, 0
	s_add_u32 s28, s28, 0x80
	s_addc_u32 s29, s29, 0
	s_mov_b32 m0, s42
	s_nop 0
	global_load_lds_dwordx4 v132, s[26:27] offset:0
	global_load_lds_dwordx4 v133, s[26:27] offset:1024
	global_load_lds_dwordx4 v134, s[26:27] offset:2048
	global_load_lds_dwordx4 v135, s[26:27] offset:3072
	s_mov_b32 m0, s43
	s_nop 0
	global_load_lds_dwordx4 v132, s[28:29] offset:0
	global_load_lds_dwordx4 v133, s[28:29] offset:1024
	global_load_lds_dwordx4 v134, s[28:29] offset:2048
	global_load_lds_dwordx4 v135, s[28:29] offset:3072
	ds_read_b128 v[64:67], v136 offset:0
	ds_read_b128 v[96:99], v140 offset:0
	ds_read_b128 v[100:103], v140 offset:2048
	ds_read_b128 v[104:107], v140 offset:4096
	ds_read_b128 v[108:111], v140 offset:6144
	ds_read_b128 v[68:71], v136 offset:2048
	ds_read_b128 v[72:75], v136 offset:4096
	ds_read_b128 v[76:79], v136 offset:6144
	s_waitcnt lgkmcnt(3)
	v_mfma_f32_16x16x32_bf16 v[0:3], v[64:67], v[96:99], v[0:3]
	v_mfma_f32_16x16x32_bf16 v[4:7], v[64:67], v[100:103], v[4:7]
	ds_read_b128 v[80:83], v137 offset:0
	v_mfma_f32_16x16x32_bf16 v[8:11], v[64:67], v[104:107], v[8:11]
	v_mfma_f32_16x16x32_bf16 v[12:15], v[64:67], v[108:111], v[12:15]
	ds_read_b128 v[112:115], v141 offset:0
	s_waitcnt lgkmcnt(4)
	v_mfma_f32_16x16x32_bf16 v[16:19], v[68:71], v[96:99], v[16:19]
	v_mfma_f32_16x16x32_bf16 v[20:23], v[68:71], v[100:103], v[20:23]
	ds_read_b128 v[116:119], v141 offset:2048
	v_mfma_f32_16x16x32_bf16 v[24:27], v[68:71], v[104:107], v[24:27]
	v_mfma_f32_16x16x32_bf16 v[28:31], v[68:71], v[108:111], v[28:31]
	ds_read_b128 v[120:123], v141 offset:4096
	s_waitcnt lgkmcnt(5)
	v_mfma_f32_16x16x32_bf16 v[32:35], v[72:75], v[96:99], v[32:35]
	v_mfma_f32_16x16x32_bf16 v[36:39], v[72:75], v[100:103], v[36:39]
	ds_read_b128 v[124:127], v141 offset:6144
	v_mfma_f32_16x16x32_bf16 v[40:43], v[72:75], v[104:107], v[40:43]
	v_mfma_f32_16x16x32_bf16 v[44:47], v[72:75], v[108:111], v[44:47]
	ds_read_b128 v[84:87], v137 offset:2048
	s_waitcnt lgkmcnt(6)
	v_mfma_f32_16x16x32_bf16 v[48:51], v[76:79], v[96:99], v[48:51]
	v_mfma_f32_16x16x32_bf16 v[52:55], v[76:79], v[100:103], v[52:55]
	ds_read_b128 v[88:91], v137 offset:4096
	v_mfma_f32_16x16x32_bf16 v[56:59], v[76:79], v[104:107], v[56:59]
	v_mfma_f32_16x16x32_bf16 v[60:63], v[76:79], v[108:111], v[60:63]
	ds_read_b128 v[92:95], v137 offset:6144
	s_waitcnt lgkmcnt(3)
	v_mfma_f32_16x16x32_bf16 v[0:3], v[80:83], v[112:115], v[0:3]
	v_mfma_f32_16x16x32_bf16 v[4:7], v[80:83], v[116:119], v[4:7]
	v_mfma_f32_16x16x32_bf16 v[8:11], v[80:83], v[120:123], v[8:11]
	v_mfma_f32_16x16x32_bf16 v[12:15], v[80:83], v[124:127], v[12:15]
	s_waitcnt lgkmcnt(2)
	v_mfma_f32_16x16x32_bf16 v[16:19], v[84:87], v[112:115], v[16:19]
	v_mfma_f32_16x16x32_bf16 v[20:23], v[84:87], v[116:119], v[20:23]
	v_mfma_f32_16x16x32_bf16 v[24:27], v[84:87], v[120:123], v[24:27]
	v_mfma_f32_16x16x32_bf16 v[28:31], v[84:87], v[124:127], v[28:31]
	s_waitcnt lgkmcnt(1)
	v_mfma_f32_16x16x32_bf16 v[32:35], v[88:91], v[112:115], v[32:35]
	v_mfma_f32_16x16x32_bf16 v[36:39], v[88:91], v[116:119], v[36:39]
	v_mfma_f32_16x16x32_bf16 v[40:43], v[88:91], v[120:123], v[40:43]
	v_mfma_f32_16x16x32_bf16 v[44:47], v[88:91], v[124:127], v[44:47]
	s_waitcnt lgkmcnt(0)
	v_mfma_f32_16x16x32_bf16 v[48:51], v[92:95], v[112:115], v[48:51]
	v_mfma_f32_16x16x32_bf16 v[52:55], v[92:95], v[116:119], v[52:55]
	v_mfma_f32_16x16x32_bf16 v[56:59], v[92:95], v[120:123], v[56:59]
	v_mfma_f32_16x16x32_bf16 v[60:63], v[92:95], v[124:127], v[60:63]
	s_waitcnt vmcnt(0)
	s_barrier
	s_add_u32 s26, s26, 0x80
	s_addc_u32 s27, s27, 0
	s_add_u32 s28, s28, 0x80
	s_addc_u32 s29, s29, 0
	s_mov_b32 m0, s40
	s_nop 0
	global_load_lds_dwordx4 v132, s[26:27] offset:0
	global_load_lds_dwordx4 v133, s[26:27] offset:1024
	global_load_lds_dwordx4 v134, s[26:27] offset:2048
	global_load_lds_dwordx4 v135, s[26:27] offset:3072
	s_mov_b32 m0, s41
	s_nop 0
	global_load_lds_dwordx4 v132, s[28:29] offset:0
	global_load_lds_dwordx4 v133, s[28:29] offset:1024
	global_load_lds_dwordx4 v134, s[28:29] offset:2048
	global_load_lds_dwordx4 v135, s[28:29] offset:3072
	ds_read_b128 v[64:67], v138 offset:0
	ds_read_b128 v[96:99], v142 offset:0
	ds_read_b128 v[100:103], v142 offset:2048
	ds_read_b128 v[104:107], v142 offset:4096
	ds_read_b128 v[108:111], v142 offset:6144
	ds_read_b128 v[68:71], v138 offset:2048
	ds_read_b128 v[72:75], v138 offset:4096
	ds_read_b128 v[76:79], v138 offset:6144
	s_waitcnt lgkmcnt(3)
	v_mfma_f32_16x16x32_bf16 v[0:3], v[64:67], v[96:99], v[0:3]
	v_mfma_f32_16x16x32_bf16 v[4:7], v[64:67], v[100:103], v[4:7]
	ds_read_b128 v[80:83], v139 offset:0
	v_mfma_f32_16x16x32_bf16 v[8:11], v[64:67], v[104:107], v[8:11]
	v_mfma_f32_16x16x32_bf16 v[12:15], v[64:67], v[108:111], v[12:15]
	ds_read_b128 v[112:115], v143 offset:0
	s_waitcnt lgkmcnt(4)
	v_mfma_f32_16x16x32_bf16 v[16:19], v[68:71], v[96:99], v[16:19]
	v_mfma_f32_16x16x32_bf16 v[20:23], v[68:71], v[100:103], v[20:23]
	ds_read_b128 v[116:119], v143 offset:2048
	v_mfma_f32_16x16x32_bf16 v[24:27], v[68:71], v[104:107], v[24:27]
	v_mfma_f32_16x16x32_bf16 v[28:31], v[68:71], v[108:111], v[28:31]
	ds_read_b128 v[120:123], v143 offset:4096
	s_waitcnt lgkmcnt(5)
	v_mfma_f32_16x16x32_bf16 v[32:35], v[72:75], v[96:99], v[32:35]
	v_mfma_f32_16x16x32_bf16 v[36:39], v[72:75], v[100:103], v[36:39]
	ds_read_b128 v[124:127], v143 offset:6144
	v_mfma_f32_16x16x32_bf16 v[40:43], v[72:75], v[104:107], v[40:43]
	v_mfma_f32_16x16x32_bf16 v[44:47], v[72:75], v[108:111], v[44:47]
	ds_read_b128 v[84:87], v139 offset:2048
	s_waitcnt lgkmcnt(6)
	v_mfma_f32_16x16x32_bf16 v[48:51], v[76:79], v[96:99], v[48:51]
	v_mfma_f32_16x16x32_bf16 v[52:55], v[76:79], v[100:103], v[52:55]
	ds_read_b128 v[88:91], v139 offset:4096
	v_mfma_f32_16x16x32_bf16 v[56:59], v[76:79], v[104:107], v[56:59]
	v_mfma_f32_16x16x32_bf16 v[60:63], v[76:79], v[108:111], v[60:63]
	ds_read_b128 v[92:95], v139 offset:6144
	s_waitcnt lgkmcnt(3)
	v_mfma_f32_16x16x32_bf16 v[0:3], v[80:83], v[112:115], v[0:3]
	v_mfma_f32_16x16x32_bf16 v[4:7], v[80:83], v[116:119], v[4:7]
	v_mfma_f32_16x16x32_bf16 v[8:11], v[80:83], v[120:123], v[8:11]
	v_mfma_f32_16x16x32_bf16 v[12:15], v[80:83], v[124:127], v[12:15]
	s_waitcnt lgkmcnt(2)
	v_mfma_f32_16x16x32_bf16 v[16:19], v[84:87], v[112:115], v[16:19]
	v_mfma_f32_16x16x32_bf16 v[20:23], v[84:87], v[116:119], v[20:23]
	v_mfma_f32_16x16x32_bf16 v[24:27], v[84:87], v[120:123], v[24:27]
	v_mfma_f32_16x16x32_bf16 v[28:31], v[84:87], v[124:127], v[28:31]
	s_waitcnt lgkmcnt(1)
	v_mfma_f32_16x16x32_bf16 v[32:35], v[88:91], v[112:115], v[32:35]
	v_mfma_f32_16x16x32_bf16 v[36:39], v[88:91], v[116:119], v[36:39]
	v_mfma_f32_16x16x32_bf16 v[40:43], v[88:91], v[120:123], v[40:43]
	v_mfma_f32_16x16x32_bf16 v[44:47], v[88:91], v[124:127], v[44:47]
	s_waitcnt lgkmcnt(0)
	v_mfma_f32_16x16x32_bf16 v[48:51], v[92:95], v[112:115], v[48:51]
	v_mfma_f32_16x16x32_bf16 v[52:55], v[92:95], v[116:119], v[52:55]
	v_mfma_f32_16x16x32_bf16 v[56:59], v[92:95], v[120:123], v[56:59]
	v_mfma_f32_16x16x32_bf16 v[60:63], v[92:95], v[124:127], v[60:63]
	s_waitcnt vmcnt(0)
	s_barrier
	s_add_u32 s26, s26, 0x80
	s_addc_u32 s27, s27, 0
	s_add_u32 s28, s28, 0x80
	s_addc_u32 s29, s29, 0
	s_mov_b32 m0, s42
	s_nop 0
	global_load_lds_dwordx4 v132, s[26:27] offset:0
	global_load_lds_dwordx4 v133, s[26:27] offset:1024
	global_load_lds_dwordx4 v134, s[26:27] offset:2048
	global_load_lds_dwordx4 v135, s[26:27] offset:3072
	s_mov_b32 m0, s43
	s_nop 0
	global_load_lds_dwordx4 v132, s[28:29] offset:0
	global_load_lds_dwordx4 v133, s[28:29] offset:1024
	global_load_lds_dwordx4 v134, s[28:29] offset:2048
	global_load_lds_dwordx4 v135, s[28:29] offset:3072
	ds_read_b128 v[64:67], v136 offset:0
	ds_read_b128 v[96:99], v140 offset:0
	ds_read_b128 v[100:103], v140 offset:2048
	ds_read_b128 v[104:107], v140 offset:4096
	ds_read_b128 v[108:111], v140 offset:6144
	ds_read_b128 v[68:71], v136 offset:2048
	ds_read_b128 v[72:75], v136 offset:4096
	ds_read_b128 v[76:79], v136 offset:6144
	s_waitcnt lgkmcnt(3)
	v_mfma_f32_16x16x32_bf16 v[0:3], v[64:67], v[96:99], v[0:3]
	v_mfma_f32_16x16x32_bf16 v[4:7], v[64:67], v[100:103], v[4:7]
	ds_read_b128 v[80:83], v137 offset:0
	v_mfma_f32_16x16x32_bf16 v[8:11], v[64:67], v[104:107], v[8:11]
	v_mfma_f32_16x16x32_bf16 v[12:15], v[64:67], v[108:111], v[12:15]
	ds_read_b128 v[112:115], v141 offset:0
	s_waitcnt lgkmcnt(4)
	v_mfma_f32_16x16x32_bf16 v[16:19], v[68:71], v[96:99], v[16:19]
	v_mfma_f32_16x16x32_bf16 v[20:23], v[68:71], v[100:103], v[20:23]
	ds_read_b128 v[116:119], v141 offset:2048
	v_mfma_f32_16x16x32_bf16 v[24:27], v[68:71], v[104:107], v[24:27]
	v_mfma_f32_16x16x32_bf16 v[28:31], v[68:71], v[108:111], v[28:31]
	ds_read_b128 v[120:123], v141 offset:4096
	s_waitcnt lgkmcnt(5)
	v_mfma_f32_16x16x32_bf16 v[32:35], v[72:75], v[96:99], v[32:35]
	v_mfma_f32_16x16x32_bf16 v[36:39], v[72:75], v[100:103], v[36:39]
	ds_read_b128 v[124:127], v141 offset:6144
	v_mfma_f32_16x16x32_bf16 v[40:43], v[72:75], v[104:107], v[40:43]
	v_mfma_f32_16x16x32_bf16 v[44:47], v[72:75], v[108:111], v[44:47]
	ds_read_b128 v[84:87], v137 offset:2048
	s_waitcnt lgkmcnt(6)
	v_mfma_f32_16x16x32_bf16 v[48:51], v[76:79], v[96:99], v[48:51]
	v_mfma_f32_16x16x32_bf16 v[52:55], v[76:79], v[100:103], v[52:55]
	ds_read_b128 v[88:91], v137 offset:4096
	v_mfma_f32_16x16x32_bf16 v[56:59], v[76:79], v[104:107], v[56:59]
	v_mfma_f32_16x16x32_bf16 v[60:63], v[76:79], v[108:111], v[60:63]
	ds_read_b128 v[92:95], v137 offset:6144
	s_waitcnt lgkmcnt(3)
	v_mfma_f32_16x16x32_bf16 v[0:3], v[80:83], v[112:115], v[0:3]
	v_mfma_f32_16x16x32_bf16 v[4:7], v[80:83], v[116:119], v[4:7]
	v_mfma_f32_16x16x32_bf16 v[8:11], v[80:83], v[120:123], v[8:11]
	v_mfma_f32_16x16x32_bf16 v[12:15], v[80:83], v[124:127], v[12:15]
	s_waitcnt lgkmcnt(2)
	v_mfma_f32_16x16x32_bf16 v[16:19], v[84:87], v[112:115], v[16:19]
	v_mfma_f32_16x16x32_bf16 v[20:23], v[84:87], v[116:119], v[20:23]
	v_mfma_f32_16x16x32_bf16 v[24:27], v[84:87], v[120:123], v[24:27]
	v_mfma_f32_16x16x32_bf16 v[28:31], v[84:87], v[124:127], v[28:31]
	s_waitcnt lgkmcnt(1)
	v_mfma_f32_16x16x32_bf16 v[32:35], v[88:91], v[112:115], v[32:35]
	v_mfma_f32_16x16x32_bf16 v[36:39], v[88:91], v[116:119], v[36:39]
	v_mfma_f32_16x16x32_bf16 v[40:43], v[88:91], v[120:123], v[40:43]
	v_mfma_f32_16x16x32_bf16 v[44:47], v[88:91], v[124:127], v[44:47]
	s_waitcnt lgkmcnt(0)
	v_mfma_f32_16x16x32_bf16 v[48:51], v[92:95], v[112:115], v[48:51]
	v_mfma_f32_16x16x32_bf16 v[52:55], v[92:95], v[116:119], v[52:55]
	v_mfma_f32_16x16x32_bf16 v[56:59], v[92:95], v[120:123], v[56:59]
	v_mfma_f32_16x16x32_bf16 v[60:63], v[92:95], v[124:127], v[60:63]
	s_waitcnt vmcnt(0)
	s_barrier
	s_add_u32 s26, s26, 0xffc80
	s_addc_u32 s27, s27, 0
	s_add_u32 s28, s28, 0x7ffc80
	s_addc_u32 s29, s29, 0
	s_mov_b32 m0, s40
	s_nop 0
	global_load_lds_dwordx4 v132, s[26:27] offset:0
	global_load_lds_dwordx4 v133, s[26:27] offset:1024
	global_load_lds_dwordx4 v134, s[26:27] offset:2048
	global_load_lds_dwordx4 v135, s[26:27] offset:3072
	s_mov_b32 m0, s41
	s_nop 0
	global_load_lds_dwordx4 v132, s[28:29] offset:0
	global_load_lds_dwordx4 v133, s[28:29] offset:1024
	global_load_lds_dwordx4 v134, s[28:29] offset:2048
	global_load_lds_dwordx4 v135, s[28:29] offset:3072
	ds_read_b128 v[64:67], v138 offset:0
	ds_read_b128 v[96:99], v142 offset:0
	ds_read_b128 v[100:103], v142 offset:2048
	ds_read_b128 v[104:107], v142 offset:4096
	ds_read_b128 v[108:111], v142 offset:6144
	ds_read_b128 v[68:71], v138 offset:2048
	ds_read_b128 v[72:75], v138 offset:4096
	ds_read_b128 v[76:79], v138 offset:6144
	s_waitcnt lgkmcnt(3)
	v_mfma_f32_16x16x32_bf16 v[0:3], v[64:67], v[96:99], v[0:3]
	v_mfma_f32_16x16x32_bf16 v[4:7], v[64:67], v[100:103], v[4:7]
	ds_read_b128 v[80:83], v139 offset:0
	v_mfma_f32_16x16x32_bf16 v[8:11], v[64:67], v[104:107], v[8:11]
	v_mfma_f32_16x16x32_bf16 v[12:15], v[64:67], v[108:111], v[12:15]
	ds_read_b128 v[112:115], v143 offset:0
	s_waitcnt lgkmcnt(4)
	v_mfma_f32_16x16x32_bf16 v[16:19], v[68:71], v[96:99], v[16:19]
	v_mfma_f32_16x16x32_bf16 v[20:23], v[68:71], v[100:103], v[20:23]
	ds_read_b128 v[116:119], v143 offset:2048
	v_mfma_f32_16x16x32_bf16 v[24:27], v[68:71], v[104:107], v[24:27]
	v_mfma_f32_16x16x32_bf16 v[28:31], v[68:71], v[108:111], v[28:31]
	ds_read_b128 v[120:123], v143 offset:4096
	s_waitcnt lgkmcnt(5)
	v_mfma_f32_16x16x32_bf16 v[32:35], v[72:75], v[96:99], v[32:35]
	v_mfma_f32_16x16x32_bf16 v[36:39], v[72:75], v[100:103], v[36:39]
	ds_read_b128 v[124:127], v143 offset:6144
	v_mfma_f32_16x16x32_bf16 v[40:43], v[72:75], v[104:107], v[40:43]
	v_mfma_f32_16x16x32_bf16 v[44:47], v[72:75], v[108:111], v[44:47]
	ds_read_b128 v[84:87], v139 offset:2048
	s_waitcnt lgkmcnt(6)
	v_mfma_f32_16x16x32_bf16 v[48:51], v[76:79], v[96:99], v[48:51]
	v_mfma_f32_16x16x32_bf16 v[52:55], v[76:79], v[100:103], v[52:55]
	ds_read_b128 v[88:91], v139 offset:4096
	v_mfma_f32_16x16x32_bf16 v[56:59], v[76:79], v[104:107], v[56:59]
	v_mfma_f32_16x16x32_bf16 v[60:63], v[76:79], v[108:111], v[60:63]
	ds_read_b128 v[92:95], v139 offset:6144
	s_waitcnt lgkmcnt(3)
	v_mfma_f32_16x16x32_bf16 v[0:3], v[80:83], v[112:115], v[0:3]
	v_mfma_f32_16x16x32_bf16 v[4:7], v[80:83], v[116:119], v[4:7]
	v_mfma_f32_16x16x32_bf16 v[8:11], v[80:83], v[120:123], v[8:11]
	v_mfma_f32_16x16x32_bf16 v[12:15], v[80:83], v[124:127], v[12:15]
	s_waitcnt lgkmcnt(2)
	v_mfma_f32_16x16x32_bf16 v[16:19], v[84:87], v[112:115], v[16:19]
	v_mfma_f32_16x16x32_bf16 v[20:23], v[84:87], v[116:119], v[20:23]
	v_mfma_f32_16x16x32_bf16 v[24:27], v[84:87], v[120:123], v[24:27]
	v_mfma_f32_16x16x32_bf16 v[28:31], v[84:87], v[124:127], v[28:31]
	s_waitcnt lgkmcnt(1)
	v_mfma_f32_16x16x32_bf16 v[32:35], v[88:91], v[112:115], v[32:35]
	v_mfma_f32_16x16x32_bf16 v[36:39], v[88:91], v[116:119], v[36:39]
	v_mfma_f32_16x16x32_bf16 v[40:43], v[88:91], v[120:123], v[40:43]
	v_mfma_f32_16x16x32_bf16 v[44:47], v[88:91], v[124:127], v[44:47]
	s_waitcnt lgkmcnt(0)
	v_mfma_f32_16x16x32_bf16 v[48:51], v[92:95], v[112:115], v[48:51]
	v_mfma_f32_16x16x32_bf16 v[52:55], v[92:95], v[116:119], v[52:55]
	v_mfma_f32_16x16x32_bf16 v[56:59], v[92:95], v[120:123], v[56:59]
	v_mfma_f32_16x16x32_bf16 v[60:63], v[92:95], v[124:127], v[60:63]
	s_nop 7
	global_load_dwordx2 v[64:65], v236, s[36:37] offset:0
	global_load_dwordx2 v[66:67], v236, s[36:37] offset:32
	global_load_dwordx2 v[68:69], v236, s[36:37] offset:64
	global_load_dwordx2 v[70:71], v236, s[36:37] offset:96
	global_load_dwordx2 v[72:73], v237, s[36:37] offset:0
	global_load_dwordx2 v[74:75], v237, s[36:37] offset:32
	global_load_dwordx2 v[76:77], v237, s[36:37] offset:64
	global_load_dwordx2 v[78:79], v237, s[36:37] offset:96
	global_load_dwordx2 v[80:81], v238, s[36:37] offset:0
	global_load_dwordx2 v[82:83], v238, s[36:37] offset:32
	global_load_dwordx2 v[84:85], v238, s[36:37] offset:64
	global_load_dwordx2 v[86:87], v238, s[36:37] offset:96
	global_load_dwordx2 v[88:89], v239, s[36:37] offset:0
	global_load_dwordx2 v[90:91], v239, s[36:37] offset:32
	global_load_dwordx2 v[92:93], v239, s[36:37] offset:64
	global_load_dwordx2 v[94:95], v239, s[36:37] offset:96
	s_waitcnt vmcnt(15)
	v_lshlrev_b32_e32 v96, 16, v64
	v_and_b32_e32 v97, 0xffff0000, v64
	v_lshlrev_b32_e32 v98, 16, v65
	v_and_b32_e32 v99, 0xffff0000, v65
	v_mul_f32_e32 v96, 0xbfb8aa3b, v96
	v_mul_f32_e32 v97, 0xbfb8aa3b, v97
	v_mul_f32_e32 v98, 0xbfb8aa3b, v98
	v_mul_f32_e32 v99, 0xbfb8aa3b, v99
	v_exp_f32_e32 v96, v96
	v_exp_f32_e32 v97, v97
	v_exp_f32_e32 v98, v98
	v_exp_f32_e32 v99, v99
	v_add_f32_e32 v96, 1.0, v96
	v_add_f32_e32 v97, 1.0, v97
	v_add_f32_e32 v98, 1.0, v98
	v_add_f32_e32 v99, 1.0, v99
	v_rcp_f32_e32 v96, v96
	v_rcp_f32_e32 v97, v97
	v_rcp_f32_e32 v98, v98
	v_rcp_f32_e32 v99, v99
	s_nop 0
	v_mul_f32_e32 v146, v96, v0
	v_mul_f32_e32 v147, v97, v1
	v_mul_f32_e32 v148, v98, v2
	v_mul_f32_e32 v149, v99, v3
	s_waitcnt vmcnt(14)
	v_lshlrev_b32_e32 v100, 16, v66
	v_and_b32_e32 v101, 0xffff0000, v66
	v_lshlrev_b32_e32 v102, 16, v67
	v_and_b32_e32 v103, 0xffff0000, v67
	v_mul_f32_e32 v100, 0xbfb8aa3b, v100
	v_mul_f32_e32 v101, 0xbfb8aa3b, v101
	v_mul_f32_e32 v102, 0xbfb8aa3b, v102
	v_mul_f32_e32 v103, 0xbfb8aa3b, v103
	v_exp_f32_e32 v100, v100
	v_exp_f32_e32 v101, v101
	v_exp_f32_e32 v102, v102
	v_exp_f32_e32 v103, v103
	v_add_f32_e32 v100, 1.0, v100
	v_add_f32_e32 v101, 1.0, v101
	v_add_f32_e32 v102, 1.0, v102
	v_add_f32_e32 v103, 1.0, v103
	v_rcp_f32_e32 v100, v100
	v_rcp_f32_e32 v101, v101
	v_rcp_f32_e32 v102, v102
	v_rcp_f32_e32 v103, v103
	s_nop 0
	v_mul_f32_e32 v162, v100, v16
	v_mul_f32_e32 v163, v101, v17
	v_mul_f32_e32 v164, v102, v18
	v_mul_f32_e32 v165, v103, v19
	s_waitcnt vmcnt(13)
	v_lshlrev_b32_e32 v96, 16, v68
	v_and_b32_e32 v97, 0xffff0000, v68
	v_lshlrev_b32_e32 v98, 16, v69
	v_and_b32_e32 v99, 0xffff0000, v69
	v_mul_f32_e32 v96, 0xbfb8aa3b, v96
	v_mul_f32_e32 v97, 0xbfb8aa3b, v97
	v_mul_f32_e32 v98, 0xbfb8aa3b, v98
	v_mul_f32_e32 v99, 0xbfb8aa3b, v99
	v_exp_f32_e32 v96, v96
	v_exp_f32_e32 v97, v97
	v_exp_f32_e32 v98, v98
	v_exp_f32_e32 v99, v99
	v_add_f32_e32 v96, 1.0, v96
	v_add_f32_e32 v97, 1.0, v97
	v_add_f32_e32 v98, 1.0, v98
	v_add_f32_e32 v99, 1.0, v99
	v_rcp_f32_e32 v96, v96
	v_rcp_f32_e32 v97, v97
	v_rcp_f32_e32 v98, v98
	v_rcp_f32_e32 v99, v99
	s_nop 0
	v_mul_f32_e32 v178, v96, v32
	v_mul_f32_e32 v179, v97, v33
	v_mul_f32_e32 v180, v98, v34
	v_mul_f32_e32 v181, v99, v35
	s_waitcnt vmcnt(12)
	v_lshlrev_b32_e32 v100, 16, v70
	v_and_b32_e32 v101, 0xffff0000, v70
	v_lshlrev_b32_e32 v102, 16, v71
	v_and_b32_e32 v103, 0xffff0000, v71
	v_mul_f32_e32 v100, 0xbfb8aa3b, v100
	v_mul_f32_e32 v101, 0xbfb8aa3b, v101
	v_mul_f32_e32 v102, 0xbfb8aa3b, v102
	v_mul_f32_e32 v103, 0xbfb8aa3b, v103
	v_exp_f32_e32 v100, v100
	v_exp_f32_e32 v101, v101
	v_exp_f32_e32 v102, v102
	v_exp_f32_e32 v103, v103
	v_add_f32_e32 v100, 1.0, v100
	v_add_f32_e32 v101, 1.0, v101
	v_add_f32_e32 v102, 1.0, v102
	v_add_f32_e32 v103, 1.0, v103
	v_rcp_f32_e32 v100, v100
	v_rcp_f32_e32 v101, v101
	v_rcp_f32_e32 v102, v102
	v_rcp_f32_e32 v103, v103
	s_nop 0
	v_mul_f32_e32 v194, v100, v48
	v_mul_f32_e32 v195, v101, v49
	v_mul_f32_e32 v196, v102, v50
	v_mul_f32_e32 v197, v103, v51
	s_waitcnt vmcnt(11)
	v_lshlrev_b32_e32 v96, 16, v72
	v_and_b32_e32 v97, 0xffff0000, v72
	v_lshlrev_b32_e32 v98, 16, v73
	v_and_b32_e32 v99, 0xffff0000, v73
	v_mul_f32_e32 v96, 0xbfb8aa3b, v96
	v_mul_f32_e32 v97, 0xbfb8aa3b, v97
	v_mul_f32_e32 v98, 0xbfb8aa3b, v98
	v_mul_f32_e32 v99, 0xbfb8aa3b, v99
	v_exp_f32_e32 v96, v96
	v_exp_f32_e32 v97, v97
	v_exp_f32_e32 v98, v98
	v_exp_f32_e32 v99, v99
	v_add_f32_e32 v96, 1.0, v96
	v_add_f32_e32 v97, 1.0, v97
	v_add_f32_e32 v98, 1.0, v98
	v_add_f32_e32 v99, 1.0, v99
	v_rcp_f32_e32 v96, v96
	v_rcp_f32_e32 v97, v97
	v_rcp_f32_e32 v98, v98
	v_rcp_f32_e32 v99, v99
	s_nop 0
	v_mul_f32_e32 v150, v96, v4
	v_mul_f32_e32 v151, v97, v5
	v_mul_f32_e32 v152, v98, v6
	v_mul_f32_e32 v153, v99, v7
	s_waitcnt vmcnt(10)
	v_lshlrev_b32_e32 v100, 16, v74
	v_and_b32_e32 v101, 0xffff0000, v74
	v_lshlrev_b32_e32 v102, 16, v75
	v_and_b32_e32 v103, 0xffff0000, v75
	v_mul_f32_e32 v100, 0xbfb8aa3b, v100
	v_mul_f32_e32 v101, 0xbfb8aa3b, v101
	v_mul_f32_e32 v102, 0xbfb8aa3b, v102
	v_mul_f32_e32 v103, 0xbfb8aa3b, v103
	v_exp_f32_e32 v100, v100
	v_exp_f32_e32 v101, v101
	v_exp_f32_e32 v102, v102
	v_exp_f32_e32 v103, v103
	v_add_f32_e32 v100, 1.0, v100
	v_add_f32_e32 v101, 1.0, v101
	v_add_f32_e32 v102, 1.0, v102
	v_add_f32_e32 v103, 1.0, v103
	v_rcp_f32_e32 v100, v100
	v_rcp_f32_e32 v101, v101
	v_rcp_f32_e32 v102, v102
	v_rcp_f32_e32 v103, v103
	s_nop 0
	v_mul_f32_e32 v166, v100, v20
	v_mul_f32_e32 v167, v101, v21
	v_mul_f32_e32 v168, v102, v22
	v_mul_f32_e32 v169, v103, v23
	s_waitcnt vmcnt(9)
	v_lshlrev_b32_e32 v96, 16, v76
	v_and_b32_e32 v97, 0xffff0000, v76
	v_lshlrev_b32_e32 v98, 16, v77
	v_and_b32_e32 v99, 0xffff0000, v77
	v_mul_f32_e32 v96, 0xbfb8aa3b, v96
	v_mul_f32_e32 v97, 0xbfb8aa3b, v97
	v_mul_f32_e32 v98, 0xbfb8aa3b, v98
	v_mul_f32_e32 v99, 0xbfb8aa3b, v99
	v_exp_f32_e32 v96, v96
	v_exp_f32_e32 v97, v97
	v_exp_f32_e32 v98, v98
	v_exp_f32_e32 v99, v99
	v_add_f32_e32 v96, 1.0, v96
	v_add_f32_e32 v97, 1.0, v97
	v_add_f32_e32 v98, 1.0, v98
	v_add_f32_e32 v99, 1.0, v99
	v_rcp_f32_e32 v96, v96
	v_rcp_f32_e32 v97, v97
	v_rcp_f32_e32 v98, v98
	v_rcp_f32_e32 v99, v99
	s_nop 0
	v_mul_f32_e32 v182, v96, v36
	v_mul_f32_e32 v183, v97, v37
	v_mul_f32_e32 v184, v98, v38
	v_mul_f32_e32 v185, v99, v39
	s_waitcnt vmcnt(8)
	v_lshlrev_b32_e32 v100, 16, v78
	v_and_b32_e32 v101, 0xffff0000, v78
	v_lshlrev_b32_e32 v102, 16, v79
	v_and_b32_e32 v103, 0xffff0000, v79
	v_mul_f32_e32 v100, 0xbfb8aa3b, v100
	v_mul_f32_e32 v101, 0xbfb8aa3b, v101
	v_mul_f32_e32 v102, 0xbfb8aa3b, v102
	v_mul_f32_e32 v103, 0xbfb8aa3b, v103
	v_exp_f32_e32 v100, v100
	v_exp_f32_e32 v101, v101
	v_exp_f32_e32 v102, v102
	v_exp_f32_e32 v103, v103
	v_add_f32_e32 v100, 1.0, v100
	v_add_f32_e32 v101, 1.0, v101
	v_add_f32_e32 v102, 1.0, v102
	v_add_f32_e32 v103, 1.0, v103
	v_rcp_f32_e32 v100, v100
	v_rcp_f32_e32 v101, v101
	v_rcp_f32_e32 v102, v102
	v_rcp_f32_e32 v103, v103
	s_nop 0
	v_mul_f32_e32 v200, v100, v52
	v_mul_f32_e32 v201, v101, v53
	v_mul_f32_e32 v202, v102, v54
	v_mul_f32_e32 v203, v103, v55
	s_waitcnt vmcnt(7)
	v_lshlrev_b32_e32 v96, 16, v80
	v_and_b32_e32 v97, 0xffff0000, v80
	v_lshlrev_b32_e32 v98, 16, v81
	v_and_b32_e32 v99, 0xffff0000, v81
	v_mul_f32_e32 v96, 0xbfb8aa3b, v96
	v_mul_f32_e32 v97, 0xbfb8aa3b, v97
	v_mul_f32_e32 v98, 0xbfb8aa3b, v98
	v_mul_f32_e32 v99, 0xbfb8aa3b, v99
	v_exp_f32_e32 v96, v96
	v_exp_f32_e32 v97, v97
	v_exp_f32_e32 v98, v98
	v_exp_f32_e32 v99, v99
	v_add_f32_e32 v96, 1.0, v96
	v_add_f32_e32 v97, 1.0, v97
	v_add_f32_e32 v98, 1.0, v98
	v_add_f32_e32 v99, 1.0, v99
	v_rcp_f32_e32 v96, v96
	v_rcp_f32_e32 v97, v97
	v_rcp_f32_e32 v98, v98
	v_rcp_f32_e32 v99, v99
	s_nop 0
	v_mul_f32_e32 v154, v96, v8
	v_mul_f32_e32 v155, v97, v9
	v_mul_f32_e32 v156, v98, v10
	v_mul_f32_e32 v157, v99, v11
	s_waitcnt vmcnt(6)
	v_lshlrev_b32_e32 v100, 16, v82
	v_and_b32_e32 v101, 0xffff0000, v82
	v_lshlrev_b32_e32 v102, 16, v83
	v_and_b32_e32 v103, 0xffff0000, v83
	v_mul_f32_e32 v100, 0xbfb8aa3b, v100
	v_mul_f32_e32 v101, 0xbfb8aa3b, v101
	v_mul_f32_e32 v102, 0xbfb8aa3b, v102
	v_mul_f32_e32 v103, 0xbfb8aa3b, v103
	v_exp_f32_e32 v100, v100
	v_exp_f32_e32 v101, v101
	v_exp_f32_e32 v102, v102
	v_exp_f32_e32 v103, v103
	v_add_f32_e32 v100, 1.0, v100
	v_add_f32_e32 v101, 1.0, v101
	v_add_f32_e32 v102, 1.0, v102
	v_add_f32_e32 v103, 1.0, v103
	v_rcp_f32_e32 v100, v100
	v_rcp_f32_e32 v101, v101
	v_rcp_f32_e32 v102, v102
	v_rcp_f32_e32 v103, v103
	s_nop 0
	v_mul_f32_e32 v170, v100, v24
	v_mul_f32_e32 v171, v101, v25
	v_mul_f32_e32 v172, v102, v26
	v_mul_f32_e32 v173, v103, v27
	s_waitcnt vmcnt(5)
	v_lshlrev_b32_e32 v96, 16, v84
	v_and_b32_e32 v97, 0xffff0000, v84
	v_lshlrev_b32_e32 v98, 16, v85
	v_and_b32_e32 v99, 0xffff0000, v85
	v_mul_f32_e32 v96, 0xbfb8aa3b, v96
	v_mul_f32_e32 v97, 0xbfb8aa3b, v97
	v_mul_f32_e32 v98, 0xbfb8aa3b, v98
	v_mul_f32_e32 v99, 0xbfb8aa3b, v99
	v_exp_f32_e32 v96, v96
	v_exp_f32_e32 v97, v97
	v_exp_f32_e32 v98, v98
	v_exp_f32_e32 v99, v99
	v_add_f32_e32 v96, 1.0, v96
	v_add_f32_e32 v97, 1.0, v97
	v_add_f32_e32 v98, 1.0, v98
	v_add_f32_e32 v99, 1.0, v99
	v_rcp_f32_e32 v96, v96
	v_rcp_f32_e32 v97, v97
	v_rcp_f32_e32 v98, v98
	v_rcp_f32_e32 v99, v99
	s_nop 0
	v_mul_f32_e32 v186, v96, v40
	v_mul_f32_e32 v187, v97, v41
	v_mul_f32_e32 v188, v98, v42
	v_mul_f32_e32 v189, v99, v43
	s_waitcnt vmcnt(4)
	v_lshlrev_b32_e32 v100, 16, v86
	v_and_b32_e32 v101, 0xffff0000, v86
	v_lshlrev_b32_e32 v102, 16, v87
	v_and_b32_e32 v103, 0xffff0000, v87
	v_mul_f32_e32 v100, 0xbfb8aa3b, v100
	v_mul_f32_e32 v101, 0xbfb8aa3b, v101
	v_mul_f32_e32 v102, 0xbfb8aa3b, v102
	v_mul_f32_e32 v103, 0xbfb8aa3b, v103
	v_exp_f32_e32 v100, v100
	v_exp_f32_e32 v101, v101
	v_exp_f32_e32 v102, v102
	v_exp_f32_e32 v103, v103
	v_add_f32_e32 v100, 1.0, v100
	v_add_f32_e32 v101, 1.0, v101
	v_add_f32_e32 v102, 1.0, v102
	v_add_f32_e32 v103, 1.0, v103
	v_rcp_f32_e32 v100, v100
	v_rcp_f32_e32 v101, v101
	v_rcp_f32_e32 v102, v102
	v_rcp_f32_e32 v103, v103
	s_nop 0
	v_mul_f32_e32 v208, v100, v56
	v_mul_f32_e32 v209, v101, v57
	v_mul_f32_e32 v210, v102, v58
	v_mul_f32_e32 v211, v103, v59
	s_waitcnt vmcnt(3)
	v_lshlrev_b32_e32 v96, 16, v88
	v_and_b32_e32 v97, 0xffff0000, v88
	v_lshlrev_b32_e32 v98, 16, v89
	v_and_b32_e32 v99, 0xffff0000, v89
	v_mul_f32_e32 v96, 0xbfb8aa3b, v96
	v_mul_f32_e32 v97, 0xbfb8aa3b, v97
	v_mul_f32_e32 v98, 0xbfb8aa3b, v98
	v_mul_f32_e32 v99, 0xbfb8aa3b, v99
	v_exp_f32_e32 v96, v96
	v_exp_f32_e32 v97, v97
	v_exp_f32_e32 v98, v98
	v_exp_f32_e32 v99, v99
	v_add_f32_e32 v96, 1.0, v96
	v_add_f32_e32 v97, 1.0, v97
	v_add_f32_e32 v98, 1.0, v98
	v_add_f32_e32 v99, 1.0, v99
	v_rcp_f32_e32 v96, v96
	v_rcp_f32_e32 v97, v97
	v_rcp_f32_e32 v98, v98
	v_rcp_f32_e32 v99, v99
	s_nop 0
	v_mul_f32_e32 v158, v96, v12
	v_mul_f32_e32 v159, v97, v13
	v_mul_f32_e32 v160, v98, v14
	v_mul_f32_e32 v161, v99, v15
	s_waitcnt vmcnt(2)
	v_lshlrev_b32_e32 v100, 16, v90
	v_and_b32_e32 v101, 0xffff0000, v90
	v_lshlrev_b32_e32 v102, 16, v91
	v_and_b32_e32 v103, 0xffff0000, v91
	v_mul_f32_e32 v100, 0xbfb8aa3b, v100
	v_mul_f32_e32 v101, 0xbfb8aa3b, v101
	v_mul_f32_e32 v102, 0xbfb8aa3b, v102
	v_mul_f32_e32 v103, 0xbfb8aa3b, v103
	v_exp_f32_e32 v100, v100
	v_exp_f32_e32 v101, v101
	v_exp_f32_e32 v102, v102
	v_exp_f32_e32 v103, v103
	v_add_f32_e32 v100, 1.0, v100
	v_add_f32_e32 v101, 1.0, v101
	v_add_f32_e32 v102, 1.0, v102
	v_add_f32_e32 v103, 1.0, v103
	v_rcp_f32_e32 v100, v100
	v_rcp_f32_e32 v101, v101
	v_rcp_f32_e32 v102, v102
	v_rcp_f32_e32 v103, v103
	s_nop 0
	v_mul_f32_e32 v174, v100, v28
	v_mul_f32_e32 v175, v101, v29
	v_mul_f32_e32 v176, v102, v30
	v_mul_f32_e32 v177, v103, v31
	s_waitcnt vmcnt(1)
	v_lshlrev_b32_e32 v96, 16, v92
	v_and_b32_e32 v97, 0xffff0000, v92
	v_lshlrev_b32_e32 v98, 16, v93
	v_and_b32_e32 v99, 0xffff0000, v93
	v_mul_f32_e32 v96, 0xbfb8aa3b, v96
	v_mul_f32_e32 v97, 0xbfb8aa3b, v97
	v_mul_f32_e32 v98, 0xbfb8aa3b, v98
	v_mul_f32_e32 v99, 0xbfb8aa3b, v99
	v_exp_f32_e32 v96, v96
	v_exp_f32_e32 v97, v97
	v_exp_f32_e32 v98, v98
	v_exp_f32_e32 v99, v99
	v_add_f32_e32 v96, 1.0, v96
	v_add_f32_e32 v97, 1.0, v97
	v_add_f32_e32 v98, 1.0, v98
	v_add_f32_e32 v99, 1.0, v99
	v_rcp_f32_e32 v96, v96
	v_rcp_f32_e32 v97, v97
	v_rcp_f32_e32 v98, v98
	v_rcp_f32_e32 v99, v99
	s_nop 0
	v_mul_f32_e32 v190, v96, v44
	v_mul_f32_e32 v191, v97, v45
	v_mul_f32_e32 v192, v98, v46
	v_mul_f32_e32 v193, v99, v47
	s_waitcnt vmcnt(0)
	v_lshlrev_b32_e32 v100, 16, v94
	v_and_b32_e32 v101, 0xffff0000, v94
	v_lshlrev_b32_e32 v102, 16, v95
	v_and_b32_e32 v103, 0xffff0000, v95
	v_mul_f32_e32 v100, 0xbfb8aa3b, v100
	v_mul_f32_e32 v101, 0xbfb8aa3b, v101
	v_mul_f32_e32 v102, 0xbfb8aa3b, v102
	v_mul_f32_e32 v103, 0xbfb8aa3b, v103
	v_exp_f32_e32 v100, v100
	v_exp_f32_e32 v101, v101
	v_exp_f32_e32 v102, v102
	v_exp_f32_e32 v103, v103
	v_add_f32_e32 v100, 1.0, v100
	v_add_f32_e32 v101, 1.0, v101
	v_add_f32_e32 v102, 1.0, v102
	v_add_f32_e32 v103, 1.0, v103
	v_rcp_f32_e32 v100, v100
	v_rcp_f32_e32 v101, v101
	v_rcp_f32_e32 v102, v102
	v_rcp_f32_e32 v103, v103
	s_nop 0
	v_mul_f32_e32 v232, v100, v60
	v_mul_f32_e32 v233, v101, v61
	v_mul_f32_e32 v234, v102, v62
	v_mul_f32_e32 v235, v103, v63
	s_waitcnt vmcnt(0)
	s_barrier
	s_add_u32 s26, s26, 0x80
	s_addc_u32 s27, s27, 0
	s_add_u32 s28, s28, 0x80
	s_addc_u32 s29, s29, 0
	s_mov_b32 m0, s42
	s_nop 0
	global_load_lds_dwordx4 v132, s[26:27] offset:0
	global_load_lds_dwordx4 v133, s[26:27] offset:1024
	global_load_lds_dwordx4 v134, s[26:27] offset:2048
	global_load_lds_dwordx4 v135, s[26:27] offset:3072
	s_mov_b32 m0, s43
	s_nop 0
	global_load_lds_dwordx4 v132, s[28:29] offset:0
	global_load_lds_dwordx4 v133, s[28:29] offset:1024
	global_load_lds_dwordx4 v134, s[28:29] offset:2048
	global_load_lds_dwordx4 v135, s[28:29] offset:3072
	ds_read_b128 v[64:67], v136 offset:0
	ds_read_b128 v[96:99], v140 offset:0
	ds_read_b128 v[100:103], v140 offset:2048
	ds_read_b128 v[104:107], v140 offset:4096
	ds_read_b128 v[108:111], v140 offset:6144
	ds_read_b128 v[68:71], v136 offset:2048
	ds_read_b128 v[72:75], v136 offset:4096
	ds_read_b128 v[76:79], v136 offset:6144
	s_waitcnt lgkmcnt(3)
	v_mfma_f32_16x16x32_bf16 v[0:3], v[64:67], v[96:99], 0
	v_mfma_f32_16x16x32_bf16 v[4:7], v[64:67], v[100:103], 0
	ds_read_b128 v[80:83], v137 offset:0
	v_mfma_f32_16x16x32_bf16 v[8:11], v[64:67], v[104:107], 0
	v_mfma_f32_16x16x32_bf16 v[12:15], v[64:67], v[108:111], 0
	ds_read_b128 v[112:115], v141 offset:0
	s_waitcnt lgkmcnt(4)
	v_mfma_f32_16x16x32_bf16 v[16:19], v[68:71], v[96:99], 0
	v_mfma_f32_16x16x32_bf16 v[20:23], v[68:71], v[100:103], 0
	ds_read_b128 v[116:119], v141 offset:2048
	v_mfma_f32_16x16x32_bf16 v[24:27], v[68:71], v[104:107], 0
	v_mfma_f32_16x16x32_bf16 v[28:31], v[68:71], v[108:111], 0
	ds_read_b128 v[120:123], v141 offset:4096
	s_waitcnt lgkmcnt(5)
	v_mfma_f32_16x16x32_bf16 v[32:35], v[72:75], v[96:99], 0
	v_mfma_f32_16x16x32_bf16 v[36:39], v[72:75], v[100:103], 0
	ds_read_b128 v[124:127], v141 offset:6144
	v_mfma_f32_16x16x32_bf16 v[40:43], v[72:75], v[104:107], 0
	v_mfma_f32_16x16x32_bf16 v[44:47], v[72:75], v[108:111], 0
	ds_read_b128 v[84:87], v137 offset:2048
	s_waitcnt lgkmcnt(6)
	v_mfma_f32_16x16x32_bf16 v[48:51], v[76:79], v[96:99], 0
	v_mfma_f32_16x16x32_bf16 v[52:55], v[76:79], v[100:103], 0
	ds_read_b128 v[88:91], v137 offset:4096
	v_mfma_f32_16x16x32_bf16 v[56:59], v[76:79], v[104:107], 0
	v_mfma_f32_16x16x32_bf16 v[60:63], v[76:79], v[108:111], 0
	ds_read_b128 v[92:95], v137 offset:6144
	s_waitcnt lgkmcnt(3)
	v_mfma_f32_16x16x32_bf16 v[0:3], v[80:83], v[112:115], v[0:3]
	v_mfma_f32_16x16x32_bf16 v[4:7], v[80:83], v[116:119], v[4:7]
	v_mfma_f32_16x16x32_bf16 v[8:11], v[80:83], v[120:123], v[8:11]
	v_mfma_f32_16x16x32_bf16 v[12:15], v[80:83], v[124:127], v[12:15]
	s_waitcnt lgkmcnt(2)
	v_mfma_f32_16x16x32_bf16 v[16:19], v[84:87], v[112:115], v[16:19]
	v_mfma_f32_16x16x32_bf16 v[20:23], v[84:87], v[116:119], v[20:23]
	v_mfma_f32_16x16x32_bf16 v[24:27], v[84:87], v[120:123], v[24:27]
	v_mfma_f32_16x16x32_bf16 v[28:31], v[84:87], v[124:127], v[28:31]
	s_waitcnt lgkmcnt(1)
	v_mfma_f32_16x16x32_bf16 v[32:35], v[88:91], v[112:115], v[32:35]
	v_mfma_f32_16x16x32_bf16 v[36:39], v[88:91], v[116:119], v[36:39]
	v_mfma_f32_16x16x32_bf16 v[40:43], v[88:91], v[120:123], v[40:43]
	v_mfma_f32_16x16x32_bf16 v[44:47], v[88:91], v[124:127], v[44:47]
	s_waitcnt lgkmcnt(0)
	v_mfma_f32_16x16x32_bf16 v[48:51], v[92:95], v[112:115], v[48:51]
	v_mfma_f32_16x16x32_bf16 v[52:55], v[92:95], v[116:119], v[52:55]
	v_mfma_f32_16x16x32_bf16 v[56:59], v[92:95], v[120:123], v[56:59]
	v_mfma_f32_16x16x32_bf16 v[60:63], v[92:95], v[124:127], v[60:63]
	s_waitcnt vmcnt(0)
	s_barrier
	s_add_u32 s26, s26, 0x80
	s_addc_u32 s27, s27, 0
	s_add_u32 s28, s28, 0x80
	s_addc_u32 s29, s29, 0
	s_mov_b32 m0, s40
	s_nop 0
	global_load_lds_dwordx4 v132, s[26:27] offset:0
	global_load_lds_dwordx4 v133, s[26:27] offset:1024
	global_load_lds_dwordx4 v134, s[26:27] offset:2048
	global_load_lds_dwordx4 v135, s[26:27] offset:3072
	s_mov_b32 m0, s41
	s_nop 0
	global_load_lds_dwordx4 v132, s[28:29] offset:0
	global_load_lds_dwordx4 v133, s[28:29] offset:1024
	global_load_lds_dwordx4 v134, s[28:29] offset:2048
	global_load_lds_dwordx4 v135, s[28:29] offset:3072
	ds_read_b128 v[64:67], v138 offset:0
	ds_read_b128 v[96:99], v142 offset:0
	ds_read_b128 v[100:103], v142 offset:2048
	ds_read_b128 v[104:107], v142 offset:4096
	ds_read_b128 v[108:111], v142 offset:6144
	ds_read_b128 v[68:71], v138 offset:2048
	ds_read_b128 v[72:75], v138 offset:4096
	ds_read_b128 v[76:79], v138 offset:6144
	s_waitcnt lgkmcnt(3)
	v_mfma_f32_16x16x32_bf16 v[0:3], v[64:67], v[96:99], v[0:3]
	v_mfma_f32_16x16x32_bf16 v[4:7], v[64:67], v[100:103], v[4:7]
	ds_read_b128 v[80:83], v139 offset:0
	v_mfma_f32_16x16x32_bf16 v[8:11], v[64:67], v[104:107], v[8:11]
	v_mfma_f32_16x16x32_bf16 v[12:15], v[64:67], v[108:111], v[12:15]
	ds_read_b128 v[112:115], v143 offset:0
	s_waitcnt lgkmcnt(4)
	v_mfma_f32_16x16x32_bf16 v[16:19], v[68:71], v[96:99], v[16:19]
	v_mfma_f32_16x16x32_bf16 v[20:23], v[68:71], v[100:103], v[20:23]
	ds_read_b128 v[116:119], v143 offset:2048
	v_mfma_f32_16x16x32_bf16 v[24:27], v[68:71], v[104:107], v[24:27]
	v_mfma_f32_16x16x32_bf16 v[28:31], v[68:71], v[108:111], v[28:31]
	ds_read_b128 v[120:123], v143 offset:4096
	s_waitcnt lgkmcnt(5)
	v_mfma_f32_16x16x32_bf16 v[32:35], v[72:75], v[96:99], v[32:35]
	v_mfma_f32_16x16x32_bf16 v[36:39], v[72:75], v[100:103], v[36:39]
	ds_read_b128 v[124:127], v143 offset:6144
	v_mfma_f32_16x16x32_bf16 v[40:43], v[72:75], v[104:107], v[40:43]
	v_mfma_f32_16x16x32_bf16 v[44:47], v[72:75], v[108:111], v[44:47]
	ds_read_b128 v[84:87], v139 offset:2048
	s_waitcnt lgkmcnt(6)
	v_mfma_f32_16x16x32_bf16 v[48:51], v[76:79], v[96:99], v[48:51]
	v_mfma_f32_16x16x32_bf16 v[52:55], v[76:79], v[100:103], v[52:55]
	ds_read_b128 v[88:91], v139 offset:4096
	v_mfma_f32_16x16x32_bf16 v[56:59], v[76:79], v[104:107], v[56:59]
	v_mfma_f32_16x16x32_bf16 v[60:63], v[76:79], v[108:111], v[60:63]
	ds_read_b128 v[92:95], v139 offset:6144
	s_waitcnt lgkmcnt(3)
	v_mfma_f32_16x16x32_bf16 v[0:3], v[80:83], v[112:115], v[0:3]
	v_mfma_f32_16x16x32_bf16 v[4:7], v[80:83], v[116:119], v[4:7]
	v_mfma_f32_16x16x32_bf16 v[8:11], v[80:83], v[120:123], v[8:11]
	v_mfma_f32_16x16x32_bf16 v[12:15], v[80:83], v[124:127], v[12:15]
	s_waitcnt lgkmcnt(2)
	v_mfma_f32_16x16x32_bf16 v[16:19], v[84:87], v[112:115], v[16:19]
	v_mfma_f32_16x16x32_bf16 v[20:23], v[84:87], v[116:119], v[20:23]
	v_mfma_f32_16x16x32_bf16 v[24:27], v[84:87], v[120:123], v[24:27]
	v_mfma_f32_16x16x32_bf16 v[28:31], v[84:87], v[124:127], v[28:31]
	s_waitcnt lgkmcnt(1)
	v_mfma_f32_16x16x32_bf16 v[32:35], v[88:91], v[112:115], v[32:35]
	v_mfma_f32_16x16x32_bf16 v[36:39], v[88:91], v[116:119], v[36:39]
	v_mfma_f32_16x16x32_bf16 v[40:43], v[88:91], v[120:123], v[40:43]
	v_mfma_f32_16x16x32_bf16 v[44:47], v[88:91], v[124:127], v[44:47]
	s_waitcnt lgkmcnt(0)
	v_mfma_f32_16x16x32_bf16 v[48:51], v[92:95], v[112:115], v[48:51]
	v_mfma_f32_16x16x32_bf16 v[52:55], v[92:95], v[116:119], v[52:55]
	v_mfma_f32_16x16x32_bf16 v[56:59], v[92:95], v[120:123], v[56:59]
	v_mfma_f32_16x16x32_bf16 v[60:63], v[92:95], v[124:127], v[60:63]
	s_waitcnt vmcnt(0)
	s_barrier
	s_add_u32 s26, s26, 0x80
	s_addc_u32 s27, s27, 0
	s_add_u32 s28, s28, 0x80
	s_addc_u32 s29, s29, 0
	s_mov_b32 m0, s42
	s_nop 0
	global_load_lds_dwordx4 v132, s[26:27] offset:0
	global_load_lds_dwordx4 v133, s[26:27] offset:1024
	global_load_lds_dwordx4 v134, s[26:27] offset:2048
	global_load_lds_dwordx4 v135, s[26:27] offset:3072
	s_mov_b32 m0, s43
	s_nop 0
	global_load_lds_dwordx4 v132, s[28:29] offset:0
	global_load_lds_dwordx4 v133, s[28:29] offset:1024
	global_load_lds_dwordx4 v134, s[28:29] offset:2048
	global_load_lds_dwordx4 v135, s[28:29] offset:3072
	ds_read_b128 v[64:67], v136 offset:0
	ds_read_b128 v[96:99], v140 offset:0
	ds_read_b128 v[100:103], v140 offset:2048
	ds_read_b128 v[104:107], v140 offset:4096
	ds_read_b128 v[108:111], v140 offset:6144
	ds_read_b128 v[68:71], v136 offset:2048
	ds_read_b128 v[72:75], v136 offset:4096
	ds_read_b128 v[76:79], v136 offset:6144
	s_waitcnt lgkmcnt(3)
	v_mfma_f32_16x16x32_bf16 v[0:3], v[64:67], v[96:99], v[0:3]
	v_mfma_f32_16x16x32_bf16 v[4:7], v[64:67], v[100:103], v[4:7]
	ds_read_b128 v[80:83], v137 offset:0
	v_mfma_f32_16x16x32_bf16 v[8:11], v[64:67], v[104:107], v[8:11]
	v_mfma_f32_16x16x32_bf16 v[12:15], v[64:67], v[108:111], v[12:15]
	ds_read_b128 v[112:115], v141 offset:0
	s_waitcnt lgkmcnt(4)
	v_mfma_f32_16x16x32_bf16 v[16:19], v[68:71], v[96:99], v[16:19]
	v_mfma_f32_16x16x32_bf16 v[20:23], v[68:71], v[100:103], v[20:23]
	ds_read_b128 v[116:119], v141 offset:2048
	v_mfma_f32_16x16x32_bf16 v[24:27], v[68:71], v[104:107], v[24:27]
	v_mfma_f32_16x16x32_bf16 v[28:31], v[68:71], v[108:111], v[28:31]
	ds_read_b128 v[120:123], v141 offset:4096
	s_waitcnt lgkmcnt(5)
	v_mfma_f32_16x16x32_bf16 v[32:35], v[72:75], v[96:99], v[32:35]
	v_mfma_f32_16x16x32_bf16 v[36:39], v[72:75], v[100:103], v[36:39]
	ds_read_b128 v[124:127], v141 offset:6144
	v_mfma_f32_16x16x32_bf16 v[40:43], v[72:75], v[104:107], v[40:43]
	v_mfma_f32_16x16x32_bf16 v[44:47], v[72:75], v[108:111], v[44:47]
	ds_read_b128 v[84:87], v137 offset:2048
	s_waitcnt lgkmcnt(6)
	v_mfma_f32_16x16x32_bf16 v[48:51], v[76:79], v[96:99], v[48:51]
	v_mfma_f32_16x16x32_bf16 v[52:55], v[76:79], v[100:103], v[52:55]
	ds_read_b128 v[88:91], v137 offset:4096
	v_mfma_f32_16x16x32_bf16 v[56:59], v[76:79], v[104:107], v[56:59]
	v_mfma_f32_16x16x32_bf16 v[60:63], v[76:79], v[108:111], v[60:63]
	ds_read_b128 v[92:95], v137 offset:6144
	s_waitcnt lgkmcnt(3)
	v_mfma_f32_16x16x32_bf16 v[0:3], v[80:83], v[112:115], v[0:3]
	v_mfma_f32_16x16x32_bf16 v[4:7], v[80:83], v[116:119], v[4:7]
	v_mfma_f32_16x16x32_bf16 v[8:11], v[80:83], v[120:123], v[8:11]
	v_mfma_f32_16x16x32_bf16 v[12:15], v[80:83], v[124:127], v[12:15]
	s_waitcnt lgkmcnt(2)
	v_mfma_f32_16x16x32_bf16 v[16:19], v[84:87], v[112:115], v[16:19]
	v_mfma_f32_16x16x32_bf16 v[20:23], v[84:87], v[116:119], v[20:23]
	v_mfma_f32_16x16x32_bf16 v[24:27], v[84:87], v[120:123], v[24:27]
	v_mfma_f32_16x16x32_bf16 v[28:31], v[84:87], v[124:127], v[28:31]
	s_waitcnt lgkmcnt(1)
	v_mfma_f32_16x16x32_bf16 v[32:35], v[88:91], v[112:115], v[32:35]
	v_mfma_f32_16x16x32_bf16 v[36:39], v[88:91], v[116:119], v[36:39]
	v_mfma_f32_16x16x32_bf16 v[40:43], v[88:91], v[120:123], v[40:43]
	v_mfma_f32_16x16x32_bf16 v[44:47], v[88:91], v[124:127], v[44:47]
	s_waitcnt lgkmcnt(0)
	v_mfma_f32_16x16x32_bf16 v[48:51], v[92:95], v[112:115], v[48:51]
	v_mfma_f32_16x16x32_bf16 v[52:55], v[92:95], v[116:119], v[52:55]
	v_mfma_f32_16x16x32_bf16 v[56:59], v[92:95], v[120:123], v[56:59]
	v_mfma_f32_16x16x32_bf16 v[60:63], v[92:95], v[124:127], v[60:63]
	s_waitcnt vmcnt(0)
	s_barrier
	s_add_u32 s26, s26, 0x80
	s_addc_u32 s27, s27, 0
	s_add_u32 s28, s28, 0x80
	s_addc_u32 s29, s29, 0
	s_mov_b32 m0, s40
	s_nop 0
	global_load_lds_dwordx4 v132, s[26:27] offset:0
	global_load_lds_dwordx4 v133, s[26:27] offset:1024
	global_load_lds_dwordx4 v134, s[26:27] offset:2048
	global_load_lds_dwordx4 v135, s[26:27] offset:3072
	s_mov_b32 m0, s41
	s_nop 0
	global_load_lds_dwordx4 v132, s[28:29] offset:0
	global_load_lds_dwordx4 v133, s[28:29] offset:1024
	global_load_lds_dwordx4 v134, s[28:29] offset:2048
	global_load_lds_dwordx4 v135, s[28:29] offset:3072
	ds_read_b128 v[64:67], v138 offset:0
	ds_read_b128 v[96:99], v142 offset:0
	ds_read_b128 v[100:103], v142 offset:2048
	ds_read_b128 v[104:107], v142 offset:4096
	ds_read_b128 v[108:111], v142 offset:6144
	ds_read_b128 v[68:71], v138 offset:2048
	ds_read_b128 v[72:75], v138 offset:4096
	ds_read_b128 v[76:79], v138 offset:6144
	s_waitcnt lgkmcnt(3)
	v_mfma_f32_16x16x32_bf16 v[0:3], v[64:67], v[96:99], v[0:3]
	v_mfma_f32_16x16x32_bf16 v[4:7], v[64:67], v[100:103], v[4:7]
	ds_read_b128 v[80:83], v139 offset:0
	v_mfma_f32_16x16x32_bf16 v[8:11], v[64:67], v[104:107], v[8:11]
	v_mfma_f32_16x16x32_bf16 v[12:15], v[64:67], v[108:111], v[12:15]
	ds_read_b128 v[112:115], v143 offset:0
	s_waitcnt lgkmcnt(4)
	v_mfma_f32_16x16x32_bf16 v[16:19], v[68:71], v[96:99], v[16:19]
	v_mfma_f32_16x16x32_bf16 v[20:23], v[68:71], v[100:103], v[20:23]
	ds_read_b128 v[116:119], v143 offset:2048
	v_mfma_f32_16x16x32_bf16 v[24:27], v[68:71], v[104:107], v[24:27]
	v_mfma_f32_16x16x32_bf16 v[28:31], v[68:71], v[108:111], v[28:31]
	ds_read_b128 v[120:123], v143 offset:4096
	s_waitcnt lgkmcnt(5)
	v_mfma_f32_16x16x32_bf16 v[32:35], v[72:75], v[96:99], v[32:35]
	v_mfma_f32_16x16x32_bf16 v[36:39], v[72:75], v[100:103], v[36:39]
	ds_read_b128 v[124:127], v143 offset:6144
	v_mfma_f32_16x16x32_bf16 v[40:43], v[72:75], v[104:107], v[40:43]
	v_mfma_f32_16x16x32_bf16 v[44:47], v[72:75], v[108:111], v[44:47]
	ds_read_b128 v[84:87], v139 offset:2048
	s_waitcnt lgkmcnt(6)
	v_mfma_f32_16x16x32_bf16 v[48:51], v[76:79], v[96:99], v[48:51]
	v_mfma_f32_16x16x32_bf16 v[52:55], v[76:79], v[100:103], v[52:55]
	ds_read_b128 v[88:91], v139 offset:4096
	v_mfma_f32_16x16x32_bf16 v[56:59], v[76:79], v[104:107], v[56:59]
	v_mfma_f32_16x16x32_bf16 v[60:63], v[76:79], v[108:111], v[60:63]
	ds_read_b128 v[92:95], v139 offset:6144
	s_waitcnt lgkmcnt(3)
	v_mfma_f32_16x16x32_bf16 v[0:3], v[80:83], v[112:115], v[0:3]
	v_mfma_f32_16x16x32_bf16 v[4:7], v[80:83], v[116:119], v[4:7]
	v_mfma_f32_16x16x32_bf16 v[8:11], v[80:83], v[120:123], v[8:11]
	v_mfma_f32_16x16x32_bf16 v[12:15], v[80:83], v[124:127], v[12:15]
	s_waitcnt lgkmcnt(2)
	v_mfma_f32_16x16x32_bf16 v[16:19], v[84:87], v[112:115], v[16:19]
	v_mfma_f32_16x16x32_bf16 v[20:23], v[84:87], v[116:119], v[20:23]
	v_mfma_f32_16x16x32_bf16 v[24:27], v[84:87], v[120:123], v[24:27]
	v_mfma_f32_16x16x32_bf16 v[28:31], v[84:87], v[124:127], v[28:31]
	s_waitcnt lgkmcnt(1)
	v_mfma_f32_16x16x32_bf16 v[32:35], v[88:91], v[112:115], v[32:35]
	v_mfma_f32_16x16x32_bf16 v[36:39], v[88:91], v[116:119], v[36:39]
	v_mfma_f32_16x16x32_bf16 v[40:43], v[88:91], v[120:123], v[40:43]
	v_mfma_f32_16x16x32_bf16 v[44:47], v[88:91], v[124:127], v[44:47]
	s_waitcnt lgkmcnt(0)
	v_mfma_f32_16x16x32_bf16 v[48:51], v[92:95], v[112:115], v[48:51]
	v_mfma_f32_16x16x32_bf16 v[52:55], v[92:95], v[116:119], v[52:55]
	v_mfma_f32_16x16x32_bf16 v[56:59], v[92:95], v[120:123], v[56:59]
	v_mfma_f32_16x16x32_bf16 v[60:63], v[92:95], v[124:127], v[60:63]
	s_waitcnt vmcnt(0)
	s_barrier
	s_add_u32 s26, s26, 0x80
	s_addc_u32 s27, s27, 0
	s_add_u32 s28, s28, 0x80
	s_addc_u32 s29, s29, 0
	s_mov_b32 m0, s42
	s_nop 0
	global_load_lds_dwordx4 v132, s[26:27] offset:0
	global_load_lds_dwordx4 v133, s[26:27] offset:1024
	global_load_lds_dwordx4 v134, s[26:27] offset:2048
	global_load_lds_dwordx4 v135, s[26:27] offset:3072
	s_mov_b32 m0, s43
	s_nop 0
	global_load_lds_dwordx4 v132, s[28:29] offset:0
	global_load_lds_dwordx4 v133, s[28:29] offset:1024
	global_load_lds_dwordx4 v134, s[28:29] offset:2048
	global_load_lds_dwordx4 v135, s[28:29] offset:3072
	ds_read_b128 v[64:67], v136 offset:0
	ds_read_b128 v[96:99], v140 offset:0
	ds_read_b128 v[100:103], v140 offset:2048
	ds_read_b128 v[104:107], v140 offset:4096
	ds_read_b128 v[108:111], v140 offset:6144
	ds_read_b128 v[68:71], v136 offset:2048
	ds_read_b128 v[72:75], v136 offset:4096
	ds_read_b128 v[76:79], v136 offset:6144
	s_waitcnt lgkmcnt(3)
	v_mfma_f32_16x16x32_bf16 v[0:3], v[64:67], v[96:99], v[0:3]
	v_mfma_f32_16x16x32_bf16 v[4:7], v[64:67], v[100:103], v[4:7]
	ds_read_b128 v[80:83], v137 offset:0
	v_mfma_f32_16x16x32_bf16 v[8:11], v[64:67], v[104:107], v[8:11]
	v_mfma_f32_16x16x32_bf16 v[12:15], v[64:67], v[108:111], v[12:15]
	ds_read_b128 v[112:115], v141 offset:0
	s_waitcnt lgkmcnt(4)
	v_mfma_f32_16x16x32_bf16 v[16:19], v[68:71], v[96:99], v[16:19]
	v_mfma_f32_16x16x32_bf16 v[20:23], v[68:71], v[100:103], v[20:23]
	ds_read_b128 v[116:119], v141 offset:2048
	v_mfma_f32_16x16x32_bf16 v[24:27], v[68:71], v[104:107], v[24:27]
	v_mfma_f32_16x16x32_bf16 v[28:31], v[68:71], v[108:111], v[28:31]
	ds_read_b128 v[120:123], v141 offset:4096
	s_waitcnt lgkmcnt(5)
	v_mfma_f32_16x16x32_bf16 v[32:35], v[72:75], v[96:99], v[32:35]
	v_mfma_f32_16x16x32_bf16 v[36:39], v[72:75], v[100:103], v[36:39]
	ds_read_b128 v[124:127], v141 offset:6144
	v_mfma_f32_16x16x32_bf16 v[40:43], v[72:75], v[104:107], v[40:43]
	v_mfma_f32_16x16x32_bf16 v[44:47], v[72:75], v[108:111], v[44:47]
	ds_read_b128 v[84:87], v137 offset:2048
	s_waitcnt lgkmcnt(6)
	v_mfma_f32_16x16x32_bf16 v[48:51], v[76:79], v[96:99], v[48:51]
	v_mfma_f32_16x16x32_bf16 v[52:55], v[76:79], v[100:103], v[52:55]
	ds_read_b128 v[88:91], v137 offset:4096
	v_mfma_f32_16x16x32_bf16 v[56:59], v[76:79], v[104:107], v[56:59]
	v_mfma_f32_16x16x32_bf16 v[60:63], v[76:79], v[108:111], v[60:63]
	ds_read_b128 v[92:95], v137 offset:6144
	s_waitcnt lgkmcnt(3)
	v_mfma_f32_16x16x32_bf16 v[0:3], v[80:83], v[112:115], v[0:3]
	v_mfma_f32_16x16x32_bf16 v[4:7], v[80:83], v[116:119], v[4:7]
	v_mfma_f32_16x16x32_bf16 v[8:11], v[80:83], v[120:123], v[8:11]
	v_mfma_f32_16x16x32_bf16 v[12:15], v[80:83], v[124:127], v[12:15]
	s_waitcnt lgkmcnt(2)
	v_mfma_f32_16x16x32_bf16 v[16:19], v[84:87], v[112:115], v[16:19]
	v_mfma_f32_16x16x32_bf16 v[20:23], v[84:87], v[116:119], v[20:23]
	v_mfma_f32_16x16x32_bf16 v[24:27], v[84:87], v[120:123], v[24:27]
	v_mfma_f32_16x16x32_bf16 v[28:31], v[84:87], v[124:127], v[28:31]
	s_waitcnt lgkmcnt(1)
	v_mfma_f32_16x16x32_bf16 v[32:35], v[88:91], v[112:115], v[32:35]
	v_mfma_f32_16x16x32_bf16 v[36:39], v[88:91], v[116:119], v[36:39]
	v_mfma_f32_16x16x32_bf16 v[40:43], v[88:91], v[120:123], v[40:43]
	v_mfma_f32_16x16x32_bf16 v[44:47], v[88:91], v[124:127], v[44:47]
	s_waitcnt lgkmcnt(0)
	v_mfma_f32_16x16x32_bf16 v[48:51], v[92:95], v[112:115], v[48:51]
	v_mfma_f32_16x16x32_bf16 v[52:55], v[92:95], v[116:119], v[52:55]
	v_mfma_f32_16x16x32_bf16 v[56:59], v[92:95], v[120:123], v[56:59]
	v_mfma_f32_16x16x32_bf16 v[60:63], v[92:95], v[124:127], v[60:63]
	s_waitcnt vmcnt(0)
	s_barrier
	s_add_u32 s26, s26, 0x80
	s_addc_u32 s27, s27, 0
	s_add_u32 s28, s28, 0x80
	s_addc_u32 s29, s29, 0
	s_mov_b32 m0, s40
	s_nop 0
	global_load_lds_dwordx4 v132, s[26:27] offset:0
	global_load_lds_dwordx4 v133, s[26:27] offset:1024
	global_load_lds_dwordx4 v134, s[26:27] offset:2048
	global_load_lds_dwordx4 v135, s[26:27] offset:3072
	s_mov_b32 m0, s41
	s_nop 0
	global_load_lds_dwordx4 v132, s[28:29] offset:0
	global_load_lds_dwordx4 v133, s[28:29] offset:1024
	global_load_lds_dwordx4 v134, s[28:29] offset:2048
	global_load_lds_dwordx4 v135, s[28:29] offset:3072
	ds_read_b128 v[64:67], v138 offset:0
	ds_read_b128 v[96:99], v142 offset:0
	ds_read_b128 v[100:103], v142 offset:2048
	ds_read_b128 v[104:107], v142 offset:4096
	ds_read_b128 v[108:111], v142 offset:6144
	ds_read_b128 v[68:71], v138 offset:2048
	ds_read_b128 v[72:75], v138 offset:4096
	ds_read_b128 v[76:79], v138 offset:6144
	s_waitcnt lgkmcnt(3)
	v_mfma_f32_16x16x32_bf16 v[0:3], v[64:67], v[96:99], v[0:3]
	v_mfma_f32_16x16x32_bf16 v[4:7], v[64:67], v[100:103], v[4:7]
	ds_read_b128 v[80:83], v139 offset:0
	v_mfma_f32_16x16x32_bf16 v[8:11], v[64:67], v[104:107], v[8:11]
	v_mfma_f32_16x16x32_bf16 v[12:15], v[64:67], v[108:111], v[12:15]
	ds_read_b128 v[112:115], v143 offset:0
	s_waitcnt lgkmcnt(4)
	v_mfma_f32_16x16x32_bf16 v[16:19], v[68:71], v[96:99], v[16:19]
	v_mfma_f32_16x16x32_bf16 v[20:23], v[68:71], v[100:103], v[20:23]
	ds_read_b128 v[116:119], v143 offset:2048
	v_mfma_f32_16x16x32_bf16 v[24:27], v[68:71], v[104:107], v[24:27]
	v_mfma_f32_16x16x32_bf16 v[28:31], v[68:71], v[108:111], v[28:31]
	ds_read_b128 v[120:123], v143 offset:4096
	s_waitcnt lgkmcnt(5)
	v_mfma_f32_16x16x32_bf16 v[32:35], v[72:75], v[96:99], v[32:35]
	v_mfma_f32_16x16x32_bf16 v[36:39], v[72:75], v[100:103], v[36:39]
	ds_read_b128 v[124:127], v143 offset:6144
	v_mfma_f32_16x16x32_bf16 v[40:43], v[72:75], v[104:107], v[40:43]
	v_mfma_f32_16x16x32_bf16 v[44:47], v[72:75], v[108:111], v[44:47]
	ds_read_b128 v[84:87], v139 offset:2048
	s_waitcnt lgkmcnt(6)
	v_mfma_f32_16x16x32_bf16 v[48:51], v[76:79], v[96:99], v[48:51]
	v_mfma_f32_16x16x32_bf16 v[52:55], v[76:79], v[100:103], v[52:55]
	ds_read_b128 v[88:91], v139 offset:4096
	v_mfma_f32_16x16x32_bf16 v[56:59], v[76:79], v[104:107], v[56:59]
	v_mfma_f32_16x16x32_bf16 v[60:63], v[76:79], v[108:111], v[60:63]
	ds_read_b128 v[92:95], v139 offset:6144
	s_waitcnt lgkmcnt(3)
	v_mfma_f32_16x16x32_bf16 v[0:3], v[80:83], v[112:115], v[0:3]
	v_mfma_f32_16x16x32_bf16 v[4:7], v[80:83], v[116:119], v[4:7]
	v_mfma_f32_16x16x32_bf16 v[8:11], v[80:83], v[120:123], v[8:11]
	v_mfma_f32_16x16x32_bf16 v[12:15], v[80:83], v[124:127], v[12:15]
	s_waitcnt lgkmcnt(2)
	v_mfma_f32_16x16x32_bf16 v[16:19], v[84:87], v[112:115], v[16:19]
	v_mfma_f32_16x16x32_bf16 v[20:23], v[84:87], v[116:119], v[20:23]
	v_mfma_f32_16x16x32_bf16 v[24:27], v[84:87], v[120:123], v[24:27]
	v_mfma_f32_16x16x32_bf16 v[28:31], v[84:87], v[124:127], v[28:31]
	s_waitcnt lgkmcnt(1)
	v_mfma_f32_16x16x32_bf16 v[32:35], v[88:91], v[112:115], v[32:35]
	v_mfma_f32_16x16x32_bf16 v[36:39], v[88:91], v[116:119], v[36:39]
	v_mfma_f32_16x16x32_bf16 v[40:43], v[88:91], v[120:123], v[40:43]
	v_mfma_f32_16x16x32_bf16 v[44:47], v[88:91], v[124:127], v[44:47]
	s_waitcnt lgkmcnt(0)
	v_mfma_f32_16x16x32_bf16 v[48:51], v[92:95], v[112:115], v[48:51]
	v_mfma_f32_16x16x32_bf16 v[52:55], v[92:95], v[116:119], v[52:55]
	v_mfma_f32_16x16x32_bf16 v[56:59], v[92:95], v[120:123], v[56:59]
	v_mfma_f32_16x16x32_bf16 v[60:63], v[92:95], v[124:127], v[60:63]
	s_waitcnt vmcnt(0)
	s_barrier
	s_add_u32 s26, s26, 0x80
	s_addc_u32 s27, s27, 0
	s_add_u32 s28, s28, 0x80
	s_addc_u32 s29, s29, 0
	s_mov_b32 m0, s42
	s_nop 0
	global_load_lds_dwordx4 v132, s[26:27] offset:0
	global_load_lds_dwordx4 v133, s[26:27] offset:1024
	global_load_lds_dwordx4 v134, s[26:27] offset:2048
	global_load_lds_dwordx4 v135, s[26:27] offset:3072
	s_mov_b32 m0, s43
	s_nop 0
	global_load_lds_dwordx4 v132, s[28:29] offset:0
	global_load_lds_dwordx4 v133, s[28:29] offset:1024
	global_load_lds_dwordx4 v134, s[28:29] offset:2048
	global_load_lds_dwordx4 v135, s[28:29] offset:3072
	ds_read_b128 v[64:67], v136 offset:0
	ds_read_b128 v[96:99], v140 offset:0
	ds_read_b128 v[100:103], v140 offset:2048
	ds_read_b128 v[104:107], v140 offset:4096
	ds_read_b128 v[108:111], v140 offset:6144
	ds_read_b128 v[68:71], v136 offset:2048
	ds_read_b128 v[72:75], v136 offset:4096
	ds_read_b128 v[76:79], v136 offset:6144
	s_waitcnt lgkmcnt(3)
	v_mfma_f32_16x16x32_bf16 v[0:3], v[64:67], v[96:99], v[0:3]
	v_mfma_f32_16x16x32_bf16 v[4:7], v[64:67], v[100:103], v[4:7]
	ds_read_b128 v[80:83], v137 offset:0
	v_mfma_f32_16x16x32_bf16 v[8:11], v[64:67], v[104:107], v[8:11]
	v_mfma_f32_16x16x32_bf16 v[12:15], v[64:67], v[108:111], v[12:15]
	ds_read_b128 v[112:115], v141 offset:0
	s_waitcnt lgkmcnt(4)
	v_mfma_f32_16x16x32_bf16 v[16:19], v[68:71], v[96:99], v[16:19]
	v_mfma_f32_16x16x32_bf16 v[20:23], v[68:71], v[100:103], v[20:23]
	ds_read_b128 v[116:119], v141 offset:2048
	v_mfma_f32_16x16x32_bf16 v[24:27], v[68:71], v[104:107], v[24:27]
	v_mfma_f32_16x16x32_bf16 v[28:31], v[68:71], v[108:111], v[28:31]
	ds_read_b128 v[120:123], v141 offset:4096
	s_waitcnt lgkmcnt(5)
	v_mfma_f32_16x16x32_bf16 v[32:35], v[72:75], v[96:99], v[32:35]
	v_mfma_f32_16x16x32_bf16 v[36:39], v[72:75], v[100:103], v[36:39]
	ds_read_b128 v[124:127], v141 offset:6144
	v_mfma_f32_16x16x32_bf16 v[40:43], v[72:75], v[104:107], v[40:43]
	v_mfma_f32_16x16x32_bf16 v[44:47], v[72:75], v[108:111], v[44:47]
	ds_read_b128 v[84:87], v137 offset:2048
	s_waitcnt lgkmcnt(6)
	v_mfma_f32_16x16x32_bf16 v[48:51], v[76:79], v[96:99], v[48:51]
	v_mfma_f32_16x16x32_bf16 v[52:55], v[76:79], v[100:103], v[52:55]
	ds_read_b128 v[88:91], v137 offset:4096
	v_mfma_f32_16x16x32_bf16 v[56:59], v[76:79], v[104:107], v[56:59]
	v_mfma_f32_16x16x32_bf16 v[60:63], v[76:79], v[108:111], v[60:63]
	ds_read_b128 v[92:95], v137 offset:6144
	s_waitcnt lgkmcnt(3)
	v_mfma_f32_16x16x32_bf16 v[0:3], v[80:83], v[112:115], v[0:3]
	v_mfma_f32_16x16x32_bf16 v[4:7], v[80:83], v[116:119], v[4:7]
	v_mfma_f32_16x16x32_bf16 v[8:11], v[80:83], v[120:123], v[8:11]
	v_mfma_f32_16x16x32_bf16 v[12:15], v[80:83], v[124:127], v[12:15]
	s_waitcnt lgkmcnt(2)
	v_mfma_f32_16x16x32_bf16 v[16:19], v[84:87], v[112:115], v[16:19]
	v_mfma_f32_16x16x32_bf16 v[20:23], v[84:87], v[116:119], v[20:23]
	v_mfma_f32_16x16x32_bf16 v[24:27], v[84:87], v[120:123], v[24:27]
	v_mfma_f32_16x16x32_bf16 v[28:31], v[84:87], v[124:127], v[28:31]
	s_waitcnt lgkmcnt(1)
	v_mfma_f32_16x16x32_bf16 v[32:35], v[88:91], v[112:115], v[32:35]
	v_mfma_f32_16x16x32_bf16 v[36:39], v[88:91], v[116:119], v[36:39]
	v_mfma_f32_16x16x32_bf16 v[40:43], v[88:91], v[120:123], v[40:43]
	v_mfma_f32_16x16x32_bf16 v[44:47], v[88:91], v[124:127], v[44:47]
	s_waitcnt lgkmcnt(0)
	v_mfma_f32_16x16x32_bf16 v[48:51], v[92:95], v[112:115], v[48:51]
	v_mfma_f32_16x16x32_bf16 v[52:55], v[92:95], v[116:119], v[52:55]
	v_mfma_f32_16x16x32_bf16 v[56:59], v[92:95], v[120:123], v[56:59]
	v_mfma_f32_16x16x32_bf16 v[60:63], v[92:95], v[124:127], v[60:63]
	s_waitcnt vmcnt(0)
	s_barrier
	s_add_u32 s26, s26, 0xffc80
	s_addc_u32 s27, s27, 0
	s_add_u32 s28, s28, 0x7ffc80
	s_addc_u32 s29, s29, 0
	s_mov_b32 m0, s40
	s_nop 0
	global_load_lds_dwordx4 v132, s[26:27] offset:0
	global_load_lds_dwordx4 v133, s[26:27] offset:1024
	global_load_lds_dwordx4 v134, s[26:27] offset:2048
	global_load_lds_dwordx4 v135, s[26:27] offset:3072
	s_mov_b32 m0, s41
	s_nop 0
	global_load_lds_dwordx4 v132, s[28:29] offset:0
	global_load_lds_dwordx4 v133, s[28:29] offset:1024
	global_load_lds_dwordx4 v134, s[28:29] offset:2048
	global_load_lds_dwordx4 v135, s[28:29] offset:3072
	ds_read_b128 v[64:67], v138 offset:0
	ds_read_b128 v[96:99], v142 offset:0
	ds_read_b128 v[100:103], v142 offset:2048
	ds_read_b128 v[104:107], v142 offset:4096
	ds_read_b128 v[108:111], v142 offset:6144
	ds_read_b128 v[68:71], v138 offset:2048
	ds_read_b128 v[72:75], v138 offset:4096
	ds_read_b128 v[76:79], v138 offset:6144
	s_waitcnt lgkmcnt(3)
	v_mfma_f32_16x16x32_bf16 v[0:3], v[64:67], v[96:99], v[0:3]
	v_mfma_f32_16x16x32_bf16 v[4:7], v[64:67], v[100:103], v[4:7]
	ds_read_b128 v[80:83], v139 offset:0
	v_mfma_f32_16x16x32_bf16 v[8:11], v[64:67], v[104:107], v[8:11]
	v_mfma_f32_16x16x32_bf16 v[12:15], v[64:67], v[108:111], v[12:15]
	ds_read_b128 v[112:115], v143 offset:0
	s_waitcnt lgkmcnt(4)
	v_mfma_f32_16x16x32_bf16 v[16:19], v[68:71], v[96:99], v[16:19]
	v_mfma_f32_16x16x32_bf16 v[20:23], v[68:71], v[100:103], v[20:23]
	ds_read_b128 v[116:119], v143 offset:2048
	v_mfma_f32_16x16x32_bf16 v[24:27], v[68:71], v[104:107], v[24:27]
	v_mfma_f32_16x16x32_bf16 v[28:31], v[68:71], v[108:111], v[28:31]
	ds_read_b128 v[120:123], v143 offset:4096
	s_waitcnt lgkmcnt(5)
	v_mfma_f32_16x16x32_bf16 v[32:35], v[72:75], v[96:99], v[32:35]
	v_mfma_f32_16x16x32_bf16 v[36:39], v[72:75], v[100:103], v[36:39]
	ds_read_b128 v[124:127], v143 offset:6144
	v_mfma_f32_16x16x32_bf16 v[40:43], v[72:75], v[104:107], v[40:43]
	v_mfma_f32_16x16x32_bf16 v[44:47], v[72:75], v[108:111], v[44:47]
	ds_read_b128 v[84:87], v139 offset:2048
	s_waitcnt lgkmcnt(6)
	v_mfma_f32_16x16x32_bf16 v[48:51], v[76:79], v[96:99], v[48:51]
	v_mfma_f32_16x16x32_bf16 v[52:55], v[76:79], v[100:103], v[52:55]
	ds_read_b128 v[88:91], v139 offset:4096
	v_mfma_f32_16x16x32_bf16 v[56:59], v[76:79], v[104:107], v[56:59]
	v_mfma_f32_16x16x32_bf16 v[60:63], v[76:79], v[108:111], v[60:63]
	ds_read_b128 v[92:95], v139 offset:6144
	s_waitcnt lgkmcnt(3)
	v_mfma_f32_16x16x32_bf16 v[0:3], v[80:83], v[112:115], v[0:3]
	v_mfma_f32_16x16x32_bf16 v[4:7], v[80:83], v[116:119], v[4:7]
	v_mfma_f32_16x16x32_bf16 v[8:11], v[80:83], v[120:123], v[8:11]
	v_mfma_f32_16x16x32_bf16 v[12:15], v[80:83], v[124:127], v[12:15]
	s_waitcnt lgkmcnt(2)
	v_mfma_f32_16x16x32_bf16 v[16:19], v[84:87], v[112:115], v[16:19]
	v_mfma_f32_16x16x32_bf16 v[20:23], v[84:87], v[116:119], v[20:23]
	v_mfma_f32_16x16x32_bf16 v[24:27], v[84:87], v[120:123], v[24:27]
	v_mfma_f32_16x16x32_bf16 v[28:31], v[84:87], v[124:127], v[28:31]
	s_waitcnt lgkmcnt(1)
	v_mfma_f32_16x16x32_bf16 v[32:35], v[88:91], v[112:115], v[32:35]
	v_mfma_f32_16x16x32_bf16 v[36:39], v[88:91], v[116:119], v[36:39]
	v_mfma_f32_16x16x32_bf16 v[40:43], v[88:91], v[120:123], v[40:43]
	v_mfma_f32_16x16x32_bf16 v[44:47], v[88:91], v[124:127], v[44:47]
	s_waitcnt lgkmcnt(0)
	v_mfma_f32_16x16x32_bf16 v[48:51], v[92:95], v[112:115], v[48:51]
	v_mfma_f32_16x16x32_bf16 v[52:55], v[92:95], v[116:119], v[52:55]
	v_mfma_f32_16x16x32_bf16 v[56:59], v[92:95], v[120:123], v[56:59]
	v_mfma_f32_16x16x32_bf16 v[60:63], v[92:95], v[124:127], v[60:63]
	s_nop 7
	s_add_u32 s36, s36, 0x800
	s_addc_u32 s37, s37, 0
	global_load_dwordx2 v[64:65], v236, s[36:37] offset:0
	global_load_dwordx2 v[66:67], v236, s[36:37] offset:32
	global_load_dwordx2 v[68:69], v236, s[36:37] offset:64
	global_load_dwordx2 v[70:71], v236, s[36:37] offset:96
	global_load_dwordx2 v[72:73], v237, s[36:37] offset:0
	global_load_dwordx2 v[74:75], v237, s[36:37] offset:32
	global_load_dwordx2 v[76:77], v237, s[36:37] offset:64
	global_load_dwordx2 v[78:79], v237, s[36:37] offset:96
	global_load_dwordx2 v[80:81], v238, s[36:37] offset:0
	global_load_dwordx2 v[82:83], v238, s[36:37] offset:32
	global_load_dwordx2 v[84:85], v238, s[36:37] offset:64
	global_load_dwordx2 v[86:87], v238, s[36:37] offset:96
	global_load_dwordx2 v[88:89], v239, s[36:37] offset:0
	global_load_dwordx2 v[90:91], v239, s[36:37] offset:32
	global_load_dwordx2 v[92:93], v239, s[36:37] offset:64
	global_load_dwordx2 v[94:95], v239, s[36:37] offset:96
	s_waitcnt vmcnt(15)
	v_lshlrev_b32_e32 v96, 16, v64
	v_and_b32_e32 v97, 0xffff0000, v64
	v_lshlrev_b32_e32 v98, 16, v65
	v_and_b32_e32 v99, 0xffff0000, v65
	v_mul_f32_e32 v96, 0xbfb8aa3b, v96
	v_mul_f32_e32 v97, 0xbfb8aa3b, v97
	v_mul_f32_e32 v98, 0xbfb8aa3b, v98
	v_mul_f32_e32 v99, 0xbfb8aa3b, v99
	v_exp_f32_e32 v96, v96
	v_exp_f32_e32 v97, v97
	v_exp_f32_e32 v98, v98
	v_exp_f32_e32 v99, v99
	v_add_f32_e32 v96, 1.0, v96
	v_add_f32_e32 v97, 1.0, v97
	v_add_f32_e32 v98, 1.0, v98
	v_add_f32_e32 v99, 1.0, v99
	v_rcp_f32_e32 v96, v96
	v_rcp_f32_e32 v97, v97
	v_rcp_f32_e32 v98, v98
	v_rcp_f32_e32 v99, v99
	s_nop 0
	v_fmac_f32_e32 v146, v96, v0
	v_fmac_f32_e32 v147, v97, v1
	v_fmac_f32_e32 v148, v98, v2
	v_fmac_f32_e32 v149, v99, v3
	s_waitcnt vmcnt(14)
	v_lshlrev_b32_e32 v100, 16, v66
	v_and_b32_e32 v101, 0xffff0000, v66
	v_lshlrev_b32_e32 v102, 16, v67
	v_and_b32_e32 v103, 0xffff0000, v67
	v_mul_f32_e32 v100, 0xbfb8aa3b, v100
	v_mul_f32_e32 v101, 0xbfb8aa3b, v101
	v_mul_f32_e32 v102, 0xbfb8aa3b, v102
	v_mul_f32_e32 v103, 0xbfb8aa3b, v103
	v_exp_f32_e32 v100, v100
	v_exp_f32_e32 v101, v101
	v_exp_f32_e32 v102, v102
	v_exp_f32_e32 v103, v103
	v_add_f32_e32 v100, 1.0, v100
	v_add_f32_e32 v101, 1.0, v101
	v_add_f32_e32 v102, 1.0, v102
	v_add_f32_e32 v103, 1.0, v103
	v_rcp_f32_e32 v100, v100
	v_rcp_f32_e32 v101, v101
	v_rcp_f32_e32 v102, v102
	v_rcp_f32_e32 v103, v103
	s_nop 0
	v_fmac_f32_e32 v162, v100, v16
	v_fmac_f32_e32 v163, v101, v17
	v_fmac_f32_e32 v164, v102, v18
	v_fmac_f32_e32 v165, v103, v19
	s_waitcnt vmcnt(13)
	v_lshlrev_b32_e32 v96, 16, v68
	v_and_b32_e32 v97, 0xffff0000, v68
	v_lshlrev_b32_e32 v98, 16, v69
	v_and_b32_e32 v99, 0xffff0000, v69
	v_mul_f32_e32 v96, 0xbfb8aa3b, v96
	v_mul_f32_e32 v97, 0xbfb8aa3b, v97
	v_mul_f32_e32 v98, 0xbfb8aa3b, v98
	v_mul_f32_e32 v99, 0xbfb8aa3b, v99
	v_exp_f32_e32 v96, v96
	v_exp_f32_e32 v97, v97
	v_exp_f32_e32 v98, v98
	v_exp_f32_e32 v99, v99
	v_add_f32_e32 v96, 1.0, v96
	v_add_f32_e32 v97, 1.0, v97
	v_add_f32_e32 v98, 1.0, v98
	v_add_f32_e32 v99, 1.0, v99
	v_rcp_f32_e32 v96, v96
	v_rcp_f32_e32 v97, v97
	v_rcp_f32_e32 v98, v98
	v_rcp_f32_e32 v99, v99
	s_nop 0
	v_fmac_f32_e32 v178, v96, v32
	v_fmac_f32_e32 v179, v97, v33
	v_fmac_f32_e32 v180, v98, v34
	v_fmac_f32_e32 v181, v99, v35
	s_waitcnt vmcnt(12)
	v_lshlrev_b32_e32 v100, 16, v70
	v_and_b32_e32 v101, 0xffff0000, v70
	v_lshlrev_b32_e32 v102, 16, v71
	v_and_b32_e32 v103, 0xffff0000, v71
	v_mul_f32_e32 v100, 0xbfb8aa3b, v100
	v_mul_f32_e32 v101, 0xbfb8aa3b, v101
	v_mul_f32_e32 v102, 0xbfb8aa3b, v102
	v_mul_f32_e32 v103, 0xbfb8aa3b, v103
	v_exp_f32_e32 v100, v100
	v_exp_f32_e32 v101, v101
	v_exp_f32_e32 v102, v102
	v_exp_f32_e32 v103, v103
	v_add_f32_e32 v100, 1.0, v100
	v_add_f32_e32 v101, 1.0, v101
	v_add_f32_e32 v102, 1.0, v102
	v_add_f32_e32 v103, 1.0, v103
	v_rcp_f32_e32 v100, v100
	v_rcp_f32_e32 v101, v101
	v_rcp_f32_e32 v102, v102
	v_rcp_f32_e32 v103, v103
	s_nop 0
	v_fmac_f32_e32 v194, v100, v48
	v_fmac_f32_e32 v195, v101, v49
	v_fmac_f32_e32 v196, v102, v50
	v_fmac_f32_e32 v197, v103, v51
	s_waitcnt vmcnt(11)
	v_lshlrev_b32_e32 v96, 16, v72
	v_and_b32_e32 v97, 0xffff0000, v72
	v_lshlrev_b32_e32 v98, 16, v73
	v_and_b32_e32 v99, 0xffff0000, v73
	v_mul_f32_e32 v96, 0xbfb8aa3b, v96
	v_mul_f32_e32 v97, 0xbfb8aa3b, v97
	v_mul_f32_e32 v98, 0xbfb8aa3b, v98
	v_mul_f32_e32 v99, 0xbfb8aa3b, v99
	v_exp_f32_e32 v96, v96
	v_exp_f32_e32 v97, v97
	v_exp_f32_e32 v98, v98
	v_exp_f32_e32 v99, v99
	v_add_f32_e32 v96, 1.0, v96
	v_add_f32_e32 v97, 1.0, v97
	v_add_f32_e32 v98, 1.0, v98
	v_add_f32_e32 v99, 1.0, v99
	v_rcp_f32_e32 v96, v96
	v_rcp_f32_e32 v97, v97
	v_rcp_f32_e32 v98, v98
	v_rcp_f32_e32 v99, v99
	s_nop 0
	v_fmac_f32_e32 v150, v96, v4
	v_fmac_f32_e32 v151, v97, v5
	v_fmac_f32_e32 v152, v98, v6
	v_fmac_f32_e32 v153, v99, v7
	s_waitcnt vmcnt(10)
	v_lshlrev_b32_e32 v100, 16, v74
	v_and_b32_e32 v101, 0xffff0000, v74
	v_lshlrev_b32_e32 v102, 16, v75
	v_and_b32_e32 v103, 0xffff0000, v75
	v_mul_f32_e32 v100, 0xbfb8aa3b, v100
	v_mul_f32_e32 v101, 0xbfb8aa3b, v101
	v_mul_f32_e32 v102, 0xbfb8aa3b, v102
	v_mul_f32_e32 v103, 0xbfb8aa3b, v103
	v_exp_f32_e32 v100, v100
	v_exp_f32_e32 v101, v101
	v_exp_f32_e32 v102, v102
	v_exp_f32_e32 v103, v103
	v_add_f32_e32 v100, 1.0, v100
	v_add_f32_e32 v101, 1.0, v101
	v_add_f32_e32 v102, 1.0, v102
	v_add_f32_e32 v103, 1.0, v103
	v_rcp_f32_e32 v100, v100
	v_rcp_f32_e32 v101, v101
	v_rcp_f32_e32 v102, v102
	v_rcp_f32_e32 v103, v103
	s_nop 0
	v_fmac_f32_e32 v166, v100, v20
	v_fmac_f32_e32 v167, v101, v21
	v_fmac_f32_e32 v168, v102, v22
	v_fmac_f32_e32 v169, v103, v23
	s_waitcnt vmcnt(9)
	v_lshlrev_b32_e32 v96, 16, v76
	v_and_b32_e32 v97, 0xffff0000, v76
	v_lshlrev_b32_e32 v98, 16, v77
	v_and_b32_e32 v99, 0xffff0000, v77
	v_mul_f32_e32 v96, 0xbfb8aa3b, v96
	v_mul_f32_e32 v97, 0xbfb8aa3b, v97
	v_mul_f32_e32 v98, 0xbfb8aa3b, v98
	v_mul_f32_e32 v99, 0xbfb8aa3b, v99
	v_exp_f32_e32 v96, v96
	v_exp_f32_e32 v97, v97
	v_exp_f32_e32 v98, v98
	v_exp_f32_e32 v99, v99
	v_add_f32_e32 v96, 1.0, v96
	v_add_f32_e32 v97, 1.0, v97
	v_add_f32_e32 v98, 1.0, v98
	v_add_f32_e32 v99, 1.0, v99
	v_rcp_f32_e32 v96, v96
	v_rcp_f32_e32 v97, v97
	v_rcp_f32_e32 v98, v98
	v_rcp_f32_e32 v99, v99
	s_nop 0
	v_fmac_f32_e32 v182, v96, v36
	v_fmac_f32_e32 v183, v97, v37
	v_fmac_f32_e32 v184, v98, v38
	v_fmac_f32_e32 v185, v99, v39
	s_waitcnt vmcnt(8)
	v_lshlrev_b32_e32 v100, 16, v78
	v_and_b32_e32 v101, 0xffff0000, v78
	v_lshlrev_b32_e32 v102, 16, v79
	v_and_b32_e32 v103, 0xffff0000, v79
	v_mul_f32_e32 v100, 0xbfb8aa3b, v100
	v_mul_f32_e32 v101, 0xbfb8aa3b, v101
	v_mul_f32_e32 v102, 0xbfb8aa3b, v102
	v_mul_f32_e32 v103, 0xbfb8aa3b, v103
	v_exp_f32_e32 v100, v100
	v_exp_f32_e32 v101, v101
	v_exp_f32_e32 v102, v102
	v_exp_f32_e32 v103, v103
	v_add_f32_e32 v100, 1.0, v100
	v_add_f32_e32 v101, 1.0, v101
	v_add_f32_e32 v102, 1.0, v102
	v_add_f32_e32 v103, 1.0, v103
	v_rcp_f32_e32 v100, v100
	v_rcp_f32_e32 v101, v101
	v_rcp_f32_e32 v102, v102
	v_rcp_f32_e32 v103, v103
	s_nop 0
	v_fmac_f32_e32 v200, v100, v52
	v_fmac_f32_e32 v201, v101, v53
	v_fmac_f32_e32 v202, v102, v54
	v_fmac_f32_e32 v203, v103, v55
	s_waitcnt vmcnt(7)
	v_lshlrev_b32_e32 v96, 16, v80
	v_and_b32_e32 v97, 0xffff0000, v80
	v_lshlrev_b32_e32 v98, 16, v81
	v_and_b32_e32 v99, 0xffff0000, v81
	v_mul_f32_e32 v96, 0xbfb8aa3b, v96
	v_mul_f32_e32 v97, 0xbfb8aa3b, v97
	v_mul_f32_e32 v98, 0xbfb8aa3b, v98
	v_mul_f32_e32 v99, 0xbfb8aa3b, v99
	v_exp_f32_e32 v96, v96
	v_exp_f32_e32 v97, v97
	v_exp_f32_e32 v98, v98
	v_exp_f32_e32 v99, v99
	v_add_f32_e32 v96, 1.0, v96
	v_add_f32_e32 v97, 1.0, v97
	v_add_f32_e32 v98, 1.0, v98
	v_add_f32_e32 v99, 1.0, v99
	v_rcp_f32_e32 v96, v96
	v_rcp_f32_e32 v97, v97
	v_rcp_f32_e32 v98, v98
	v_rcp_f32_e32 v99, v99
	s_nop 0
	v_fmac_f32_e32 v154, v96, v8
	v_fmac_f32_e32 v155, v97, v9
	v_fmac_f32_e32 v156, v98, v10
	v_fmac_f32_e32 v157, v99, v11
	s_waitcnt vmcnt(6)
	v_lshlrev_b32_e32 v100, 16, v82
	v_and_b32_e32 v101, 0xffff0000, v82
	v_lshlrev_b32_e32 v102, 16, v83
	v_and_b32_e32 v103, 0xffff0000, v83
	v_mul_f32_e32 v100, 0xbfb8aa3b, v100
	v_mul_f32_e32 v101, 0xbfb8aa3b, v101
	v_mul_f32_e32 v102, 0xbfb8aa3b, v102
	v_mul_f32_e32 v103, 0xbfb8aa3b, v103
	v_exp_f32_e32 v100, v100
	v_exp_f32_e32 v101, v101
	v_exp_f32_e32 v102, v102
	v_exp_f32_e32 v103, v103
	v_add_f32_e32 v100, 1.0, v100
	v_add_f32_e32 v101, 1.0, v101
	v_add_f32_e32 v102, 1.0, v102
	v_add_f32_e32 v103, 1.0, v103
	v_rcp_f32_e32 v100, v100
	v_rcp_f32_e32 v101, v101
	v_rcp_f32_e32 v102, v102
	v_rcp_f32_e32 v103, v103
	s_nop 0
	v_fmac_f32_e32 v170, v100, v24
	v_fmac_f32_e32 v171, v101, v25
	v_fmac_f32_e32 v172, v102, v26
	v_fmac_f32_e32 v173, v103, v27
	s_waitcnt vmcnt(5)
	v_lshlrev_b32_e32 v96, 16, v84
	v_and_b32_e32 v97, 0xffff0000, v84
	v_lshlrev_b32_e32 v98, 16, v85
	v_and_b32_e32 v99, 0xffff0000, v85
	v_mul_f32_e32 v96, 0xbfb8aa3b, v96
	v_mul_f32_e32 v97, 0xbfb8aa3b, v97
	v_mul_f32_e32 v98, 0xbfb8aa3b, v98
	v_mul_f32_e32 v99, 0xbfb8aa3b, v99
	v_exp_f32_e32 v96, v96
	v_exp_f32_e32 v97, v97
	v_exp_f32_e32 v98, v98
	v_exp_f32_e32 v99, v99
	v_add_f32_e32 v96, 1.0, v96
	v_add_f32_e32 v97, 1.0, v97
	v_add_f32_e32 v98, 1.0, v98
	v_add_f32_e32 v99, 1.0, v99
	v_rcp_f32_e32 v96, v96
	v_rcp_f32_e32 v97, v97
	v_rcp_f32_e32 v98, v98
	v_rcp_f32_e32 v99, v99
	s_nop 0
	v_fmac_f32_e32 v186, v96, v40
	v_fmac_f32_e32 v187, v97, v41
	v_fmac_f32_e32 v188, v98, v42
	v_fmac_f32_e32 v189, v99, v43
	s_waitcnt vmcnt(4)
	v_lshlrev_b32_e32 v100, 16, v86
	v_and_b32_e32 v101, 0xffff0000, v86
	v_lshlrev_b32_e32 v102, 16, v87
	v_and_b32_e32 v103, 0xffff0000, v87
	v_mul_f32_e32 v100, 0xbfb8aa3b, v100
	v_mul_f32_e32 v101, 0xbfb8aa3b, v101
	v_mul_f32_e32 v102, 0xbfb8aa3b, v102
	v_mul_f32_e32 v103, 0xbfb8aa3b, v103
	v_exp_f32_e32 v100, v100
	v_exp_f32_e32 v101, v101
	v_exp_f32_e32 v102, v102
	v_exp_f32_e32 v103, v103
	v_add_f32_e32 v100, 1.0, v100
	v_add_f32_e32 v101, 1.0, v101
	v_add_f32_e32 v102, 1.0, v102
	v_add_f32_e32 v103, 1.0, v103
	v_rcp_f32_e32 v100, v100
	v_rcp_f32_e32 v101, v101
	v_rcp_f32_e32 v102, v102
	v_rcp_f32_e32 v103, v103
	s_nop 0
	v_fmac_f32_e32 v208, v100, v56
	v_fmac_f32_e32 v209, v101, v57
	v_fmac_f32_e32 v210, v102, v58
	v_fmac_f32_e32 v211, v103, v59
	s_waitcnt vmcnt(3)
	v_lshlrev_b32_e32 v96, 16, v88
	v_and_b32_e32 v97, 0xffff0000, v88
	v_lshlrev_b32_e32 v98, 16, v89
	v_and_b32_e32 v99, 0xffff0000, v89
	v_mul_f32_e32 v96, 0xbfb8aa3b, v96
	v_mul_f32_e32 v97, 0xbfb8aa3b, v97
	v_mul_f32_e32 v98, 0xbfb8aa3b, v98
	v_mul_f32_e32 v99, 0xbfb8aa3b, v99
	v_exp_f32_e32 v96, v96
	v_exp_f32_e32 v97, v97
	v_exp_f32_e32 v98, v98
	v_exp_f32_e32 v99, v99
	v_add_f32_e32 v96, 1.0, v96
	v_add_f32_e32 v97, 1.0, v97
	v_add_f32_e32 v98, 1.0, v98
	v_add_f32_e32 v99, 1.0, v99
	v_rcp_f32_e32 v96, v96
	v_rcp_f32_e32 v97, v97
	v_rcp_f32_e32 v98, v98
	v_rcp_f32_e32 v99, v99
	s_nop 0
	v_fmac_f32_e32 v158, v96, v12
	v_fmac_f32_e32 v159, v97, v13
	v_fmac_f32_e32 v160, v98, v14
	v_fmac_f32_e32 v161, v99, v15
	s_waitcnt vmcnt(2)
	v_lshlrev_b32_e32 v100, 16, v90
	v_and_b32_e32 v101, 0xffff0000, v90
	v_lshlrev_b32_e32 v102, 16, v91
	v_and_b32_e32 v103, 0xffff0000, v91
	v_mul_f32_e32 v100, 0xbfb8aa3b, v100
	v_mul_f32_e32 v101, 0xbfb8aa3b, v101
	v_mul_f32_e32 v102, 0xbfb8aa3b, v102
	v_mul_f32_e32 v103, 0xbfb8aa3b, v103
	v_exp_f32_e32 v100, v100
	v_exp_f32_e32 v101, v101
	v_exp_f32_e32 v102, v102
	v_exp_f32_e32 v103, v103
	v_add_f32_e32 v100, 1.0, v100
	v_add_f32_e32 v101, 1.0, v101
	v_add_f32_e32 v102, 1.0, v102
	v_add_f32_e32 v103, 1.0, v103
	v_rcp_f32_e32 v100, v100
	v_rcp_f32_e32 v101, v101
	v_rcp_f32_e32 v102, v102
	v_rcp_f32_e32 v103, v103
	s_nop 0
	v_fmac_f32_e32 v174, v100, v28
	v_fmac_f32_e32 v175, v101, v29
	v_fmac_f32_e32 v176, v102, v30
	v_fmac_f32_e32 v177, v103, v31
	s_waitcnt vmcnt(1)
	v_lshlrev_b32_e32 v96, 16, v92
	v_and_b32_e32 v97, 0xffff0000, v92
	v_lshlrev_b32_e32 v98, 16, v93
	v_and_b32_e32 v99, 0xffff0000, v93
	v_mul_f32_e32 v96, 0xbfb8aa3b, v96
	v_mul_f32_e32 v97, 0xbfb8aa3b, v97
	v_mul_f32_e32 v98, 0xbfb8aa3b, v98
	v_mul_f32_e32 v99, 0xbfb8aa3b, v99
	v_exp_f32_e32 v96, v96
	v_exp_f32_e32 v97, v97
	v_exp_f32_e32 v98, v98
	v_exp_f32_e32 v99, v99
	v_add_f32_e32 v96, 1.0, v96
	v_add_f32_e32 v97, 1.0, v97
	v_add_f32_e32 v98, 1.0, v98
	v_add_f32_e32 v99, 1.0, v99
	v_rcp_f32_e32 v96, v96
	v_rcp_f32_e32 v97, v97
	v_rcp_f32_e32 v98, v98
	v_rcp_f32_e32 v99, v99
	s_nop 0
	v_fmac_f32_e32 v190, v96, v44
	v_fmac_f32_e32 v191, v97, v45
	v_fmac_f32_e32 v192, v98, v46
	v_fmac_f32_e32 v193, v99, v47
	s_waitcnt vmcnt(0)
	v_lshlrev_b32_e32 v100, 16, v94
	v_and_b32_e32 v101, 0xffff0000, v94
	v_lshlrev_b32_e32 v102, 16, v95
	v_and_b32_e32 v103, 0xffff0000, v95
	v_mul_f32_e32 v100, 0xbfb8aa3b, v100
	v_mul_f32_e32 v101, 0xbfb8aa3b, v101
	v_mul_f32_e32 v102, 0xbfb8aa3b, v102
	v_mul_f32_e32 v103, 0xbfb8aa3b, v103
	v_exp_f32_e32 v100, v100
	v_exp_f32_e32 v101, v101
	v_exp_f32_e32 v102, v102
	v_exp_f32_e32 v103, v103
	v_add_f32_e32 v100, 1.0, v100
	v_add_f32_e32 v101, 1.0, v101
	v_add_f32_e32 v102, 1.0, v102
	v_add_f32_e32 v103, 1.0, v103
	v_rcp_f32_e32 v100, v100
	v_rcp_f32_e32 v101, v101
	v_rcp_f32_e32 v102, v102
	v_rcp_f32_e32 v103, v103
	s_nop 0
	v_fmac_f32_e32 v232, v100, v60
	v_fmac_f32_e32 v233, v101, v61
	v_fmac_f32_e32 v234, v102, v62
	v_fmac_f32_e32 v235, v103, v63
	s_waitcnt vmcnt(0)
	s_barrier
	s_add_u32 s26, s26, 0x80
	s_addc_u32 s27, s27, 0
	s_add_u32 s28, s28, 0x80
	s_addc_u32 s29, s29, 0
	s_mov_b32 m0, s42
	s_nop 0
	global_load_lds_dwordx4 v132, s[26:27] offset:0
	global_load_lds_dwordx4 v133, s[26:27] offset:1024
	global_load_lds_dwordx4 v134, s[26:27] offset:2048
	global_load_lds_dwordx4 v135, s[26:27] offset:3072
	s_mov_b32 m0, s43
	s_nop 0
	global_load_lds_dwordx4 v132, s[28:29] offset:0
	global_load_lds_dwordx4 v133, s[28:29] offset:1024
	global_load_lds_dwordx4 v134, s[28:29] offset:2048
	global_load_lds_dwordx4 v135, s[28:29] offset:3072
	ds_read_b128 v[64:67], v136 offset:0
	ds_read_b128 v[96:99], v140 offset:0
	ds_read_b128 v[100:103], v140 offset:2048
	ds_read_b128 v[104:107], v140 offset:4096
	ds_read_b128 v[108:111], v140 offset:6144
	ds_read_b128 v[68:71], v136 offset:2048
	ds_read_b128 v[72:75], v136 offset:4096
	ds_read_b128 v[76:79], v136 offset:6144
	s_waitcnt lgkmcnt(3)
	v_mfma_f32_16x16x32_bf16 v[0:3], v[64:67], v[96:99], 0
	v_mfma_f32_16x16x32_bf16 v[4:7], v[64:67], v[100:103], 0
	ds_read_b128 v[80:83], v137 offset:0
	v_mfma_f32_16x16x32_bf16 v[8:11], v[64:67], v[104:107], 0
	v_mfma_f32_16x16x32_bf16 v[12:15], v[64:67], v[108:111], 0
	ds_read_b128 v[112:115], v141 offset:0
	s_waitcnt lgkmcnt(4)
	v_mfma_f32_16x16x32_bf16 v[16:19], v[68:71], v[96:99], 0
	v_mfma_f32_16x16x32_bf16 v[20:23], v[68:71], v[100:103], 0
	ds_read_b128 v[116:119], v141 offset:2048
	v_mfma_f32_16x16x32_bf16 v[24:27], v[68:71], v[104:107], 0
	v_mfma_f32_16x16x32_bf16 v[28:31], v[68:71], v[108:111], 0
	ds_read_b128 v[120:123], v141 offset:4096
	s_waitcnt lgkmcnt(5)
	v_mfma_f32_16x16x32_bf16 v[32:35], v[72:75], v[96:99], 0
	v_mfma_f32_16x16x32_bf16 v[36:39], v[72:75], v[100:103], 0
	ds_read_b128 v[124:127], v141 offset:6144
	v_mfma_f32_16x16x32_bf16 v[40:43], v[72:75], v[104:107], 0
	v_mfma_f32_16x16x32_bf16 v[44:47], v[72:75], v[108:111], 0
	ds_read_b128 v[84:87], v137 offset:2048
	s_waitcnt lgkmcnt(6)
	v_mfma_f32_16x16x32_bf16 v[48:51], v[76:79], v[96:99], 0
	v_mfma_f32_16x16x32_bf16 v[52:55], v[76:79], v[100:103], 0
	ds_read_b128 v[88:91], v137 offset:4096
	v_mfma_f32_16x16x32_bf16 v[56:59], v[76:79], v[104:107], 0
	v_mfma_f32_16x16x32_bf16 v[60:63], v[76:79], v[108:111], 0
	ds_read_b128 v[92:95], v137 offset:6144
	s_waitcnt lgkmcnt(3)
	v_mfma_f32_16x16x32_bf16 v[0:3], v[80:83], v[112:115], v[0:3]
	v_mfma_f32_16x16x32_bf16 v[4:7], v[80:83], v[116:119], v[4:7]
	v_mfma_f32_16x16x32_bf16 v[8:11], v[80:83], v[120:123], v[8:11]
	v_mfma_f32_16x16x32_bf16 v[12:15], v[80:83], v[124:127], v[12:15]
	s_waitcnt lgkmcnt(2)
	v_mfma_f32_16x16x32_bf16 v[16:19], v[84:87], v[112:115], v[16:19]
	v_mfma_f32_16x16x32_bf16 v[20:23], v[84:87], v[116:119], v[20:23]
	v_mfma_f32_16x16x32_bf16 v[24:27], v[84:87], v[120:123], v[24:27]
	v_mfma_f32_16x16x32_bf16 v[28:31], v[84:87], v[124:127], v[28:31]
	s_waitcnt lgkmcnt(1)
	v_mfma_f32_16x16x32_bf16 v[32:35], v[88:91], v[112:115], v[32:35]
	v_mfma_f32_16x16x32_bf16 v[36:39], v[88:91], v[116:119], v[36:39]
	v_mfma_f32_16x16x32_bf16 v[40:43], v[88:91], v[120:123], v[40:43]
	v_mfma_f32_16x16x32_bf16 v[44:47], v[88:91], v[124:127], v[44:47]
	s_waitcnt lgkmcnt(0)
	v_mfma_f32_16x16x32_bf16 v[48:51], v[92:95], v[112:115], v[48:51]
	v_mfma_f32_16x16x32_bf16 v[52:55], v[92:95], v[116:119], v[52:55]
	v_mfma_f32_16x16x32_bf16 v[56:59], v[92:95], v[120:123], v[56:59]
	v_mfma_f32_16x16x32_bf16 v[60:63], v[92:95], v[124:127], v[60:63]
	s_waitcnt vmcnt(0)
	s_barrier
	s_add_u32 s26, s26, 0x80
	s_addc_u32 s27, s27, 0
	s_add_u32 s28, s28, 0x80
	s_addc_u32 s29, s29, 0
	s_mov_b32 m0, s40
	s_nop 0
	global_load_lds_dwordx4 v132, s[26:27] offset:0
	global_load_lds_dwordx4 v133, s[26:27] offset:1024
	global_load_lds_dwordx4 v134, s[26:27] offset:2048
	global_load_lds_dwordx4 v135, s[26:27] offset:3072
	s_mov_b32 m0, s41
	s_nop 0
	global_load_lds_dwordx4 v132, s[28:29] offset:0
	global_load_lds_dwordx4 v133, s[28:29] offset:1024
	global_load_lds_dwordx4 v134, s[28:29] offset:2048
	global_load_lds_dwordx4 v135, s[28:29] offset:3072
	ds_read_b128 v[64:67], v138 offset:0
	ds_read_b128 v[96:99], v142 offset:0
	ds_read_b128 v[100:103], v142 offset:2048
	ds_read_b128 v[104:107], v142 offset:4096
	ds_read_b128 v[108:111], v142 offset:6144
	ds_read_b128 v[68:71], v138 offset:2048
	ds_read_b128 v[72:75], v138 offset:4096
	ds_read_b128 v[76:79], v138 offset:6144
	s_waitcnt lgkmcnt(3)
	v_mfma_f32_16x16x32_bf16 v[0:3], v[64:67], v[96:99], v[0:3]
	v_mfma_f32_16x16x32_bf16 v[4:7], v[64:67], v[100:103], v[4:7]
	ds_read_b128 v[80:83], v139 offset:0
	v_mfma_f32_16x16x32_bf16 v[8:11], v[64:67], v[104:107], v[8:11]
	v_mfma_f32_16x16x32_bf16 v[12:15], v[64:67], v[108:111], v[12:15]
	ds_read_b128 v[112:115], v143 offset:0
	s_waitcnt lgkmcnt(4)
	v_mfma_f32_16x16x32_bf16 v[16:19], v[68:71], v[96:99], v[16:19]
	v_mfma_f32_16x16x32_bf16 v[20:23], v[68:71], v[100:103], v[20:23]
	ds_read_b128 v[116:119], v143 offset:2048
	v_mfma_f32_16x16x32_bf16 v[24:27], v[68:71], v[104:107], v[24:27]
	v_mfma_f32_16x16x32_bf16 v[28:31], v[68:71], v[108:111], v[28:31]
	ds_read_b128 v[120:123], v143 offset:4096
	s_waitcnt lgkmcnt(5)
	v_mfma_f32_16x16x32_bf16 v[32:35], v[72:75], v[96:99], v[32:35]
	v_mfma_f32_16x16x32_bf16 v[36:39], v[72:75], v[100:103], v[36:39]
	ds_read_b128 v[124:127], v143 offset:6144
	v_mfma_f32_16x16x32_bf16 v[40:43], v[72:75], v[104:107], v[40:43]
	v_mfma_f32_16x16x32_bf16 v[44:47], v[72:75], v[108:111], v[44:47]
	ds_read_b128 v[84:87], v139 offset:2048
	s_waitcnt lgkmcnt(6)
	v_mfma_f32_16x16x32_bf16 v[48:51], v[76:79], v[96:99], v[48:51]
	v_mfma_f32_16x16x32_bf16 v[52:55], v[76:79], v[100:103], v[52:55]
	ds_read_b128 v[88:91], v139 offset:4096
	v_mfma_f32_16x16x32_bf16 v[56:59], v[76:79], v[104:107], v[56:59]
	v_mfma_f32_16x16x32_bf16 v[60:63], v[76:79], v[108:111], v[60:63]
	ds_read_b128 v[92:95], v139 offset:6144
	s_waitcnt lgkmcnt(3)
	v_mfma_f32_16x16x32_bf16 v[0:3], v[80:83], v[112:115], v[0:3]
	v_mfma_f32_16x16x32_bf16 v[4:7], v[80:83], v[116:119], v[4:7]
	v_mfma_f32_16x16x32_bf16 v[8:11], v[80:83], v[120:123], v[8:11]
	v_mfma_f32_16x16x32_bf16 v[12:15], v[80:83], v[124:127], v[12:15]
	s_waitcnt lgkmcnt(2)
	v_mfma_f32_16x16x32_bf16 v[16:19], v[84:87], v[112:115], v[16:19]
	v_mfma_f32_16x16x32_bf16 v[20:23], v[84:87], v[116:119], v[20:23]
	v_mfma_f32_16x16x32_bf16 v[24:27], v[84:87], v[120:123], v[24:27]
	v_mfma_f32_16x16x32_bf16 v[28:31], v[84:87], v[124:127], v[28:31]
	s_waitcnt lgkmcnt(1)
	v_mfma_f32_16x16x32_bf16 v[32:35], v[88:91], v[112:115], v[32:35]
	v_mfma_f32_16x16x32_bf16 v[36:39], v[88:91], v[116:119], v[36:39]
	v_mfma_f32_16x16x32_bf16 v[40:43], v[88:91], v[120:123], v[40:43]
	v_mfma_f32_16x16x32_bf16 v[44:47], v[88:91], v[124:127], v[44:47]
	s_waitcnt lgkmcnt(0)
	v_mfma_f32_16x16x32_bf16 v[48:51], v[92:95], v[112:115], v[48:51]
	v_mfma_f32_16x16x32_bf16 v[52:55], v[92:95], v[116:119], v[52:55]
	v_mfma_f32_16x16x32_bf16 v[56:59], v[92:95], v[120:123], v[56:59]
	v_mfma_f32_16x16x32_bf16 v[60:63], v[92:95], v[124:127], v[60:63]
	s_waitcnt vmcnt(0)
	s_barrier
	s_add_u32 s26, s26, 0x80
	s_addc_u32 s27, s27, 0
	s_add_u32 s28, s28, 0x80
	s_addc_u32 s29, s29, 0
	s_mov_b32 m0, s42
	s_nop 0
	global_load_lds_dwordx4 v132, s[26:27] offset:0
	global_load_lds_dwordx4 v133, s[26:27] offset:1024
	global_load_lds_dwordx4 v134, s[26:27] offset:2048
	global_load_lds_dwordx4 v135, s[26:27] offset:3072
	s_mov_b32 m0, s43
	s_nop 0
	global_load_lds_dwordx4 v132, s[28:29] offset:0
	global_load_lds_dwordx4 v133, s[28:29] offset:1024
	global_load_lds_dwordx4 v134, s[28:29] offset:2048
	global_load_lds_dwordx4 v135, s[28:29] offset:3072
	ds_read_b128 v[64:67], v136 offset:0
	ds_read_b128 v[96:99], v140 offset:0
	ds_read_b128 v[100:103], v140 offset:2048
	ds_read_b128 v[104:107], v140 offset:4096
	ds_read_b128 v[108:111], v140 offset:6144
	ds_read_b128 v[68:71], v136 offset:2048
	ds_read_b128 v[72:75], v136 offset:4096
	ds_read_b128 v[76:79], v136 offset:6144
	s_waitcnt lgkmcnt(3)
	v_mfma_f32_16x16x32_bf16 v[0:3], v[64:67], v[96:99], v[0:3]
	v_mfma_f32_16x16x32_bf16 v[4:7], v[64:67], v[100:103], v[4:7]
	ds_read_b128 v[80:83], v137 offset:0
	v_mfma_f32_16x16x32_bf16 v[8:11], v[64:67], v[104:107], v[8:11]
	v_mfma_f32_16x16x32_bf16 v[12:15], v[64:67], v[108:111], v[12:15]
	ds_read_b128 v[112:115], v141 offset:0
	s_waitcnt lgkmcnt(4)
	v_mfma_f32_16x16x32_bf16 v[16:19], v[68:71], v[96:99], v[16:19]
	v_mfma_f32_16x16x32_bf16 v[20:23], v[68:71], v[100:103], v[20:23]
	ds_read_b128 v[116:119], v141 offset:2048
	v_mfma_f32_16x16x32_bf16 v[24:27], v[68:71], v[104:107], v[24:27]
	v_mfma_f32_16x16x32_bf16 v[28:31], v[68:71], v[108:111], v[28:31]
	ds_read_b128 v[120:123], v141 offset:4096
	s_waitcnt lgkmcnt(5)
	v_mfma_f32_16x16x32_bf16 v[32:35], v[72:75], v[96:99], v[32:35]
	v_mfma_f32_16x16x32_bf16 v[36:39], v[72:75], v[100:103], v[36:39]
	ds_read_b128 v[124:127], v141 offset:6144
	v_mfma_f32_16x16x32_bf16 v[40:43], v[72:75], v[104:107], v[40:43]
	v_mfma_f32_16x16x32_bf16 v[44:47], v[72:75], v[108:111], v[44:47]
	ds_read_b128 v[84:87], v137 offset:2048
	s_waitcnt lgkmcnt(6)
	v_mfma_f32_16x16x32_bf16 v[48:51], v[76:79], v[96:99], v[48:51]
	v_mfma_f32_16x16x32_bf16 v[52:55], v[76:79], v[100:103], v[52:55]
	ds_read_b128 v[88:91], v137 offset:4096
	v_mfma_f32_16x16x32_bf16 v[56:59], v[76:79], v[104:107], v[56:59]
	v_mfma_f32_16x16x32_bf16 v[60:63], v[76:79], v[108:111], v[60:63]
	ds_read_b128 v[92:95], v137 offset:6144
	s_waitcnt lgkmcnt(3)
	v_mfma_f32_16x16x32_bf16 v[0:3], v[80:83], v[112:115], v[0:3]
	v_mfma_f32_16x16x32_bf16 v[4:7], v[80:83], v[116:119], v[4:7]
	v_mfma_f32_16x16x32_bf16 v[8:11], v[80:83], v[120:123], v[8:11]
	v_mfma_f32_16x16x32_bf16 v[12:15], v[80:83], v[124:127], v[12:15]
	s_waitcnt lgkmcnt(2)
	v_mfma_f32_16x16x32_bf16 v[16:19], v[84:87], v[112:115], v[16:19]
	v_mfma_f32_16x16x32_bf16 v[20:23], v[84:87], v[116:119], v[20:23]
	v_mfma_f32_16x16x32_bf16 v[24:27], v[84:87], v[120:123], v[24:27]
	v_mfma_f32_16x16x32_bf16 v[28:31], v[84:87], v[124:127], v[28:31]
	s_waitcnt lgkmcnt(1)
	v_mfma_f32_16x16x32_bf16 v[32:35], v[88:91], v[112:115], v[32:35]
	v_mfma_f32_16x16x32_bf16 v[36:39], v[88:91], v[116:119], v[36:39]
	v_mfma_f32_16x16x32_bf16 v[40:43], v[88:91], v[120:123], v[40:43]
	v_mfma_f32_16x16x32_bf16 v[44:47], v[88:91], v[124:127], v[44:47]
	s_waitcnt lgkmcnt(0)
	v_mfma_f32_16x16x32_bf16 v[48:51], v[92:95], v[112:115], v[48:51]
	v_mfma_f32_16x16x32_bf16 v[52:55], v[92:95], v[116:119], v[52:55]
	v_mfma_f32_16x16x32_bf16 v[56:59], v[92:95], v[120:123], v[56:59]
	v_mfma_f32_16x16x32_bf16 v[60:63], v[92:95], v[124:127], v[60:63]
	s_waitcnt vmcnt(0)
	s_barrier
	s_add_u32 s26, s26, 0x80
	s_addc_u32 s27, s27, 0
	s_add_u32 s28, s28, 0x80
	s_addc_u32 s29, s29, 0
	s_mov_b32 m0, s40
	s_nop 0
	global_load_lds_dwordx4 v132, s[26:27] offset:0
	global_load_lds_dwordx4 v133, s[26:27] offset:1024
	global_load_lds_dwordx4 v134, s[26:27] offset:2048
	global_load_lds_dwordx4 v135, s[26:27] offset:3072
	s_mov_b32 m0, s41
	s_nop 0
	global_load_lds_dwordx4 v132, s[28:29] offset:0
	global_load_lds_dwordx4 v133, s[28:29] offset:1024
	global_load_lds_dwordx4 v134, s[28:29] offset:2048
	global_load_lds_dwordx4 v135, s[28:29] offset:3072
	ds_read_b128 v[64:67], v138 offset:0
	ds_read_b128 v[96:99], v142 offset:0
	ds_read_b128 v[100:103], v142 offset:2048
	ds_read_b128 v[104:107], v142 offset:4096
	ds_read_b128 v[108:111], v142 offset:6144
	ds_read_b128 v[68:71], v138 offset:2048
	ds_read_b128 v[72:75], v138 offset:4096
	ds_read_b128 v[76:79], v138 offset:6144
	s_waitcnt lgkmcnt(3)
	v_mfma_f32_16x16x32_bf16 v[0:3], v[64:67], v[96:99], v[0:3]
	v_mfma_f32_16x16x32_bf16 v[4:7], v[64:67], v[100:103], v[4:7]
	ds_read_b128 v[80:83], v139 offset:0
	v_mfma_f32_16x16x32_bf16 v[8:11], v[64:67], v[104:107], v[8:11]
	v_mfma_f32_16x16x32_bf16 v[12:15], v[64:67], v[108:111], v[12:15]
	ds_read_b128 v[112:115], v143 offset:0
	s_waitcnt lgkmcnt(4)
	v_mfma_f32_16x16x32_bf16 v[16:19], v[68:71], v[96:99], v[16:19]
	v_mfma_f32_16x16x32_bf16 v[20:23], v[68:71], v[100:103], v[20:23]
	ds_read_b128 v[116:119], v143 offset:2048
	v_mfma_f32_16x16x32_bf16 v[24:27], v[68:71], v[104:107], v[24:27]
	v_mfma_f32_16x16x32_bf16 v[28:31], v[68:71], v[108:111], v[28:31]
	ds_read_b128 v[120:123], v143 offset:4096
	s_waitcnt lgkmcnt(5)
	v_mfma_f32_16x16x32_bf16 v[32:35], v[72:75], v[96:99], v[32:35]
	v_mfma_f32_16x16x32_bf16 v[36:39], v[72:75], v[100:103], v[36:39]
	ds_read_b128 v[124:127], v143 offset:6144
	v_mfma_f32_16x16x32_bf16 v[40:43], v[72:75], v[104:107], v[40:43]
	v_mfma_f32_16x16x32_bf16 v[44:47], v[72:75], v[108:111], v[44:47]
	ds_read_b128 v[84:87], v139 offset:2048
	s_waitcnt lgkmcnt(6)
	v_mfma_f32_16x16x32_bf16 v[48:51], v[76:79], v[96:99], v[48:51]
	v_mfma_f32_16x16x32_bf16 v[52:55], v[76:79], v[100:103], v[52:55]
	ds_read_b128 v[88:91], v139 offset:4096
	v_mfma_f32_16x16x32_bf16 v[56:59], v[76:79], v[104:107], v[56:59]
	v_mfma_f32_16x16x32_bf16 v[60:63], v[76:79], v[108:111], v[60:63]
	ds_read_b128 v[92:95], v139 offset:6144
	s_waitcnt lgkmcnt(3)
	v_mfma_f32_16x16x32_bf16 v[0:3], v[80:83], v[112:115], v[0:3]
	v_mfma_f32_16x16x32_bf16 v[4:7], v[80:83], v[116:119], v[4:7]
	v_mfma_f32_16x16x32_bf16 v[8:11], v[80:83], v[120:123], v[8:11]
	v_mfma_f32_16x16x32_bf16 v[12:15], v[80:83], v[124:127], v[12:15]
	s_waitcnt lgkmcnt(2)
	v_mfma_f32_16x16x32_bf16 v[16:19], v[84:87], v[112:115], v[16:19]
	v_mfma_f32_16x16x32_bf16 v[20:23], v[84:87], v[116:119], v[20:23]
	v_mfma_f32_16x16x32_bf16 v[24:27], v[84:87], v[120:123], v[24:27]
	v_mfma_f32_16x16x32_bf16 v[28:31], v[84:87], v[124:127], v[28:31]
	s_waitcnt lgkmcnt(1)
	v_mfma_f32_16x16x32_bf16 v[32:35], v[88:91], v[112:115], v[32:35]
	v_mfma_f32_16x16x32_bf16 v[36:39], v[88:91], v[116:119], v[36:39]
	v_mfma_f32_16x16x32_bf16 v[40:43], v[88:91], v[120:123], v[40:43]
	v_mfma_f32_16x16x32_bf16 v[44:47], v[88:91], v[124:127], v[44:47]
	s_waitcnt lgkmcnt(0)
	v_mfma_f32_16x16x32_bf16 v[48:51], v[92:95], v[112:115], v[48:51]
	v_mfma_f32_16x16x32_bf16 v[52:55], v[92:95], v[116:119], v[52:55]
	v_mfma_f32_16x16x32_bf16 v[56:59], v[92:95], v[120:123], v[56:59]
	v_mfma_f32_16x16x32_bf16 v[60:63], v[92:95], v[124:127], v[60:63]
	s_waitcnt vmcnt(0)
	s_barrier
	s_add_u32 s26, s26, 0x80
	s_addc_u32 s27, s27, 0
	s_add_u32 s28, s28, 0x80
	s_addc_u32 s29, s29, 0
	s_mov_b32 m0, s42
	s_nop 0
	global_load_lds_dwordx4 v132, s[26:27] offset:0
	global_load_lds_dwordx4 v133, s[26:27] offset:1024
	global_load_lds_dwordx4 v134, s[26:27] offset:2048
	global_load_lds_dwordx4 v135, s[26:27] offset:3072
	s_mov_b32 m0, s43
	s_nop 0
	global_load_lds_dwordx4 v132, s[28:29] offset:0
	global_load_lds_dwordx4 v133, s[28:29] offset:1024
	global_load_lds_dwordx4 v134, s[28:29] offset:2048
	global_load_lds_dwordx4 v135, s[28:29] offset:3072
	ds_read_b128 v[64:67], v136 offset:0
	ds_read_b128 v[96:99], v140 offset:0
	ds_read_b128 v[100:103], v140 offset:2048
	ds_read_b128 v[104:107], v140 offset:4096
	ds_read_b128 v[108:111], v140 offset:6144
	ds_read_b128 v[68:71], v136 offset:2048
	ds_read_b128 v[72:75], v136 offset:4096
	ds_read_b128 v[76:79], v136 offset:6144
	s_waitcnt lgkmcnt(3)
	v_mfma_f32_16x16x32_bf16 v[0:3], v[64:67], v[96:99], v[0:3]
	v_mfma_f32_16x16x32_bf16 v[4:7], v[64:67], v[100:103], v[4:7]
	ds_read_b128 v[80:83], v137 offset:0
	v_mfma_f32_16x16x32_bf16 v[8:11], v[64:67], v[104:107], v[8:11]
	v_mfma_f32_16x16x32_bf16 v[12:15], v[64:67], v[108:111], v[12:15]
	ds_read_b128 v[112:115], v141 offset:0
	s_waitcnt lgkmcnt(4)
	v_mfma_f32_16x16x32_bf16 v[16:19], v[68:71], v[96:99], v[16:19]
	v_mfma_f32_16x16x32_bf16 v[20:23], v[68:71], v[100:103], v[20:23]
	ds_read_b128 v[116:119], v141 offset:2048
	v_mfma_f32_16x16x32_bf16 v[24:27], v[68:71], v[104:107], v[24:27]
	v_mfma_f32_16x16x32_bf16 v[28:31], v[68:71], v[108:111], v[28:31]
	ds_read_b128 v[120:123], v141 offset:4096
	s_waitcnt lgkmcnt(5)
	v_mfma_f32_16x16x32_bf16 v[32:35], v[72:75], v[96:99], v[32:35]
	v_mfma_f32_16x16x32_bf16 v[36:39], v[72:75], v[100:103], v[36:39]
	ds_read_b128 v[124:127], v141 offset:6144
	v_mfma_f32_16x16x32_bf16 v[40:43], v[72:75], v[104:107], v[40:43]
	v_mfma_f32_16x16x32_bf16 v[44:47], v[72:75], v[108:111], v[44:47]
	ds_read_b128 v[84:87], v137 offset:2048
	s_waitcnt lgkmcnt(6)
	v_mfma_f32_16x16x32_bf16 v[48:51], v[76:79], v[96:99], v[48:51]
	v_mfma_f32_16x16x32_bf16 v[52:55], v[76:79], v[100:103], v[52:55]
	ds_read_b128 v[88:91], v137 offset:4096
	v_mfma_f32_16x16x32_bf16 v[56:59], v[76:79], v[104:107], v[56:59]
	v_mfma_f32_16x16x32_bf16 v[60:63], v[76:79], v[108:111], v[60:63]
	ds_read_b128 v[92:95], v137 offset:6144
	s_waitcnt lgkmcnt(3)
	v_mfma_f32_16x16x32_bf16 v[0:3], v[80:83], v[112:115], v[0:3]
	v_mfma_f32_16x16x32_bf16 v[4:7], v[80:83], v[116:119], v[4:7]
	v_mfma_f32_16x16x32_bf16 v[8:11], v[80:83], v[120:123], v[8:11]
	v_mfma_f32_16x16x32_bf16 v[12:15], v[80:83], v[124:127], v[12:15]
	s_waitcnt lgkmcnt(2)
	v_mfma_f32_16x16x32_bf16 v[16:19], v[84:87], v[112:115], v[16:19]
	v_mfma_f32_16x16x32_bf16 v[20:23], v[84:87], v[116:119], v[20:23]
	v_mfma_f32_16x16x32_bf16 v[24:27], v[84:87], v[120:123], v[24:27]
	v_mfma_f32_16x16x32_bf16 v[28:31], v[84:87], v[124:127], v[28:31]
	s_waitcnt lgkmcnt(1)
	v_mfma_f32_16x16x32_bf16 v[32:35], v[88:91], v[112:115], v[32:35]
	v_mfma_f32_16x16x32_bf16 v[36:39], v[88:91], v[116:119], v[36:39]
	v_mfma_f32_16x16x32_bf16 v[40:43], v[88:91], v[120:123], v[40:43]
	v_mfma_f32_16x16x32_bf16 v[44:47], v[88:91], v[124:127], v[44:47]
	s_waitcnt lgkmcnt(0)
	v_mfma_f32_16x16x32_bf16 v[48:51], v[92:95], v[112:115], v[48:51]
	v_mfma_f32_16x16x32_bf16 v[52:55], v[92:95], v[116:119], v[52:55]
	v_mfma_f32_16x16x32_bf16 v[56:59], v[92:95], v[120:123], v[56:59]
	v_mfma_f32_16x16x32_bf16 v[60:63], v[92:95], v[124:127], v[60:63]
	s_waitcnt vmcnt(0)
	s_barrier
	s_add_u32 s26, s26, 0x80
	s_addc_u32 s27, s27, 0
	s_add_u32 s28, s28, 0x80
	s_addc_u32 s29, s29, 0
	s_mov_b32 m0, s40
	s_nop 0
	global_load_lds_dwordx4 v132, s[26:27] offset:0
	global_load_lds_dwordx4 v133, s[26:27] offset:1024
	global_load_lds_dwordx4 v134, s[26:27] offset:2048
	global_load_lds_dwordx4 v135, s[26:27] offset:3072
	s_mov_b32 m0, s41
	s_nop 0
	global_load_lds_dwordx4 v132, s[28:29] offset:0
	global_load_lds_dwordx4 v133, s[28:29] offset:1024
	global_load_lds_dwordx4 v134, s[28:29] offset:2048
	global_load_lds_dwordx4 v135, s[28:29] offset:3072
	ds_read_b128 v[64:67], v138 offset:0
	ds_read_b128 v[96:99], v142 offset:0
	ds_read_b128 v[100:103], v142 offset:2048
	ds_read_b128 v[104:107], v142 offset:4096
	ds_read_b128 v[108:111], v142 offset:6144
	ds_read_b128 v[68:71], v138 offset:2048
	ds_read_b128 v[72:75], v138 offset:4096
	ds_read_b128 v[76:79], v138 offset:6144
	s_waitcnt lgkmcnt(3)
	v_mfma_f32_16x16x32_bf16 v[0:3], v[64:67], v[96:99], v[0:3]
	v_mfma_f32_16x16x32_bf16 v[4:7], v[64:67], v[100:103], v[4:7]
	ds_read_b128 v[80:83], v139 offset:0
	v_mfma_f32_16x16x32_bf16 v[8:11], v[64:67], v[104:107], v[8:11]
	v_mfma_f32_16x16x32_bf16 v[12:15], v[64:67], v[108:111], v[12:15]
	ds_read_b128 v[112:115], v143 offset:0
	s_waitcnt lgkmcnt(4)
	v_mfma_f32_16x16x32_bf16 v[16:19], v[68:71], v[96:99], v[16:19]
	v_mfma_f32_16x16x32_bf16 v[20:23], v[68:71], v[100:103], v[20:23]
	ds_read_b128 v[116:119], v143 offset:2048
	v_mfma_f32_16x16x32_bf16 v[24:27], v[68:71], v[104:107], v[24:27]
	v_mfma_f32_16x16x32_bf16 v[28:31], v[68:71], v[108:111], v[28:31]
	ds_read_b128 v[120:123], v143 offset:4096
	s_waitcnt lgkmcnt(5)
	v_mfma_f32_16x16x32_bf16 v[32:35], v[72:75], v[96:99], v[32:35]
	v_mfma_f32_16x16x32_bf16 v[36:39], v[72:75], v[100:103], v[36:39]
	ds_read_b128 v[124:127], v143 offset:6144
	v_mfma_f32_16x16x32_bf16 v[40:43], v[72:75], v[104:107], v[40:43]
	v_mfma_f32_16x16x32_bf16 v[44:47], v[72:75], v[108:111], v[44:47]
	ds_read_b128 v[84:87], v139 offset:2048
	s_waitcnt lgkmcnt(6)
	v_mfma_f32_16x16x32_bf16 v[48:51], v[76:79], v[96:99], v[48:51]
	v_mfma_f32_16x16x32_bf16 v[52:55], v[76:79], v[100:103], v[52:55]
	ds_read_b128 v[88:91], v139 offset:4096
	v_mfma_f32_16x16x32_bf16 v[56:59], v[76:79], v[104:107], v[56:59]
	v_mfma_f32_16x16x32_bf16 v[60:63], v[76:79], v[108:111], v[60:63]
	ds_read_b128 v[92:95], v139 offset:6144
	s_waitcnt lgkmcnt(3)
	v_mfma_f32_16x16x32_bf16 v[0:3], v[80:83], v[112:115], v[0:3]
	v_mfma_f32_16x16x32_bf16 v[4:7], v[80:83], v[116:119], v[4:7]
	v_mfma_f32_16x16x32_bf16 v[8:11], v[80:83], v[120:123], v[8:11]
	v_mfma_f32_16x16x32_bf16 v[12:15], v[80:83], v[124:127], v[12:15]
	s_waitcnt lgkmcnt(2)
	v_mfma_f32_16x16x32_bf16 v[16:19], v[84:87], v[112:115], v[16:19]
	v_mfma_f32_16x16x32_bf16 v[20:23], v[84:87], v[116:119], v[20:23]
	v_mfma_f32_16x16x32_bf16 v[24:27], v[84:87], v[120:123], v[24:27]
	v_mfma_f32_16x16x32_bf16 v[28:31], v[84:87], v[124:127], v[28:31]
	s_waitcnt lgkmcnt(1)
	v_mfma_f32_16x16x32_bf16 v[32:35], v[88:91], v[112:115], v[32:35]
	v_mfma_f32_16x16x32_bf16 v[36:39], v[88:91], v[116:119], v[36:39]
	v_mfma_f32_16x16x32_bf16 v[40:43], v[88:91], v[120:123], v[40:43]
	v_mfma_f32_16x16x32_bf16 v[44:47], v[88:91], v[124:127], v[44:47]
	s_waitcnt lgkmcnt(0)
	v_mfma_f32_16x16x32_bf16 v[48:51], v[92:95], v[112:115], v[48:51]
	v_mfma_f32_16x16x32_bf16 v[52:55], v[92:95], v[116:119], v[52:55]
	v_mfma_f32_16x16x32_bf16 v[56:59], v[92:95], v[120:123], v[56:59]
	v_mfma_f32_16x16x32_bf16 v[60:63], v[92:95], v[124:127], v[60:63]
	s_waitcnt vmcnt(0)
	s_barrier
	s_add_u32 s26, s26, 0x80
	s_addc_u32 s27, s27, 0
	s_add_u32 s28, s28, 0x80
	s_addc_u32 s29, s29, 0
	s_mov_b32 m0, s42
	s_nop 0
	global_load_lds_dwordx4 v132, s[26:27] offset:0
	global_load_lds_dwordx4 v133, s[26:27] offset:1024
	global_load_lds_dwordx4 v134, s[26:27] offset:2048
	global_load_lds_dwordx4 v135, s[26:27] offset:3072
	s_mov_b32 m0, s43
	s_nop 0
	global_load_lds_dwordx4 v132, s[28:29] offset:0
	global_load_lds_dwordx4 v133, s[28:29] offset:1024
	global_load_lds_dwordx4 v134, s[28:29] offset:2048
	global_load_lds_dwordx4 v135, s[28:29] offset:3072
	ds_read_b128 v[64:67], v136 offset:0
	ds_read_b128 v[96:99], v140 offset:0
	ds_read_b128 v[100:103], v140 offset:2048
	ds_read_b128 v[104:107], v140 offset:4096
	ds_read_b128 v[108:111], v140 offset:6144
	ds_read_b128 v[68:71], v136 offset:2048
	ds_read_b128 v[72:75], v136 offset:4096
	ds_read_b128 v[76:79], v136 offset:6144
	s_waitcnt lgkmcnt(3)
	v_mfma_f32_16x16x32_bf16 v[0:3], v[64:67], v[96:99], v[0:3]
	v_mfma_f32_16x16x32_bf16 v[4:7], v[64:67], v[100:103], v[4:7]
	ds_read_b128 v[80:83], v137 offset:0
	v_mfma_f32_16x16x32_bf16 v[8:11], v[64:67], v[104:107], v[8:11]
	v_mfma_f32_16x16x32_bf16 v[12:15], v[64:67], v[108:111], v[12:15]
	ds_read_b128 v[112:115], v141 offset:0
	s_waitcnt lgkmcnt(4)
	v_mfma_f32_16x16x32_bf16 v[16:19], v[68:71], v[96:99], v[16:19]
	v_mfma_f32_16x16x32_bf16 v[20:23], v[68:71], v[100:103], v[20:23]
	ds_read_b128 v[116:119], v141 offset:2048
	v_mfma_f32_16x16x32_bf16 v[24:27], v[68:71], v[104:107], v[24:27]
	v_mfma_f32_16x16x32_bf16 v[28:31], v[68:71], v[108:111], v[28:31]
	ds_read_b128 v[120:123], v141 offset:4096
	s_waitcnt lgkmcnt(5)
	v_mfma_f32_16x16x32_bf16 v[32:35], v[72:75], v[96:99], v[32:35]
	v_mfma_f32_16x16x32_bf16 v[36:39], v[72:75], v[100:103], v[36:39]
	ds_read_b128 v[124:127], v141 offset:6144
	v_mfma_f32_16x16x32_bf16 v[40:43], v[72:75], v[104:107], v[40:43]
	v_mfma_f32_16x16x32_bf16 v[44:47], v[72:75], v[108:111], v[44:47]
	ds_read_b128 v[84:87], v137 offset:2048
	s_waitcnt lgkmcnt(6)
	v_mfma_f32_16x16x32_bf16 v[48:51], v[76:79], v[96:99], v[48:51]
	v_mfma_f32_16x16x32_bf16 v[52:55], v[76:79], v[100:103], v[52:55]
	ds_read_b128 v[88:91], v137 offset:4096
	v_mfma_f32_16x16x32_bf16 v[56:59], v[76:79], v[104:107], v[56:59]
	v_mfma_f32_16x16x32_bf16 v[60:63], v[76:79], v[108:111], v[60:63]
	ds_read_b128 v[92:95], v137 offset:6144
	s_waitcnt lgkmcnt(3)
	v_mfma_f32_16x16x32_bf16 v[0:3], v[80:83], v[112:115], v[0:3]
	v_mfma_f32_16x16x32_bf16 v[4:7], v[80:83], v[116:119], v[4:7]
	v_mfma_f32_16x16x32_bf16 v[8:11], v[80:83], v[120:123], v[8:11]
	v_mfma_f32_16x16x32_bf16 v[12:15], v[80:83], v[124:127], v[12:15]
	s_waitcnt lgkmcnt(2)
	v_mfma_f32_16x16x32_bf16 v[16:19], v[84:87], v[112:115], v[16:19]
	v_mfma_f32_16x16x32_bf16 v[20:23], v[84:87], v[116:119], v[20:23]
	v_mfma_f32_16x16x32_bf16 v[24:27], v[84:87], v[120:123], v[24:27]
	v_mfma_f32_16x16x32_bf16 v[28:31], v[84:87], v[124:127], v[28:31]
	s_waitcnt lgkmcnt(1)
	v_mfma_f32_16x16x32_bf16 v[32:35], v[88:91], v[112:115], v[32:35]
	v_mfma_f32_16x16x32_bf16 v[36:39], v[88:91], v[116:119], v[36:39]
	v_mfma_f32_16x16x32_bf16 v[40:43], v[88:91], v[120:123], v[40:43]
	v_mfma_f32_16x16x32_bf16 v[44:47], v[88:91], v[124:127], v[44:47]
	s_waitcnt lgkmcnt(0)
	v_mfma_f32_16x16x32_bf16 v[48:51], v[92:95], v[112:115], v[48:51]
	v_mfma_f32_16x16x32_bf16 v[52:55], v[92:95], v[116:119], v[52:55]
	v_mfma_f32_16x16x32_bf16 v[56:59], v[92:95], v[120:123], v[56:59]
	v_mfma_f32_16x16x32_bf16 v[60:63], v[92:95], v[124:127], v[60:63]
	s_waitcnt vmcnt(0)
	s_barrier
	ds_read_b128 v[64:67], v138 offset:0
	ds_read_b128 v[96:99], v142 offset:0
	ds_read_b128 v[100:103], v142 offset:2048
	ds_read_b128 v[104:107], v142 offset:4096
	ds_read_b128 v[108:111], v142 offset:6144
	ds_read_b128 v[68:71], v138 offset:2048
	ds_read_b128 v[72:75], v138 offset:4096
	ds_read_b128 v[76:79], v138 offset:6144
	s_waitcnt lgkmcnt(3)
	v_mfma_f32_16x16x32_bf16 v[0:3], v[64:67], v[96:99], v[0:3]
	v_mfma_f32_16x16x32_bf16 v[4:7], v[64:67], v[100:103], v[4:7]
	ds_read_b128 v[80:83], v139 offset:0
	v_mfma_f32_16x16x32_bf16 v[8:11], v[64:67], v[104:107], v[8:11]
	v_mfma_f32_16x16x32_bf16 v[12:15], v[64:67], v[108:111], v[12:15]
	ds_read_b128 v[112:115], v143 offset:0
	s_waitcnt lgkmcnt(4)
	v_mfma_f32_16x16x32_bf16 v[16:19], v[68:71], v[96:99], v[16:19]
	v_mfma_f32_16x16x32_bf16 v[20:23], v[68:71], v[100:103], v[20:23]
	ds_read_b128 v[116:119], v143 offset:2048
	v_mfma_f32_16x16x32_bf16 v[24:27], v[68:71], v[104:107], v[24:27]
	v_mfma_f32_16x16x32_bf16 v[28:31], v[68:71], v[108:111], v[28:31]
	ds_read_b128 v[120:123], v143 offset:4096
	s_waitcnt lgkmcnt(5)
	v_mfma_f32_16x16x32_bf16 v[32:35], v[72:75], v[96:99], v[32:35]
	v_mfma_f32_16x16x32_bf16 v[36:39], v[72:75], v[100:103], v[36:39]
	ds_read_b128 v[124:127], v143 offset:6144
	v_mfma_f32_16x16x32_bf16 v[40:43], v[72:75], v[104:107], v[40:43]
	v_mfma_f32_16x16x32_bf16 v[44:47], v[72:75], v[108:111], v[44:47]
	ds_read_b128 v[84:87], v139 offset:2048
	s_waitcnt lgkmcnt(6)
	v_mfma_f32_16x16x32_bf16 v[48:51], v[76:79], v[96:99], v[48:51]
	v_mfma_f32_16x16x32_bf16 v[52:55], v[76:79], v[100:103], v[52:55]
	ds_read_b128 v[88:91], v139 offset:4096
	v_mfma_f32_16x16x32_bf16 v[56:59], v[76:79], v[104:107], v[56:59]
	v_mfma_f32_16x16x32_bf16 v[60:63], v[76:79], v[108:111], v[60:63]
	ds_read_b128 v[92:95], v139 offset:6144
	s_waitcnt lgkmcnt(3)
	v_mfma_f32_16x16x32_bf16 v[0:3], v[80:83], v[112:115], v[0:3]
	v_mfma_f32_16x16x32_bf16 v[4:7], v[80:83], v[116:119], v[4:7]
	v_mfma_f32_16x16x32_bf16 v[8:11], v[80:83], v[120:123], v[8:11]
	v_mfma_f32_16x16x32_bf16 v[12:15], v[80:83], v[124:127], v[12:15]
	s_waitcnt lgkmcnt(2)
	v_mfma_f32_16x16x32_bf16 v[16:19], v[84:87], v[112:115], v[16:19]
	v_mfma_f32_16x16x32_bf16 v[20:23], v[84:87], v[116:119], v[20:23]
	v_mfma_f32_16x16x32_bf16 v[24:27], v[84:87], v[120:123], v[24:27]
	v_mfma_f32_16x16x32_bf16 v[28:31], v[84:87], v[124:127], v[28:31]
	s_waitcnt lgkmcnt(1)
	v_mfma_f32_16x16x32_bf16 v[32:35], v[88:91], v[112:115], v[32:35]
	v_mfma_f32_16x16x32_bf16 v[36:39], v[88:91], v[116:119], v[36:39]
	v_mfma_f32_16x16x32_bf16 v[40:43], v[88:91], v[120:123], v[40:43]
	v_mfma_f32_16x16x32_bf16 v[44:47], v[88:91], v[124:127], v[44:47]
	s_waitcnt lgkmcnt(0)
	v_mfma_f32_16x16x32_bf16 v[48:51], v[92:95], v[112:115], v[48:51]
	v_mfma_f32_16x16x32_bf16 v[52:55], v[92:95], v[116:119], v[52:55]
	v_mfma_f32_16x16x32_bf16 v[56:59], v[92:95], v[120:123], v[56:59]
	v_mfma_f32_16x16x32_bf16 v[60:63], v[92:95], v[124:127], v[60:63]
	s_nop 7
	s_add_u32 s36, s36, 0x800
	s_addc_u32 s37, s37, 0
	global_load_dwordx2 v[64:65], v236, s[36:37] offset:0
	global_load_dwordx2 v[66:67], v236, s[36:37] offset:32
	global_load_dwordx2 v[68:69], v236, s[36:37] offset:64
	global_load_dwordx2 v[70:71], v236, s[36:37] offset:96
	global_load_dwordx2 v[72:73], v237, s[36:37] offset:0
	global_load_dwordx2 v[74:75], v237, s[36:37] offset:32
	global_load_dwordx2 v[76:77], v237, s[36:37] offset:64
	global_load_dwordx2 v[78:79], v237, s[36:37] offset:96
	global_load_dwordx2 v[80:81], v238, s[36:37] offset:0
	global_load_dwordx2 v[82:83], v238, s[36:37] offset:32
	global_load_dwordx2 v[84:85], v238, s[36:37] offset:64
	global_load_dwordx2 v[86:87], v238, s[36:37] offset:96
	global_load_dwordx2 v[88:89], v239, s[36:37] offset:0
	global_load_dwordx2 v[90:91], v239, s[36:37] offset:32
	global_load_dwordx2 v[92:93], v239, s[36:37] offset:64
	global_load_dwordx2 v[94:95], v239, s[36:37] offset:96
	s_waitcnt vmcnt(15)
	v_lshlrev_b32_e32 v96, 16, v64
	v_and_b32_e32 v97, 0xffff0000, v64
	v_lshlrev_b32_e32 v98, 16, v65
	v_and_b32_e32 v99, 0xffff0000, v65
	v_mul_f32_e32 v96, 0xbfb8aa3b, v96
	v_mul_f32_e32 v97, 0xbfb8aa3b, v97
	v_mul_f32_e32 v98, 0xbfb8aa3b, v98
	v_mul_f32_e32 v99, 0xbfb8aa3b, v99
	v_exp_f32_e32 v96, v96
	v_exp_f32_e32 v97, v97
	v_exp_f32_e32 v98, v98
	v_exp_f32_e32 v99, v99
	v_add_f32_e32 v96, 1.0, v96
	v_add_f32_e32 v97, 1.0, v97
	v_add_f32_e32 v98, 1.0, v98
	v_add_f32_e32 v99, 1.0, v99
	v_rcp_f32_e32 v96, v96
	v_rcp_f32_e32 v97, v97
	v_rcp_f32_e32 v98, v98
	v_rcp_f32_e32 v99, v99
	s_nop 0
	v_fmac_f32_e32 v146, v96, v0
	v_fmac_f32_e32 v147, v97, v1
	v_fmac_f32_e32 v148, v98, v2
	v_fmac_f32_e32 v149, v99, v3
	s_waitcnt vmcnt(14)
	v_lshlrev_b32_e32 v100, 16, v66
	v_and_b32_e32 v101, 0xffff0000, v66
	v_lshlrev_b32_e32 v102, 16, v67
	v_and_b32_e32 v103, 0xffff0000, v67
	v_mul_f32_e32 v100, 0xbfb8aa3b, v100
	v_mul_f32_e32 v101, 0xbfb8aa3b, v101
	v_mul_f32_e32 v102, 0xbfb8aa3b, v102
	v_mul_f32_e32 v103, 0xbfb8aa3b, v103
	v_exp_f32_e32 v100, v100
	v_exp_f32_e32 v101, v101
	v_exp_f32_e32 v102, v102
	v_exp_f32_e32 v103, v103
	v_add_f32_e32 v100, 1.0, v100
	v_add_f32_e32 v101, 1.0, v101
	v_add_f32_e32 v102, 1.0, v102
	v_add_f32_e32 v103, 1.0, v103
	v_rcp_f32_e32 v100, v100
	v_rcp_f32_e32 v101, v101
	v_rcp_f32_e32 v102, v102
	v_rcp_f32_e32 v103, v103
	s_nop 0
	v_fmac_f32_e32 v162, v100, v16
	v_fmac_f32_e32 v163, v101, v17
	v_fmac_f32_e32 v164, v102, v18
	v_fmac_f32_e32 v165, v103, v19
	s_waitcnt vmcnt(13)
	v_lshlrev_b32_e32 v96, 16, v68
	v_and_b32_e32 v97, 0xffff0000, v68
	v_lshlrev_b32_e32 v98, 16, v69
	v_and_b32_e32 v99, 0xffff0000, v69
	v_mul_f32_e32 v96, 0xbfb8aa3b, v96
	v_mul_f32_e32 v97, 0xbfb8aa3b, v97
	v_mul_f32_e32 v98, 0xbfb8aa3b, v98
	v_mul_f32_e32 v99, 0xbfb8aa3b, v99
	v_exp_f32_e32 v96, v96
	v_exp_f32_e32 v97, v97
	v_exp_f32_e32 v98, v98
	v_exp_f32_e32 v99, v99
	v_add_f32_e32 v96, 1.0, v96
	v_add_f32_e32 v97, 1.0, v97
	v_add_f32_e32 v98, 1.0, v98
	v_add_f32_e32 v99, 1.0, v99
	v_rcp_f32_e32 v96, v96
	v_rcp_f32_e32 v97, v97
	v_rcp_f32_e32 v98, v98
	v_rcp_f32_e32 v99, v99
	s_nop 0
	v_fmac_f32_e32 v178, v96, v32
	v_fmac_f32_e32 v179, v97, v33
	v_fmac_f32_e32 v180, v98, v34
	v_fmac_f32_e32 v181, v99, v35
	s_waitcnt vmcnt(12)
	v_lshlrev_b32_e32 v100, 16, v70
	v_and_b32_e32 v101, 0xffff0000, v70
	v_lshlrev_b32_e32 v102, 16, v71
	v_and_b32_e32 v103, 0xffff0000, v71
	v_mul_f32_e32 v100, 0xbfb8aa3b, v100
	v_mul_f32_e32 v101, 0xbfb8aa3b, v101
	v_mul_f32_e32 v102, 0xbfb8aa3b, v102
	v_mul_f32_e32 v103, 0xbfb8aa3b, v103
	v_exp_f32_e32 v100, v100
	v_exp_f32_e32 v101, v101
	v_exp_f32_e32 v102, v102
	v_exp_f32_e32 v103, v103
	v_add_f32_e32 v100, 1.0, v100
	v_add_f32_e32 v101, 1.0, v101
	v_add_f32_e32 v102, 1.0, v102
	v_add_f32_e32 v103, 1.0, v103
	v_rcp_f32_e32 v100, v100
	v_rcp_f32_e32 v101, v101
	v_rcp_f32_e32 v102, v102
	v_rcp_f32_e32 v103, v103
	s_nop 0
	v_fmac_f32_e32 v194, v100, v48
	v_fmac_f32_e32 v195, v101, v49
	v_fmac_f32_e32 v196, v102, v50
	v_fmac_f32_e32 v197, v103, v51
	s_waitcnt vmcnt(11)
	v_lshlrev_b32_e32 v96, 16, v72
	v_and_b32_e32 v97, 0xffff0000, v72
	v_lshlrev_b32_e32 v98, 16, v73
	v_and_b32_e32 v99, 0xffff0000, v73
	v_mul_f32_e32 v96, 0xbfb8aa3b, v96
	v_mul_f32_e32 v97, 0xbfb8aa3b, v97
	v_mul_f32_e32 v98, 0xbfb8aa3b, v98
	v_mul_f32_e32 v99, 0xbfb8aa3b, v99
	v_exp_f32_e32 v96, v96
	v_exp_f32_e32 v97, v97
	v_exp_f32_e32 v98, v98
	v_exp_f32_e32 v99, v99
	v_add_f32_e32 v96, 1.0, v96
	v_add_f32_e32 v97, 1.0, v97
	v_add_f32_e32 v98, 1.0, v98
	v_add_f32_e32 v99, 1.0, v99
	v_rcp_f32_e32 v96, v96
	v_rcp_f32_e32 v97, v97
	v_rcp_f32_e32 v98, v98
	v_rcp_f32_e32 v99, v99
	s_nop 0
	v_fmac_f32_e32 v150, v96, v4
	v_fmac_f32_e32 v151, v97, v5
	v_fmac_f32_e32 v152, v98, v6
	v_fmac_f32_e32 v153, v99, v7
	s_waitcnt vmcnt(10)
	v_lshlrev_b32_e32 v100, 16, v74
	v_and_b32_e32 v101, 0xffff0000, v74
	v_lshlrev_b32_e32 v102, 16, v75
	v_and_b32_e32 v103, 0xffff0000, v75
	v_mul_f32_e32 v100, 0xbfb8aa3b, v100
	v_mul_f32_e32 v101, 0xbfb8aa3b, v101
	v_mul_f32_e32 v102, 0xbfb8aa3b, v102
	v_mul_f32_e32 v103, 0xbfb8aa3b, v103
	v_exp_f32_e32 v100, v100
	v_exp_f32_e32 v101, v101
	v_exp_f32_e32 v102, v102
	v_exp_f32_e32 v103, v103
	v_add_f32_e32 v100, 1.0, v100
	v_add_f32_e32 v101, 1.0, v101
	v_add_f32_e32 v102, 1.0, v102
	v_add_f32_e32 v103, 1.0, v103
	v_rcp_f32_e32 v100, v100
	v_rcp_f32_e32 v101, v101
	v_rcp_f32_e32 v102, v102
	v_rcp_f32_e32 v103, v103
	s_nop 0
	v_fmac_f32_e32 v166, v100, v20
	v_fmac_f32_e32 v167, v101, v21
	v_fmac_f32_e32 v168, v102, v22
	v_fmac_f32_e32 v169, v103, v23
	s_waitcnt vmcnt(9)
	v_lshlrev_b32_e32 v96, 16, v76
	v_and_b32_e32 v97, 0xffff0000, v76
	v_lshlrev_b32_e32 v98, 16, v77
	v_and_b32_e32 v99, 0xffff0000, v77
	v_mul_f32_e32 v96, 0xbfb8aa3b, v96
	v_mul_f32_e32 v97, 0xbfb8aa3b, v97
	v_mul_f32_e32 v98, 0xbfb8aa3b, v98
	v_mul_f32_e32 v99, 0xbfb8aa3b, v99
	v_exp_f32_e32 v96, v96
	v_exp_f32_e32 v97, v97
	v_exp_f32_e32 v98, v98
	v_exp_f32_e32 v99, v99
	v_add_f32_e32 v96, 1.0, v96
	v_add_f32_e32 v97, 1.0, v97
	v_add_f32_e32 v98, 1.0, v98
	v_add_f32_e32 v99, 1.0, v99
	v_rcp_f32_e32 v96, v96
	v_rcp_f32_e32 v97, v97
	v_rcp_f32_e32 v98, v98
	v_rcp_f32_e32 v99, v99
	s_nop 0
	v_fmac_f32_e32 v182, v96, v36
	v_fmac_f32_e32 v183, v97, v37
	v_fmac_f32_e32 v184, v98, v38
	v_fmac_f32_e32 v185, v99, v39
	s_waitcnt vmcnt(8)
	v_lshlrev_b32_e32 v100, 16, v78
	v_and_b32_e32 v101, 0xffff0000, v78
	v_lshlrev_b32_e32 v102, 16, v79
	v_and_b32_e32 v103, 0xffff0000, v79
	v_mul_f32_e32 v100, 0xbfb8aa3b, v100
	v_mul_f32_e32 v101, 0xbfb8aa3b, v101
	v_mul_f32_e32 v102, 0xbfb8aa3b, v102
	v_mul_f32_e32 v103, 0xbfb8aa3b, v103
	v_exp_f32_e32 v100, v100
	v_exp_f32_e32 v101, v101
	v_exp_f32_e32 v102, v102
	v_exp_f32_e32 v103, v103
	v_add_f32_e32 v100, 1.0, v100
	v_add_f32_e32 v101, 1.0, v101
	v_add_f32_e32 v102, 1.0, v102
	v_add_f32_e32 v103, 1.0, v103
	v_rcp_f32_e32 v100, v100
	v_rcp_f32_e32 v101, v101
	v_rcp_f32_e32 v102, v102
	v_rcp_f32_e32 v103, v103
	s_nop 0
	v_fmac_f32_e32 v200, v100, v52
	v_fmac_f32_e32 v201, v101, v53
	v_fmac_f32_e32 v202, v102, v54
	v_fmac_f32_e32 v203, v103, v55
	s_waitcnt vmcnt(7)
	v_lshlrev_b32_e32 v96, 16, v80
	v_and_b32_e32 v97, 0xffff0000, v80
	v_lshlrev_b32_e32 v98, 16, v81
	v_and_b32_e32 v99, 0xffff0000, v81
	v_mul_f32_e32 v96, 0xbfb8aa3b, v96
	v_mul_f32_e32 v97, 0xbfb8aa3b, v97
	v_mul_f32_e32 v98, 0xbfb8aa3b, v98
	v_mul_f32_e32 v99, 0xbfb8aa3b, v99
	v_exp_f32_e32 v96, v96
	v_exp_f32_e32 v97, v97
	v_exp_f32_e32 v98, v98
	v_exp_f32_e32 v99, v99
	v_add_f32_e32 v96, 1.0, v96
	v_add_f32_e32 v97, 1.0, v97
	v_add_f32_e32 v98, 1.0, v98
	v_add_f32_e32 v99, 1.0, v99
	v_rcp_f32_e32 v96, v96
	v_rcp_f32_e32 v97, v97
	v_rcp_f32_e32 v98, v98
	v_rcp_f32_e32 v99, v99
	s_nop 0
	v_fmac_f32_e32 v154, v96, v8
	v_fmac_f32_e32 v155, v97, v9
	v_fmac_f32_e32 v156, v98, v10
	v_fmac_f32_e32 v157, v99, v11
	s_waitcnt vmcnt(6)
	v_lshlrev_b32_e32 v100, 16, v82
	v_and_b32_e32 v101, 0xffff0000, v82
	v_lshlrev_b32_e32 v102, 16, v83
	v_and_b32_e32 v103, 0xffff0000, v83
	v_mul_f32_e32 v100, 0xbfb8aa3b, v100
	v_mul_f32_e32 v101, 0xbfb8aa3b, v101
	v_mul_f32_e32 v102, 0xbfb8aa3b, v102
	v_mul_f32_e32 v103, 0xbfb8aa3b, v103
	v_exp_f32_e32 v100, v100
	v_exp_f32_e32 v101, v101
	v_exp_f32_e32 v102, v102
	v_exp_f32_e32 v103, v103
	v_add_f32_e32 v100, 1.0, v100
	v_add_f32_e32 v101, 1.0, v101
	v_add_f32_e32 v102, 1.0, v102
	v_add_f32_e32 v103, 1.0, v103
	v_rcp_f32_e32 v100, v100
	v_rcp_f32_e32 v101, v101
	v_rcp_f32_e32 v102, v102
	v_rcp_f32_e32 v103, v103
	s_nop 0
	v_fmac_f32_e32 v170, v100, v24
	v_fmac_f32_e32 v171, v101, v25
	v_fmac_f32_e32 v172, v102, v26
	v_fmac_f32_e32 v173, v103, v27
	s_waitcnt vmcnt(5)
	v_lshlrev_b32_e32 v96, 16, v84
	v_and_b32_e32 v97, 0xffff0000, v84
	v_lshlrev_b32_e32 v98, 16, v85
	v_and_b32_e32 v99, 0xffff0000, v85
	v_mul_f32_e32 v96, 0xbfb8aa3b, v96
	v_mul_f32_e32 v97, 0xbfb8aa3b, v97
	v_mul_f32_e32 v98, 0xbfb8aa3b, v98
	v_mul_f32_e32 v99, 0xbfb8aa3b, v99
	v_exp_f32_e32 v96, v96
	v_exp_f32_e32 v97, v97
	v_exp_f32_e32 v98, v98
	v_exp_f32_e32 v99, v99
	v_add_f32_e32 v96, 1.0, v96
	v_add_f32_e32 v97, 1.0, v97
	v_add_f32_e32 v98, 1.0, v98
	v_add_f32_e32 v99, 1.0, v99
	v_rcp_f32_e32 v96, v96
	v_rcp_f32_e32 v97, v97
	v_rcp_f32_e32 v98, v98
	v_rcp_f32_e32 v99, v99
	s_nop 0
	v_fmac_f32_e32 v186, v96, v40
	v_fmac_f32_e32 v187, v97, v41
	v_fmac_f32_e32 v188, v98, v42
	v_fmac_f32_e32 v189, v99, v43
	s_waitcnt vmcnt(4)
	v_lshlrev_b32_e32 v100, 16, v86
	v_and_b32_e32 v101, 0xffff0000, v86
	v_lshlrev_b32_e32 v102, 16, v87
	v_and_b32_e32 v103, 0xffff0000, v87
	v_mul_f32_e32 v100, 0xbfb8aa3b, v100
	v_mul_f32_e32 v101, 0xbfb8aa3b, v101
	v_mul_f32_e32 v102, 0xbfb8aa3b, v102
	v_mul_f32_e32 v103, 0xbfb8aa3b, v103
	v_exp_f32_e32 v100, v100
	v_exp_f32_e32 v101, v101
	v_exp_f32_e32 v102, v102
	v_exp_f32_e32 v103, v103
	v_add_f32_e32 v100, 1.0, v100
	v_add_f32_e32 v101, 1.0, v101
	v_add_f32_e32 v102, 1.0, v102
	v_add_f32_e32 v103, 1.0, v103
	v_rcp_f32_e32 v100, v100
	v_rcp_f32_e32 v101, v101
	v_rcp_f32_e32 v102, v102
	v_rcp_f32_e32 v103, v103
	s_nop 0
	v_fmac_f32_e32 v208, v100, v56
	v_fmac_f32_e32 v209, v101, v57
	v_fmac_f32_e32 v210, v102, v58
	v_fmac_f32_e32 v211, v103, v59
	s_waitcnt vmcnt(3)
	v_lshlrev_b32_e32 v96, 16, v88
	v_and_b32_e32 v97, 0xffff0000, v88
	v_lshlrev_b32_e32 v98, 16, v89
	v_and_b32_e32 v99, 0xffff0000, v89
	v_mul_f32_e32 v96, 0xbfb8aa3b, v96
	v_mul_f32_e32 v97, 0xbfb8aa3b, v97
	v_mul_f32_e32 v98, 0xbfb8aa3b, v98
	v_mul_f32_e32 v99, 0xbfb8aa3b, v99
	v_exp_f32_e32 v96, v96
	v_exp_f32_e32 v97, v97
	v_exp_f32_e32 v98, v98
	v_exp_f32_e32 v99, v99
	v_add_f32_e32 v96, 1.0, v96
	v_add_f32_e32 v97, 1.0, v97
	v_add_f32_e32 v98, 1.0, v98
	v_add_f32_e32 v99, 1.0, v99
	v_rcp_f32_e32 v96, v96
	v_rcp_f32_e32 v97, v97
	v_rcp_f32_e32 v98, v98
	v_rcp_f32_e32 v99, v99
	s_nop 0
	v_fmac_f32_e32 v158, v96, v12
	v_fmac_f32_e32 v159, v97, v13
	v_fmac_f32_e32 v160, v98, v14
	v_fmac_f32_e32 v161, v99, v15
	s_waitcnt vmcnt(2)
	v_lshlrev_b32_e32 v100, 16, v90
	v_and_b32_e32 v101, 0xffff0000, v90
	v_lshlrev_b32_e32 v102, 16, v91
	v_and_b32_e32 v103, 0xffff0000, v91
	v_mul_f32_e32 v100, 0xbfb8aa3b, v100
	v_mul_f32_e32 v101, 0xbfb8aa3b, v101
	v_mul_f32_e32 v102, 0xbfb8aa3b, v102
	v_mul_f32_e32 v103, 0xbfb8aa3b, v103
	v_exp_f32_e32 v100, v100
	v_exp_f32_e32 v101, v101
	v_exp_f32_e32 v102, v102
	v_exp_f32_e32 v103, v103
	v_add_f32_e32 v100, 1.0, v100
	v_add_f32_e32 v101, 1.0, v101
	v_add_f32_e32 v102, 1.0, v102
	v_add_f32_e32 v103, 1.0, v103
	v_rcp_f32_e32 v100, v100
	v_rcp_f32_e32 v101, v101
	v_rcp_f32_e32 v102, v102
	v_rcp_f32_e32 v103, v103
	s_nop 0
	v_fmac_f32_e32 v174, v100, v28
	v_fmac_f32_e32 v175, v101, v29
	v_fmac_f32_e32 v176, v102, v30
	v_fmac_f32_e32 v177, v103, v31
	s_waitcnt vmcnt(1)
	v_lshlrev_b32_e32 v96, 16, v92
	v_and_b32_e32 v97, 0xffff0000, v92
	v_lshlrev_b32_e32 v98, 16, v93
	v_and_b32_e32 v99, 0xffff0000, v93
	v_mul_f32_e32 v96, 0xbfb8aa3b, v96
	v_mul_f32_e32 v97, 0xbfb8aa3b, v97
	v_mul_f32_e32 v98, 0xbfb8aa3b, v98
	v_mul_f32_e32 v99, 0xbfb8aa3b, v99
	v_exp_f32_e32 v96, v96
	v_exp_f32_e32 v97, v97
	v_exp_f32_e32 v98, v98
	v_exp_f32_e32 v99, v99
	v_add_f32_e32 v96, 1.0, v96
	v_add_f32_e32 v97, 1.0, v97
	v_add_f32_e32 v98, 1.0, v98
	v_add_f32_e32 v99, 1.0, v99
	v_rcp_f32_e32 v96, v96
	v_rcp_f32_e32 v97, v97
	v_rcp_f32_e32 v98, v98
	v_rcp_f32_e32 v99, v99
	s_nop 0
	v_fmac_f32_e32 v190, v96, v44
	v_fmac_f32_e32 v191, v97, v45
	v_fmac_f32_e32 v192, v98, v46
	v_fmac_f32_e32 v193, v99, v47
	s_waitcnt vmcnt(0)
	v_lshlrev_b32_e32 v100, 16, v94
	v_and_b32_e32 v101, 0xffff0000, v94
	v_lshlrev_b32_e32 v102, 16, v95
	v_and_b32_e32 v103, 0xffff0000, v95
	v_mul_f32_e32 v100, 0xbfb8aa3b, v100
	v_mul_f32_e32 v101, 0xbfb8aa3b, v101
	v_mul_f32_e32 v102, 0xbfb8aa3b, v102
	v_mul_f32_e32 v103, 0xbfb8aa3b, v103
	v_exp_f32_e32 v100, v100
	v_exp_f32_e32 v101, v101
	v_exp_f32_e32 v102, v102
	v_exp_f32_e32 v103, v103
	v_add_f32_e32 v100, 1.0, v100
	v_add_f32_e32 v101, 1.0, v101
	v_add_f32_e32 v102, 1.0, v102
	v_add_f32_e32 v103, 1.0, v103
	v_rcp_f32_e32 v100, v100
	v_rcp_f32_e32 v101, v101
	v_rcp_f32_e32 v102, v102
	v_rcp_f32_e32 v103, v103
	s_nop 0
	v_fmac_f32_e32 v232, v100, v60
	v_fmac_f32_e32 v233, v101, v61
	v_fmac_f32_e32 v234, v102, v62
	v_fmac_f32_e32 v235, v103, v63
	v_cvt_pk_bf16_f32 v146, v146, v147
	v_cvt_pk_bf16_f32 v147, v148, v149
	global_store_dwordx2 v240, v[146:147], s[44:45] offset:0
	v_cvt_pk_bf16_f32 v162, v162, v163
	v_cvt_pk_bf16_f32 v163, v164, v165
	global_store_dwordx2 v240, v[162:163], s[44:45] offset:32
	v_cvt_pk_bf16_f32 v178, v178, v179
	v_cvt_pk_bf16_f32 v179, v180, v181
	global_store_dwordx2 v240, v[178:179], s[44:45] offset:64
	v_cvt_pk_bf16_f32 v194, v194, v195
	v_cvt_pk_bf16_f32 v195, v196, v197
	global_store_dwordx2 v240, v[194:195], s[44:45] offset:96
	v_cvt_pk_bf16_f32 v150, v150, v151
	v_cvt_pk_bf16_f32 v151, v152, v153
	global_store_dwordx2 v241, v[150:151], s[44:45] offset:0
	v_cvt_pk_bf16_f32 v166, v166, v167
	v_cvt_pk_bf16_f32 v167, v168, v169
	global_store_dwordx2 v241, v[166:167], s[44:45] offset:32
	v_cvt_pk_bf16_f32 v182, v182, v183
	v_cvt_pk_bf16_f32 v183, v184, v185
	global_store_dwordx2 v241, v[182:183], s[44:45] offset:64
	v_cvt_pk_bf16_f32 v200, v200, v201
	v_cvt_pk_bf16_f32 v201, v202, v203
	global_store_dwordx2 v241, v[200:201], s[44:45] offset:96
	v_cvt_pk_bf16_f32 v154, v154, v155
	v_cvt_pk_bf16_f32 v155, v156, v157
	global_store_dwordx2 v242, v[154:155], s[44:45] offset:0
	v_cvt_pk_bf16_f32 v170, v170, v171
	v_cvt_pk_bf16_f32 v171, v172, v173
	global_store_dwordx2 v242, v[170:171], s[44:45] offset:32
	v_cvt_pk_bf16_f32 v186, v186, v187
	v_cvt_pk_bf16_f32 v187, v188, v189
	global_store_dwordx2 v242, v[186:187], s[44:45] offset:64
	v_cvt_pk_bf16_f32 v208, v208, v209
	v_cvt_pk_bf16_f32 v209, v210, v211
	global_store_dwordx2 v242, v[208:209], s[44:45] offset:96
	v_cvt_pk_bf16_f32 v158, v158, v159
	v_cvt_pk_bf16_f32 v159, v160, v161
	global_store_dwordx2 v243, v[158:159], s[44:45] offset:0
	v_cvt_pk_bf16_f32 v174, v174, v175
	v_cvt_pk_bf16_f32 v175, v176, v177
	global_store_dwordx2 v243, v[174:175], s[44:45] offset:32
	v_cvt_pk_bf16_f32 v190, v190, v191
	v_cvt_pk_bf16_f32 v191, v192, v193
	global_store_dwordx2 v243, v[190:191], s[44:45] offset:64
	v_cvt_pk_bf16_f32 v232, v232, v233
	v_cvt_pk_bf16_f32 v233, v234, v235
	global_store_dwordx2 v243, v[232:233], s[44:45] offset:96
	v_readlane_b32 s38, v255, 35
	s_add_i32 s25, s25, s38
	s_cmpk_lt_u32 s25, 0x200
	s_cbranch_scc1 .Lgbr_tile
	v_readlane_b32 s36, v255, 33
	v_readlane_b32 s37, v255, 34
	v_readlane_b32 s38, v255, 35
	v_readlane_b32 s39, v255, 36

.LBB0_152:
	s_waitcnt vmcnt(0)
	v_lshlrev_b32_e32 v68, 16, v196
	v_lshlrev_b32_e32 v69, 16, v197
	v_lshlrev_b32_e32 v70, 16, v200
	v_lshlrev_b32_e32 v67, 16, v201
	v_lshlrev_b32_e32 v81, 16, v202
	v_lshlrev_b32_e32 v39, 16, v64
	s_waitcnt vmcnt(0)
	v_lshlrev_b32_e32 v36, 16, v80
	v_lshlrev_b32_e32 v42, 16, v42
	v_lshlrev_b32_e32 v44, 16, v44
	v_lshlrev_b32_e32 v64, 16, v43
	v_add_f32_e32 v43, v81, v39
	v_lshlrev_b32_e32 v38, 16, v79
	v_lshlrev_b32_e32 v46, 16, v46
	v_lshlrev_b32_e32 v47, 16, v47
	v_lshlrev_b32_e32 v79, 16, v59
	v_lshlrev_b32_e32 v59, 16, v58
	v_lshlrev_b32_e32 v58, 16, v57
	v_fma_f32 v57, v43, 0.5, -v36
	v_add_f32_e32 v43, v67, v42
	v_add_f32_e32 v80, v44, v36
	v_lshlrev_b32_e32 v78, 16, v78
	v_lshlrev_b32_e32 v48, 16, v48
	v_lshlrev_b32_e32 v49, 16, v49
	v_fma_f32 v67, v43, 0.5, -v38
	v_fmac_f32_e32 v36, v41, v57
	v_fma_f32 v57, v80, 0.5, -v39
	v_add_f32_e32 v80, v46, v38
	v_add_f32_e32 v81, v47, v39
	v_lshlrev_b32_e32 v45, 16, v45
	v_lshlrev_b32_e32 v53, 16, v53
	v_fmac_f32_e32 v38, v40, v67
	v_fma_f32 v67, v80, 0.5, -v42
	v_add_f32_e32 v80, v48, v78
	v_fmac_f32_e32 v39, v41, v57
	v_fma_f32 v57, v81, 0.5, -v44
	v_add_f32_e32 v81, v49, v42
	v_lshlrev_b32_e32 v37, 16, v82
	v_lshlrev_b32_e32 v52, 16, v52
	v_fma_f32 v80, v80, 0.5, -v45
	v_fmac_f32_e32 v42, v40, v67
	v_fma_f32 v67, v81, 0.5, -v46
	v_add_f32_e32 v81, v53, v45
	v_lshlrev_b32_e32 v54, 16, v54
	v_add_f32_e32 v43, v45, v37
	v_fmac_f32_e32 v45, v50, v80
	v_fma_f32 v80, v81, 0.5, -v48
	v_add_f32_e32 v81, v52, v44
	v_lshlrev_b32_e32 v56, 16, v56
	v_fmac_f32_e32 v44, v41, v57
	v_fma_f32 v57, v81, 0.5, -v47
	v_add_f32_e32 v81, v54, v46
	v_lshlrev_b32_e32 v55, 16, v55
	v_fmac_f32_e32 v46, v40, v67
	v_fma_f32 v67, v81, 0.5, -v49
	v_add_f32_e32 v81, v56, v48
	v_fmac_f32_e32 v48, v50, v80
	v_fma_f32 v80, v81, 0.5, -v53
	v_add_f32_e32 v81, v55, v47
	v_fmac_f32_e32 v47, v41, v57
	v_fma_f32 v57, v81, 0.5, -v52
	v_add_f32_e32 v81, v79, v49
	v_fmac_f32_e32 v49, v40, v67
	v_fma_f32 v67, v81, 0.5, -v54
	v_add_f32_e32 v81, v59, v53
	v_lshlrev_b32_e32 v66, 16, v66
	v_fmac_f32_e32 v53, v50, v80
	v_fma_f32 v80, v81, 0.5, -v56
	v_add_f32_e32 v81, v58, v52
	v_fmac_f32_e32 v52, v41, v57
	v_add_f32_e32 v57, v64, v54
	v_fmac_f32_e32 v54, v40, v67
	v_add_f32_e32 v67, v66, v56
	v_lshlrev_b32_e32 v65, 16, v65
	v_fma_f32 v81, v81, 0.5, -v55
	v_fmac_f32_e32 v56, v50, v80
	v_fma_f32 v80, v67, 0.5, -v59
	v_add_f32_e32 v67, v65, v55
	v_add_f32_e32 v69, v69, v58
	v_fmac_f32_e32 v55, v41, v81
	v_fma_f32 v81, v67, 0.5, -v58
	v_lshlrev_b32_e32 v67, 16, v51
	v_fma_f32 v69, v69, 0.5, -v65
	v_add_f32_e32 v51, v67, v79
	v_fmac_f32_e32 v58, v41, v81
	v_fmac_f32_e32 v65, v41, v69
	v_add_f32_e32 v41, v68, v64
	v_fma_f32 v57, v57, 0.5, -v79
	v_fma_f32 v51, v51, 0.5, -v64
	v_fma_f32 v41, v41, 0.5, -v67
	v_readlane_b32 s0, v255, 44
	v_fma_f32 v57, v40, v57, v79
	v_add_f32_e32 v70, v70, v59
	v_fmac_f32_e32 v64, v40, v51
	v_fmac_f32_e32 v67, v40, v41
	v_add_f32_e32 v40, v71, v78
	v_readlane_b32 s1, v255, 45
	v_add_u32_e32 v34, 0x100, v0
	v_fma_f32 v43, v43, 0.5, -v78
	v_fma_f32 v70, v70, 0.5, -v66
	v_fma_f32 v40, v40, 0.5, -v37
	v_lshl_add_u64 v[0:1], v[0:1], 0, s[0:1]
	v_readlane_b32 s0, v252, 17
	v_fma_f32 v43, v50, v43, v78
	v_fmac_f32_e32 v59, v50, v80
	v_fmac_f32_e32 v66, v50, v70
	v_fmac_f32_e32 v37, v50, v40
	v_lshlrev_b64 v[50:51], 2, v[0:1]
	v_readlane_b32 s10, v252, 27
	v_readlane_b32 s11, v252, 28
	v_readlane_b32 s14, v252, 31
	v_readlane_b32 s15, v252, 32
	v_lshl_add_u64 v[0:1], s[10:11], 0, v[50:51]
	global_load_dword v41, v[74:75], off offset:1024
	v_lshl_add_u64 v[50:51], s[14:15], 0, v[50:51]
	global_load_dword v40, v[0:1], off offset:1024
	s_nop 0
	global_load_dword v1, v[72:73], off offset:1024
	global_load_dword v0, v[50:51], off offset:1024
	s_nop 0
	global_load_dword v50, v[60:61], off offset:1024
	global_load_dword v51, v[62:63], off offset:1024
	v_ashrrev_i32_e32 v35, 31, v34
	v_readlane_b32 s2, v252, 19
	v_readlane_b32 s3, v252, 20
	v_readlane_b32 s4, v252, 21
	v_readlane_b32 s5, v252, 22
	v_readlane_b32 s2, v254, 33
	v_readlane_b32 s3, v254, 34
	v_readlane_b32 s4, v254, 53
	v_readlane_b32 s8, v252, 25
	v_readlane_b32 s5, v254, 54
	v_readlane_b32 s6, v252, 23
	v_readlane_b32 s7, v252, 24
	s_mov_b32 s8, 0x1000000
	v_readlane_b32 s1, v252, 18
	v_readlane_b32 s6, v254, 55
	v_readlane_b32 s7, v254, 56
	v_readlane_b32 s0, v254, 27
	v_readlane_b32 s1, v254, 28
	v_readlane_b32 s9, v252, 26
	v_readlane_b32 s12, v252, 29
	v_readlane_b32 s13, v252, 30
	s_waitcnt vmcnt(5)
	v_add_f32_e32 v28, v28, v41
	v_mul_f32_e32 v28, 0xbfb8aa3b, v28
	s_waitcnt vmcnt(1)
	v_mul_f32_e32 v60, v65, v50
	v_mul_f32_e32 v61, v60, v60
	v_exp_f32_e32 v28, v28
	v_add_f32_e32 v30, v30, v40
	v_mov_b32_dpp v61, v61 quad_perm:[1,0,3,2] row_mask:0xf bank_mask:0xf bound_ctrl:1
	v_fmac_f32_e32 v61, v60, v60
	v_mul_f32_e32 v30, 0xbfb8aa3b, v30
	v_exp_f32_e32 v30, v30
	v_add_f32_dpp v61, v61, v61 quad_perm:[2,3,0,1] row_mask:0xf bank_mask:0xf bound_ctrl:1
	v_add_f32_e32 v28, 1.0, v28
	v_rcp_f32_e32 v28, v28
	v_add_f32_dpp v61, v61, v61 row_half_mirror row_mask:0xf bank_mask:0xf bound_ctrl:1
	v_add_f32_e32 v26, v26, v1
	v_add_f32_e32 v30, 1.0, v30
	v_add_f32_dpp v61, v61, v61 row_ror:8 row_mask:0xf bank_mask:0xf bound_ctrl:1
	ds_bpermute_b32 v62, v77, v61
	v_mul_f32_e32 v26, 0xbfb8aa3b, v26
	v_rcp_f32_e32 v30, v30
	v_exp_f32_e32 v26, v26
	v_add_f32_e32 v32, v32, v0
	s_waitcnt lgkmcnt(0)
	v_add_f32_e32 v61, v61, v62
	ds_bpermute_b32 v62, v76, v61
	v_mul_f32_e32 v28, 0xbf1b4598, v28
	v_mul_f32_e32 v32, 0xbfb8aa3b, v32
	v_mul_f32_e32 v28, 0x3fb8aa3b, v28
	v_exp_f32_e32 v32, v32
	s_waitcnt lgkmcnt(0)
	v_add_f32_e32 v61, v61, v62
	v_add_f32_e32 v61, 0x2b8cbccc, v61
	v_rsq_f32_e32 v61, v61
	v_exp_f32_e32 v28, v28
	v_mul_f32_e32 v30, 0xbf1b4598, v30
	v_add_f32_e32 v26, 1.0, v26
	v_mul_f32_e32 v68, v60, v61
	v_lshl_add_u64 v[60:61], s[66:67], 0, v[34:35]
	v_lshlrev_b64 v[60:61], 2, v[60:61]
	v_lshl_add_u64 v[62:63], s[22:23], 0, v[60:61]
	v_mul_f32_e32 v30, 0x3fb8aa3b, v30
	v_rcp_f32_e32 v26, v26
	global_store_dword v[62:63], v67, off
	v_lshl_add_u64 v[62:63], s[30:31], 0, v[60:61]
	v_exp_f32_e32 v30, v30
	global_store_dword v[62:63], v68, off
	v_lshl_add_u64 v[62:63], s[2:3], 0, v[60:61]
	v_add_f32_e32 v32, 1.0, v32
	global_store_dword v[62:63], v66, off
	v_lshl_add_u64 v[62:63], s[4:5], 0, v[60:61]
	v_rcp_f32_e32 v32, v32
	global_store_dword v[62:63], v28, off
	v_add_co_u32_e32 v62, vcc, s8, v62
	v_mul_f32_e32 v28, v26, v68
	s_nop 0
	v_addc_co_u32_e32 v63, vcc, 0, v63, vcc
	v_add_f32_e32 v26, -1.0, v26
	global_store_dword v[62:63], v30, off
	v_lshl_add_u64 v[62:63], s[6:7], 0, v[60:61]
	s_waitcnt vmcnt(5)
	v_fma_f32 v26, v51, v26, 1.0
	global_store_dword v[62:63], v28, off
	v_add_co_u32_e32 v62, vcc, s8, v62
	v_mul_f32_e32 v26, v65, v26
	v_lshl_add_u64 v[60:61], s[0:1], 0, v[60:61]
	v_addc_co_u32_e32 v63, vcc, 0, v63, vcc
	global_store_dword v[60:61], v26, off
	v_add_f32_e32 v26, -1.0, v32
	v_fma_f32 v26, v51, v26, 1.0
	v_add_co_u32_e32 v60, vcc, s8, v60
	v_mul_f32_e32 v26, v65, v26
	s_nop 0
	v_addc_co_u32_e32 v61, vcc, 0, v61, vcc
	v_mul_f32_e32 v28, v32, v68
	global_store_dword v[60:61], v26, off
	v_mul_f32_e32 v26, v58, v50
	global_store_dword v[62:63], v28, off
	v_mul_f32_e32 v28, v26, v26
	v_add_f32_e32 v20, v20, v41
	v_mul_f32_e32 v20, 0xbfb8aa3b, v20
	v_mov_b32_dpp v28, v28 quad_perm:[1,0,3,2] row_mask:0xf bank_mask:0xf bound_ctrl:1
	v_fmac_f32_e32 v28, v26, v26
	v_exp_f32_e32 v20, v20
	v_add_f32_e32 v22, v22, v40
	v_add_f32_dpp v28, v28, v28 quad_perm:[2,3,0,1] row_mask:0xf bank_mask:0xf bound_ctrl:1
	v_mul_f32_e32 v22, 0xbfb8aa3b, v22
	v_exp_f32_e32 v22, v22
	v_add_f32_dpp v28, v28, v28 row_half_mirror row_mask:0xf bank_mask:0xf bound_ctrl:1
	v_add_f32_e32 v20, 1.0, v20
	v_rcp_f32_e32 v20, v20
	v_add_f32_dpp v28, v28, v28 row_ror:8 row_mask:0xf bank_mask:0xf bound_ctrl:1
	ds_bpermute_b32 v30, v77, v28
	v_add_f32_e32 v18, v18, v1
	v_add_f32_e32 v22, 1.0, v22
	v_mul_f32_e32 v18, 0xbfb8aa3b, v18
	v_rcp_f32_e32 v22, v22
	s_waitcnt lgkmcnt(0)
	v_add_f32_e32 v28, v28, v30
	ds_bpermute_b32 v30, v76, v28
	v_exp_f32_e32 v18, v18
	v_add_f32_e32 v24, v24, v0
	v_mul_f32_e32 v20, 0xbf1b4598, v20
	v_mul_f32_e32 v24, 0xbfb8aa3b, v24
	s_waitcnt lgkmcnt(0)
	v_add_f32_e32 v28, v28, v30
	v_add_f32_e32 v28, 0x2b8cbccc, v28
	v_rsq_f32_e32 v28, v28
	v_mul_f32_e32 v20, 0x3fb8aa3b, v20
	v_exp_f32_e32 v24, v24
	v_exp_f32_e32 v20, v20
	v_mul_f32_e32 v30, v26, v28
	v_add_f32_e32 v26, v29, v41
	v_mul_f32_e32 v26, 0xbfb8aa3b, v26
	v_exp_f32_e32 v26, v26
	v_mul_f32_e32 v22, 0xbf1b4598, v22
	v_add_f32_e32 v18, 1.0, v18
	v_mul_f32_e32 v22, 0x3fb8aa3b, v22
	v_add_f32_e32 v26, 1.0, v26
	v_rcp_f32_e32 v26, v26
	v_rcp_f32_e32 v18, v18
	v_exp_f32_e32 v22, v22
	v_add_f32_e32 v24, 1.0, v24
	v_mul_f32_e32 v26, 0xbf1b4598, v26
	v_mul_f32_e32 v26, 0x3fb8aa3b, v26
	v_exp_f32_e32 v32, v26
	v_add_f32_e32 v26, v31, v40
	v_mul_f32_e32 v26, 0xbfb8aa3b, v26
	v_exp_f32_e32 v26, v26
	v_rcp_f32_e32 v24, v24
	v_add_f32_e32 v12, v12, v41
	v_mul_f32_e32 v12, 0xbfb8aa3b, v12
	v_add_f32_e32 v26, 1.0, v26
	v_rcp_f32_e32 v26, v26
	v_exp_f32_e32 v12, v12
	v_add_f32_e32 v14, v14, v40
	v_mul_f32_e32 v14, 0xbfb8aa3b, v14
	v_mul_f32_e32 v26, 0xbf1b4598, v26
	v_mul_f32_e32 v26, 0x3fb8aa3b, v26
	v_exp_f32_e32 v31, v26
	v_add_f32_e32 v26, v27, v1
	v_mul_f32_e32 v26, 0xbfb8aa3b, v26
	v_exp_f32_e32 v26, v26
	v_exp_f32_e32 v14, v14
	v_add_f32_e32 v12, 1.0, v12
	v_rcp_f32_e32 v12, v12
	v_add_f32_e32 v26, 1.0, v26
	v_rcp_f32_e32 v60, v26
	v_add_f32_e32 v26, v33, v0
	v_mul_f32_e32 v26, 0xbfb8aa3b, v26
	v_exp_f32_e32 v26, v26
	v_add_f32_e32 v10, v10, v1
	v_add_f32_e32 v14, 1.0, v14
	v_mul_f32_e32 v10, 0xbfb8aa3b, v10
	v_add_f32_e32 v26, 1.0, v26
	v_rcp_f32_e32 v33, v26
	v_lshl_add_u64 v[26:27], s[68:69], 0, v[34:35]
	v_lshlrev_b64 v[26:27], 2, v[26:27]
	v_lshl_add_u64 v[28:29], s[22:23], 0, v[26:27]
	global_store_dword v[28:29], v64, off
	v_lshl_add_u64 v[28:29], s[30:31], 0, v[26:27]
	global_store_dword v[28:29], v30, off
	v_lshl_add_u64 v[28:29], s[2:3], 0, v[26:27]
	global_store_dword v[28:29], v59, off
	v_lshl_add_u64 v[28:29], s[4:5], 0, v[26:27]
	global_store_dword v[28:29], v32, off
	v_add_co_u32_e32 v28, vcc, s8, v28
	v_rcp_f32_e32 v14, v14
	s_nop 0
	v_addc_co_u32_e32 v29, vcc, 0, v29, vcc
	global_store_dword v[28:29], v31, off
	v_mul_f32_e32 v31, v60, v30
	v_lshl_add_u64 v[28:29], s[6:7], 0, v[26:27]
	global_store_dword v[28:29], v31, off
	v_add_co_u32_e32 v28, vcc, s8, v28
	v_mul_f32_e32 v30, v33, v30
	s_nop 0
	v_addc_co_u32_e32 v29, vcc, 0, v29, vcc
	global_store_dword v[28:29], v30, off
	v_add_f32_e32 v28, -1.0, v60
	v_fma_f32 v28, v51, v28, 1.0
	v_mul_f32_e32 v28, v58, v28
	v_lshl_add_u64 v[26:27], s[0:1], 0, v[26:27]
	global_store_dword v[26:27], v28, off
	v_add_f32_e32 v28, -1.0, v33
	v_fma_f32 v28, v51, v28, 1.0
	v_add_co_u32_e32 v26, vcc, s8, v26
	v_mul_f32_e32 v28, v58, v28
	s_nop 0
	v_addc_co_u32_e32 v27, vcc, 0, v27, vcc
	global_store_dword v[26:27], v28, off
	v_mul_f32_e32 v26, v55, v50
	v_mul_f32_e32 v27, v26, v26
	v_exp_f32_e32 v10, v10
	v_add_f32_e32 v16, v16, v0
	v_mov_b32_dpp v27, v27 quad_perm:[1,0,3,2] row_mask:0xf bank_mask:0xf bound_ctrl:1
	v_fmac_f32_e32 v27, v26, v26
	v_mul_f32_e32 v12, 0xbf1b4598, v12
	v_mul_f32_e32 v16, 0xbfb8aa3b, v16
	v_add_f32_dpp v27, v27, v27 quad_perm:[2,3,0,1] row_mask:0xf bank_mask:0xf bound_ctrl:1
	v_mul_f32_e32 v12, 0x3fb8aa3b, v12
	v_exp_f32_e32 v16, v16
	v_add_f32_dpp v27, v27, v27 row_half_mirror row_mask:0xf bank_mask:0xf bound_ctrl:1
	v_exp_f32_e32 v12, v12
	v_mul_f32_e32 v14, 0xbf1b4598, v14
	v_add_f32_dpp v27, v27, v27 row_ror:8 row_mask:0xf bank_mask:0xf bound_ctrl:1
	ds_bpermute_b32 v28, v77, v27
	v_add_f32_e32 v10, 1.0, v10
	v_mul_f32_e32 v14, 0x3fb8aa3b, v14
	v_rcp_f32_e32 v10, v10
	v_exp_f32_e32 v14, v14
	s_waitcnt lgkmcnt(0)
	v_add_f32_e32 v27, v27, v28
	ds_bpermute_b32 v28, v76, v27
	v_add_f32_e32 v16, 1.0, v16
	v_rcp_f32_e32 v16, v16
	v_add_f32_e32 v4, v4, v41
	v_mul_f32_e32 v4, 0xbfb8aa3b, v4
	s_waitcnt lgkmcnt(0)
	v_add_f32_e32 v27, v27, v28
	v_add_f32_e32 v27, 0x2b8cbccc, v27
	v_rsq_f32_e32 v27, v27
	v_exp_f32_e32 v4, v4
	v_add_f32_e32 v6, v6, v40
	v_mul_f32_e32 v6, 0xbfb8aa3b, v6
	v_mul_f32_e32 v30, v26, v27
	v_lshl_add_u64 v[26:27], s[48:49], 0, v[34:35]
	v_lshlrev_b64 v[26:27], 2, v[26:27]
	v_lshl_add_u64 v[28:29], s[22:23], 0, v[26:27]
	global_store_dword v[28:29], v57, off
	v_lshl_add_u64 v[28:29], s[30:31], 0, v[26:27]
	global_store_dword v[28:29], v30, off
	v_lshl_add_u64 v[28:29], s[2:3], 0, v[26:27]
	global_store_dword v[28:29], v56, off
	v_lshl_add_u64 v[28:29], s[4:5], 0, v[26:27]
	global_store_dword v[28:29], v20, off
	v_add_co_u32_e32 v28, vcc, s8, v28
	v_mul_f32_e32 v20, v18, v30
	s_nop 0
	v_addc_co_u32_e32 v29, vcc, 0, v29, vcc
	v_add_f32_e32 v18, -1.0, v18
	global_store_dword v[28:29], v22, off
	v_lshl_add_u64 v[28:29], s[6:7], 0, v[26:27]
	v_fma_f32 v18, v51, v18, 1.0
	global_store_dword v[28:29], v20, off
	v_add_co_u32_e32 v28, vcc, s8, v28
	v_mul_f32_e32 v18, v55, v18
	v_lshl_add_u64 v[26:27], s[0:1], 0, v[26:27]
	v_addc_co_u32_e32 v29, vcc, 0, v29, vcc
	global_store_dword v[26:27], v18, off
	v_add_f32_e32 v18, -1.0, v24
	v_fma_f32 v18, v51, v18, 1.0
	v_add_co_u32_e32 v26, vcc, s8, v26
	v_mul_f32_e32 v18, v55, v18
	s_nop 0
	v_addc_co_u32_e32 v27, vcc, 0, v27, vcc
	v_mul_f32_e32 v20, v24, v30
	global_store_dword v[26:27], v18, off
	v_mul_f32_e32 v18, v52, v50
	global_store_dword v[28:29], v20, off
	v_mul_f32_e32 v20, v18, v18
	v_exp_f32_e32 v6, v6
	v_add_f32_e32 v4, 1.0, v4
	v_mov_b32_dpp v20, v20 quad_perm:[1,0,3,2] row_mask:0xf bank_mask:0xf bound_ctrl:1
	v_fmac_f32_e32 v20, v18, v18
	v_rcp_f32_e32 v4, v4
	v_add_f32_e32 v2, v2, v1
	v_add_f32_dpp v20, v20, v20 quad_perm:[2,3,0,1] row_mask:0xf bank_mask:0xf bound_ctrl:1
	v_add_f32_e32 v6, 1.0, v6
	v_mul_f32_e32 v2, 0xbfb8aa3b, v2
	v_add_f32_dpp v20, v20, v20 row_half_mirror row_mask:0xf bank_mask:0xf bound_ctrl:1
	v_rcp_f32_e32 v6, v6
	v_exp_f32_e32 v2, v2
	v_add_f32_dpp v20, v20, v20 row_ror:8 row_mask:0xf bank_mask:0xf bound_ctrl:1
	ds_bpermute_b32 v22, v77, v20
	v_add_f32_e32 v8, v8, v0
	v_mul_f32_e32 v4, 0xbf1b4598, v4
	v_mul_f32_e32 v8, 0xbfb8aa3b, v8
	v_mul_f32_e32 v4, 0x3fb8aa3b, v4
	s_waitcnt lgkmcnt(0)
	v_add_f32_e32 v20, v20, v22
	ds_bpermute_b32 v22, v76, v20
	v_exp_f32_e32 v8, v8
	v_exp_f32_e32 v4, v4
	v_mul_f32_e32 v6, 0xbf1b4598, v6
	v_add_f32_e32 v2, 1.0, v2
	s_waitcnt lgkmcnt(0)
	v_add_f32_e32 v20, v20, v22
	v_add_f32_e32 v20, 0x2b8cbccc, v20
	v_rsq_f32_e32 v20, v20
	v_mul_f32_e32 v6, 0x3fb8aa3b, v6
	v_rcp_f32_e32 v2, v2
	v_exp_f32_e32 v6, v6
	v_mul_f32_e32 v22, v18, v20
	v_add_f32_e32 v18, v21, v41
	v_mul_f32_e32 v18, 0xbfb8aa3b, v18
	v_exp_f32_e32 v18, v18
	v_add_f32_e32 v8, 1.0, v8
	v_rcp_f32_e32 v8, v8
	v_add_f32_e32 v18, 1.0, v18
	v_rcp_f32_e32 v18, v18
	s_nop 0
	v_mul_f32_e32 v18, 0xbf1b4598, v18
	v_mul_f32_e32 v18, 0x3fb8aa3b, v18
	v_exp_f32_e32 v24, v18
	v_add_f32_e32 v18, v23, v40
	v_mul_f32_e32 v18, 0xbfb8aa3b, v18
	v_exp_f32_e32 v18, v18
	s_nop 0
	v_add_f32_e32 v18, 1.0, v18
	v_rcp_f32_e32 v18, v18
	s_nop 0
	v_mul_f32_e32 v18, 0xbf1b4598, v18
	v_mul_f32_e32 v18, 0x3fb8aa3b, v18
	v_exp_f32_e32 v23, v18
	v_add_f32_e32 v18, v19, v1
	v_mul_f32_e32 v18, 0xbfb8aa3b, v18
	v_exp_f32_e32 v18, v18
	s_nop 0
	v_add_f32_e32 v18, 1.0, v18
	v_rcp_f32_e32 v26, v18
	v_add_f32_e32 v18, v25, v0
	v_mul_f32_e32 v18, 0xbfb8aa3b, v18
	v_exp_f32_e32 v18, v18
	s_nop 0
	v_add_f32_e32 v18, 1.0, v18
	v_rcp_f32_e32 v25, v18
	v_lshl_add_u64 v[18:19], s[50:51], 0, v[34:35]
	v_lshlrev_b64 v[18:19], 2, v[18:19]
	v_lshl_add_u64 v[20:21], s[22:23], 0, v[18:19]
	global_store_dword v[20:21], v54, off
	v_lshl_add_u64 v[20:21], s[30:31], 0, v[18:19]
	global_store_dword v[20:21], v22, off
	v_lshl_add_u64 v[20:21], s[2:3], 0, v[18:19]
	global_store_dword v[20:21], v53, off
	v_lshl_add_u64 v[20:21], s[4:5], 0, v[18:19]
	global_store_dword v[20:21], v24, off
	v_add_co_u32_e32 v20, vcc, s8, v20
	s_nop 1
	v_addc_co_u32_e32 v21, vcc, 0, v21, vcc
	global_store_dword v[20:21], v23, off
	v_mul_f32_e32 v23, v26, v22
	v_lshl_add_u64 v[20:21], s[6:7], 0, v[18:19]
	global_store_dword v[20:21], v23, off
	v_add_co_u32_e32 v20, vcc, s8, v20
	v_mul_f32_e32 v22, v25, v22
	s_nop 0
	v_addc_co_u32_e32 v21, vcc, 0, v21, vcc
	global_store_dword v[20:21], v22, off
	v_add_f32_e32 v20, -1.0, v26
	v_fma_f32 v20, v51, v20, 1.0
	v_mul_f32_e32 v20, v52, v20
	v_lshl_add_u64 v[18:19], s[0:1], 0, v[18:19]
	global_store_dword v[18:19], v20, off
	v_add_f32_e32 v20, -1.0, v25
	v_fma_f32 v20, v51, v20, 1.0
	v_add_co_u32_e32 v18, vcc, s8, v18
	v_mul_f32_e32 v20, v52, v20
	s_nop 0
	v_addc_co_u32_e32 v19, vcc, 0, v19, vcc
	global_store_dword v[18:19], v20, off
	v_mul_f32_e32 v18, v47, v50
	v_mul_f32_e32 v19, v18, v18
	s_nop 1
	v_mov_b32_dpp v19, v19 quad_perm:[1,0,3,2] row_mask:0xf bank_mask:0xf bound_ctrl:1
	v_fmac_f32_e32 v19, v18, v18
	s_nop 1
	v_add_f32_dpp v19, v19, v19 quad_perm:[2,3,0,1] row_mask:0xf bank_mask:0xf bound_ctrl:1
	s_nop 1
	v_add_f32_dpp v19, v19, v19 row_half_mirror row_mask:0xf bank_mask:0xf bound_ctrl:1
	s_nop 1
	v_add_f32_dpp v19, v19, v19 row_ror:8 row_mask:0xf bank_mask:0xf bound_ctrl:1
	ds_bpermute_b32 v20, v77, v19
	s_waitcnt lgkmcnt(0)
	v_add_f32_e32 v19, v19, v20
	ds_bpermute_b32 v20, v76, v19
	s_waitcnt lgkmcnt(0)
	v_add_f32_e32 v19, v19, v20
	v_add_f32_e32 v19, 0x2b8cbccc, v19
	v_rsq_f32_e32 v19, v19
	s_nop 0
	v_mul_f32_e32 v22, v18, v19
	v_lshl_add_u64 v[18:19], s[52:53], 0, v[34:35]
	v_lshlrev_b64 v[18:19], 2, v[18:19]
	v_lshl_add_u64 v[20:21], s[22:23], 0, v[18:19]
	global_store_dword v[20:21], v49, off
	v_lshl_add_u64 v[20:21], s[30:31], 0, v[18:19]
	global_store_dword v[20:21], v22, off
	v_lshl_add_u64 v[20:21], s[2:3], 0, v[18:19]
	global_store_dword v[20:21], v48, off
	v_lshl_add_u64 v[20:21], s[4:5], 0, v[18:19]
	global_store_dword v[20:21], v12, off
	v_add_co_u32_e32 v20, vcc, s8, v20
	v_mul_f32_e32 v12, v10, v22
	s_nop 0
	v_addc_co_u32_e32 v21, vcc, 0, v21, vcc
	v_add_f32_e32 v10, -1.0, v10
	global_store_dword v[20:21], v14, off
	v_lshl_add_u64 v[20:21], s[6:7], 0, v[18:19]
	v_fma_f32 v10, v51, v10, 1.0
	global_store_dword v[20:21], v12, off
	v_add_co_u32_e32 v20, vcc, s8, v20
	v_mul_f32_e32 v10, v47, v10
	v_lshl_add_u64 v[18:19], s[0:1], 0, v[18:19]
	v_addc_co_u32_e32 v21, vcc, 0, v21, vcc
	global_store_dword v[18:19], v10, off
	v_add_f32_e32 v10, -1.0, v16
	v_fma_f32 v10, v51, v10, 1.0
	v_add_co_u32_e32 v18, vcc, s8, v18
	v_mul_f32_e32 v10, v47, v10
	s_nop 0
	v_addc_co_u32_e32 v19, vcc, 0, v19, vcc
	v_mul_f32_e32 v12, v16, v22
	global_store_dword v[18:19], v10, off
	v_mul_f32_e32 v10, v44, v50
	global_store_dword v[20:21], v12, off
	v_mul_f32_e32 v12, v10, v10
	s_nop 1
	v_mov_b32_dpp v12, v12 quad_perm:[1,0,3,2] row_mask:0xf bank_mask:0xf bound_ctrl:1
	v_fmac_f32_e32 v12, v10, v10
	s_nop 1
	v_add_f32_dpp v12, v12, v12 quad_perm:[2,3,0,1] row_mask:0xf bank_mask:0xf bound_ctrl:1
	s_nop 1
	v_add_f32_dpp v12, v12, v12 row_half_mirror row_mask:0xf bank_mask:0xf bound_ctrl:1
	s_nop 1
	v_add_f32_dpp v12, v12, v12 row_ror:8 row_mask:0xf bank_mask:0xf bound_ctrl:1
	ds_bpermute_b32 v14, v77, v12
	s_waitcnt lgkmcnt(0)
	v_add_f32_e32 v12, v12, v14
	ds_bpermute_b32 v14, v76, v12
	s_waitcnt lgkmcnt(0)
	v_add_f32_e32 v12, v12, v14
	v_add_f32_e32 v12, 0x2b8cbccc, v12
	v_rsq_f32_e32 v12, v12
	s_nop 0
	v_mul_f32_e32 v14, v10, v12
	v_add_f32_e32 v10, v13, v41
	v_mul_f32_e32 v10, 0xbfb8aa3b, v10
	v_exp_f32_e32 v10, v10
	s_nop 0
	v_add_f32_e32 v10, 1.0, v10
	v_rcp_f32_e32 v10, v10
	s_nop 0
	v_mul_f32_e32 v10, 0xbf1b4598, v10
	v_mul_f32_e32 v10, 0x3fb8aa3b, v10
	v_exp_f32_e32 v16, v10
	v_add_f32_e32 v10, v15, v40
	v_mul_f32_e32 v10, 0xbfb8aa3b, v10
	v_exp_f32_e32 v10, v10
	s_nop 0
	v_add_f32_e32 v10, 1.0, v10
	v_rcp_f32_e32 v10, v10
	s_nop 0
	v_mul_f32_e32 v10, 0xbf1b4598, v10
	v_mul_f32_e32 v10, 0x3fb8aa3b, v10
	v_exp_f32_e32 v15, v10
	v_add_f32_e32 v10, v11, v1
	v_mul_f32_e32 v10, 0xbfb8aa3b, v10
	v_exp_f32_e32 v10, v10
	v_add_f32_e32 v1, v3, v1
	v_mul_f32_e32 v1, 0xbfb8aa3b, v1
	v_exp_f32_e32 v1, v1
	v_add_f32_e32 v10, 1.0, v10
	v_rcp_f32_e32 v18, v10
	v_add_f32_e32 v10, v17, v0
	v_mul_f32_e32 v10, 0xbfb8aa3b, v10
	v_exp_f32_e32 v10, v10
	v_add_f32_e32 v0, v9, v0
	v_mul_f32_e32 v0, 0xbfb8aa3b, v0
	v_exp_f32_e32 v0, v0
	v_add_f32_e32 v10, 1.0, v10
	v_rcp_f32_e32 v17, v10
	v_lshl_add_u64 v[10:11], s[46:47], 0, v[34:35]
	v_lshlrev_b64 v[10:11], 2, v[10:11]
	v_lshl_add_u64 v[12:13], s[22:23], 0, v[10:11]
	global_store_dword v[12:13], v46, off
	v_lshl_add_u64 v[12:13], s[30:31], 0, v[10:11]
	global_store_dword v[12:13], v14, off
	v_lshl_add_u64 v[12:13], s[2:3], 0, v[10:11]
	global_store_dword v[12:13], v45, off
	v_lshl_add_u64 v[12:13], s[4:5], 0, v[10:11]
	global_store_dword v[12:13], v16, off
	v_add_co_u32_e32 v12, vcc, s8, v12
	v_add_f32_e32 v1, 1.0, v1
	s_nop 0
	v_addc_co_u32_e32 v13, vcc, 0, v13, vcc
	global_store_dword v[12:13], v15, off
	v_mul_f32_e32 v15, v18, v14
	v_lshl_add_u64 v[12:13], s[6:7], 0, v[10:11]
	global_store_dword v[12:13], v15, off
	v_add_co_u32_e32 v12, vcc, s8, v12
	v_mul_f32_e32 v14, v17, v14
	s_nop 0
	v_addc_co_u32_e32 v13, vcc, 0, v13, vcc
	global_store_dword v[12:13], v14, off
	v_add_f32_e32 v12, -1.0, v18
	v_fma_f32 v12, v51, v12, 1.0
	v_mul_f32_e32 v12, v44, v12
	v_lshl_add_u64 v[10:11], s[0:1], 0, v[10:11]
	global_store_dword v[10:11], v12, off
	v_add_f32_e32 v12, -1.0, v17
	v_fma_f32 v12, v51, v12, 1.0
	v_add_co_u32_e32 v10, vcc, s8, v10
	v_mul_f32_e32 v12, v44, v12
	s_nop 0
	v_addc_co_u32_e32 v11, vcc, 0, v11, vcc
	global_store_dword v[10:11], v12, off
	v_mul_f32_e32 v10, v39, v50
	v_mul_f32_e32 v11, v10, v10
	v_add_f32_e32 v0, 1.0, v0
	s_mov_b64 s[46:47], s[18:19]
	v_mov_b32_dpp v11, v11 quad_perm:[1,0,3,2] row_mask:0xf bank_mask:0xf bound_ctrl:1
	v_fmac_f32_e32 v11, v10, v10
	s_mov_b64 s[18:19], s[16:17]
	s_mov_b32 s16, s71
	v_add_f32_dpp v11, v11, v11 quad_perm:[2,3,0,1] row_mask:0xf bank_mask:0xf bound_ctrl:1
	s_nop 1
	v_add_f32_dpp v11, v11, v11 row_half_mirror row_mask:0xf bank_mask:0xf bound_ctrl:1
	s_nop 1
	v_add_f32_dpp v11, v11, v11 row_ror:8 row_mask:0xf bank_mask:0xf bound_ctrl:1
	ds_bpermute_b32 v12, v77, v11
	s_waitcnt lgkmcnt(0)
	v_add_f32_e32 v11, v11, v12
	ds_bpermute_b32 v12, v76, v11
	s_waitcnt lgkmcnt(0)
	v_add_f32_e32 v11, v11, v12
	v_add_f32_e32 v11, 0x2b8cbccc, v11
	v_rsq_f32_e32 v11, v11
	s_nop 0
	v_mul_f32_e32 v14, v10, v11
	v_lshl_add_u64 v[10:11], s[44:45], 0, v[34:35]
	v_lshlrev_b64 v[10:11], 2, v[10:11]
	v_lshl_add_u64 v[12:13], s[22:23], 0, v[10:11]
	global_store_dword v[12:13], v42, off
	v_lshl_add_u64 v[12:13], s[30:31], 0, v[10:11]
	global_store_dword v[12:13], v14, off
	v_lshl_add_u64 v[12:13], s[2:3], 0, v[10:11]
	global_store_dword v[12:13], v43, off
	v_lshl_add_u64 v[12:13], s[4:5], 0, v[10:11]
	global_store_dword v[12:13], v4, off
	v_add_co_u32_e32 v12, vcc, s8, v12
	v_mul_f32_e32 v4, v2, v14
	s_nop 0
	v_addc_co_u32_e32 v13, vcc, 0, v13, vcc
	v_add_f32_e32 v2, -1.0, v2
	global_store_dword v[12:13], v6, off
	v_lshl_add_u64 v[12:13], s[6:7], 0, v[10:11]
	v_fma_f32 v2, v51, v2, 1.0
	global_store_dword v[12:13], v4, off
	v_add_co_u32_e32 v12, vcc, s8, v12
	v_mul_f32_e32 v2, v39, v2
	v_lshl_add_u64 v[10:11], s[0:1], 0, v[10:11]
	v_addc_co_u32_e32 v13, vcc, 0, v13, vcc
	global_store_dword v[10:11], v2, off
	v_add_f32_e32 v2, -1.0, v8
	v_fma_f32 v2, v51, v2, 1.0
	v_add_co_u32_e32 v10, vcc, s8, v10
	v_mul_f32_e32 v2, v39, v2
	s_nop 0
	v_addc_co_u32_e32 v11, vcc, 0, v11, vcc
	v_mul_f32_e32 v4, v8, v14
	global_store_dword v[10:11], v2, off
	v_mul_f32_e32 v2, v36, v50
	global_store_dword v[12:13], v4, off
	v_mul_f32_e32 v4, v2, v2
	v_rcp_f32_e32 v8, v0
	s_nop 0
	v_mov_b32_dpp v4, v4 quad_perm:[1,0,3,2] row_mask:0xf bank_mask:0xf bound_ctrl:1
	v_fmac_f32_e32 v4, v2, v2
	s_nop 1
	v_add_f32_dpp v4, v4, v4 quad_perm:[2,3,0,1] row_mask:0xf bank_mask:0xf bound_ctrl:1
	s_nop 1
	v_add_f32_dpp v4, v4, v4 row_half_mirror row_mask:0xf bank_mask:0xf bound_ctrl:1
	s_nop 1
	v_add_f32_dpp v4, v4, v4 row_ror:8 row_mask:0xf bank_mask:0xf bound_ctrl:1
	ds_bpermute_b32 v6, v77, v4
	s_waitcnt lgkmcnt(0)
	v_add_f32_e32 v4, v4, v6
	ds_bpermute_b32 v6, v76, v4
	s_waitcnt lgkmcnt(0)
	v_add_f32_e32 v4, v4, v6
	v_add_f32_e32 v4, 0x2b8cbccc, v4
	v_rsq_f32_e32 v4, v4
	s_nop 0
	v_mul_f32_e32 v4, v2, v4
	v_add_f32_e32 v2, v5, v41
	v_mul_f32_e32 v2, 0xbfb8aa3b, v2
	v_exp_f32_e32 v2, v2
	s_nop 0
	v_add_f32_e32 v2, 1.0, v2
	v_rcp_f32_e32 v2, v2
	s_nop 0
	v_mul_f32_e32 v2, 0xbf1b4598, v2
	v_mul_f32_e32 v2, 0x3fb8aa3b, v2
	v_exp_f32_e32 v5, v2
	v_add_f32_e32 v2, v7, v40
	v_mul_f32_e32 v2, 0xbfb8aa3b, v2
	v_exp_f32_e32 v2, v2
	v_rcp_f32_e32 v7, v1
	v_lshl_add_u64 v[0:1], s[56:57], 0, v[34:35]
	v_lshlrev_b64 v[0:1], 2, v[0:1]
	v_add_f32_e32 v2, 1.0, v2
	v_rcp_f32_e32 v2, v2
	s_nop 0
	v_mul_f32_e32 v2, 0xbf1b4598, v2
	v_mul_f32_e32 v2, 0x3fb8aa3b, v2
	v_exp_f32_e32 v6, v2
	v_lshl_add_u64 v[2:3], s[22:23], 0, v[0:1]
	global_store_dword v[2:3], v38, off
	v_lshl_add_u64 v[2:3], s[30:31], 0, v[0:1]
	global_store_dword v[2:3], v4, off
	v_lshl_add_u64 v[2:3], s[2:3], 0, v[0:1]
	global_store_dword v[2:3], v37, off
	v_lshl_add_u64 v[2:3], s[4:5], 0, v[0:1]
	global_store_dword v[2:3], v5, off
	v_add_co_u32_e32 v2, vcc, s8, v2
	v_mul_f32_e32 v5, v7, v4
	s_nop 0
	v_addc_co_u32_e32 v3, vcc, 0, v3, vcc
	global_store_dword v[2:3], v6, off
	v_lshl_add_u64 v[2:3], s[6:7], 0, v[0:1]
	global_store_dword v[2:3], v5, off
	v_add_co_u32_e32 v2, vcc, s8, v2
	v_mul_f32_e32 v4, v8, v4
	s_nop 0
	v_addc_co_u32_e32 v3, vcc, 0, v3, vcc
	global_store_dword v[2:3], v4, off
	v_add_f32_e32 v2, -1.0, v7
	v_fma_f32 v2, v51, v2, 1.0
	v_mul_f32_e32 v2, v36, v2
	v_lshl_add_u64 v[0:1], s[0:1], 0, v[0:1]
	global_store_dword v[0:1], v2, off
	v_add_f32_e32 v2, -1.0, v8
	v_fma_f32 v2, v51, v2, 1.0
	v_add_co_u32_e32 v0, vcc, 0x1000000, v0
	v_readlane_b32 s2, v255, 31
	v_mul_f32_e32 v2, v36, v2
	v_addc_co_u32_e32 v1, vcc, 0, v1, vcc
	v_readlane_b32 s3, v255, 32
	global_store_dword v[0:1], v2, off
	s_waitcnt vmcnt(63) expcnt(7) lgkmcnt(15)
	s_barrier

.Llora_loop:
	s_add_i32 s0, s1, 3
	s_min_u32 s0, s0, 63
	s_lshl_b32 s0, s0, 11
	v_add_u32_e32 v186, s0, v188
	global_load_dword v170, v186, s[26:27]
	global_load_dword v171, v186, s[28:29]
	global_load_dword v172, v186, s[36:37]
	global_load_dword v173, v186, s[38:39]
	global_load_dword v174, v186, s[26:27] offset:1024
	global_load_dword v175, v186, s[28:29] offset:1024
	global_load_dword v176, v186, s[36:37] offset:1024
	global_load_dword v177, v186, s[38:39] offset:1024
	ds_read_b128 v[104:107], v187 offset:128
	ds_read_b128 v[108:111], v187 offset:144
	ds_read_b128 v[112:115], v187 offset:160
	ds_read_b128 v[116:119], v187 offset:176
	ds_read_b128 v[120:123], v187 offset:192
	ds_read_b128 v[132:135], v187 offset:208
	ds_read_b128 v[136:139], v187 offset:224
	ds_read_b128 v[140:143], v187 offset:240
	s_waitcnt vmcnt(24)
	s_waitcnt lgkmcnt(8)
	v_pk_fma_f32 v[66:67], v[146:147], v[72:73], v[66:67] op_sel:[0,0,0] op_sel_hi:[0,1,1]
	v_pk_fma_f32 v[52:53], v[146:147], v[74:75], v[52:53] op_sel:[0,0,0] op_sel_hi:[0,1,1]
	v_pk_fma_f32 v[44:45], v[146:147], v[76:77], v[44:45] op_sel:[0,0,0] op_sel_hi:[0,1,1]
	v_pk_fma_f32 v[36:37], v[146:147], v[78:79], v[36:37] op_sel:[0,0,0] op_sel_hi:[0,1,1]
	v_pk_fma_f32 v[28:29], v[150:151], v[72:73], v[28:29] op_sel:[0,0,0] op_sel_hi:[0,1,1]
	v_pk_fma_f32 v[20:21], v[150:151], v[74:75], v[20:21] op_sel:[0,0,0] op_sel_hi:[0,1,1]
	v_pk_fma_f32 v[12:13], v[150:151], v[76:77], v[12:13] op_sel:[0,0,0] op_sel_hi:[0,1,1]
	v_pk_fma_f32 v[4:5], v[150:151], v[78:79], v[4:5] op_sel:[0,0,0] op_sel_hi:[0,1,1]
	v_pk_fma_f32 v[68:69], v[146:147], v[80:81], v[68:69] op_sel:[1,0,0] op_sel_hi:[1,1,1]
	v_pk_fma_f32 v[54:55], v[146:147], v[82:83], v[54:55] op_sel:[1,0,0] op_sel_hi:[1,1,1]
	v_pk_fma_f32 v[46:47], v[146:147], v[84:85], v[46:47] op_sel:[1,0,0] op_sel_hi:[1,1,1]
	v_pk_fma_f32 v[38:39], v[146:147], v[86:87], v[38:39] op_sel:[1,0,0] op_sel_hi:[1,1,1]
	v_pk_fma_f32 v[30:31], v[150:151], v[80:81], v[30:31] op_sel:[1,0,0] op_sel_hi:[1,1,1]
	v_pk_fma_f32 v[22:23], v[150:151], v[82:83], v[22:23] op_sel:[1,0,0] op_sel_hi:[1,1,1]
	v_pk_fma_f32 v[14:15], v[150:151], v[84:85], v[14:15] op_sel:[1,0,0] op_sel_hi:[1,1,1]
	v_pk_fma_f32 v[6:7], v[150:151], v[86:87], v[6:7] op_sel:[1,0,0] op_sel_hi:[1,1,1]
	v_pk_fma_f32 v[64:65], v[148:149], v[88:89], v[64:65] op_sel:[0,0,0] op_sel_hi:[0,1,1]
	v_pk_fma_f32 v[50:51], v[148:149], v[90:91], v[50:51] op_sel:[0,0,0] op_sel_hi:[0,1,1]
	v_pk_fma_f32 v[42:43], v[148:149], v[92:93], v[42:43] op_sel:[0,0,0] op_sel_hi:[0,1,1]
	v_pk_fma_f32 v[34:35], v[148:149], v[94:95], v[34:35] op_sel:[0,0,0] op_sel_hi:[0,1,1]
	v_pk_fma_f32 v[26:27], v[152:153], v[88:89], v[26:27] op_sel:[0,0,0] op_sel_hi:[0,1,1]
	v_pk_fma_f32 v[18:19], v[152:153], v[90:91], v[18:19] op_sel:[0,0,0] op_sel_hi:[0,1,1]
	v_pk_fma_f32 v[10:11], v[152:153], v[92:93], v[10:11] op_sel:[0,0,0] op_sel_hi:[0,1,1]
	v_pk_fma_f32 v[2:3], v[152:153], v[94:95], v[2:3] op_sel:[0,0,0] op_sel_hi:[0,1,1]
	v_pk_fma_f32 v[70:71], v[148:149], v[96:97], v[70:71] op_sel:[1,0,0] op_sel_hi:[1,1,1]
	v_pk_fma_f32 v[56:57], v[148:149], v[98:99], v[56:57] op_sel:[1,0,0] op_sel_hi:[1,1,1]
	v_pk_fma_f32 v[48:49], v[148:149], v[100:101], v[48:49] op_sel:[1,0,0] op_sel_hi:[1,1,1]
	v_pk_fma_f32 v[40:41], v[148:149], v[102:103], v[40:41] op_sel:[1,0,0] op_sel_hi:[1,1,1]
	v_pk_fma_f32 v[32:33], v[152:153], v[96:97], v[32:33] op_sel:[1,0,0] op_sel_hi:[1,1,1]
	v_pk_fma_f32 v[24:25], v[152:153], v[98:99], v[24:25] op_sel:[1,0,0] op_sel_hi:[1,1,1]
	v_pk_fma_f32 v[16:17], v[152:153], v[100:101], v[16:17] op_sel:[1,0,0] op_sel_hi:[1,1,1]
	v_pk_fma_f32 v[8:9], v[152:153], v[102:103], v[8:9] op_sel:[1,0,0] op_sel_hi:[1,1,1]
	s_add_i32 s0, s1, 4
	s_min_u32 s0, s0, 63
	s_lshl_b32 s0, s0, 11
	v_add_u32_e32 v186, s0, v188
	global_load_dword v146, v186, s[26:27]
	global_load_dword v147, v186, s[28:29]
	global_load_dword v148, v186, s[36:37]
	global_load_dword v149, v186, s[38:39]
	global_load_dword v150, v186, s[26:27] offset:1024
	global_load_dword v151, v186, s[28:29] offset:1024
	global_load_dword v152, v186, s[36:37] offset:1024
	global_load_dword v153, v186, s[38:39] offset:1024
	ds_read_b128 v[72:75], v187 offset:256
	ds_read_b128 v[76:79], v187 offset:272
	ds_read_b128 v[80:83], v187 offset:288
	ds_read_b128 v[84:87], v187 offset:304
	ds_read_b128 v[88:91], v187 offset:320
	ds_read_b128 v[92:95], v187 offset:336
	ds_read_b128 v[96:99], v187 offset:352
	ds_read_b128 v[100:103], v187 offset:368
	s_waitcnt vmcnt(24)
	s_waitcnt lgkmcnt(8)
	v_pk_fma_f32 v[66:67], v[154:155], v[104:105], v[66:67] op_sel:[0,0,0] op_sel_hi:[0,1,1]
	v_pk_fma_f32 v[52:53], v[154:155], v[106:107], v[52:53] op_sel:[0,0,0] op_sel_hi:[0,1,1]
	v_pk_fma_f32 v[44:45], v[154:155], v[108:109], v[44:45] op_sel:[0,0,0] op_sel_hi:[0,1,1]
	v_pk_fma_f32 v[36:37], v[154:155], v[110:111], v[36:37] op_sel:[0,0,0] op_sel_hi:[0,1,1]
	v_pk_fma_f32 v[28:29], v[158:159], v[104:105], v[28:29] op_sel:[0,0,0] op_sel_hi:[0,1,1]
	v_pk_fma_f32 v[20:21], v[158:159], v[106:107], v[20:21] op_sel:[0,0,0] op_sel_hi:[0,1,1]
	v_pk_fma_f32 v[12:13], v[158:159], v[108:109], v[12:13] op_sel:[0,0,0] op_sel_hi:[0,1,1]
	v_pk_fma_f32 v[4:5], v[158:159], v[110:111], v[4:5] op_sel:[0,0,0] op_sel_hi:[0,1,1]
	v_pk_fma_f32 v[68:69], v[154:155], v[112:113], v[68:69] op_sel:[1,0,0] op_sel_hi:[1,1,1]
	v_pk_fma_f32 v[54:55], v[154:155], v[114:115], v[54:55] op_sel:[1,0,0] op_sel_hi:[1,1,1]
	v_pk_fma_f32 v[46:47], v[154:155], v[116:117], v[46:47] op_sel:[1,0,0] op_sel_hi:[1,1,1]
	v_pk_fma_f32 v[38:39], v[154:155], v[118:119], v[38:39] op_sel:[1,0,0] op_sel_hi:[1,1,1]
	v_pk_fma_f32 v[30:31], v[158:159], v[112:113], v[30:31] op_sel:[1,0,0] op_sel_hi:[1,1,1]
	v_pk_fma_f32 v[22:23], v[158:159], v[114:115], v[22:23] op_sel:[1,0,0] op_sel_hi:[1,1,1]
	v_pk_fma_f32 v[14:15], v[158:159], v[116:117], v[14:15] op_sel:[1,0,0] op_sel_hi:[1,1,1]
	v_pk_fma_f32 v[6:7], v[158:159], v[118:119], v[6:7] op_sel:[1,0,0] op_sel_hi:[1,1,1]
	v_pk_fma_f32 v[64:65], v[156:157], v[120:121], v[64:65] op_sel:[0,0,0] op_sel_hi:[0,1,1]
	v_pk_fma_f32 v[50:51], v[156:157], v[122:123], v[50:51] op_sel:[0,0,0] op_sel_hi:[0,1,1]
	v_pk_fma_f32 v[42:43], v[156:157], v[132:133], v[42:43] op_sel:[0,0,0] op_sel_hi:[0,1,1]
	v_pk_fma_f32 v[34:35], v[156:157], v[134:135], v[34:35] op_sel:[0,0,0] op_sel_hi:[0,1,1]
	v_pk_fma_f32 v[26:27], v[160:161], v[120:121], v[26:27] op_sel:[0,0,0] op_sel_hi:[0,1,1]
	v_pk_fma_f32 v[18:19], v[160:161], v[122:123], v[18:19] op_sel:[0,0,0] op_sel_hi:[0,1,1]
	v_pk_fma_f32 v[10:11], v[160:161], v[132:133], v[10:11] op_sel:[0,0,0] op_sel_hi:[0,1,1]
	v_pk_fma_f32 v[2:3], v[160:161], v[134:135], v[2:3] op_sel:[0,0,0] op_sel_hi:[0,1,1]
	v_pk_fma_f32 v[70:71], v[156:157], v[136:137], v[70:71] op_sel:[1,0,0] op_sel_hi:[1,1,1]
	v_pk_fma_f32 v[56:57], v[156:157], v[138:139], v[56:57] op_sel:[1,0,0] op_sel_hi:[1,1,1]
	v_pk_fma_f32 v[48:49], v[156:157], v[140:141], v[48:49] op_sel:[1,0,0] op_sel_hi:[1,1,1]
	v_pk_fma_f32 v[40:41], v[156:157], v[142:143], v[40:41] op_sel:[1,0,0] op_sel_hi:[1,1,1]
	v_pk_fma_f32 v[32:33], v[160:161], v[136:137], v[32:33] op_sel:[1,0,0] op_sel_hi:[1,1,1]
	v_pk_fma_f32 v[24:25], v[160:161], v[138:139], v[24:25] op_sel:[1,0,0] op_sel_hi:[1,1,1]
	v_pk_fma_f32 v[16:17], v[160:161], v[140:141], v[16:17] op_sel:[1,0,0] op_sel_hi:[1,1,1]
	v_pk_fma_f32 v[8:9], v[160:161], v[142:143], v[8:9] op_sel:[1,0,0] op_sel_hi:[1,1,1]
	s_add_i32 s0, s1, 5
	s_min_u32 s0, s0, 63
	s_lshl_b32 s0, s0, 11
	v_add_u32_e32 v186, s0, v188
	global_load_dword v154, v186, s[26:27]
	global_load_dword v155, v186, s[28:29]
	global_load_dword v156, v186, s[36:37]
	global_load_dword v157, v186, s[38:39]
	global_load_dword v158, v186, s[26:27] offset:1024
	global_load_dword v159, v186, s[28:29] offset:1024
	global_load_dword v160, v186, s[36:37] offset:1024
	global_load_dword v161, v186, s[38:39] offset:1024
	ds_read_b128 v[104:107], v187 offset:384
	ds_read_b128 v[108:111], v187 offset:400
	ds_read_b128 v[112:115], v187 offset:416
	ds_read_b128 v[116:119], v187 offset:432
	ds_read_b128 v[120:123], v187 offset:448
	ds_read_b128 v[132:135], v187 offset:464
	ds_read_b128 v[136:139], v187 offset:480
	ds_read_b128 v[140:143], v187 offset:496
	s_waitcnt vmcnt(24)
	s_waitcnt lgkmcnt(8)
	v_pk_fma_f32 v[66:67], v[162:163], v[72:73], v[66:67] op_sel:[0,0,0] op_sel_hi:[0,1,1]
	v_pk_fma_f32 v[52:53], v[162:163], v[74:75], v[52:53] op_sel:[0,0,0] op_sel_hi:[0,1,1]
	v_pk_fma_f32 v[44:45], v[162:163], v[76:77], v[44:45] op_sel:[0,0,0] op_sel_hi:[0,1,1]
	v_pk_fma_f32 v[36:37], v[162:163], v[78:79], v[36:37] op_sel:[0,0,0] op_sel_hi:[0,1,1]
	v_pk_fma_f32 v[28:29], v[166:167], v[72:73], v[28:29] op_sel:[0,0,0] op_sel_hi:[0,1,1]
	v_pk_fma_f32 v[20:21], v[166:167], v[74:75], v[20:21] op_sel:[0,0,0] op_sel_hi:[0,1,1]
	v_pk_fma_f32 v[12:13], v[166:167], v[76:77], v[12:13] op_sel:[0,0,0] op_sel_hi:[0,1,1]
	v_pk_fma_f32 v[4:5], v[166:167], v[78:79], v[4:5] op_sel:[0,0,0] op_sel_hi:[0,1,1]
	v_pk_fma_f32 v[68:69], v[162:163], v[80:81], v[68:69] op_sel:[1,0,0] op_sel_hi:[1,1,1]
	v_pk_fma_f32 v[54:55], v[162:163], v[82:83], v[54:55] op_sel:[1,0,0] op_sel_hi:[1,1,1]
	v_pk_fma_f32 v[46:47], v[162:163], v[84:85], v[46:47] op_sel:[1,0,0] op_sel_hi:[1,1,1]
	v_pk_fma_f32 v[38:39], v[162:163], v[86:87], v[38:39] op_sel:[1,0,0] op_sel_hi:[1,1,1]
	v_pk_fma_f32 v[30:31], v[166:167], v[80:81], v[30:31] op_sel:[1,0,0] op_sel_hi:[1,1,1]
	v_pk_fma_f32 v[22:23], v[166:167], v[82:83], v[22:23] op_sel:[1,0,0] op_sel_hi:[1,1,1]
	v_pk_fma_f32 v[14:15], v[166:167], v[84:85], v[14:15] op_sel:[1,0,0] op_sel_hi:[1,1,1]
	v_pk_fma_f32 v[6:7], v[166:167], v[86:87], v[6:7] op_sel:[1,0,0] op_sel_hi:[1,1,1]
	v_pk_fma_f32 v[64:65], v[164:165], v[88:89], v[64:65] op_sel:[0,0,0] op_sel_hi:[0,1,1]
	v_pk_fma_f32 v[50:51], v[164:165], v[90:91], v[50:51] op_sel:[0,0,0] op_sel_hi:[0,1,1]
	v_pk_fma_f32 v[42:43], v[164:165], v[92:93], v[42:43] op_sel:[0,0,0] op_sel_hi:[0,1,1]
	v_pk_fma_f32 v[34:35], v[164:165], v[94:95], v[34:35] op_sel:[0,0,0] op_sel_hi:[0,1,1]
	v_pk_fma_f32 v[26:27], v[168:169], v[88:89], v[26:27] op_sel:[0,0,0] op_sel_hi:[0,1,1]
	v_pk_fma_f32 v[18:19], v[168:169], v[90:91], v[18:19] op_sel:[0,0,0] op_sel_hi:[0,1,1]
	v_pk_fma_f32 v[10:11], v[168:169], v[92:93], v[10:11] op_sel:[0,0,0] op_sel_hi:[0,1,1]
	v_pk_fma_f32 v[2:3], v[168:169], v[94:95], v[2:3] op_sel:[0,0,0] op_sel_hi:[0,1,1]
	v_pk_fma_f32 v[70:71], v[164:165], v[96:97], v[70:71] op_sel:[1,0,0] op_sel_hi:[1,1,1]
	v_pk_fma_f32 v[56:57], v[164:165], v[98:99], v[56:57] op_sel:[1,0,0] op_sel_hi:[1,1,1]
	v_pk_fma_f32 v[48:49], v[164:165], v[100:101], v[48:49] op_sel:[1,0,0] op_sel_hi:[1,1,1]
	v_pk_fma_f32 v[40:41], v[164:165], v[102:103], v[40:41] op_sel:[1,0,0] op_sel_hi:[1,1,1]
	v_pk_fma_f32 v[32:33], v[168:169], v[96:97], v[32:33] op_sel:[1,0,0] op_sel_hi:[1,1,1]
	v_pk_fma_f32 v[24:25], v[168:169], v[98:99], v[24:25] op_sel:[1,0,0] op_sel_hi:[1,1,1]
	v_pk_fma_f32 v[16:17], v[168:169], v[100:101], v[16:17] op_sel:[1,0,0] op_sel_hi:[1,1,1]
	v_pk_fma_f32 v[8:9], v[168:169], v[102:103], v[8:9] op_sel:[1,0,0] op_sel_hi:[1,1,1]
	s_add_i32 s0, s1, 6
	s_min_u32 s0, s0, 63
	s_lshl_b32 s0, s0, 11
	v_add_u32_e32 v186, s0, v188
	global_load_dword v162, v186, s[26:27]
	global_load_dword v163, v186, s[28:29]
	global_load_dword v164, v186, s[36:37]
	global_load_dword v165, v186, s[38:39]
	global_load_dword v166, v186, s[26:27] offset:1024
	global_load_dword v167, v186, s[28:29] offset:1024
	global_load_dword v168, v186, s[36:37] offset:1024
	global_load_dword v169, v186, s[38:39] offset:1024
	ds_read_b128 v[72:75], v187 offset:512
	ds_read_b128 v[76:79], v187 offset:528
	ds_read_b128 v[80:83], v187 offset:544
	ds_read_b128 v[84:87], v187 offset:560
	ds_read_b128 v[88:91], v187 offset:576
	ds_read_b128 v[92:95], v187 offset:592
	ds_read_b128 v[96:99], v187 offset:608
	ds_read_b128 v[100:103], v187 offset:624
	s_waitcnt vmcnt(24)
	s_waitcnt lgkmcnt(8)
	v_pk_fma_f32 v[66:67], v[170:171], v[104:105], v[66:67] op_sel:[0,0,0] op_sel_hi:[0,1,1]
	v_pk_fma_f32 v[52:53], v[170:171], v[106:107], v[52:53] op_sel:[0,0,0] op_sel_hi:[0,1,1]
	v_pk_fma_f32 v[44:45], v[170:171], v[108:109], v[44:45] op_sel:[0,0,0] op_sel_hi:[0,1,1]
	v_pk_fma_f32 v[36:37], v[170:171], v[110:111], v[36:37] op_sel:[0,0,0] op_sel_hi:[0,1,1]
	v_pk_fma_f32 v[28:29], v[174:175], v[104:105], v[28:29] op_sel:[0,0,0] op_sel_hi:[0,1,1]
	v_pk_fma_f32 v[20:21], v[174:175], v[106:107], v[20:21] op_sel:[0,0,0] op_sel_hi:[0,1,1]
	v_pk_fma_f32 v[12:13], v[174:175], v[108:109], v[12:13] op_sel:[0,0,0] op_sel_hi:[0,1,1]
	v_pk_fma_f32 v[4:5], v[174:175], v[110:111], v[4:5] op_sel:[0,0,0] op_sel_hi:[0,1,1]
	v_pk_fma_f32 v[68:69], v[170:171], v[112:113], v[68:69] op_sel:[1,0,0] op_sel_hi:[1,1,1]
	v_pk_fma_f32 v[54:55], v[170:171], v[114:115], v[54:55] op_sel:[1,0,0] op_sel_hi:[1,1,1]
	v_pk_fma_f32 v[46:47], v[170:171], v[116:117], v[46:47] op_sel:[1,0,0] op_sel_hi:[1,1,1]
	v_pk_fma_f32 v[38:39], v[170:171], v[118:119], v[38:39] op_sel:[1,0,0] op_sel_hi:[1,1,1]
	v_pk_fma_f32 v[30:31], v[174:175], v[112:113], v[30:31] op_sel:[1,0,0] op_sel_hi:[1,1,1]
	v_pk_fma_f32 v[22:23], v[174:175], v[114:115], v[22:23] op_sel:[1,0,0] op_sel_hi:[1,1,1]
	v_pk_fma_f32 v[14:15], v[174:175], v[116:117], v[14:15] op_sel:[1,0,0] op_sel_hi:[1,1,1]
	v_pk_fma_f32 v[6:7], v[174:175], v[118:119], v[6:7] op_sel:[1,0,0] op_sel_hi:[1,1,1]
	v_pk_fma_f32 v[64:65], v[172:173], v[120:121], v[64:65] op_sel:[0,0,0] op_sel_hi:[0,1,1]
	v_pk_fma_f32 v[50:51], v[172:173], v[122:123], v[50:51] op_sel:[0,0,0] op_sel_hi:[0,1,1]
	v_pk_fma_f32 v[42:43], v[172:173], v[132:133], v[42:43] op_sel:[0,0,0] op_sel_hi:[0,1,1]
	v_pk_fma_f32 v[34:35], v[172:173], v[134:135], v[34:35] op_sel:[0,0,0] op_sel_hi:[0,1,1]
	v_pk_fma_f32 v[26:27], v[176:177], v[120:121], v[26:27] op_sel:[0,0,0] op_sel_hi:[0,1,1]
	v_pk_fma_f32 v[18:19], v[176:177], v[122:123], v[18:19] op_sel:[0,0,0] op_sel_hi:[0,1,1]
	v_pk_fma_f32 v[10:11], v[176:177], v[132:133], v[10:11] op_sel:[0,0,0] op_sel_hi:[0,1,1]
	v_pk_fma_f32 v[2:3], v[176:177], v[134:135], v[2:3] op_sel:[0,0,0] op_sel_hi:[0,1,1]
	v_pk_fma_f32 v[70:71], v[172:173], v[136:137], v[70:71] op_sel:[1,0,0] op_sel_hi:[1,1,1]
	v_pk_fma_f32 v[56:57], v[172:173], v[138:139], v[56:57] op_sel:[1,0,0] op_sel_hi:[1,1,1]
	v_pk_fma_f32 v[48:49], v[172:173], v[140:141], v[48:49] op_sel:[1,0,0] op_sel_hi:[1,1,1]
	v_pk_fma_f32 v[40:41], v[172:173], v[142:143], v[40:41] op_sel:[1,0,0] op_sel_hi:[1,1,1]
	v_pk_fma_f32 v[32:33], v[176:177], v[136:137], v[32:33] op_sel:[1,0,0] op_sel_hi:[1,1,1]
	v_pk_fma_f32 v[24:25], v[176:177], v[138:139], v[24:25] op_sel:[1,0,0] op_sel_hi:[1,1,1]
	v_pk_fma_f32 v[16:17], v[176:177], v[140:141], v[16:17] op_sel:[1,0,0] op_sel_hi:[1,1,1]
	v_pk_fma_f32 v[8:9], v[176:177], v[142:143], v[8:9] op_sel:[1,0,0] op_sel_hi:[1,1,1]
	v_add_u32_e32 v187, 0x200, v187
	s_add_i32 s1, s1, 4
	s_cmp_lt_u32 s1, 64
	s_cbranch_scc1 .Llora_loop
	s_waitcnt vmcnt(0) lgkmcnt(0)
	s_cmpk_lt_i32 s25, 0x200
	s_movk_i32 s0, 0x7f8
	s_cselect_b32 s0, 0xf8, s0
	v_lshl_add_u64 v[58:59], v[0:1], 2, s[46:47]
	s_and_b32 s0, s0, s60
	s_mul_i32 s26, s60, 0x4a00
	v_readlane_b32 s2, v254, 63
	v_add_co_u32_e32 v62, vcc, 0x1000, v58
	s_mul_hi_i32 s1, s60, 0x4a00
	v_readlane_b32 s3, v255, 0
	s_add_u32 s40, s2, s26
	v_lshl_add_u64 v[60:61], v[0:1], 1, v[232:233]
	v_addc_co_u32_e32 v63, vcc, 0, v59, vcc
	s_addc_u32 s41, s3, s1
	global_load_dword v75, v[58:59], off
	global_load_dword v76, v[58:59], off offset:2048
	global_load_dword v74, v[62:63], off
	v_lshl_add_u64 v[62:63], s[40:41], 0, v[60:61]
	global_load_ushort v80, v[62:63], off
	s_cmp_lg_u32 s0, 0
	s_cselect_b64 s[0:1], -1, 0
	v_lshl_add_u64 v[60:61], s[2:3], 0, v[60:61]
	v_mov_b32_e32 v77, 0
	s_and_b64 vcc, exec, s[0:1]
	v_mov_b32_e32 v87, 0
	v_mov_b32_e32 v190, 0
	s_cbranch_vccz .LBB0_241
	s_add_i32 s26, s60, -1
	v_mad_i64_i32 v[62:63], s[26:27], s26, v214, v[60:61]
	global_load_ushort v190, v[62:63], off
.LBB0_241:
	s_or_b32 s44, s60, 1
	v_lshl_add_u64 v[62:63], v[0:1], 1, v[234:235]
	v_mad_i64_i32 v[72:73], s[26:27], s44, v214, v[60:61]
	v_lshl_add_u64 v[78:79], s[40:41], 0, v[62:63]
	global_load_ushort v83, v[72:73], off
	global_load_ushort v84, v[78:79], off
	v_cndmask_b32_e64 v72, 0, 1, s[0:1]
	s_andn2_b64 vcc, exec, s[0:1]
	v_readlane_b32 s0, v254, 63
	v_readlane_b32 s1, v255, 0
	v_cmp_ne_u32_e64 s[36:37], 1, v72
	s_nop 0
	v_lshl_add_u64 v[72:73], s[0:1], 0, v[62:63]
	v_mov_b32_e32 v191, 0
	s_cbranch_vccnz .LBB0_243
	s_add_i32 s0, s60, -1
	v_mad_i64_i32 v[62:63], s[0:1], s0, v214, v[72:73]
	global_load_ushort v191, v[62:63], off
.LBB0_243:
	s_mul_hi_i32 s63, s44, 0x4a00
	s_mul_i32 s62, s44, 0x4a00
	v_lshl_add_u64 v[62:63], v[0:1], 1, v[236:237]
	v_lshl_add_u64 v[78:79], v[72:73], 0, s[62:63]
	v_lshl_add_u64 v[88:89], s[40:41], 0, v[62:63]
	global_load_ushort v86, v[78:79], off
	global_load_ushort v85, v[88:89], off
	v_readlane_b32 s0, v254, 63
	v_readlane_b32 s1, v255, 0
	v_mov_b32_e32 v79, 0
	s_and_b64 vcc, exec, s[36:37]
	v_lshl_add_u64 v[62:63], s[0:1], 0, v[62:63]
	v_mov_b32_e32 v88, 0
	v_mov_b32_e32 v192, 0
	s_cbranch_vccnz .LBB0_245
	s_add_i32 s0, s60, -1
	v_mad_i64_i32 v[88:89], s[0:1], s0, v214, v[62:63]
	global_load_ushort v192, v[88:89], off
.LBB0_245:
	s_or_b32 s58, s60, 4
	v_lshl_add_u64 v[90:91], v[62:63], 0, s[62:63]
	s_or_b32 s64, s60, 2
	v_mad_i64_i32 v[98:99], s[0:1], s58, v214, v[62:63]
	s_or_b32 s54, s60, 5
	global_load_ushort v89, v[90:91], off
	global_load_ushort v108, v[98:99], off
	v_mad_i64_i32 v[90:91], s[0:1], s64, v214, v[60:61]
	v_mad_i64_i32 v[98:99], s[0:1], s54, v214, v[60:61]
	global_load_ushort v90, v[90:91], off
	v_mad_i64_i32 v[92:93], s[0:1], s64, v214, v[72:73]
	global_load_ushort v110, v[98:99], off
	v_mad_i64_i32 v[98:99], s[0:1], s54, v214, v[72:73]
	global_load_ushort v91, v[92:93], off
	global_load_ushort v111, v[98:99], off
	v_mad_i64_i32 v[92:93], s[0:1], s64, v214, v[62:63]
	s_or_b32 s42, s60, 3
	v_mad_i64_i32 v[98:99], s[0:1], s54, v214, v[62:63]
	s_or_b32 s26, s60, 6
	global_load_ushort v92, v[92:93], off
	v_mad_i64_i32 v[94:95], s[0:1], s42, v214, v[60:61]
	global_load_ushort v112, v[98:99], off
	v_mad_i64_i32 v[98:99], s[0:1], s26, v214, v[60:61]
	global_load_ushort v93, v[94:95], off
	global_load_ushort v82, v[98:99], off
	v_mad_i64_i32 v[94:95], s[0:1], s42, v214, v[72:73]
	v_mad_i64_i32 v[98:99], s[0:1], s26, v214, v[72:73]
	global_load_ushort v94, v[94:95], off
	v_mad_i64_i32 v[96:97], s[0:1], s42, v214, v[62:63]
	global_load_ushort v78, v[98:99], off
	v_mad_i64_i32 v[98:99], s[0:1], s26, v214, v[62:63]
	s_or_b32 s28, s60, 7
	global_load_ushort v95, v[96:97], off
	global_load_ushort v113, v[98:99], off
	v_mad_i64_i32 v[96:97], s[0:1], s58, v214, v[60:61]
	v_mad_i64_i32 v[100:101], s[0:1], s28, v214, v[62:63]
	global_load_ushort v109, v[96:97], off
	global_load_ushort v114, v[100:101], off
	v_mad_i64_i32 v[96:97], s[0:1], s58, v214, v[72:73]
	v_mad_i64_i32 v[98:99], s[0:1], s28, v214, v[60:61]
	global_load_ushort v96, v[96:97], off
	s_cmpk_lt_i32 s28, 0x1000
	global_load_ushort v97, v[98:99], off
	v_mad_i64_i32 v[98:99], s[0:1], s28, v214, v[72:73]
	global_load_ushort v98, v[98:99], off
	s_movk_i32 s0, 0xf800
	s_cselect_b32 s0, 0xffffff00, s0
	s_or_b32 s27, s0, s28
	s_cmp_lg_u32 s27, -1
	s_mov_b32 s71, s16
	s_cselect_b64 s[0:1], -1, 0
	s_cmp_eq_u32 s27, -1
	v_mov_b32_e32 v193, 0
	s_cbranch_scc1 .LBB0_247
	s_add_i32 s27, s60, 8
	v_mad_i64_i32 v[60:61], s[38:39], s27, v214, v[60:61]
	global_load_ushort v193, v[60:61], off
.LBB0_247:
	v_cndmask_b32_e64 v61, 0, 1, s[0:1]
	s_mov_b64 s[16:17], s[18:19]
	v_mov_b32_e32 v60, 0
	v_cmp_ne_u32_e64 s[38:39], 1, v61
	s_andn2_b64 vcc, exec, s[0:1]
	v_mov_b32_e32 v61, 0
	v_mov_b32_e32 v194, 0
	s_cbranch_vccnz .LBB0_249
	s_add_i32 s0, s60, 8
	v_mad_i64_i32 v[72:73], s[0:1], s0, v214, v[72:73]
	global_load_ushort v194, v[72:73], off
.LBB0_249:
	s_mov_b64 s[18:19], s[46:47]
	s_ashr_i32 s61, s60, 31
	s_ashr_i32 s45, s44, 31
	s_ashr_i32 s65, s64, 31
	s_ashr_i32 s43, s42, 31
	s_ashr_i32 s59, s58, 31
	s_ashr_i32 s55, s54, 31
	s_ashr_i32 s27, s26, 31
	s_and_b64 vcc, exec, s[38:39]
	s_ashr_i32 s29, s28, 31
	v_mov_b32_e32 v195, 0
	s_cbranch_vccnz .LBB0_251
	s_add_i32 s0, s60, 8
	v_mad_i64_i32 v[62:63], s[0:1], s0, v214, v[62:63]
	global_load_ushort v195, v[62:63], off
.LBB0_251:
	s_waitcnt vmcnt(0)
	v_lshlrev_b32_e32 v87, 16, v190
	v_lshlrev_b32_e32 v77, 16, v191
	v_lshlrev_b32_e32 v88, 16, v192
	v_lshlrev_b32_e32 v79, 16, v193
	v_lshlrev_b32_e32 v61, 16, v194
	v_lshlrev_b32_e32 v60, 16, v195
	v_lshlrev_b32_e32 v81, 16, v78
	s_waitcnt vmcnt(0)
	v_lshlrev_b32_e32 v62, 16, v98
	v_add_f32_e32 v61, v61, v81
	v_lshlrev_b32_e32 v107, 16, v80
	v_lshlrev_b32_e32 v100, 16, v90
	v_fma_f32 v61, v61, 0.5, -v62
	v_lshlrev_b32_e32 v82, 16, v82
	v_lshlrev_b32_e32 v72, 16, v83
	v_add_f32_e32 v80, v107, v100
	v_fma_f32 v78, v76, v61, v62
	v_lshlrev_b32_e32 v61, 16, v97
	v_add_f32_e32 v63, v79, v82
	v_fma_f32 v80, v80, 0.5, -v72
	v_fma_f32 v63, v63, 0.5, -v61
	v_lshlrev_b32_e32 v105, 16, v84
	v_fma_f32 v104, v75, v80, v72
	v_lshlrev_b32_e32 v80, 16, v91
	v_fma_f32 v79, v75, v63, v61
	v_lshlrev_b32_e32 v63, 16, v86
	v_lshlrev_b32_e32 v103, 16, v89
	v_add_f32_e32 v83, v105, v80
	v_lshlrev_b32_e32 v86, 16, v94
	v_lshlrev_b32_e32 v106, 16, v85
	v_add_f32_e32 v73, v88, v103
	v_fma_f32 v83, v83, 0.5, -v63
	v_lshlrev_b32_e32 v101, 16, v92
	v_add_f32_e32 v84, v63, v86
	v_fma_f32 v73, v73, 0.5, -v106
	v_fma_f32 v102, v76, v83, v63
	v_add_f32_e32 v83, v106, v101
	v_lshlrev_b32_e32 v97, 16, v93
	v_fma_f32 v84, v84, 0.5, -v80
	v_lshlrev_b32_e32 v98, 16, v95
	v_lshlrev_b32_e32 v91, 16, v96
	v_fmac_f32_e32 v106, v74, v73
	v_fma_f32 v73, v83, 0.5, -v103
	v_add_f32_e32 v83, v72, v97
	v_fma_f32 v99, v76, v84, v80
	v_add_f32_e32 v84, v103, v98
	v_lshlrev_b32_e32 v93, 16, v109
	v_add_f32_e32 v80, v80, v91
	v_fma_f32 v83, v83, 0.5, -v100
	v_fmac_f32_e32 v103, v74, v73
	v_fma_f32 v73, v84, 0.5, -v101
	v_add_f32_e32 v84, v100, v93
	v_fma_f32 v80, v80, 0.5, -v86
	v_lshlrev_b32_e32 v94, 16, v108
	v_fmac_f32_e32 v100, v75, v83
	v_fma_f32 v83, v84, 0.5, -v97
	v_fma_f32 v96, v76, v80, v86
	v_add_f32_e32 v80, v101, v94
	v_lshlrev_b32_e32 v85, 16, v110
	v_lshlrev_b32_e32 v84, 16, v111
	v_fmac_f32_e32 v101, v74, v73
	v_fma_f32 v73, v80, 0.5, -v98
	v_add_f32_e32 v80, v97, v85
	v_fmac_f32_e32 v97, v75, v83
	v_add_f32_e32 v83, v86, v84
	v_lshlrev_b32_e32 v86, 16, v112
	v_add_f32_e32 v88, v98, v86
	v_add_f32_e32 v61, v85, v61
	v_fma_f32 v80, v80, 0.5, -v93
	v_fmac_f32_e32 v98, v74, v73
	v_fma_f32 v73, v88, 0.5, -v94
	v_add_f32_e32 v88, v93, v82
	v_fma_f32 v61, v61, 0.5, -v82
	v_fmac_f32_e32 v93, v75, v80
	v_fma_f32 v80, v88, 0.5, -v85
	v_fmac_f32_e32 v82, v75, v61
	v_add_f32_e32 v61, v84, v62
	v_fma_f32 v83, v83, 0.5, -v91
	v_add_f32_e32 v88, v91, v81
	v_fmac_f32_e32 v85, v75, v80
	v_fma_f32 v61, v61, 0.5, -v81
	v_lshlrev_b32_e32 v80, 16, v114
	v_fmac_f32_e32 v91, v76, v83
	v_fma_f32 v83, v88, 0.5, -v84
	v_lshlrev_b32_e32 v88, 16, v113
	v_fmac_f32_e32 v81, v76, v61
	v_add_f32_e32 v61, v86, v80
	v_fma_f32 v61, v61, 0.5, -v88
	v_fmac_f32_e32 v84, v76, v83
	v_fma_f32 v83, v74, v61, v88
	v_add_f32_e32 v61, v77, v63
	v_fma_f32 v61, v61, 0.5, -v105
	v_fmac_f32_e32 v105, v76, v61
	v_add_f32_e32 v61, v87, v72
	v_fma_f32 v61, v61, 0.5, -v107
	v_and_b32_e32 v62, 64, v205
	v_fmac_f32_e32 v107, v75, v61
	v_xor_b32_e32 v61, 16, v205
	v_add_u32_e32 v62, 64, v62
	v_cmp_lt_i32_e32 vcc, v61, v62
	v_add_f32_e32 v60, v60, v88
	v_fma_f32 v60, v60, 0.5, -v80
	v_cndmask_b32_e32 v61, v205, v61, vcc
	v_lshlrev_b32_e32 v77, 2, v61
	v_xor_b32_e32 v61, 32, v205
	v_cmp_lt_i32_e32 vcc, v61, v62
	v_fmac_f32_e32 v80, v74, v60
	v_add_u32_e32 v60, s88, v0
	v_cndmask_b32_e32 v61, v205, v61, vcc
	v_add_f32_e32 v89, v94, v88
	v_lshlrev_b32_e32 v76, 2, v61
	v_ashrrev_i32_e32 v61, 31, v60
	v_readlane_b32 s0, v252, 17
	v_fmac_f32_e32 v94, v74, v73
	v_fma_f32 v73, v89, 0.5, -v86
	v_lshlrev_b64 v[62:63], 2, v[60:61]
	v_readlane_b32 s1, v252, 18
	v_readlane_b32 s2, v252, 19
	v_readlane_b32 s3, v252, 20
	v_readlane_b32 s4, v252, 21
	v_readlane_b32 s5, v252, 22
	v_readlane_b32 s6, v252, 23
	v_readlane_b32 s7, v252, 24
	v_readlane_b32 s8, v252, 25
	v_readlane_b32 s9, v252, 26
	v_readlane_b32 s10, v252, 27
	v_readlane_b32 s11, v252, 28
	v_readlane_b32 s12, v252, 29
	v_readlane_b32 s13, v252, 30
	v_readlane_b32 s14, v252, 31
	v_readlane_b32 s15, v252, 32
	v_subrev_u32_e32 v60, s90, v60
	v_fmac_f32_e32 v86, v74, v73
	v_lshl_add_u64 v[74:75], s[10:11], 0, v[62:63]
	v_lshl_add_u64 v[72:73], s[14:15], 0, v[62:63]
	v_ashrrev_i32_e32 v61, 31, v60
	v_readlane_b32 s0, v252, 33
	v_lshlrev_b64 v[62:63], 2, v[60:61]
	v_readlane_b32 s2, v252, 35
	v_readlane_b32 s3, v252, 36
	global_load_dword v90, v[74:75], off
	global_load_dword v89, v[74:75], off offset:2048
	v_lshl_add_u64 v[60:61], s[2:3], 0, v[62:63]
	global_load_dword v88, v[72:73], off
	global_load_dword v87, v[72:73], off offset:2048
	global_load_dword v92, v[60:61], off
	v_readlane_b32 s4, v252, 37
	v_readlane_b32 s5, v252, 38
	s_lshl_b64 s[66:67], s[60:61], 9
	v_readlane_b32 s2, v254, 33
	v_lshl_add_u64 v[62:63], s[4:5], 0, v[62:63]
	global_load_dword v95, v[62:63], off
	v_readlane_b32 s3, v254, 34
	v_readlane_b32 s4, v254, 53
	v_readlane_b32 s8, v252, 41
	v_readlane_b32 s5, v254, 54
	v_readlane_b32 s6, v252, 39
	v_readlane_b32 s7, v252, 40
	s_mov_b32 s8, 0x1000000
	v_readlane_b32 s6, v254, 55
	v_readlane_b32 s7, v254, 56
	v_readlane_b32 s1, v252, 34
	v_readlane_b32 s0, v254, 27
	v_readlane_b32 s1, v254, 28
	s_lshl_b64 s[68:69], s[44:45], 9
	s_lshl_b64 s[48:49], s[64:65], 9
	s_lshl_b64 s[50:51], s[42:43], 9
	s_lshl_b64 s[52:53], s[58:59], 9
	s_lshl_b64 s[46:47], s[54:55], 9
	s_lshl_b64 s[44:45], s[26:27], 9
	s_lshl_b64 s[56:57], s[28:29], 9
	v_readlane_b32 s9, v252, 42
	v_readlane_b32 s10, v252, 43
	v_readlane_b32 s11, v252, 44
	v_readlane_b32 s12, v252, 45
	v_readlane_b32 s13, v252, 46
	v_readlane_b32 s14, v252, 47
	v_readlane_b32 s15, v252, 48
	s_waitcnt vmcnt(5)
	v_add_f32_e32 v66, v66, v90
	v_mul_f32_e32 v66, 0xbfb8aa3b, v66
	v_exp_f32_e32 v66, v66
	s_waitcnt vmcnt(4)
	v_add_f32_e32 v68, v68, v89
	s_waitcnt vmcnt(1)
	v_mul_f32_e32 v108, v105, v92
	v_mul_f32_e32 v109, v108, v108
	v_mul_f32_e32 v68, 0xbfb8aa3b, v68
	v_exp_f32_e32 v68, v68
	v_mov_b32_dpp v109, v109 quad_perm:[1,0,3,2] row_mask:0xf bank_mask:0xf bound_ctrl:1
	v_fmac_f32_e32 v109, v108, v108
	v_add_f32_e32 v66, 1.0, v66
	v_rcp_f32_e32 v66, v66
	v_add_f32_dpp v109, v109, v109 quad_perm:[2,3,0,1] row_mask:0xf bank_mask:0xf bound_ctrl:1
	v_add_f32_e32 v68, 1.0, v68
	v_add_f32_e32 v64, v64, v88
	v_add_f32_dpp v109, v109, v109 row_half_mirror row_mask:0xf bank_mask:0xf bound_ctrl:1
	v_rcp_f32_e32 v68, v68
	v_mul_f32_e32 v64, 0xbfb8aa3b, v64
	v_add_f32_dpp v109, v109, v109 row_ror:8 row_mask:0xf bank_mask:0xf bound_ctrl:1
	ds_bpermute_b32 v110, v77, v109
	v_exp_f32_e32 v64, v64
	v_add_f32_e32 v70, v70, v87
	v_mul_f32_e32 v66, 0xbf1b4598, v66
	v_mul_f32_e32 v70, 0xbfb8aa3b, v70
	s_waitcnt lgkmcnt(0)
	v_add_f32_e32 v109, v109, v110
	ds_bpermute_b32 v110, v76, v109
	v_mul_f32_e32 v66, 0x3fb8aa3b, v66
	v_exp_f32_e32 v70, v70
	v_exp_f32_e32 v66, v66
	v_mul_f32_e32 v68, 0xbf1b4598, v68
	s_waitcnt lgkmcnt(0)
	v_add_f32_e32 v109, v109, v110
	v_add_f32_e32 v109, 0x2b8cbccc, v109
	v_rsq_f32_e32 v109, v109
	v_mul_f32_e32 v68, 0x3fb8aa3b, v68
	v_add_f32_e32 v64, 1.0, v64
	v_exp_f32_e32 v68, v68
	v_mul_f32_e32 v112, v108, v109
	v_lshl_add_u64 v[108:109], s[66:67], 0, v[0:1]
	v_lshlrev_b64 v[108:109], 2, v[108:109]
	v_lshl_add_u64 v[110:111], s[22:23], 0, v[108:109]
	global_store_dword v[110:111], v107, off
	v_lshl_add_u64 v[110:111], s[30:31], 0, v[108:109]
	v_rcp_f32_e32 v64, v64
	global_store_dword v[110:111], v112, off
	v_lshl_add_u64 v[110:111], s[2:3], 0, v[108:109]
	v_add_f32_e32 v70, 1.0, v70
	global_store_dword v[110:111], v106, off
	v_lshl_add_u64 v[106:107], s[4:5], 0, v[108:109]
	v_rcp_f32_e32 v70, v70
	global_store_dword v[106:107], v66, off
	v_add_co_u32_e32 v106, vcc, s8, v106
	v_mul_f32_e32 v66, v64, v112
	s_nop 0
	v_addc_co_u32_e32 v107, vcc, 0, v107, vcc
	global_store_dword v[106:107], v68, off
	v_lshl_add_u64 v[106:107], s[6:7], 0, v[108:109]
	global_store_dword v[106:107], v66, off
	v_add_co_u32_e32 v106, vcc, s8, v106
	v_add_f32_e32 v64, -1.0, v64
	v_mul_f32_e32 v66, v70, v112
	v_addc_co_u32_e32 v107, vcc, 0, v107, vcc
	s_waitcnt vmcnt(6)
	v_fma_f32 v64, v95, v64, 1.0
	global_store_dword v[106:107], v66, off
	v_mul_f32_e32 v64, v105, v64
	v_lshl_add_u64 v[106:107], s[0:1], 0, v[108:109]
	global_store_dword v[106:107], v64, off
	v_add_f32_e32 v64, -1.0, v70
	v_fma_f32 v64, v95, v64, 1.0
	v_add_co_u32_e32 v106, vcc, s8, v106
	v_mul_f32_e32 v64, v105, v64
	s_nop 0
	v_addc_co_u32_e32 v107, vcc, 0, v107, vcc
	global_store_dword v[106:107], v64, off
	v_mul_f32_e32 v64, v102, v92
	v_mul_f32_e32 v66, v64, v64
	v_add_f32_e32 v52, v52, v90
	v_mul_f32_e32 v52, 0xbfb8aa3b, v52
	v_mov_b32_dpp v66, v66 quad_perm:[1,0,3,2] row_mask:0xf bank_mask:0xf bound_ctrl:1
	v_fmac_f32_e32 v66, v64, v64
	v_exp_f32_e32 v52, v52
	v_add_f32_e32 v54, v54, v89
	v_add_f32_dpp v66, v66, v66 quad_perm:[2,3,0,1] row_mask:0xf bank_mask:0xf bound_ctrl:1
	v_mul_f32_e32 v54, 0xbfb8aa3b, v54
	v_exp_f32_e32 v54, v54
	v_add_f32_dpp v66, v66, v66 row_half_mirror row_mask:0xf bank_mask:0xf bound_ctrl:1
	v_add_f32_e32 v52, 1.0, v52
	v_rcp_f32_e32 v52, v52
	v_add_f32_dpp v66, v66, v66 row_ror:8 row_mask:0xf bank_mask:0xf bound_ctrl:1
	ds_bpermute_b32 v68, v77, v66
	v_add_f32_e32 v50, v50, v88
	v_add_f32_e32 v54, 1.0, v54
	v_mul_f32_e32 v50, 0xbfb8aa3b, v50
	v_rcp_f32_e32 v54, v54
	s_waitcnt lgkmcnt(0)
	v_add_f32_e32 v66, v66, v68
	ds_bpermute_b32 v68, v76, v66
	v_exp_f32_e32 v50, v50
	v_add_f32_e32 v56, v56, v87
	v_mul_f32_e32 v52, 0xbf1b4598, v52
	v_mul_f32_e32 v56, 0xbfb8aa3b, v56
	s_waitcnt lgkmcnt(0)
	v_add_f32_e32 v66, v66, v68
	v_add_f32_e32 v66, 0x2b8cbccc, v66
	v_rsq_f32_e32 v66, v66
	v_mul_f32_e32 v52, 0x3fb8aa3b, v52
	v_exp_f32_e32 v56, v56
	v_exp_f32_e32 v52, v52
	v_mul_f32_e32 v68, v64, v66
	v_add_f32_e32 v64, v67, v90
	v_mul_f32_e32 v64, 0xbfb8aa3b, v64
	v_exp_f32_e32 v64, v64
	v_mul_f32_e32 v54, 0xbf1b4598, v54
	v_add_f32_e32 v50, 1.0, v50
	v_mul_f32_e32 v54, 0x3fb8aa3b, v54
	v_add_f32_e32 v64, 1.0, v64
	v_rcp_f32_e32 v64, v64
	v_rcp_f32_e32 v50, v50
	v_exp_f32_e32 v54, v54
	v_add_f32_e32 v56, 1.0, v56
	v_mul_f32_e32 v64, 0xbf1b4598, v64
	v_mul_f32_e32 v64, 0x3fb8aa3b, v64
	v_exp_f32_e32 v70, v64
	v_add_f32_e32 v64, v69, v89
	v_mul_f32_e32 v64, 0xbfb8aa3b, v64
	v_exp_f32_e32 v64, v64
	v_rcp_f32_e32 v56, v56
	v_add_f32_e32 v44, v44, v90
	v_mul_f32_e32 v44, 0xbfb8aa3b, v44
	v_add_f32_e32 v64, 1.0, v64
	v_rcp_f32_e32 v64, v64
	v_exp_f32_e32 v44, v44
	v_add_f32_e32 v46, v46, v89
	v_mul_f32_e32 v46, 0xbfb8aa3b, v46
	v_mul_f32_e32 v64, 0xbf1b4598, v64
	v_mul_f32_e32 v64, 0x3fb8aa3b, v64
	v_exp_f32_e32 v69, v64
	v_add_f32_e32 v64, v65, v88
	v_mul_f32_e32 v64, 0xbfb8aa3b, v64
	v_exp_f32_e32 v64, v64
	v_exp_f32_e32 v46, v46
	v_add_f32_e32 v44, 1.0, v44
	v_rcp_f32_e32 v44, v44
	v_add_f32_e32 v64, 1.0, v64
	v_rcp_f32_e32 v105, v64
	v_add_f32_e32 v64, v71, v87
	v_mul_f32_e32 v64, 0xbfb8aa3b, v64
	v_exp_f32_e32 v64, v64
	v_add_f32_e32 v42, v42, v88
	v_add_f32_e32 v46, 1.0, v46
	v_mul_f32_e32 v42, 0xbfb8aa3b, v42
	v_add_f32_e32 v64, 1.0, v64
	v_rcp_f32_e32 v71, v64
	v_lshl_add_u64 v[64:65], s[68:69], 0, v[0:1]
	v_lshlrev_b64 v[64:65], 2, v[64:65]
	v_lshl_add_u64 v[66:67], s[22:23], 0, v[64:65]
	global_store_dword v[66:67], v104, off
	v_lshl_add_u64 v[66:67], s[30:31], 0, v[64:65]
	global_store_dword v[66:67], v68, off
	v_lshl_add_u64 v[66:67], s[2:3], 0, v[64:65]
	global_store_dword v[66:67], v103, off
	v_lshl_add_u64 v[66:67], s[4:5], 0, v[64:65]
	global_store_dword v[66:67], v70, off
	v_add_co_u32_e32 v66, vcc, s8, v66
	v_rcp_f32_e32 v46, v46
	s_nop 0
	v_addc_co_u32_e32 v67, vcc, 0, v67, vcc
	global_store_dword v[66:67], v69, off
	v_mul_f32_e32 v69, v105, v68
	v_lshl_add_u64 v[66:67], s[6:7], 0, v[64:65]
	global_store_dword v[66:67], v69, off
	v_add_co_u32_e32 v66, vcc, s8, v66
	v_mul_f32_e32 v68, v71, v68
	s_nop 0
	v_addc_co_u32_e32 v67, vcc, 0, v67, vcc
	global_store_dword v[66:67], v68, off
	v_add_f32_e32 v66, -1.0, v105
	v_fma_f32 v66, v95, v66, 1.0
	v_mul_f32_e32 v66, v102, v66
	v_lshl_add_u64 v[64:65], s[0:1], 0, v[64:65]
	global_store_dword v[64:65], v66, off
	v_add_f32_e32 v66, -1.0, v71
	v_fma_f32 v66, v95, v66, 1.0
	v_add_co_u32_e32 v64, vcc, s8, v64
	v_mul_f32_e32 v66, v102, v66
	s_nop 0
	v_addc_co_u32_e32 v65, vcc, 0, v65, vcc
	global_store_dword v[64:65], v66, off
	v_mul_f32_e32 v64, v99, v92
	v_mul_f32_e32 v65, v64, v64
	v_exp_f32_e32 v42, v42
	v_add_f32_e32 v48, v48, v87
	v_mov_b32_dpp v65, v65 quad_perm:[1,0,3,2] row_mask:0xf bank_mask:0xf bound_ctrl:1
	v_fmac_f32_e32 v65, v64, v64
	v_mul_f32_e32 v44, 0xbf1b4598, v44
	v_mul_f32_e32 v48, 0xbfb8aa3b, v48
	v_add_f32_dpp v65, v65, v65 quad_perm:[2,3,0,1] row_mask:0xf bank_mask:0xf bound_ctrl:1
	v_mul_f32_e32 v44, 0x3fb8aa3b, v44
	v_exp_f32_e32 v48, v48
	v_add_f32_dpp v65, v65, v65 row_half_mirror row_mask:0xf bank_mask:0xf bound_ctrl:1
	v_exp_f32_e32 v44, v44
	v_mul_f32_e32 v46, 0xbf1b4598, v46
	v_add_f32_dpp v65, v65, v65 row_ror:8 row_mask:0xf bank_mask:0xf bound_ctrl:1
	ds_bpermute_b32 v66, v77, v65
	v_add_f32_e32 v42, 1.0, v42
	v_mul_f32_e32 v46, 0x3fb8aa3b, v46
	v_rcp_f32_e32 v42, v42
	v_exp_f32_e32 v46, v46
	s_waitcnt lgkmcnt(0)
	v_add_f32_e32 v65, v65, v66
	ds_bpermute_b32 v66, v76, v65
	v_add_f32_e32 v48, 1.0, v48
	v_rcp_f32_e32 v48, v48
	v_add_f32_e32 v36, v36, v90
	v_mul_f32_e32 v36, 0xbfb8aa3b, v36
	s_waitcnt lgkmcnt(0)
	v_add_f32_e32 v65, v65, v66
	v_add_f32_e32 v65, 0x2b8cbccc, v65
	v_rsq_f32_e32 v65, v65
	v_exp_f32_e32 v36, v36
	v_add_f32_e32 v38, v38, v89
	v_mul_f32_e32 v38, 0xbfb8aa3b, v38
	v_mul_f32_e32 v68, v64, v65
	v_lshl_add_u64 v[64:65], s[48:49], 0, v[0:1]
	v_lshlrev_b64 v[64:65], 2, v[64:65]
	v_lshl_add_u64 v[66:67], s[22:23], 0, v[64:65]
	global_store_dword v[66:67], v100, off
	v_lshl_add_u64 v[66:67], s[30:31], 0, v[64:65]
	global_store_dword v[66:67], v68, off
	v_lshl_add_u64 v[66:67], s[2:3], 0, v[64:65]
	global_store_dword v[66:67], v101, off
	v_lshl_add_u64 v[66:67], s[4:5], 0, v[64:65]
	global_store_dword v[66:67], v52, off
	v_add_co_u32_e32 v66, vcc, s8, v66
	v_mul_f32_e32 v52, v50, v68
	s_nop 0
	v_addc_co_u32_e32 v67, vcc, 0, v67, vcc
	v_add_f32_e32 v50, -1.0, v50
	global_store_dword v[66:67], v54, off
	v_lshl_add_u64 v[66:67], s[6:7], 0, v[64:65]
	v_fma_f32 v50, v95, v50, 1.0
	global_store_dword v[66:67], v52, off
	v_add_co_u32_e32 v66, vcc, s8, v66
	v_mul_f32_e32 v50, v99, v50
	v_lshl_add_u64 v[64:65], s[0:1], 0, v[64:65]
	v_addc_co_u32_e32 v67, vcc, 0, v67, vcc
	global_store_dword v[64:65], v50, off
	v_add_f32_e32 v50, -1.0, v56
	v_fma_f32 v50, v95, v50, 1.0
	v_add_co_u32_e32 v64, vcc, s8, v64
	v_mul_f32_e32 v50, v99, v50
	s_nop 0
	v_addc_co_u32_e32 v65, vcc, 0, v65, vcc
	v_mul_f32_e32 v52, v56, v68
	global_store_dword v[64:65], v50, off
	v_mul_f32_e32 v50, v96, v92
	global_store_dword v[66:67], v52, off
	v_mul_f32_e32 v52, v50, v50
	v_exp_f32_e32 v38, v38
	v_add_f32_e32 v36, 1.0, v36
	v_mov_b32_dpp v52, v52 quad_perm:[1,0,3,2] row_mask:0xf bank_mask:0xf bound_ctrl:1
	v_fmac_f32_e32 v52, v50, v50
	v_rcp_f32_e32 v36, v36
	v_add_f32_e32 v34, v34, v88
	v_add_f32_dpp v52, v52, v52 quad_perm:[2,3,0,1] row_mask:0xf bank_mask:0xf bound_ctrl:1
	v_add_f32_e32 v38, 1.0, v38
	v_mul_f32_e32 v34, 0xbfb8aa3b, v34
	v_add_f32_dpp v52, v52, v52 row_half_mirror row_mask:0xf bank_mask:0xf bound_ctrl:1
	v_rcp_f32_e32 v38, v38
	v_exp_f32_e32 v34, v34
	v_add_f32_dpp v52, v52, v52 row_ror:8 row_mask:0xf bank_mask:0xf bound_ctrl:1
	ds_bpermute_b32 v54, v77, v52
	v_add_f32_e32 v40, v40, v87
	v_mul_f32_e32 v36, 0xbf1b4598, v36
	v_mul_f32_e32 v40, 0xbfb8aa3b, v40
	v_mul_f32_e32 v36, 0x3fb8aa3b, v36
	s_waitcnt lgkmcnt(0)
	v_add_f32_e32 v52, v52, v54
	ds_bpermute_b32 v54, v76, v52
	v_exp_f32_e32 v40, v40
	v_exp_f32_e32 v36, v36
	v_mul_f32_e32 v38, 0xbf1b4598, v38
	v_add_f32_e32 v34, 1.0, v34
	s_waitcnt lgkmcnt(0)
	v_add_f32_e32 v52, v52, v54
	v_add_f32_e32 v52, 0x2b8cbccc, v52
	v_rsq_f32_e32 v52, v52
	v_mul_f32_e32 v38, 0x3fb8aa3b, v38
	v_rcp_f32_e32 v34, v34
	v_exp_f32_e32 v38, v38
	v_mul_f32_e32 v54, v50, v52
	v_add_f32_e32 v50, v53, v90
	v_mul_f32_e32 v50, 0xbfb8aa3b, v50
	v_exp_f32_e32 v50, v50
	v_add_f32_e32 v40, 1.0, v40
	v_rcp_f32_e32 v40, v40
	v_mov_b32_e32 v69, 0
	v_add_f32_e32 v50, 1.0, v50
	v_rcp_f32_e32 v50, v50
	v_mov_b32_e32 v68, 0
	v_mul_f32_e32 v50, 0xbf1b4598, v50
	v_mul_f32_e32 v50, 0x3fb8aa3b, v50
	v_exp_f32_e32 v56, v50
	v_add_f32_e32 v50, v55, v89
	v_mul_f32_e32 v50, 0xbfb8aa3b, v50
	v_exp_f32_e32 v50, v50
	s_nop 0
	v_add_f32_e32 v50, 1.0, v50
	v_rcp_f32_e32 v50, v50
	s_nop 0
	v_mul_f32_e32 v50, 0xbf1b4598, v50
	v_mul_f32_e32 v50, 0x3fb8aa3b, v50
	v_exp_f32_e32 v55, v50
	v_add_f32_e32 v50, v51, v88
	v_mul_f32_e32 v50, 0xbfb8aa3b, v50
	v_exp_f32_e32 v50, v50
	s_nop 0
	v_add_f32_e32 v50, 1.0, v50
	v_rcp_f32_e32 v64, v50
	v_add_f32_e32 v50, v57, v87
	v_mul_f32_e32 v50, 0xbfb8aa3b, v50
	v_exp_f32_e32 v50, v50
	s_nop 0
	v_add_f32_e32 v50, 1.0, v50
	v_rcp_f32_e32 v57, v50
	v_lshl_add_u64 v[50:51], s[50:51], 0, v[0:1]
	v_lshlrev_b64 v[50:51], 2, v[50:51]
	v_lshl_add_u64 v[52:53], s[22:23], 0, v[50:51]
	global_store_dword v[52:53], v97, off
	v_lshl_add_u64 v[52:53], s[30:31], 0, v[50:51]
	global_store_dword v[52:53], v54, off
	v_lshl_add_u64 v[52:53], s[2:3], 0, v[50:51]
	global_store_dword v[52:53], v98, off
	v_lshl_add_u64 v[52:53], s[4:5], 0, v[50:51]
	global_store_dword v[52:53], v56, off
	v_add_co_u32_e32 v52, vcc, s8, v52
	s_nop 1
	v_addc_co_u32_e32 v53, vcc, 0, v53, vcc
	global_store_dword v[52:53], v55, off
	v_mul_f32_e32 v55, v64, v54
	v_lshl_add_u64 v[52:53], s[6:7], 0, v[50:51]
	global_store_dword v[52:53], v55, off
	v_add_co_u32_e32 v52, vcc, s8, v52
	v_mul_f32_e32 v54, v57, v54
	s_nop 0
	v_addc_co_u32_e32 v53, vcc, 0, v53, vcc
	global_store_dword v[52:53], v54, off
	v_add_f32_e32 v52, -1.0, v64
	v_fma_f32 v52, v95, v52, 1.0
	v_mul_f32_e32 v52, v96, v52
	v_lshl_add_u64 v[50:51], s[0:1], 0, v[50:51]
	global_store_dword v[50:51], v52, off
	v_add_f32_e32 v52, -1.0, v57
	v_fma_f32 v52, v95, v52, 1.0
	v_add_co_u32_e32 v50, vcc, s8, v50
	v_mul_f32_e32 v52, v96, v52
	s_nop 0
	v_addc_co_u32_e32 v51, vcc, 0, v51, vcc
	global_store_dword v[50:51], v52, off
	v_mul_f32_e32 v50, v91, v92
	v_mul_f32_e32 v51, v50, v50
	s_nop 1
	v_mov_b32_dpp v51, v51 quad_perm:[1,0,3,2] row_mask:0xf bank_mask:0xf bound_ctrl:1
	v_fmac_f32_e32 v51, v50, v50
	s_nop 1
	v_add_f32_dpp v51, v51, v51 quad_perm:[2,3,0,1] row_mask:0xf bank_mask:0xf bound_ctrl:1
	s_nop 1
	v_add_f32_dpp v51, v51, v51 row_half_mirror row_mask:0xf bank_mask:0xf bound_ctrl:1
	s_nop 1
	v_add_f32_dpp v51, v51, v51 row_ror:8 row_mask:0xf bank_mask:0xf bound_ctrl:1
	ds_bpermute_b32 v52, v77, v51
	s_waitcnt lgkmcnt(0)
	v_add_f32_e32 v51, v51, v52
	ds_bpermute_b32 v52, v76, v51
	s_waitcnt lgkmcnt(0)
	v_add_f32_e32 v51, v51, v52
	v_add_f32_e32 v51, 0x2b8cbccc, v51
	v_rsq_f32_e32 v51, v51
	s_nop 0
	v_mul_f32_e32 v54, v50, v51
	v_lshl_add_u64 v[50:51], s[52:53], 0, v[0:1]
	v_lshlrev_b64 v[50:51], 2, v[50:51]
	v_lshl_add_u64 v[52:53], s[22:23], 0, v[50:51]
	global_store_dword v[52:53], v93, off
	v_lshl_add_u64 v[52:53], s[30:31], 0, v[50:51]
	global_store_dword v[52:53], v54, off
	v_lshl_add_u64 v[52:53], s[2:3], 0, v[50:51]
	global_store_dword v[52:53], v94, off
	v_lshl_add_u64 v[52:53], s[4:5], 0, v[50:51]
	global_store_dword v[52:53], v44, off
	v_add_co_u32_e32 v52, vcc, s8, v52
	v_mul_f32_e32 v44, v42, v54
	s_nop 0
	v_addc_co_u32_e32 v53, vcc, 0, v53, vcc
	v_add_f32_e32 v42, -1.0, v42
	global_store_dword v[52:53], v46, off
	v_lshl_add_u64 v[52:53], s[6:7], 0, v[50:51]
	v_fma_f32 v42, v95, v42, 1.0
	global_store_dword v[52:53], v44, off
	v_add_co_u32_e32 v52, vcc, s8, v52
	v_mul_f32_e32 v42, v91, v42
	v_lshl_add_u64 v[50:51], s[0:1], 0, v[50:51]
	v_addc_co_u32_e32 v53, vcc, 0, v53, vcc
	global_store_dword v[50:51], v42, off
	v_add_f32_e32 v42, -1.0, v48
	v_fma_f32 v42, v95, v42, 1.0
	v_add_co_u32_e32 v50, vcc, s8, v50
	v_mul_f32_e32 v42, v91, v42
	s_nop 0
	v_addc_co_u32_e32 v51, vcc, 0, v51, vcc
	v_mul_f32_e32 v44, v48, v54
	global_store_dword v[50:51], v42, off
	v_mul_f32_e32 v42, v84, v92
	global_store_dword v[52:53], v44, off
	v_mul_f32_e32 v44, v42, v42
	s_nop 1
	v_mov_b32_dpp v44, v44 quad_perm:[1,0,3,2] row_mask:0xf bank_mask:0xf bound_ctrl:1
	v_fmac_f32_e32 v44, v42, v42
	s_nop 1
	v_add_f32_dpp v44, v44, v44 quad_perm:[2,3,0,1] row_mask:0xf bank_mask:0xf bound_ctrl:1
	s_nop 1
	v_add_f32_dpp v44, v44, v44 row_half_mirror row_mask:0xf bank_mask:0xf bound_ctrl:1
	s_nop 1
	v_add_f32_dpp v44, v44, v44 row_ror:8 row_mask:0xf bank_mask:0xf bound_ctrl:1
	ds_bpermute_b32 v46, v77, v44
	s_waitcnt lgkmcnt(0)
	v_add_f32_e32 v44, v44, v46
	ds_bpermute_b32 v46, v76, v44
	s_waitcnt lgkmcnt(0)
	v_add_f32_e32 v44, v44, v46
	v_add_f32_e32 v44, 0x2b8cbccc, v44
	v_rsq_f32_e32 v44, v44
	s_nop 0
	v_mul_f32_e32 v46, v42, v44
	v_add_f32_e32 v42, v45, v90
	v_mul_f32_e32 v42, 0xbfb8aa3b, v42
	v_exp_f32_e32 v42, v42
	s_nop 0
	v_add_f32_e32 v42, 1.0, v42
	v_rcp_f32_e32 v42, v42
	s_nop 0
	v_mul_f32_e32 v42, 0xbf1b4598, v42
	v_mul_f32_e32 v42, 0x3fb8aa3b, v42
	v_exp_f32_e32 v48, v42
	v_add_f32_e32 v42, v47, v89
	v_mul_f32_e32 v42, 0xbfb8aa3b, v42
	v_exp_f32_e32 v42, v42
	s_nop 0
	v_add_f32_e32 v42, 1.0, v42
	v_rcp_f32_e32 v42, v42
	s_nop 0
	v_mul_f32_e32 v42, 0xbf1b4598, v42
	v_mul_f32_e32 v42, 0x3fb8aa3b, v42
	v_exp_f32_e32 v47, v42
	v_add_f32_e32 v42, v43, v88
	v_mul_f32_e32 v42, 0xbfb8aa3b, v42
	v_exp_f32_e32 v42, v42
	s_nop 0
	v_add_f32_e32 v42, 1.0, v42
	v_rcp_f32_e32 v50, v42
	v_add_f32_e32 v42, v49, v87
	v_mul_f32_e32 v42, 0xbfb8aa3b, v42
	v_exp_f32_e32 v42, v42
	s_nop 0
	v_add_f32_e32 v42, 1.0, v42
	v_rcp_f32_e32 v49, v42
	v_lshl_add_u64 v[42:43], s[46:47], 0, v[0:1]
	v_lshlrev_b64 v[42:43], 2, v[42:43]
	v_lshl_add_u64 v[44:45], s[22:23], 0, v[42:43]
	global_store_dword v[44:45], v85, off
	v_lshl_add_u64 v[44:45], s[30:31], 0, v[42:43]
	global_store_dword v[44:45], v46, off
	v_lshl_add_u64 v[44:45], s[2:3], 0, v[42:43]
	global_store_dword v[44:45], v86, off
	v_lshl_add_u64 v[44:45], s[4:5], 0, v[42:43]
	global_store_dword v[44:45], v48, off
	v_add_co_u32_e32 v44, vcc, s8, v44
	s_nop 1
	v_addc_co_u32_e32 v45, vcc, 0, v45, vcc
	global_store_dword v[44:45], v47, off
	v_mul_f32_e32 v47, v50, v46
	v_lshl_add_u64 v[44:45], s[6:7], 0, v[42:43]
	global_store_dword v[44:45], v47, off
	v_add_co_u32_e32 v44, vcc, s8, v44
	v_mul_f32_e32 v46, v49, v46
	s_nop 0
	v_addc_co_u32_e32 v45, vcc, 0, v45, vcc
	global_store_dword v[44:45], v46, off
	v_add_f32_e32 v44, -1.0, v50
	v_fma_f32 v44, v95, v44, 1.0
	v_mul_f32_e32 v44, v84, v44
	v_lshl_add_u64 v[42:43], s[0:1], 0, v[42:43]
	global_store_dword v[42:43], v44, off
	v_add_f32_e32 v44, -1.0, v49
	v_fma_f32 v44, v95, v44, 1.0
	v_add_co_u32_e32 v42, vcc, s8, v42
	v_mul_f32_e32 v44, v84, v44
	s_nop 0
	v_addc_co_u32_e32 v43, vcc, 0, v43, vcc
	global_store_dword v[42:43], v44, off
	v_mul_f32_e32 v42, v81, v92
	v_mul_f32_e32 v43, v42, v42
	s_nop 1
	v_mov_b32_dpp v43, v43 quad_perm:[1,0,3,2] row_mask:0xf bank_mask:0xf bound_ctrl:1
	v_fmac_f32_e32 v43, v42, v42
	s_nop 1
	v_add_f32_dpp v43, v43, v43 quad_perm:[2,3,0,1] row_mask:0xf bank_mask:0xf bound_ctrl:1
	s_nop 1
	v_add_f32_dpp v43, v43, v43 row_half_mirror row_mask:0xf bank_mask:0xf bound_ctrl:1
	s_nop 1
	v_add_f32_dpp v43, v43, v43 row_ror:8 row_mask:0xf bank_mask:0xf bound_ctrl:1
	ds_bpermute_b32 v44, v77, v43
	s_waitcnt lgkmcnt(0)
	v_add_f32_e32 v43, v43, v44
	ds_bpermute_b32 v44, v76, v43
	s_waitcnt lgkmcnt(0)
	v_add_f32_e32 v43, v43, v44
	v_add_f32_e32 v43, 0x2b8cbccc, v43
	v_rsq_f32_e32 v43, v43
	s_nop 0
	v_mul_f32_e32 v46, v42, v43
	v_lshl_add_u64 v[42:43], s[44:45], 0, v[0:1]
	v_lshlrev_b64 v[42:43], 2, v[42:43]
	v_lshl_add_u64 v[44:45], s[22:23], 0, v[42:43]
	global_store_dword v[44:45], v82, off
	v_lshl_add_u64 v[44:45], s[30:31], 0, v[42:43]
	global_store_dword v[44:45], v46, off
	v_lshl_add_u64 v[44:45], s[2:3], 0, v[42:43]
	global_store_dword v[44:45], v83, off
	v_lshl_add_u64 v[44:45], s[4:5], 0, v[42:43]
	global_store_dword v[44:45], v36, off
	v_add_co_u32_e32 v44, vcc, s8, v44
	v_mul_f32_e32 v36, v34, v46
	s_nop 0
	v_addc_co_u32_e32 v45, vcc, 0, v45, vcc
	v_add_f32_e32 v34, -1.0, v34
	global_store_dword v[44:45], v38, off
	v_lshl_add_u64 v[44:45], s[6:7], 0, v[42:43]
	v_fma_f32 v34, v95, v34, 1.0
	global_store_dword v[44:45], v36, off
	v_add_co_u32_e32 v44, vcc, s8, v44
	v_mul_f32_e32 v34, v81, v34
	v_lshl_add_u64 v[42:43], s[0:1], 0, v[42:43]
	v_addc_co_u32_e32 v45, vcc, 0, v45, vcc
	global_store_dword v[42:43], v34, off
	v_add_f32_e32 v34, -1.0, v40
	v_fma_f32 v34, v95, v34, 1.0
	v_add_co_u32_e32 v42, vcc, s8, v42
	v_mul_f32_e32 v34, v81, v34
	s_nop 0
	v_addc_co_u32_e32 v43, vcc, 0, v43, vcc
	v_mul_f32_e32 v36, v40, v46
	global_store_dword v[42:43], v34, off
	v_mul_f32_e32 v34, v78, v92
	global_store_dword v[44:45], v36, off
	v_mul_f32_e32 v36, v34, v34
	s_nop 1
	v_mov_b32_dpp v36, v36 quad_perm:[1,0,3,2] row_mask:0xf bank_mask:0xf bound_ctrl:1
	v_fmac_f32_e32 v36, v34, v34
	s_nop 1
	v_add_f32_dpp v36, v36, v36 quad_perm:[2,3,0,1] row_mask:0xf bank_mask:0xf bound_ctrl:1
	s_nop 1
	v_add_f32_dpp v36, v36, v36 row_half_mirror row_mask:0xf bank_mask:0xf bound_ctrl:1
	s_nop 1
	v_add_f32_dpp v36, v36, v36 row_ror:8 row_mask:0xf bank_mask:0xf bound_ctrl:1
	ds_bpermute_b32 v38, v77, v36
	s_waitcnt lgkmcnt(0)
	v_add_f32_e32 v36, v36, v38
	ds_bpermute_b32 v38, v76, v36
	s_waitcnt lgkmcnt(0)
	v_add_f32_e32 v36, v36, v38
	v_add_f32_e32 v36, 0x2b8cbccc, v36
	v_rsq_f32_e32 v36, v36
	s_nop 0
	v_mul_f32_e32 v38, v34, v36
	v_add_f32_e32 v34, v37, v90
	v_mul_f32_e32 v34, 0xbfb8aa3b, v34
	v_exp_f32_e32 v34, v34
	s_nop 0
	v_add_f32_e32 v34, 1.0, v34
	v_rcp_f32_e32 v34, v34
	s_nop 0
	v_mul_f32_e32 v34, 0xbf1b4598, v34
	v_mul_f32_e32 v34, 0x3fb8aa3b, v34
	v_exp_f32_e32 v40, v34
	v_add_f32_e32 v34, v39, v89
	v_mul_f32_e32 v34, 0xbfb8aa3b, v34
	v_exp_f32_e32 v34, v34
	s_nop 0
	v_add_f32_e32 v34, 1.0, v34
	v_rcp_f32_e32 v34, v34
	s_nop 0
	v_mul_f32_e32 v34, 0xbf1b4598, v34
	v_mul_f32_e32 v34, 0x3fb8aa3b, v34
	v_exp_f32_e32 v39, v34
	v_add_f32_e32 v34, v35, v88
	v_mul_f32_e32 v34, 0xbfb8aa3b, v34
	v_exp_f32_e32 v34, v34
	s_nop 0
	v_add_f32_e32 v34, 1.0, v34
	v_rcp_f32_e32 v42, v34
	v_add_f32_e32 v34, v41, v87
	v_mul_f32_e32 v34, 0xbfb8aa3b, v34
	v_exp_f32_e32 v34, v34
	s_nop 0
	v_add_f32_e32 v34, 1.0, v34
	v_rcp_f32_e32 v41, v34
	v_lshl_add_u64 v[34:35], s[56:57], 0, v[0:1]
	v_lshlrev_b64 v[34:35], 2, v[34:35]
	v_lshl_add_u64 v[36:37], s[22:23], 0, v[34:35]
	global_store_dword v[36:37], v79, off
	v_lshl_add_u64 v[36:37], s[30:31], 0, v[34:35]
	global_store_dword v[36:37], v38, off
	v_lshl_add_u64 v[36:37], s[2:3], 0, v[34:35]
	global_store_dword v[36:37], v80, off
	v_lshl_add_u64 v[36:37], s[4:5], 0, v[34:35]
	global_store_dword v[36:37], v40, off
	v_add_co_u32_e32 v36, vcc, s8, v36
	s_nop 1
	v_addc_co_u32_e32 v37, vcc, 0, v37, vcc
	global_store_dword v[36:37], v39, off
	v_mul_f32_e32 v39, v42, v38
	v_lshl_add_u64 v[36:37], s[6:7], 0, v[34:35]
	global_store_dword v[36:37], v39, off
	v_add_co_u32_e32 v36, vcc, s8, v36
	v_mul_f32_e32 v38, v41, v38
	s_nop 0
	v_addc_co_u32_e32 v37, vcc, 0, v37, vcc
	global_store_dword v[36:37], v38, off
	v_add_f32_e32 v36, -1.0, v42
	v_fma_f32 v36, v95, v36, 1.0
	v_mul_f32_e32 v36, v78, v36
	v_lshl_add_u64 v[34:35], s[0:1], 0, v[34:35]
	global_store_dword v[34:35], v36, off
	v_add_f32_e32 v36, -1.0, v41
	v_fma_f32 v36, v95, v36, 1.0
	v_add_co_u32_e32 v34, vcc, 0x1000000, v34
	v_mul_f32_e32 v36, v78, v36
	s_nop 0
	v_addc_co_u32_e32 v35, vcc, 0, v35, vcc
	v_readlane_b32 s0, v254, 63
	global_store_dword v[34:35], v36, off
	v_lshl_add_u64 v[36:37], v[0:1], 1, v[238:239]
	v_readlane_b32 s1, v255, 0
	v_add_co_u32_e32 v38, vcc, 0x1000, v58
	s_nop 0
	v_lshl_add_u64 v[34:35], s[0:1], 0, v[36:37]
	v_addc_co_u32_e32 v39, vcc, 0, v59, vcc
	v_lshl_add_u64 v[36:37], s[40:41], 0, v[36:37]
	global_load_dword v40, v[58:59], off offset:1024
	global_load_dword v41, v[58:59], off offset:3072
	global_load_dword v50, v[38:39], off offset:1024
	global_load_ushort v51, v[36:37], off
	s_and_b64 vcc, exec, s[36:37]
	v_mov_b32_e32 v196, 0
	s_cbranch_vccnz .LBB0_253
	s_add_i32 s0, s60, -1
	v_mad_i64_i32 v[36:37], s[0:1], s0, v214, v[34:35]
	global_load_ushort v196, v[36:37], off
.LBB0_253:
	v_lshl_add_u64 v[36:37], v[0:1], 1, v[240:241]
	v_lshl_add_u64 v[38:39], v[34:35], 0, s[62:63]
	v_lshl_add_u64 v[44:45], s[40:41], 0, v[36:37]
	global_load_ushort v43, v[38:39], off
	global_load_ushort v65, v[44:45], off
	v_readlane_b32 s0, v254, 63
	v_readlane_b32 s1, v255, 0
	s_and_b64 vcc, exec, s[36:37]
	s_nop 0
	v_lshl_add_u64 v[36:37], s[0:1], 0, v[36:37]
	v_mov_b32_e32 v197, 0
	s_cbranch_vccnz .LBB0_255
	s_add_i32 s0, s60, -1
	v_mad_i64_i32 v[38:39], s[0:1], s0, v214, v[36:37]
	global_load_ushort v197, v[38:39], off
.LBB0_255:
	v_lshl_add_u64 v[38:39], v[0:1], 1, v[242:243]
	v_lshl_add_u64 v[44:45], v[36:37], 0, s[62:63]
	v_lshl_add_u64 v[46:47], s[40:41], 0, v[38:39]
	global_load_ushort v57, v[44:45], off
	global_load_ushort v66, v[46:47], off
	v_readlane_b32 s0, v254, 63
	v_readlane_b32 s1, v255, 0
	v_mov_b32_e32 v67, 0
	s_and_b64 vcc, exec, s[36:37]
	v_lshl_add_u64 v[38:39], s[0:1], 0, v[38:39]
	v_mov_b32_e32 v70, 0
	v_mov_b32_e32 v200, 0
	s_cbranch_vccnz .LBB0_257
	s_add_i32 s0, s60, -1
	v_mad_i64_i32 v[44:45], s[0:1], s0, v214, v[38:39]
	global_load_ushort v200, v[44:45], off
.LBB0_257:
	s_mul_hi_i32 s1, s28, 0x4a00
	s_mul_i32 s0, s28, 0x4a00
	s_mul_hi_i32 s37, s64, 0x4a00
	s_mul_i32 s36, s64, 0x4a00
	v_lshl_add_u64 v[44:45], v[38:39], 0, s[62:63]
	v_lshl_add_u64 v[82:83], v[38:39], 0, s[0:1]
	global_load_ushort v58, v[44:45], off
	s_mul_hi_i32 s41, s42, 0x4a00
	global_load_ushort v82, v[82:83], off
	v_lshl_add_u64 v[44:45], v[34:35], 0, s[36:37]
	global_load_ushort v59, v[44:45], off
	v_lshl_add_u64 v[44:45], v[36:37], 0, s[36:37]
	s_mul_i32 s40, s42, 0x4a00
	global_load_ushort v55, v[44:45], off
	v_lshl_add_u64 v[44:45], v[38:39], 0, s[36:37]
	global_load_ushort v56, v[44:45], off
	v_lshl_add_u64 v[44:45], v[34:35], 0, s[40:41]
	global_load_ushort v54, v[44:45], off
	v_lshl_add_u64 v[44:45], v[36:37], 0, s[40:41]
	s_mul_hi_i32 s43, s58, 0x4a00
	s_mul_i32 s42, s58, 0x4a00
	global_load_ushort v52, v[44:45], off
	v_lshl_add_u64 v[44:45], v[38:39], 0, s[40:41]
	global_load_ushort v53, v[44:45], off
	v_lshl_add_u64 v[44:45], v[34:35], 0, s[42:43]
	global_load_ushort v49, v[44:45], off
	v_lshl_add_u64 v[44:45], v[36:37], 0, s[42:43]
	s_mul_hi_i32 s55, s54, 0x4a00
	s_mulk_i32 s54, 0x4a00
	global_load_ushort v47, v[44:45], off
	v_lshl_add_u64 v[44:45], v[38:39], 0, s[42:43]
	global_load_ushort v48, v[44:45], off
	v_lshl_add_u64 v[44:45], v[34:35], 0, s[54:55]
	s_mul_hi_i32 s27, s26, 0x4a00
	s_mulk_i32 s26, 0x4a00
	global_load_ushort v46, v[44:45], off
	v_lshl_add_u64 v[44:45], v[36:37], 0, s[54:55]
	v_lshl_add_u64 v[78:79], v[38:39], 0, s[54:55]
	global_load_ushort v44, v[44:45], off
	v_lshl_add_u64 v[80:81], v[34:35], 0, s[0:1]
	global_load_ushort v45, v[78:79], off
	v_lshl_add_u64 v[78:79], v[34:35], 0, s[26:27]
	global_load_ushort v42, v[78:79], off
	v_lshl_add_u64 v[78:79], v[36:37], 0, s[26:27]
	global_load_ushort v64, v[78:79], off
	v_lshl_add_u64 v[78:79], v[38:39], 0, s[26:27]
	global_load_ushort v78, v[78:79], off
	s_and_b64 vcc, exec, s[38:39]
	global_load_ushort v79, v[80:81], off
	v_lshl_add_u64 v[80:81], v[36:37], 0, s[0:1]
	global_load_ushort v80, v[80:81], off
	v_mov_b32_e32 v201, 0
	s_cbranch_vccnz .LBB0_259
	s_add_i32 s0, s60, 8
	v_mad_i64_i32 v[34:35], s[0:1], s0, v214, v[34:35]
	global_load_ushort v201, v[34:35], off
.LBB0_259:
	v_mov_b32_e32 v71, 0
	s_and_b64 vcc, exec, s[38:39]
	v_mov_b32_e32 v81, 0
	v_mov_b32_e32 v202, 0
	s_cbranch_vccnz .LBB0_261
	s_add_i32 s0, s60, 8
	v_mad_i64_i32 v[34:35], s[0:1], s0, v214, v[36:37]
	global_load_ushort v202, v[34:35], off

.LBB0_274:
	v_readlane_b32 s0, v254, 13
	v_readlane_b32 s1, v254, 14
	s_andn2_b64 vcc, exec, s[0:1]
	s_cbranch_vccnz .LBB0_365
	v_and_b32_e32 v150, 63, v128
	v_lshrrev_b32_e32 v151, 6, v128
	v_lshrrev_b32_e32 v152, 3, v150
	v_readfirstlane_b32 s0, v151
	v_and_b32_e32 v153, 7, v150
	v_xor_b32_e32 v153, v153, v152
	v_lshlrev_b32_e32 v153, 4, v153
	v_lshl_add_u32 v153, v152, 11, v153
	s_lshl_b32 s1, s0, 16
	v_add_u32_e32 v132, s1, v153
	v_add_u32_e32 v133, 0x3c00, v132
	v_add_u32_e32 v134, 0x7800, v132
	v_add_u32_e32 v135, 0xb400, v132
	s_lshl_b32 s1, s0, 12
	s_add_u32 s5, s1, 0
	s_add_u32 s6, s1, 16384
	s_add_u32 s7, s1, 45056
	s_add_u32 s8, s1, 61440
	v_and_b32_e32 v152, 15, v150
	v_lshrrev_b32_e32 v153, 4, v150
	v_and_b32_e32 v154, 7, v152
	v_xor_b32_e32 v154, v154, v153
	v_lshlrev_b32_e32 v154, 4, v154
	v_lshl_add_u32 v154, v152, 7, v154
	s_lshr_b32 s1, s0, 1
	s_lshl_b32 s1, s1, 13
	v_add_u32_e32 v136, s1, v154
	v_xor_b32_e32 v137, 64, v136
	v_add_u32_e32 v138, 0xb000, v136
	v_add_u32_e32 v139, 0xb000, v137
	s_and_b32 s1, s0, 1
	s_lshl_b32 s1, s1, 13
	s_add_u32 s1, s1, 16384
	v_add_u32_e32 v140, s1, v154
	v_xor_b32_e32 v141, 64, v140
	v_add_u32_e32 v142, 0xb000, v140
	v_add_u32_e32 v143, 0xb000, v141
	s_and_b32 s1, s0, 1
	s_lshl_b32 s1, s1, 6
	v_add_u32_e32 v152, s1, v152
	v_lshlrev_b32_e32 v152, 12, v152
	v_lshlrev_b32_e32 v153, 4, v153
	s_lshr_b32 s1, s0, 1
	s_lshl_b32 s1, s1, 8
	v_add_u32_e32 v154, s1, v153
	v_add_u32_e32 v146, v152, v154
	v_add_u32_e32 v147, 0x10000, v146
	v_add_u32_e32 v148, 0x20000, v146
	v_add_u32_e32 v149, 0x30000, v146
	v_mov_b32_e32 v155, v154
	v_readlane_b32 s25, v252, 0
	s_and_b32 s0, s25, 63
	s_lshr_b32 s1, s25, 6
	s_lshl_b32 s4, s70, 21
	s_lshl_b32 s39, s1, 18
	s_add_u32 s4, s4, s39
	s_add_u32 s4, s4, 0x5600000
	s_add_u32 s26, s96, s4
	s_addc_u32 s27, s97, 0
	s_lshl_b32 s4, s0, 18
	s_add_u32 s4, s4, 0x82a6100
	s_add_u32 s28, s96, s4
	s_addc_u32 s29, s97, 0
	s_mov_b32 m0, s5
	s_nop 0
	global_load_lds_dwordx4 v132, s[26:27] offset:0
	global_load_lds_dwordx4 v133, s[26:27] offset:1024
	global_load_lds_dwordx4 v134, s[26:27] offset:2048
	global_load_lds_dwordx4 v135, s[26:27] offset:3072
	s_mov_b32 m0, s6
	s_nop 0
	global_load_lds_dwordx4 v132, s[28:29] offset:0
	global_load_lds_dwordx4 v133, s[28:29] offset:1024
	global_load_lds_dwordx4 v134, s[28:29] offset:2048
	global_load_lds_dwordx4 v135, s[28:29] offset:3072
	s_waitcnt vmcnt(0)
.Lgout_tile:
	s_waitcnt vmcnt(0)
	s_barrier
	s_add_u32 s26, s26, 0x80
	s_addc_u32 s27, s27, 0
	s_add_u32 s28, s28, 0x80
	s_addc_u32 s29, s29, 0
	s_mov_b32 m0, s7
	s_nop 0
	global_load_lds_dwordx4 v132, s[26:27] offset:0
	global_load_lds_dwordx4 v133, s[26:27] offset:1024
	global_load_lds_dwordx4 v134, s[26:27] offset:2048
	global_load_lds_dwordx4 v135, s[26:27] offset:3072
	s_mov_b32 m0, s8
	s_nop 0
	global_load_lds_dwordx4 v132, s[28:29] offset:0
	global_load_lds_dwordx4 v133, s[28:29] offset:1024
	global_load_lds_dwordx4 v134, s[28:29] offset:2048
	global_load_lds_dwordx4 v135, s[28:29] offset:3072
	ds_read_b128 v[64:67], v136 offset:0
	ds_read_b128 v[96:99], v140 offset:0
	ds_read_b128 v[100:103], v140 offset:2048
	ds_read_b128 v[104:107], v140 offset:4096
	ds_read_b128 v[108:111], v140 offset:6144
	ds_read_b128 v[68:71], v136 offset:2048
	ds_read_b128 v[72:75], v136 offset:4096
	ds_read_b128 v[76:79], v136 offset:6144
	s_waitcnt lgkmcnt(3)
	v_mfma_f32_16x16x32_bf16 v[0:3], v[64:67], v[96:99], 0
	v_mfma_f32_16x16x32_bf16 v[4:7], v[64:67], v[100:103], 0
	ds_read_b128 v[80:83], v137 offset:0
	v_mfma_f32_16x16x32_bf16 v[8:11], v[64:67], v[104:107], 0
	v_mfma_f32_16x16x32_bf16 v[12:15], v[64:67], v[108:111], 0
	ds_read_b128 v[112:115], v141 offset:0
	s_waitcnt lgkmcnt(4)
	v_mfma_f32_16x16x32_bf16 v[16:19], v[68:71], v[96:99], 0
	v_mfma_f32_16x16x32_bf16 v[20:23], v[68:71], v[100:103], 0
	ds_read_b128 v[116:119], v141 offset:2048
	v_mfma_f32_16x16x32_bf16 v[24:27], v[68:71], v[104:107], 0
	v_mfma_f32_16x16x32_bf16 v[28:31], v[68:71], v[108:111], 0
	ds_read_b128 v[120:123], v141 offset:4096
	s_waitcnt lgkmcnt(5)
	v_mfma_f32_16x16x32_bf16 v[32:35], v[72:75], v[96:99], 0
	v_mfma_f32_16x16x32_bf16 v[36:39], v[72:75], v[100:103], 0
	ds_read_b128 v[124:127], v141 offset:6144
	v_mfma_f32_16x16x32_bf16 v[40:43], v[72:75], v[104:107], 0
	v_mfma_f32_16x16x32_bf16 v[44:47], v[72:75], v[108:111], 0
	ds_read_b128 v[84:87], v137 offset:2048
	s_waitcnt lgkmcnt(6)
	v_mfma_f32_16x16x32_bf16 v[48:51], v[76:79], v[96:99], 0
	v_mfma_f32_16x16x32_bf16 v[52:55], v[76:79], v[100:103], 0
	ds_read_b128 v[88:91], v137 offset:4096
	v_mfma_f32_16x16x32_bf16 v[56:59], v[76:79], v[104:107], 0
	v_mfma_f32_16x16x32_bf16 v[60:63], v[76:79], v[108:111], 0
	ds_read_b128 v[92:95], v137 offset:6144
	s_waitcnt lgkmcnt(3)
	v_mfma_f32_16x16x32_bf16 v[0:3], v[80:83], v[112:115], v[0:3]
	v_mfma_f32_16x16x32_bf16 v[4:7], v[80:83], v[116:119], v[4:7]
	v_mfma_f32_16x16x32_bf16 v[8:11], v[80:83], v[120:123], v[8:11]
	v_mfma_f32_16x16x32_bf16 v[12:15], v[80:83], v[124:127], v[12:15]
	s_waitcnt lgkmcnt(2)
	v_mfma_f32_16x16x32_bf16 v[16:19], v[84:87], v[112:115], v[16:19]
	v_mfma_f32_16x16x32_bf16 v[20:23], v[84:87], v[116:119], v[20:23]
	v_mfma_f32_16x16x32_bf16 v[24:27], v[84:87], v[120:123], v[24:27]
	v_mfma_f32_16x16x32_bf16 v[28:31], v[84:87], v[124:127], v[28:31]
	s_waitcnt lgkmcnt(1)
	v_mfma_f32_16x16x32_bf16 v[32:35], v[88:91], v[112:115], v[32:35]
	v_mfma_f32_16x16x32_bf16 v[36:39], v[88:91], v[116:119], v[36:39]
	v_mfma_f32_16x16x32_bf16 v[40:43], v[88:91], v[120:123], v[40:43]
	v_mfma_f32_16x16x32_bf16 v[44:47], v[88:91], v[124:127], v[44:47]
	s_waitcnt lgkmcnt(0)
	v_mfma_f32_16x16x32_bf16 v[48:51], v[92:95], v[112:115], v[48:51]
	v_mfma_f32_16x16x32_bf16 v[52:55], v[92:95], v[116:119], v[52:55]
	v_mfma_f32_16x16x32_bf16 v[56:59], v[92:95], v[120:123], v[56:59]
	v_mfma_f32_16x16x32_bf16 v[60:63], v[92:95], v[124:127], v[60:63]
	s_waitcnt vmcnt(0)
	s_barrier
	s_add_u32 s26, s26, 0x80
	s_addc_u32 s27, s27, 0
	s_add_u32 s28, s28, 0x80
	s_addc_u32 s29, s29, 0
	s_mov_b32 m0, s5
	s_nop 0
	global_load_lds_dwordx4 v132, s[26:27] offset:0
	global_load_lds_dwordx4 v133, s[26:27] offset:1024
	global_load_lds_dwordx4 v134, s[26:27] offset:2048
	global_load_lds_dwordx4 v135, s[26:27] offset:3072
	s_mov_b32 m0, s6
	s_nop 0
	global_load_lds_dwordx4 v132, s[28:29] offset:0
	global_load_lds_dwordx4 v133, s[28:29] offset:1024
	global_load_lds_dwordx4 v134, s[28:29] offset:2048
	global_load_lds_dwordx4 v135, s[28:29] offset:3072
	ds_read_b128 v[64:67], v138 offset:0
	ds_read_b128 v[96:99], v142 offset:0
	ds_read_b128 v[100:103], v142 offset:2048
	ds_read_b128 v[104:107], v142 offset:4096
	ds_read_b128 v[108:111], v142 offset:6144
	ds_read_b128 v[68:71], v138 offset:2048
	ds_read_b128 v[72:75], v138 offset:4096
	ds_read_b128 v[76:79], v138 offset:6144
	s_waitcnt lgkmcnt(3)
	v_mfma_f32_16x16x32_bf16 v[0:3], v[64:67], v[96:99], v[0:3]
	v_mfma_f32_16x16x32_bf16 v[4:7], v[64:67], v[100:103], v[4:7]
	ds_read_b128 v[80:83], v139 offset:0
	v_mfma_f32_16x16x32_bf16 v[8:11], v[64:67], v[104:107], v[8:11]
	v_mfma_f32_16x16x32_bf16 v[12:15], v[64:67], v[108:111], v[12:15]
	ds_read_b128 v[112:115], v143 offset:0
	s_waitcnt lgkmcnt(4)
	v_mfma_f32_16x16x32_bf16 v[16:19], v[68:71], v[96:99], v[16:19]
	v_mfma_f32_16x16x32_bf16 v[20:23], v[68:71], v[100:103], v[20:23]
	ds_read_b128 v[116:119], v143 offset:2048
	v_mfma_f32_16x16x32_bf16 v[24:27], v[68:71], v[104:107], v[24:27]
	v_mfma_f32_16x16x32_bf16 v[28:31], v[68:71], v[108:111], v[28:31]
	ds_read_b128 v[120:123], v143 offset:4096
	s_waitcnt lgkmcnt(5)
	v_mfma_f32_16x16x32_bf16 v[32:35], v[72:75], v[96:99], v[32:35]
	v_mfma_f32_16x16x32_bf16 v[36:39], v[72:75], v[100:103], v[36:39]
	ds_read_b128 v[124:127], v143 offset:6144
	v_mfma_f32_16x16x32_bf16 v[40:43], v[72:75], v[104:107], v[40:43]
	v_mfma_f32_16x16x32_bf16 v[44:47], v[72:75], v[108:111], v[44:47]
	ds_read_b128 v[84:87], v139 offset:2048
	s_waitcnt lgkmcnt(6)
	v_mfma_f32_16x16x32_bf16 v[48:51], v[76:79], v[96:99], v[48:51]
	v_mfma_f32_16x16x32_bf16 v[52:55], v[76:79], v[100:103], v[52:55]
	ds_read_b128 v[88:91], v139 offset:4096
	v_mfma_f32_16x16x32_bf16 v[56:59], v[76:79], v[104:107], v[56:59]
	v_mfma_f32_16x16x32_bf16 v[60:63], v[76:79], v[108:111], v[60:63]
	ds_read_b128 v[92:95], v139 offset:6144
	s_waitcnt lgkmcnt(3)
	v_mfma_f32_16x16x32_bf16 v[0:3], v[80:83], v[112:115], v[0:3]
	v_mfma_f32_16x16x32_bf16 v[4:7], v[80:83], v[116:119], v[4:7]
	v_mfma_f32_16x16x32_bf16 v[8:11], v[80:83], v[120:123], v[8:11]
	v_mfma_f32_16x16x32_bf16 v[12:15], v[80:83], v[124:127], v[12:15]
	s_waitcnt lgkmcnt(2)
	v_mfma_f32_16x16x32_bf16 v[16:19], v[84:87], v[112:115], v[16:19]
	v_mfma_f32_16x16x32_bf16 v[20:23], v[84:87], v[116:119], v[20:23]
	v_mfma_f32_16x16x32_bf16 v[24:27], v[84:87], v[120:123], v[24:27]
	v_mfma_f32_16x16x32_bf16 v[28:31], v[84:87], v[124:127], v[28:31]
	s_waitcnt lgkmcnt(1)
	v_mfma_f32_16x16x32_bf16 v[32:35], v[88:91], v[112:115], v[32:35]
	v_mfma_f32_16x16x32_bf16 v[36:39], v[88:91], v[116:119], v[36:39]
	v_mfma_f32_16x16x32_bf16 v[40:43], v[88:91], v[120:123], v[40:43]
	v_mfma_f32_16x16x32_bf16 v[44:47], v[88:91], v[124:127], v[44:47]
	s_waitcnt lgkmcnt(0)
	v_mfma_f32_16x16x32_bf16 v[48:51], v[92:95], v[112:115], v[48:51]
	v_mfma_f32_16x16x32_bf16 v[52:55], v[92:95], v[116:119], v[52:55]
	v_mfma_f32_16x16x32_bf16 v[56:59], v[92:95], v[120:123], v[56:59]
	v_mfma_f32_16x16x32_bf16 v[60:63], v[92:95], v[124:127], v[60:63]
	s_waitcnt vmcnt(0)
	s_barrier
	s_add_u32 s26, s26, 0x80
	s_addc_u32 s27, s27, 0
	s_add_u32 s28, s28, 0x80
	s_addc_u32 s29, s29, 0
	s_mov_b32 m0, s7
	s_nop 0
	global_load_lds_dwordx4 v132, s[26:27] offset:0
	global_load_lds_dwordx4 v133, s[26:27] offset:1024
	global_load_lds_dwordx4 v134, s[26:27] offset:2048
	global_load_lds_dwordx4 v135, s[26:27] offset:3072
	s_mov_b32 m0, s8
	s_nop 0
	global_load_lds_dwordx4 v132, s[28:29] offset:0
	global_load_lds_dwordx4 v133, s[28:29] offset:1024
	global_load_lds_dwordx4 v134, s[28:29] offset:2048
	global_load_lds_dwordx4 v135, s[28:29] offset:3072
	ds_read_b128 v[64:67], v136 offset:0
	ds_read_b128 v[96:99], v140 offset:0
	ds_read_b128 v[100:103], v140 offset:2048
	ds_read_b128 v[104:107], v140 offset:4096
	ds_read_b128 v[108:111], v140 offset:6144
	ds_read_b128 v[68:71], v136 offset:2048
	ds_read_b128 v[72:75], v136 offset:4096
	ds_read_b128 v[76:79], v136 offset:6144
	s_waitcnt lgkmcnt(3)
	v_mfma_f32_16x16x32_bf16 v[0:3], v[64:67], v[96:99], v[0:3]
	v_mfma_f32_16x16x32_bf16 v[4:7], v[64:67], v[100:103], v[4:7]
	ds_read_b128 v[80:83], v137 offset:0
	v_mfma_f32_16x16x32_bf16 v[8:11], v[64:67], v[104:107], v[8:11]
	v_mfma_f32_16x16x32_bf16 v[12:15], v[64:67], v[108:111], v[12:15]
	ds_read_b128 v[112:115], v141 offset:0
	s_waitcnt lgkmcnt(4)
	v_mfma_f32_16x16x32_bf16 v[16:19], v[68:71], v[96:99], v[16:19]
	v_mfma_f32_16x16x32_bf16 v[20:23], v[68:71], v[100:103], v[20:23]
	ds_read_b128 v[116:119], v141 offset:2048
	v_mfma_f32_16x16x32_bf16 v[24:27], v[68:71], v[104:107], v[24:27]
	v_mfma_f32_16x16x32_bf16 v[28:31], v[68:71], v[108:111], v[28:31]
	ds_read_b128 v[120:123], v141 offset:4096
	s_waitcnt lgkmcnt(5)
	v_mfma_f32_16x16x32_bf16 v[32:35], v[72:75], v[96:99], v[32:35]
	v_mfma_f32_16x16x32_bf16 v[36:39], v[72:75], v[100:103], v[36:39]
	ds_read_b128 v[124:127], v141 offset:6144
	v_mfma_f32_16x16x32_bf16 v[40:43], v[72:75], v[104:107], v[40:43]
	v_mfma_f32_16x16x32_bf16 v[44:47], v[72:75], v[108:111], v[44:47]
	ds_read_b128 v[84:87], v137 offset:2048
	s_waitcnt lgkmcnt(6)
	v_mfma_f32_16x16x32_bf16 v[48:51], v[76:79], v[96:99], v[48:51]
	v_mfma_f32_16x16x32_bf16 v[52:55], v[76:79], v[100:103], v[52:55]
	ds_read_b128 v[88:91], v137 offset:4096
	v_mfma_f32_16x16x32_bf16 v[56:59], v[76:79], v[104:107], v[56:59]
	v_mfma_f32_16x16x32_bf16 v[60:63], v[76:79], v[108:111], v[60:63]
	ds_read_b128 v[92:95], v137 offset:6144
	s_waitcnt lgkmcnt(3)
	v_mfma_f32_16x16x32_bf16 v[0:3], v[80:83], v[112:115], v[0:3]
	v_mfma_f32_16x16x32_bf16 v[4:7], v[80:83], v[116:119], v[4:7]
	v_mfma_f32_16x16x32_bf16 v[8:11], v[80:83], v[120:123], v[8:11]
	v_mfma_f32_16x16x32_bf16 v[12:15], v[80:83], v[124:127], v[12:15]
	s_waitcnt lgkmcnt(2)
	v_mfma_f32_16x16x32_bf16 v[16:19], v[84:87], v[112:115], v[16:19]
	v_mfma_f32_16x16x32_bf16 v[20:23], v[84:87], v[116:119], v[20:23]
	v_mfma_f32_16x16x32_bf16 v[24:27], v[84:87], v[120:123], v[24:27]
	v_mfma_f32_16x16x32_bf16 v[28:31], v[84:87], v[124:127], v[28:31]
	s_waitcnt lgkmcnt(1)
	v_mfma_f32_16x16x32_bf16 v[32:35], v[88:91], v[112:115], v[32:35]
	v_mfma_f32_16x16x32_bf16 v[36:39], v[88:91], v[116:119], v[36:39]
	v_mfma_f32_16x16x32_bf16 v[40:43], v[88:91], v[120:123], v[40:43]
	v_mfma_f32_16x16x32_bf16 v[44:47], v[88:91], v[124:127], v[44:47]
	s_waitcnt lgkmcnt(0)
	v_mfma_f32_16x16x32_bf16 v[48:51], v[92:95], v[112:115], v[48:51]
	v_mfma_f32_16x16x32_bf16 v[52:55], v[92:95], v[116:119], v[52:55]
	v_mfma_f32_16x16x32_bf16 v[56:59], v[92:95], v[120:123], v[56:59]
	v_mfma_f32_16x16x32_bf16 v[60:63], v[92:95], v[124:127], v[60:63]
	s_waitcnt vmcnt(0)
	s_barrier
	s_add_u32 s26, s26, 0x80
	s_addc_u32 s27, s27, 0
	s_add_u32 s28, s28, 0x80
	s_addc_u32 s29, s29, 0
	s_mov_b32 m0, s5
	s_nop 0
	global_load_lds_dwordx4 v132, s[26:27] offset:0
	global_load_lds_dwordx4 v133, s[26:27] offset:1024
	global_load_lds_dwordx4 v134, s[26:27] offset:2048
	global_load_lds_dwordx4 v135, s[26:27] offset:3072
	s_mov_b32 m0, s6
	s_nop 0
	global_load_lds_dwordx4 v132, s[28:29] offset:0
	global_load_lds_dwordx4 v133, s[28:29] offset:1024
	global_load_lds_dwordx4 v134, s[28:29] offset:2048
	global_load_lds_dwordx4 v135, s[28:29] offset:3072
	ds_read_b128 v[64:67], v138 offset:0
	ds_read_b128 v[96:99], v142 offset:0
	ds_read_b128 v[100:103], v142 offset:2048
	ds_read_b128 v[104:107], v142 offset:4096
	ds_read_b128 v[108:111], v142 offset:6144
	ds_read_b128 v[68:71], v138 offset:2048
	ds_read_b128 v[72:75], v138 offset:4096
	ds_read_b128 v[76:79], v138 offset:6144
	s_waitcnt lgkmcnt(3)
	v_mfma_f32_16x16x32_bf16 v[0:3], v[64:67], v[96:99], v[0:3]
	v_mfma_f32_16x16x32_bf16 v[4:7], v[64:67], v[100:103], v[4:7]
	ds_read_b128 v[80:83], v139 offset:0
	v_mfma_f32_16x16x32_bf16 v[8:11], v[64:67], v[104:107], v[8:11]
	v_mfma_f32_16x16x32_bf16 v[12:15], v[64:67], v[108:111], v[12:15]
	ds_read_b128 v[112:115], v143 offset:0
	s_waitcnt lgkmcnt(4)
	v_mfma_f32_16x16x32_bf16 v[16:19], v[68:71], v[96:99], v[16:19]
	v_mfma_f32_16x16x32_bf16 v[20:23], v[68:71], v[100:103], v[20:23]
	ds_read_b128 v[116:119], v143 offset:2048
	v_mfma_f32_16x16x32_bf16 v[24:27], v[68:71], v[104:107], v[24:27]
	v_mfma_f32_16x16x32_bf16 v[28:31], v[68:71], v[108:111], v[28:31]
	ds_read_b128 v[120:123], v143 offset:4096
	s_waitcnt lgkmcnt(5)
	v_mfma_f32_16x16x32_bf16 v[32:35], v[72:75], v[96:99], v[32:35]
	v_mfma_f32_16x16x32_bf16 v[36:39], v[72:75], v[100:103], v[36:39]
	ds_read_b128 v[124:127], v143 offset:6144
	v_mfma_f32_16x16x32_bf16 v[40:43], v[72:75], v[104:107], v[40:43]
	v_mfma_f32_16x16x32_bf16 v[44:47], v[72:75], v[108:111], v[44:47]
	ds_read_b128 v[84:87], v139 offset:2048
	s_waitcnt lgkmcnt(6)
	v_mfma_f32_16x16x32_bf16 v[48:51], v[76:79], v[96:99], v[48:51]
	v_mfma_f32_16x16x32_bf16 v[52:55], v[76:79], v[100:103], v[52:55]
	ds_read_b128 v[88:91], v139 offset:4096
	v_mfma_f32_16x16x32_bf16 v[56:59], v[76:79], v[104:107], v[56:59]
	v_mfma_f32_16x16x32_bf16 v[60:63], v[76:79], v[108:111], v[60:63]
	ds_read_b128 v[92:95], v139 offset:6144
	s_waitcnt lgkmcnt(3)
	v_mfma_f32_16x16x32_bf16 v[0:3], v[80:83], v[112:115], v[0:3]
	v_mfma_f32_16x16x32_bf16 v[4:7], v[80:83], v[116:119], v[4:7]
	v_mfma_f32_16x16x32_bf16 v[8:11], v[80:83], v[120:123], v[8:11]
	v_mfma_f32_16x16x32_bf16 v[12:15], v[80:83], v[124:127], v[12:15]
	s_waitcnt lgkmcnt(2)
	v_mfma_f32_16x16x32_bf16 v[16:19], v[84:87], v[112:115], v[16:19]
	v_mfma_f32_16x16x32_bf16 v[20:23], v[84:87], v[116:119], v[20:23]
	v_mfma_f32_16x16x32_bf16 v[24:27], v[84:87], v[120:123], v[24:27]
	v_mfma_f32_16x16x32_bf16 v[28:31], v[84:87], v[124:127], v[28:31]
	s_waitcnt lgkmcnt(1)
	v_mfma_f32_16x16x32_bf16 v[32:35], v[88:91], v[112:115], v[32:35]
	v_mfma_f32_16x16x32_bf16 v[36:39], v[88:91], v[116:119], v[36:39]
	v_mfma_f32_16x16x32_bf16 v[40:43], v[88:91], v[120:123], v[40:43]
	v_mfma_f32_16x16x32_bf16 v[44:47], v[88:91], v[124:127], v[44:47]
	s_waitcnt lgkmcnt(0)
	v_mfma_f32_16x16x32_bf16 v[48:51], v[92:95], v[112:115], v[48:51]
	v_mfma_f32_16x16x32_bf16 v[52:55], v[92:95], v[116:119], v[52:55]
	v_mfma_f32_16x16x32_bf16 v[56:59], v[92:95], v[120:123], v[56:59]
	v_mfma_f32_16x16x32_bf16 v[60:63], v[92:95], v[124:127], v[60:63]
	s_waitcnt vmcnt(0)
	s_barrier
	s_add_u32 s26, s26, 0x80
	s_addc_u32 s27, s27, 0
	s_add_u32 s28, s28, 0x80
	s_addc_u32 s29, s29, 0
	s_mov_b32 m0, s7
	s_nop 0
	global_load_lds_dwordx4 v132, s[26:27] offset:0
	global_load_lds_dwordx4 v133, s[26:27] offset:1024
	global_load_lds_dwordx4 v134, s[26:27] offset:2048
	global_load_lds_dwordx4 v135, s[26:27] offset:3072
	s_mov_b32 m0, s8
	s_nop 0
	global_load_lds_dwordx4 v132, s[28:29] offset:0
	global_load_lds_dwordx4 v133, s[28:29] offset:1024
	global_load_lds_dwordx4 v134, s[28:29] offset:2048
	global_load_lds_dwordx4 v135, s[28:29] offset:3072
	ds_read_b128 v[64:67], v136 offset:0
	ds_read_b128 v[96:99], v140 offset:0
	ds_read_b128 v[100:103], v140 offset:2048
	ds_read_b128 v[104:107], v140 offset:4096
	ds_read_b128 v[108:111], v140 offset:6144
	ds_read_b128 v[68:71], v136 offset:2048
	ds_read_b128 v[72:75], v136 offset:4096
	ds_read_b128 v[76:79], v136 offset:6144
	s_waitcnt lgkmcnt(3)
	v_mfma_f32_16x16x32_bf16 v[0:3], v[64:67], v[96:99], v[0:3]
	v_mfma_f32_16x16x32_bf16 v[4:7], v[64:67], v[100:103], v[4:7]
	ds_read_b128 v[80:83], v137 offset:0
	v_mfma_f32_16x16x32_bf16 v[8:11], v[64:67], v[104:107], v[8:11]
	v_mfma_f32_16x16x32_bf16 v[12:15], v[64:67], v[108:111], v[12:15]
	ds_read_b128 v[112:115], v141 offset:0
	s_waitcnt lgkmcnt(4)
	v_mfma_f32_16x16x32_bf16 v[16:19], v[68:71], v[96:99], v[16:19]
	v_mfma_f32_16x16x32_bf16 v[20:23], v[68:71], v[100:103], v[20:23]
	ds_read_b128 v[116:119], v141 offset:2048
	v_mfma_f32_16x16x32_bf16 v[24:27], v[68:71], v[104:107], v[24:27]
	v_mfma_f32_16x16x32_bf16 v[28:31], v[68:71], v[108:111], v[28:31]
	ds_read_b128 v[120:123], v141 offset:4096
	s_waitcnt lgkmcnt(5)
	v_mfma_f32_16x16x32_bf16 v[32:35], v[72:75], v[96:99], v[32:35]
	v_mfma_f32_16x16x32_bf16 v[36:39], v[72:75], v[100:103], v[36:39]
	ds_read_b128 v[124:127], v141 offset:6144
	v_mfma_f32_16x16x32_bf16 v[40:43], v[72:75], v[104:107], v[40:43]
	v_mfma_f32_16x16x32_bf16 v[44:47], v[72:75], v[108:111], v[44:47]
	ds_read_b128 v[84:87], v137 offset:2048
	s_waitcnt lgkmcnt(6)
	v_mfma_f32_16x16x32_bf16 v[48:51], v[76:79], v[96:99], v[48:51]
	v_mfma_f32_16x16x32_bf16 v[52:55], v[76:79], v[100:103], v[52:55]
	ds_read_b128 v[88:91], v137 offset:4096
	v_mfma_f32_16x16x32_bf16 v[56:59], v[76:79], v[104:107], v[56:59]
	v_mfma_f32_16x16x32_bf16 v[60:63], v[76:79], v[108:111], v[60:63]
	ds_read_b128 v[92:95], v137 offset:6144
	s_waitcnt lgkmcnt(3)
	v_mfma_f32_16x16x32_bf16 v[0:3], v[80:83], v[112:115], v[0:3]
	v_mfma_f32_16x16x32_bf16 v[4:7], v[80:83], v[116:119], v[4:7]
	v_mfma_f32_16x16x32_bf16 v[8:11], v[80:83], v[120:123], v[8:11]
	v_mfma_f32_16x16x32_bf16 v[12:15], v[80:83], v[124:127], v[12:15]
	s_waitcnt lgkmcnt(2)
	v_mfma_f32_16x16x32_bf16 v[16:19], v[84:87], v[112:115], v[16:19]
	v_mfma_f32_16x16x32_bf16 v[20:23], v[84:87], v[116:119], v[20:23]
	v_mfma_f32_16x16x32_bf16 v[24:27], v[84:87], v[120:123], v[24:27]
	v_mfma_f32_16x16x32_bf16 v[28:31], v[84:87], v[124:127], v[28:31]
	s_waitcnt lgkmcnt(1)
	v_mfma_f32_16x16x32_bf16 v[32:35], v[88:91], v[112:115], v[32:35]
	v_mfma_f32_16x16x32_bf16 v[36:39], v[88:91], v[116:119], v[36:39]
	v_mfma_f32_16x16x32_bf16 v[40:43], v[88:91], v[120:123], v[40:43]
	v_mfma_f32_16x16x32_bf16 v[44:47], v[88:91], v[124:127], v[44:47]
	s_waitcnt lgkmcnt(0)
	v_mfma_f32_16x16x32_bf16 v[48:51], v[92:95], v[112:115], v[48:51]
	v_mfma_f32_16x16x32_bf16 v[52:55], v[92:95], v[116:119], v[52:55]
	v_mfma_f32_16x16x32_bf16 v[56:59], v[92:95], v[120:123], v[56:59]
	v_mfma_f32_16x16x32_bf16 v[60:63], v[92:95], v[124:127], v[60:63]
	s_waitcnt vmcnt(0)
	s_barrier
	s_add_u32 s26, s26, 0x80
	s_addc_u32 s27, s27, 0
	s_add_u32 s28, s28, 0x80
	s_addc_u32 s29, s29, 0
	s_mov_b32 m0, s5
	s_nop 0
	global_load_lds_dwordx4 v132, s[26:27] offset:0
	global_load_lds_dwordx4 v133, s[26:27] offset:1024
	global_load_lds_dwordx4 v134, s[26:27] offset:2048
	global_load_lds_dwordx4 v135, s[26:27] offset:3072
	s_mov_b32 m0, s6
	s_nop 0
	global_load_lds_dwordx4 v132, s[28:29] offset:0
	global_load_lds_dwordx4 v133, s[28:29] offset:1024
	global_load_lds_dwordx4 v134, s[28:29] offset:2048
	global_load_lds_dwordx4 v135, s[28:29] offset:3072
	ds_read_b128 v[64:67], v138 offset:0
	ds_read_b128 v[96:99], v142 offset:0
	ds_read_b128 v[100:103], v142 offset:2048
	ds_read_b128 v[104:107], v142 offset:4096
	ds_read_b128 v[108:111], v142 offset:6144
	ds_read_b128 v[68:71], v138 offset:2048
	ds_read_b128 v[72:75], v138 offset:4096
	ds_read_b128 v[76:79], v138 offset:6144
	s_waitcnt lgkmcnt(3)
	v_mfma_f32_16x16x32_bf16 v[0:3], v[64:67], v[96:99], v[0:3]
	v_mfma_f32_16x16x32_bf16 v[4:7], v[64:67], v[100:103], v[4:7]
	ds_read_b128 v[80:83], v139 offset:0
	v_mfma_f32_16x16x32_bf16 v[8:11], v[64:67], v[104:107], v[8:11]
	v_mfma_f32_16x16x32_bf16 v[12:15], v[64:67], v[108:111], v[12:15]
	ds_read_b128 v[112:115], v143 offset:0
	s_waitcnt lgkmcnt(4)
	v_mfma_f32_16x16x32_bf16 v[16:19], v[68:71], v[96:99], v[16:19]
	v_mfma_f32_16x16x32_bf16 v[20:23], v[68:71], v[100:103], v[20:23]
	ds_read_b128 v[116:119], v143 offset:2048
	v_mfma_f32_16x16x32_bf16 v[24:27], v[68:71], v[104:107], v[24:27]
	v_mfma_f32_16x16x32_bf16 v[28:31], v[68:71], v[108:111], v[28:31]
	ds_read_b128 v[120:123], v143 offset:4096
	s_waitcnt lgkmcnt(5)
	v_mfma_f32_16x16x32_bf16 v[32:35], v[72:75], v[96:99], v[32:35]
	v_mfma_f32_16x16x32_bf16 v[36:39], v[72:75], v[100:103], v[36:39]
	ds_read_b128 v[124:127], v143 offset:6144
	v_mfma_f32_16x16x32_bf16 v[40:43], v[72:75], v[104:107], v[40:43]
	v_mfma_f32_16x16x32_bf16 v[44:47], v[72:75], v[108:111], v[44:47]
	ds_read_b128 v[84:87], v139 offset:2048
	s_waitcnt lgkmcnt(6)
	v_mfma_f32_16x16x32_bf16 v[48:51], v[76:79], v[96:99], v[48:51]
	v_mfma_f32_16x16x32_bf16 v[52:55], v[76:79], v[100:103], v[52:55]
	ds_read_b128 v[88:91], v139 offset:4096
	v_mfma_f32_16x16x32_bf16 v[56:59], v[76:79], v[104:107], v[56:59]
	v_mfma_f32_16x16x32_bf16 v[60:63], v[76:79], v[108:111], v[60:63]
	ds_read_b128 v[92:95], v139 offset:6144
	s_waitcnt lgkmcnt(3)
	v_mfma_f32_16x16x32_bf16 v[0:3], v[80:83], v[112:115], v[0:3]
	v_mfma_f32_16x16x32_bf16 v[4:7], v[80:83], v[116:119], v[4:7]
	v_mfma_f32_16x16x32_bf16 v[8:11], v[80:83], v[120:123], v[8:11]
	v_mfma_f32_16x16x32_bf16 v[12:15], v[80:83], v[124:127], v[12:15]
	s_waitcnt lgkmcnt(2)
	v_mfma_f32_16x16x32_bf16 v[16:19], v[84:87], v[112:115], v[16:19]
	v_mfma_f32_16x16x32_bf16 v[20:23], v[84:87], v[116:119], v[20:23]
	v_mfma_f32_16x16x32_bf16 v[24:27], v[84:87], v[120:123], v[24:27]
	v_mfma_f32_16x16x32_bf16 v[28:31], v[84:87], v[124:127], v[28:31]
	s_waitcnt lgkmcnt(1)
	v_mfma_f32_16x16x32_bf16 v[32:35], v[88:91], v[112:115], v[32:35]
	v_mfma_f32_16x16x32_bf16 v[36:39], v[88:91], v[116:119], v[36:39]
	v_mfma_f32_16x16x32_bf16 v[40:43], v[88:91], v[120:123], v[40:43]
	v_mfma_f32_16x16x32_bf16 v[44:47], v[88:91], v[124:127], v[44:47]
	s_waitcnt lgkmcnt(0)
	v_mfma_f32_16x16x32_bf16 v[48:51], v[92:95], v[112:115], v[48:51]
	v_mfma_f32_16x16x32_bf16 v[52:55], v[92:95], v[116:119], v[52:55]
	v_mfma_f32_16x16x32_bf16 v[56:59], v[92:95], v[120:123], v[56:59]
	v_mfma_f32_16x16x32_bf16 v[60:63], v[92:95], v[124:127], v[60:63]
	s_waitcnt vmcnt(0)
	s_barrier
	s_add_u32 s26, s26, 0x80
	s_addc_u32 s27, s27, 0
	s_add_u32 s28, s28, 0x80
	s_addc_u32 s29, s29, 0
	s_mov_b32 m0, s7
	s_nop 0
	global_load_lds_dwordx4 v132, s[26:27] offset:0
	global_load_lds_dwordx4 v133, s[26:27] offset:1024
	global_load_lds_dwordx4 v134, s[26:27] offset:2048
	global_load_lds_dwordx4 v135, s[26:27] offset:3072
	s_mov_b32 m0, s8
	s_nop 0
	global_load_lds_dwordx4 v132, s[28:29] offset:0
	global_load_lds_dwordx4 v133, s[28:29] offset:1024
	global_load_lds_dwordx4 v134, s[28:29] offset:2048
	global_load_lds_dwordx4 v135, s[28:29] offset:3072
	ds_read_b128 v[64:67], v136 offset:0
	ds_read_b128 v[96:99], v140 offset:0
	ds_read_b128 v[100:103], v140 offset:2048
	ds_read_b128 v[104:107], v140 offset:4096
	ds_read_b128 v[108:111], v140 offset:6144
	ds_read_b128 v[68:71], v136 offset:2048
	ds_read_b128 v[72:75], v136 offset:4096
	ds_read_b128 v[76:79], v136 offset:6144
	s_waitcnt lgkmcnt(3)
	v_mfma_f32_16x16x32_bf16 v[0:3], v[64:67], v[96:99], v[0:3]
	v_mfma_f32_16x16x32_bf16 v[4:7], v[64:67], v[100:103], v[4:7]
	ds_read_b128 v[80:83], v137 offset:0
	v_mfma_f32_16x16x32_bf16 v[8:11], v[64:67], v[104:107], v[8:11]
	v_mfma_f32_16x16x32_bf16 v[12:15], v[64:67], v[108:111], v[12:15]
	ds_read_b128 v[112:115], v141 offset:0
	s_waitcnt lgkmcnt(4)
	v_mfma_f32_16x16x32_bf16 v[16:19], v[68:71], v[96:99], v[16:19]
	v_mfma_f32_16x16x32_bf16 v[20:23], v[68:71], v[100:103], v[20:23]
	ds_read_b128 v[116:119], v141 offset:2048
	v_mfma_f32_16x16x32_bf16 v[24:27], v[68:71], v[104:107], v[24:27]
	v_mfma_f32_16x16x32_bf16 v[28:31], v[68:71], v[108:111], v[28:31]
	ds_read_b128 v[120:123], v141 offset:4096
	s_waitcnt lgkmcnt(5)
	v_mfma_f32_16x16x32_bf16 v[32:35], v[72:75], v[96:99], v[32:35]
	v_mfma_f32_16x16x32_bf16 v[36:39], v[72:75], v[100:103], v[36:39]
	ds_read_b128 v[124:127], v141 offset:6144
	v_mfma_f32_16x16x32_bf16 v[40:43], v[72:75], v[104:107], v[40:43]
	v_mfma_f32_16x16x32_bf16 v[44:47], v[72:75], v[108:111], v[44:47]
	ds_read_b128 v[84:87], v137 offset:2048
	s_waitcnt lgkmcnt(6)
	v_mfma_f32_16x16x32_bf16 v[48:51], v[76:79], v[96:99], v[48:51]
	v_mfma_f32_16x16x32_bf16 v[52:55], v[76:79], v[100:103], v[52:55]
	ds_read_b128 v[88:91], v137 offset:4096
	v_mfma_f32_16x16x32_bf16 v[56:59], v[76:79], v[104:107], v[56:59]
	v_mfma_f32_16x16x32_bf16 v[60:63], v[76:79], v[108:111], v[60:63]
	ds_read_b128 v[92:95], v137 offset:6144
	s_waitcnt lgkmcnt(3)
	v_mfma_f32_16x16x32_bf16 v[0:3], v[80:83], v[112:115], v[0:3]
	v_mfma_f32_16x16x32_bf16 v[4:7], v[80:83], v[116:119], v[4:7]
	v_mfma_f32_16x16x32_bf16 v[8:11], v[80:83], v[120:123], v[8:11]
	v_mfma_f32_16x16x32_bf16 v[12:15], v[80:83], v[124:127], v[12:15]
	s_waitcnt lgkmcnt(2)
	v_mfma_f32_16x16x32_bf16 v[16:19], v[84:87], v[112:115], v[16:19]
	v_mfma_f32_16x16x32_bf16 v[20:23], v[84:87], v[116:119], v[20:23]
	v_mfma_f32_16x16x32_bf16 v[24:27], v[84:87], v[120:123], v[24:27]
	v_mfma_f32_16x16x32_bf16 v[28:31], v[84:87], v[124:127], v[28:31]
	s_waitcnt lgkmcnt(1)
	v_mfma_f32_16x16x32_bf16 v[32:35], v[88:91], v[112:115], v[32:35]
	v_mfma_f32_16x16x32_bf16 v[36:39], v[88:91], v[116:119], v[36:39]
	v_mfma_f32_16x16x32_bf16 v[40:43], v[88:91], v[120:123], v[40:43]
	v_mfma_f32_16x16x32_bf16 v[44:47], v[88:91], v[124:127], v[44:47]
	s_waitcnt lgkmcnt(0)
	v_mfma_f32_16x16x32_bf16 v[48:51], v[92:95], v[112:115], v[48:51]
	v_mfma_f32_16x16x32_bf16 v[52:55], v[92:95], v[116:119], v[52:55]
	v_mfma_f32_16x16x32_bf16 v[56:59], v[92:95], v[120:123], v[56:59]
	v_mfma_f32_16x16x32_bf16 v[60:63], v[92:95], v[124:127], v[60:63]
	s_waitcnt vmcnt(0)
	s_barrier
	s_add_u32 s26, s26, 0x80
	s_addc_u32 s27, s27, 0
	s_add_u32 s28, s28, 0x80
	s_addc_u32 s29, s29, 0
	s_mov_b32 m0, s5
	s_nop 0
	global_load_lds_dwordx4 v132, s[26:27] offset:0
	global_load_lds_dwordx4 v133, s[26:27] offset:1024
	global_load_lds_dwordx4 v134, s[26:27] offset:2048
	global_load_lds_dwordx4 v135, s[26:27] offset:3072
	s_mov_b32 m0, s6
	s_nop 0
	global_load_lds_dwordx4 v132, s[28:29] offset:0
	global_load_lds_dwordx4 v133, s[28:29] offset:1024
	global_load_lds_dwordx4 v134, s[28:29] offset:2048
	global_load_lds_dwordx4 v135, s[28:29] offset:3072
	ds_read_b128 v[64:67], v138 offset:0
	ds_read_b128 v[96:99], v142 offset:0
	ds_read_b128 v[100:103], v142 offset:2048
	ds_read_b128 v[104:107], v142 offset:4096
	ds_read_b128 v[108:111], v142 offset:6144
	ds_read_b128 v[68:71], v138 offset:2048
	ds_read_b128 v[72:75], v138 offset:4096
	ds_read_b128 v[76:79], v138 offset:6144
	s_waitcnt lgkmcnt(3)
	v_mfma_f32_16x16x32_bf16 v[0:3], v[64:67], v[96:99], v[0:3]
	v_mfma_f32_16x16x32_bf16 v[4:7], v[64:67], v[100:103], v[4:7]
	ds_read_b128 v[80:83], v139 offset:0
	v_mfma_f32_16x16x32_bf16 v[8:11], v[64:67], v[104:107], v[8:11]
	v_mfma_f32_16x16x32_bf16 v[12:15], v[64:67], v[108:111], v[12:15]
	ds_read_b128 v[112:115], v143 offset:0
	s_waitcnt lgkmcnt(4)
	v_mfma_f32_16x16x32_bf16 v[16:19], v[68:71], v[96:99], v[16:19]
	v_mfma_f32_16x16x32_bf16 v[20:23], v[68:71], v[100:103], v[20:23]
	ds_read_b128 v[116:119], v143 offset:2048
	v_mfma_f32_16x16x32_bf16 v[24:27], v[68:71], v[104:107], v[24:27]
	v_mfma_f32_16x16x32_bf16 v[28:31], v[68:71], v[108:111], v[28:31]
	ds_read_b128 v[120:123], v143 offset:4096
	s_waitcnt lgkmcnt(5)
	v_mfma_f32_16x16x32_bf16 v[32:35], v[72:75], v[96:99], v[32:35]
	v_mfma_f32_16x16x32_bf16 v[36:39], v[72:75], v[100:103], v[36:39]
	ds_read_b128 v[124:127], v143 offset:6144
	v_mfma_f32_16x16x32_bf16 v[40:43], v[72:75], v[104:107], v[40:43]
	v_mfma_f32_16x16x32_bf16 v[44:47], v[72:75], v[108:111], v[44:47]
	ds_read_b128 v[84:87], v139 offset:2048
	s_waitcnt lgkmcnt(6)
	v_mfma_f32_16x16x32_bf16 v[48:51], v[76:79], v[96:99], v[48:51]
	v_mfma_f32_16x16x32_bf16 v[52:55], v[76:79], v[100:103], v[52:55]
	ds_read_b128 v[88:91], v139 offset:4096
	v_mfma_f32_16x16x32_bf16 v[56:59], v[76:79], v[104:107], v[56:59]
	v_mfma_f32_16x16x32_bf16 v[60:63], v[76:79], v[108:111], v[60:63]
	ds_read_b128 v[92:95], v139 offset:6144
	s_waitcnt lgkmcnt(3)
	v_mfma_f32_16x16x32_bf16 v[0:3], v[80:83], v[112:115], v[0:3]
	v_mfma_f32_16x16x32_bf16 v[4:7], v[80:83], v[116:119], v[4:7]
	v_mfma_f32_16x16x32_bf16 v[8:11], v[80:83], v[120:123], v[8:11]
	v_mfma_f32_16x16x32_bf16 v[12:15], v[80:83], v[124:127], v[12:15]
	s_waitcnt lgkmcnt(2)
	v_mfma_f32_16x16x32_bf16 v[16:19], v[84:87], v[112:115], v[16:19]
	v_mfma_f32_16x16x32_bf16 v[20:23], v[84:87], v[116:119], v[20:23]
	v_mfma_f32_16x16x32_bf16 v[24:27], v[84:87], v[120:123], v[24:27]
	v_mfma_f32_16x16x32_bf16 v[28:31], v[84:87], v[124:127], v[28:31]
	s_waitcnt lgkmcnt(1)
	v_mfma_f32_16x16x32_bf16 v[32:35], v[88:91], v[112:115], v[32:35]
	v_mfma_f32_16x16x32_bf16 v[36:39], v[88:91], v[116:119], v[36:39]
	v_mfma_f32_16x16x32_bf16 v[40:43], v[88:91], v[120:123], v[40:43]
	v_mfma_f32_16x16x32_bf16 v[44:47], v[88:91], v[124:127], v[44:47]
	s_waitcnt lgkmcnt(0)
	v_mfma_f32_16x16x32_bf16 v[48:51], v[92:95], v[112:115], v[48:51]
	v_mfma_f32_16x16x32_bf16 v[52:55], v[92:95], v[116:119], v[52:55]
	v_mfma_f32_16x16x32_bf16 v[56:59], v[92:95], v[120:123], v[56:59]
	v_mfma_f32_16x16x32_bf16 v[60:63], v[92:95], v[124:127], v[60:63]
	s_waitcnt vmcnt(0)
	s_barrier
	s_add_u32 s26, s26, 0x80
	s_addc_u32 s27, s27, 0
	s_add_u32 s28, s28, 0x80
	s_addc_u32 s29, s29, 0
	s_mov_b32 m0, s7
	s_nop 0
	global_load_lds_dwordx4 v132, s[26:27] offset:0
	global_load_lds_dwordx4 v133, s[26:27] offset:1024
	global_load_lds_dwordx4 v134, s[26:27] offset:2048
	global_load_lds_dwordx4 v135, s[26:27] offset:3072
	s_mov_b32 m0, s8
	s_nop 0
	global_load_lds_dwordx4 v132, s[28:29] offset:0
	global_load_lds_dwordx4 v133, s[28:29] offset:1024
	global_load_lds_dwordx4 v134, s[28:29] offset:2048
	global_load_lds_dwordx4 v135, s[28:29] offset:3072
	ds_read_b128 v[64:67], v136 offset:0
	ds_read_b128 v[96:99], v140 offset:0
	ds_read_b128 v[100:103], v140 offset:2048
	ds_read_b128 v[104:107], v140 offset:4096
	ds_read_b128 v[108:111], v140 offset:6144
	ds_read_b128 v[68:71], v136 offset:2048
	ds_read_b128 v[72:75], v136 offset:4096
	ds_read_b128 v[76:79], v136 offset:6144
	s_waitcnt lgkmcnt(3)
	v_mfma_f32_16x16x32_bf16 v[0:3], v[64:67], v[96:99], v[0:3]
	v_mfma_f32_16x16x32_bf16 v[4:7], v[64:67], v[100:103], v[4:7]
	ds_read_b128 v[80:83], v137 offset:0
	v_mfma_f32_16x16x32_bf16 v[8:11], v[64:67], v[104:107], v[8:11]
	v_mfma_f32_16x16x32_bf16 v[12:15], v[64:67], v[108:111], v[12:15]
	ds_read_b128 v[112:115], v141 offset:0
	s_waitcnt lgkmcnt(4)
	v_mfma_f32_16x16x32_bf16 v[16:19], v[68:71], v[96:99], v[16:19]
	v_mfma_f32_16x16x32_bf16 v[20:23], v[68:71], v[100:103], v[20:23]
	ds_read_b128 v[116:119], v141 offset:2048
	v_mfma_f32_16x16x32_bf16 v[24:27], v[68:71], v[104:107], v[24:27]
	v_mfma_f32_16x16x32_bf16 v[28:31], v[68:71], v[108:111], v[28:31]
	ds_read_b128 v[120:123], v141 offset:4096
	s_waitcnt lgkmcnt(5)
	v_mfma_f32_16x16x32_bf16 v[32:35], v[72:75], v[96:99], v[32:35]
	v_mfma_f32_16x16x32_bf16 v[36:39], v[72:75], v[100:103], v[36:39]
	ds_read_b128 v[124:127], v141 offset:6144
	v_mfma_f32_16x16x32_bf16 v[40:43], v[72:75], v[104:107], v[40:43]
	v_mfma_f32_16x16x32_bf16 v[44:47], v[72:75], v[108:111], v[44:47]
	ds_read_b128 v[84:87], v137 offset:2048
	s_waitcnt lgkmcnt(6)
	v_mfma_f32_16x16x32_bf16 v[48:51], v[76:79], v[96:99], v[48:51]
	v_mfma_f32_16x16x32_bf16 v[52:55], v[76:79], v[100:103], v[52:55]
	ds_read_b128 v[88:91], v137 offset:4096
	v_mfma_f32_16x16x32_bf16 v[56:59], v[76:79], v[104:107], v[56:59]
	v_mfma_f32_16x16x32_bf16 v[60:63], v[76:79], v[108:111], v[60:63]
	ds_read_b128 v[92:95], v137 offset:6144
	s_waitcnt lgkmcnt(3)
	v_mfma_f32_16x16x32_bf16 v[0:3], v[80:83], v[112:115], v[0:3]
	v_mfma_f32_16x16x32_bf16 v[4:7], v[80:83], v[116:119], v[4:7]
	v_mfma_f32_16x16x32_bf16 v[8:11], v[80:83], v[120:123], v[8:11]
	v_mfma_f32_16x16x32_bf16 v[12:15], v[80:83], v[124:127], v[12:15]
	s_waitcnt lgkmcnt(2)
	v_mfma_f32_16x16x32_bf16 v[16:19], v[84:87], v[112:115], v[16:19]
	v_mfma_f32_16x16x32_bf16 v[20:23], v[84:87], v[116:119], v[20:23]
	v_mfma_f32_16x16x32_bf16 v[24:27], v[84:87], v[120:123], v[24:27]
	v_mfma_f32_16x16x32_bf16 v[28:31], v[84:87], v[124:127], v[28:31]
	s_waitcnt lgkmcnt(1)
	v_mfma_f32_16x16x32_bf16 v[32:35], v[88:91], v[112:115], v[32:35]
	v_mfma_f32_16x16x32_bf16 v[36:39], v[88:91], v[116:119], v[36:39]
	v_mfma_f32_16x16x32_bf16 v[40:43], v[88:91], v[120:123], v[40:43]
	v_mfma_f32_16x16x32_bf16 v[44:47], v[88:91], v[124:127], v[44:47]
	s_waitcnt lgkmcnt(0)
	v_mfma_f32_16x16x32_bf16 v[48:51], v[92:95], v[112:115], v[48:51]
	v_mfma_f32_16x16x32_bf16 v[52:55], v[92:95], v[116:119], v[52:55]
	v_mfma_f32_16x16x32_bf16 v[56:59], v[92:95], v[120:123], v[56:59]
	v_mfma_f32_16x16x32_bf16 v[60:63], v[92:95], v[124:127], v[60:63]
	s_waitcnt vmcnt(0)
	s_barrier
	s_add_u32 s26, s26, 0x80
	s_addc_u32 s27, s27, 0
	s_add_u32 s28, s28, 0x80
	s_addc_u32 s29, s29, 0
	s_mov_b32 m0, s5
	s_nop 0
	global_load_lds_dwordx4 v132, s[26:27] offset:0
	global_load_lds_dwordx4 v133, s[26:27] offset:1024
	global_load_lds_dwordx4 v134, s[26:27] offset:2048
	global_load_lds_dwordx4 v135, s[26:27] offset:3072
	s_mov_b32 m0, s6
	s_nop 0
	global_load_lds_dwordx4 v132, s[28:29] offset:0
	global_load_lds_dwordx4 v133, s[28:29] offset:1024
	global_load_lds_dwordx4 v134, s[28:29] offset:2048
	global_load_lds_dwordx4 v135, s[28:29] offset:3072
	ds_read_b128 v[64:67], v138 offset:0
	ds_read_b128 v[96:99], v142 offset:0
	ds_read_b128 v[100:103], v142 offset:2048
	ds_read_b128 v[104:107], v142 offset:4096
	ds_read_b128 v[108:111], v142 offset:6144
	ds_read_b128 v[68:71], v138 offset:2048
	ds_read_b128 v[72:75], v138 offset:4096
	ds_read_b128 v[76:79], v138 offset:6144
	s_waitcnt lgkmcnt(3)
	v_mfma_f32_16x16x32_bf16 v[0:3], v[64:67], v[96:99], v[0:3]
	v_mfma_f32_16x16x32_bf16 v[4:7], v[64:67], v[100:103], v[4:7]
	ds_read_b128 v[80:83], v139 offset:0
	v_mfma_f32_16x16x32_bf16 v[8:11], v[64:67], v[104:107], v[8:11]
	v_mfma_f32_16x16x32_bf16 v[12:15], v[64:67], v[108:111], v[12:15]
	ds_read_b128 v[112:115], v143 offset:0
	s_waitcnt lgkmcnt(4)
	v_mfma_f32_16x16x32_bf16 v[16:19], v[68:71], v[96:99], v[16:19]
	v_mfma_f32_16x16x32_bf16 v[20:23], v[68:71], v[100:103], v[20:23]
	ds_read_b128 v[116:119], v143 offset:2048
	v_mfma_f32_16x16x32_bf16 v[24:27], v[68:71], v[104:107], v[24:27]
	v_mfma_f32_16x16x32_bf16 v[28:31], v[68:71], v[108:111], v[28:31]
	ds_read_b128 v[120:123], v143 offset:4096
	s_waitcnt lgkmcnt(5)
	v_mfma_f32_16x16x32_bf16 v[32:35], v[72:75], v[96:99], v[32:35]
	v_mfma_f32_16x16x32_bf16 v[36:39], v[72:75], v[100:103], v[36:39]
	ds_read_b128 v[124:127], v143 offset:6144
	v_mfma_f32_16x16x32_bf16 v[40:43], v[72:75], v[104:107], v[40:43]
	v_mfma_f32_16x16x32_bf16 v[44:47], v[72:75], v[108:111], v[44:47]
	ds_read_b128 v[84:87], v139 offset:2048
	s_waitcnt lgkmcnt(6)
	v_mfma_f32_16x16x32_bf16 v[48:51], v[76:79], v[96:99], v[48:51]
	v_mfma_f32_16x16x32_bf16 v[52:55], v[76:79], v[100:103], v[52:55]
	ds_read_b128 v[88:91], v139 offset:4096
	v_mfma_f32_16x16x32_bf16 v[56:59], v[76:79], v[104:107], v[56:59]
	v_mfma_f32_16x16x32_bf16 v[60:63], v[76:79], v[108:111], v[60:63]
	ds_read_b128 v[92:95], v139 offset:6144
	s_waitcnt lgkmcnt(3)
	v_mfma_f32_16x16x32_bf16 v[0:3], v[80:83], v[112:115], v[0:3]
	v_mfma_f32_16x16x32_bf16 v[4:7], v[80:83], v[116:119], v[4:7]
	v_mfma_f32_16x16x32_bf16 v[8:11], v[80:83], v[120:123], v[8:11]
	v_mfma_f32_16x16x32_bf16 v[12:15], v[80:83], v[124:127], v[12:15]
	s_waitcnt lgkmcnt(2)
	v_mfma_f32_16x16x32_bf16 v[16:19], v[84:87], v[112:115], v[16:19]
	v_mfma_f32_16x16x32_bf16 v[20:23], v[84:87], v[116:119], v[20:23]
	v_mfma_f32_16x16x32_bf16 v[24:27], v[84:87], v[120:123], v[24:27]
	v_mfma_f32_16x16x32_bf16 v[28:31], v[84:87], v[124:127], v[28:31]
	s_waitcnt lgkmcnt(1)
	v_mfma_f32_16x16x32_bf16 v[32:35], v[88:91], v[112:115], v[32:35]
	v_mfma_f32_16x16x32_bf16 v[36:39], v[88:91], v[116:119], v[36:39]
	v_mfma_f32_16x16x32_bf16 v[40:43], v[88:91], v[120:123], v[40:43]
	v_mfma_f32_16x16x32_bf16 v[44:47], v[88:91], v[124:127], v[44:47]
	s_waitcnt lgkmcnt(0)
	v_mfma_f32_16x16x32_bf16 v[48:51], v[92:95], v[112:115], v[48:51]
	v_mfma_f32_16x16x32_bf16 v[52:55], v[92:95], v[116:119], v[52:55]
	v_mfma_f32_16x16x32_bf16 v[56:59], v[92:95], v[120:123], v[56:59]
	v_mfma_f32_16x16x32_bf16 v[60:63], v[92:95], v[124:127], v[60:63]
	s_waitcnt vmcnt(0)
	s_barrier
	s_add_u32 s26, s26, 0x80
	s_addc_u32 s27, s27, 0
	s_add_u32 s28, s28, 0x80
	s_addc_u32 s29, s29, 0
	s_mov_b32 m0, s7
	s_nop 0
	global_load_lds_dwordx4 v132, s[26:27] offset:0
	global_load_lds_dwordx4 v133, s[26:27] offset:1024
	global_load_lds_dwordx4 v134, s[26:27] offset:2048
	global_load_lds_dwordx4 v135, s[26:27] offset:3072
	s_mov_b32 m0, s8
	s_nop 0
	global_load_lds_dwordx4 v132, s[28:29] offset:0
	global_load_lds_dwordx4 v133, s[28:29] offset:1024
	global_load_lds_dwordx4 v134, s[28:29] offset:2048
	global_load_lds_dwordx4 v135, s[28:29] offset:3072
	ds_read_b128 v[64:67], v136 offset:0
	ds_read_b128 v[96:99], v140 offset:0
	ds_read_b128 v[100:103], v140 offset:2048
	ds_read_b128 v[104:107], v140 offset:4096
	ds_read_b128 v[108:111], v140 offset:6144
	ds_read_b128 v[68:71], v136 offset:2048
	ds_read_b128 v[72:75], v136 offset:4096
	ds_read_b128 v[76:79], v136 offset:6144
	s_waitcnt lgkmcnt(3)
	v_mfma_f32_16x16x32_bf16 v[0:3], v[64:67], v[96:99], v[0:3]
	v_mfma_f32_16x16x32_bf16 v[4:7], v[64:67], v[100:103], v[4:7]
	ds_read_b128 v[80:83], v137 offset:0
	v_mfma_f32_16x16x32_bf16 v[8:11], v[64:67], v[104:107], v[8:11]
	v_mfma_f32_16x16x32_bf16 v[12:15], v[64:67], v[108:111], v[12:15]
	ds_read_b128 v[112:115], v141 offset:0
	s_waitcnt lgkmcnt(4)
	v_mfma_f32_16x16x32_bf16 v[16:19], v[68:71], v[96:99], v[16:19]
	v_mfma_f32_16x16x32_bf16 v[20:23], v[68:71], v[100:103], v[20:23]
	ds_read_b128 v[116:119], v141 offset:2048
	v_mfma_f32_16x16x32_bf16 v[24:27], v[68:71], v[104:107], v[24:27]
	v_mfma_f32_16x16x32_bf16 v[28:31], v[68:71], v[108:111], v[28:31]
	ds_read_b128 v[120:123], v141 offset:4096
	s_waitcnt lgkmcnt(5)
	v_mfma_f32_16x16x32_bf16 v[32:35], v[72:75], v[96:99], v[32:35]
	v_mfma_f32_16x16x32_bf16 v[36:39], v[72:75], v[100:103], v[36:39]
	ds_read_b128 v[124:127], v141 offset:6144
	v_mfma_f32_16x16x32_bf16 v[40:43], v[72:75], v[104:107], v[40:43]
	v_mfma_f32_16x16x32_bf16 v[44:47], v[72:75], v[108:111], v[44:47]
	ds_read_b128 v[84:87], v137 offset:2048
	s_waitcnt lgkmcnt(6)
	v_mfma_f32_16x16x32_bf16 v[48:51], v[76:79], v[96:99], v[48:51]
	v_mfma_f32_16x16x32_bf16 v[52:55], v[76:79], v[100:103], v[52:55]
	ds_read_b128 v[88:91], v137 offset:4096
	v_mfma_f32_16x16x32_bf16 v[56:59], v[76:79], v[104:107], v[56:59]
	v_mfma_f32_16x16x32_bf16 v[60:63], v[76:79], v[108:111], v[60:63]
	ds_read_b128 v[92:95], v137 offset:6144
	s_waitcnt lgkmcnt(3)
	v_mfma_f32_16x16x32_bf16 v[0:3], v[80:83], v[112:115], v[0:3]
	v_mfma_f32_16x16x32_bf16 v[4:7], v[80:83], v[116:119], v[4:7]
	v_mfma_f32_16x16x32_bf16 v[8:11], v[80:83], v[120:123], v[8:11]
	v_mfma_f32_16x16x32_bf16 v[12:15], v[80:83], v[124:127], v[12:15]
	s_waitcnt lgkmcnt(2)
	v_mfma_f32_16x16x32_bf16 v[16:19], v[84:87], v[112:115], v[16:19]
	v_mfma_f32_16x16x32_bf16 v[20:23], v[84:87], v[116:119], v[20:23]
	v_mfma_f32_16x16x32_bf16 v[24:27], v[84:87], v[120:123], v[24:27]
	v_mfma_f32_16x16x32_bf16 v[28:31], v[84:87], v[124:127], v[28:31]
	s_waitcnt lgkmcnt(1)
	v_mfma_f32_16x16x32_bf16 v[32:35], v[88:91], v[112:115], v[32:35]
	v_mfma_f32_16x16x32_bf16 v[36:39], v[88:91], v[116:119], v[36:39]
	v_mfma_f32_16x16x32_bf16 v[40:43], v[88:91], v[120:123], v[40:43]
	v_mfma_f32_16x16x32_bf16 v[44:47], v[88:91], v[124:127], v[44:47]
	s_waitcnt lgkmcnt(0)
	v_mfma_f32_16x16x32_bf16 v[48:51], v[92:95], v[112:115], v[48:51]
	v_mfma_f32_16x16x32_bf16 v[52:55], v[92:95], v[116:119], v[52:55]
	v_mfma_f32_16x16x32_bf16 v[56:59], v[92:95], v[120:123], v[56:59]
	v_mfma_f32_16x16x32_bf16 v[60:63], v[92:95], v[124:127], v[60:63]
	s_waitcnt vmcnt(0)
	s_barrier
	s_add_u32 s26, s26, 0x80
	s_addc_u32 s27, s27, 0
	s_add_u32 s28, s28, 0x80
	s_addc_u32 s29, s29, 0
	s_mov_b32 m0, s5
	s_nop 0
	global_load_lds_dwordx4 v132, s[26:27] offset:0
	global_load_lds_dwordx4 v133, s[26:27] offset:1024
	global_load_lds_dwordx4 v134, s[26:27] offset:2048
	global_load_lds_dwordx4 v135, s[26:27] offset:3072
	s_mov_b32 m0, s6
	s_nop 0
	global_load_lds_dwordx4 v132, s[28:29] offset:0
	global_load_lds_dwordx4 v133, s[28:29] offset:1024
	global_load_lds_dwordx4 v134, s[28:29] offset:2048
	global_load_lds_dwordx4 v135, s[28:29] offset:3072
	ds_read_b128 v[64:67], v138 offset:0
	ds_read_b128 v[96:99], v142 offset:0
	ds_read_b128 v[100:103], v142 offset:2048
	ds_read_b128 v[104:107], v142 offset:4096
	ds_read_b128 v[108:111], v142 offset:6144
	ds_read_b128 v[68:71], v138 offset:2048
	ds_read_b128 v[72:75], v138 offset:4096
	ds_read_b128 v[76:79], v138 offset:6144
	s_waitcnt lgkmcnt(3)
	v_mfma_f32_16x16x32_bf16 v[0:3], v[64:67], v[96:99], v[0:3]
	v_mfma_f32_16x16x32_bf16 v[4:7], v[64:67], v[100:103], v[4:7]
	ds_read_b128 v[80:83], v139 offset:0
	v_mfma_f32_16x16x32_bf16 v[8:11], v[64:67], v[104:107], v[8:11]
	v_mfma_f32_16x16x32_bf16 v[12:15], v[64:67], v[108:111], v[12:15]
	ds_read_b128 v[112:115], v143 offset:0
	s_waitcnt lgkmcnt(4)
	v_mfma_f32_16x16x32_bf16 v[16:19], v[68:71], v[96:99], v[16:19]
	v_mfma_f32_16x16x32_bf16 v[20:23], v[68:71], v[100:103], v[20:23]
	ds_read_b128 v[116:119], v143 offset:2048
	v_mfma_f32_16x16x32_bf16 v[24:27], v[68:71], v[104:107], v[24:27]
	v_mfma_f32_16x16x32_bf16 v[28:31], v[68:71], v[108:111], v[28:31]
	ds_read_b128 v[120:123], v143 offset:4096
	s_waitcnt lgkmcnt(5)
	v_mfma_f32_16x16x32_bf16 v[32:35], v[72:75], v[96:99], v[32:35]
	v_mfma_f32_16x16x32_bf16 v[36:39], v[72:75], v[100:103], v[36:39]
	ds_read_b128 v[124:127], v143 offset:6144
	v_mfma_f32_16x16x32_bf16 v[40:43], v[72:75], v[104:107], v[40:43]
	v_mfma_f32_16x16x32_bf16 v[44:47], v[72:75], v[108:111], v[44:47]
	ds_read_b128 v[84:87], v139 offset:2048
	s_waitcnt lgkmcnt(6)
	v_mfma_f32_16x16x32_bf16 v[48:51], v[76:79], v[96:99], v[48:51]
	v_mfma_f32_16x16x32_bf16 v[52:55], v[76:79], v[100:103], v[52:55]
	ds_read_b128 v[88:91], v139 offset:4096
	v_mfma_f32_16x16x32_bf16 v[56:59], v[76:79], v[104:107], v[56:59]
	v_mfma_f32_16x16x32_bf16 v[60:63], v[76:79], v[108:111], v[60:63]
	ds_read_b128 v[92:95], v139 offset:6144
	s_waitcnt lgkmcnt(3)
	v_mfma_f32_16x16x32_bf16 v[0:3], v[80:83], v[112:115], v[0:3]
	v_mfma_f32_16x16x32_bf16 v[4:7], v[80:83], v[116:119], v[4:7]
	v_mfma_f32_16x16x32_bf16 v[8:11], v[80:83], v[120:123], v[8:11]
	v_mfma_f32_16x16x32_bf16 v[12:15], v[80:83], v[124:127], v[12:15]
	s_waitcnt lgkmcnt(2)
	v_mfma_f32_16x16x32_bf16 v[16:19], v[84:87], v[112:115], v[16:19]
	v_mfma_f32_16x16x32_bf16 v[20:23], v[84:87], v[116:119], v[20:23]
	v_mfma_f32_16x16x32_bf16 v[24:27], v[84:87], v[120:123], v[24:27]
	v_mfma_f32_16x16x32_bf16 v[28:31], v[84:87], v[124:127], v[28:31]
	s_waitcnt lgkmcnt(1)
	v_mfma_f32_16x16x32_bf16 v[32:35], v[88:91], v[112:115], v[32:35]
	v_mfma_f32_16x16x32_bf16 v[36:39], v[88:91], v[116:119], v[36:39]
	v_mfma_f32_16x16x32_bf16 v[40:43], v[88:91], v[120:123], v[40:43]
	v_mfma_f32_16x16x32_bf16 v[44:47], v[88:91], v[124:127], v[44:47]
	s_waitcnt lgkmcnt(0)
	v_mfma_f32_16x16x32_bf16 v[48:51], v[92:95], v[112:115], v[48:51]
	v_mfma_f32_16x16x32_bf16 v[52:55], v[92:95], v[116:119], v[52:55]
	v_mfma_f32_16x16x32_bf16 v[56:59], v[92:95], v[120:123], v[56:59]
	v_mfma_f32_16x16x32_bf16 v[60:63], v[92:95], v[124:127], v[60:63]
	s_waitcnt vmcnt(0)
	s_barrier
	s_add_u32 s26, s26, 0x80
	s_addc_u32 s27, s27, 0
	s_add_u32 s28, s28, 0x80
	s_addc_u32 s29, s29, 0
	s_mov_b32 m0, s7
	s_nop 0
	global_load_lds_dwordx4 v132, s[26:27] offset:0
	global_load_lds_dwordx4 v133, s[26:27] offset:1024
	global_load_lds_dwordx4 v134, s[26:27] offset:2048
	global_load_lds_dwordx4 v135, s[26:27] offset:3072
	s_mov_b32 m0, s8
	s_nop 0
	global_load_lds_dwordx4 v132, s[28:29] offset:0
	global_load_lds_dwordx4 v133, s[28:29] offset:1024
	global_load_lds_dwordx4 v134, s[28:29] offset:2048
	global_load_lds_dwordx4 v135, s[28:29] offset:3072
	ds_read_b128 v[64:67], v136 offset:0
	ds_read_b128 v[96:99], v140 offset:0
	ds_read_b128 v[100:103], v140 offset:2048
	ds_read_b128 v[104:107], v140 offset:4096
	ds_read_b128 v[108:111], v140 offset:6144
	ds_read_b128 v[68:71], v136 offset:2048
	ds_read_b128 v[72:75], v136 offset:4096
	ds_read_b128 v[76:79], v136 offset:6144
	s_waitcnt lgkmcnt(3)
	v_mfma_f32_16x16x32_bf16 v[0:3], v[64:67], v[96:99], v[0:3]
	v_mfma_f32_16x16x32_bf16 v[4:7], v[64:67], v[100:103], v[4:7]
	ds_read_b128 v[80:83], v137 offset:0
	v_mfma_f32_16x16x32_bf16 v[8:11], v[64:67], v[104:107], v[8:11]
	v_mfma_f32_16x16x32_bf16 v[12:15], v[64:67], v[108:111], v[12:15]
	ds_read_b128 v[112:115], v141 offset:0
	s_waitcnt lgkmcnt(4)
	v_mfma_f32_16x16x32_bf16 v[16:19], v[68:71], v[96:99], v[16:19]
	v_mfma_f32_16x16x32_bf16 v[20:23], v[68:71], v[100:103], v[20:23]
	ds_read_b128 v[116:119], v141 offset:2048
	v_mfma_f32_16x16x32_bf16 v[24:27], v[68:71], v[104:107], v[24:27]
	v_mfma_f32_16x16x32_bf16 v[28:31], v[68:71], v[108:111], v[28:31]
	ds_read_b128 v[120:123], v141 offset:4096
	s_waitcnt lgkmcnt(5)
	v_mfma_f32_16x16x32_bf16 v[32:35], v[72:75], v[96:99], v[32:35]
	v_mfma_f32_16x16x32_bf16 v[36:39], v[72:75], v[100:103], v[36:39]
	ds_read_b128 v[124:127], v141 offset:6144
	v_mfma_f32_16x16x32_bf16 v[40:43], v[72:75], v[104:107], v[40:43]
	v_mfma_f32_16x16x32_bf16 v[44:47], v[72:75], v[108:111], v[44:47]
	ds_read_b128 v[84:87], v137 offset:2048
	s_waitcnt lgkmcnt(6)
	v_mfma_f32_16x16x32_bf16 v[48:51], v[76:79], v[96:99], v[48:51]
	v_mfma_f32_16x16x32_bf16 v[52:55], v[76:79], v[100:103], v[52:55]
	ds_read_b128 v[88:91], v137 offset:4096
	v_mfma_f32_16x16x32_bf16 v[56:59], v[76:79], v[104:107], v[56:59]
	v_mfma_f32_16x16x32_bf16 v[60:63], v[76:79], v[108:111], v[60:63]
	ds_read_b128 v[92:95], v137 offset:6144
	s_waitcnt lgkmcnt(3)
	v_mfma_f32_16x16x32_bf16 v[0:3], v[80:83], v[112:115], v[0:3]
	v_mfma_f32_16x16x32_bf16 v[4:7], v[80:83], v[116:119], v[4:7]
	v_mfma_f32_16x16x32_bf16 v[8:11], v[80:83], v[120:123], v[8:11]
	v_mfma_f32_16x16x32_bf16 v[12:15], v[80:83], v[124:127], v[12:15]
	s_waitcnt lgkmcnt(2)
	v_mfma_f32_16x16x32_bf16 v[16:19], v[84:87], v[112:115], v[16:19]
	v_mfma_f32_16x16x32_bf16 v[20:23], v[84:87], v[116:119], v[20:23]
	v_mfma_f32_16x16x32_bf16 v[24:27], v[84:87], v[120:123], v[24:27]
	v_mfma_f32_16x16x32_bf16 v[28:31], v[84:87], v[124:127], v[28:31]
	s_waitcnt lgkmcnt(1)
	v_mfma_f32_16x16x32_bf16 v[32:35], v[88:91], v[112:115], v[32:35]
	v_mfma_f32_16x16x32_bf16 v[36:39], v[88:91], v[116:119], v[36:39]
	v_mfma_f32_16x16x32_bf16 v[40:43], v[88:91], v[120:123], v[40:43]
	v_mfma_f32_16x16x32_bf16 v[44:47], v[88:91], v[124:127], v[44:47]
	s_waitcnt lgkmcnt(0)
	v_mfma_f32_16x16x32_bf16 v[48:51], v[92:95], v[112:115], v[48:51]
	v_mfma_f32_16x16x32_bf16 v[52:55], v[92:95], v[116:119], v[52:55]
	v_mfma_f32_16x16x32_bf16 v[56:59], v[92:95], v[120:123], v[56:59]
	v_mfma_f32_16x16x32_bf16 v[60:63], v[92:95], v[124:127], v[60:63]
	s_waitcnt vmcnt(0)
	s_barrier
	s_add_u32 s26, s26, 0x80
	s_addc_u32 s27, s27, 0
	s_add_u32 s28, s28, 0x80
	s_addc_u32 s29, s29, 0
	s_mov_b32 m0, s5
	s_nop 0
	global_load_lds_dwordx4 v132, s[26:27] offset:0
	global_load_lds_dwordx4 v133, s[26:27] offset:1024
	global_load_lds_dwordx4 v134, s[26:27] offset:2048
	global_load_lds_dwordx4 v135, s[26:27] offset:3072
	s_mov_b32 m0, s6
	s_nop 0
	global_load_lds_dwordx4 v132, s[28:29] offset:0
	global_load_lds_dwordx4 v133, s[28:29] offset:1024
	global_load_lds_dwordx4 v134, s[28:29] offset:2048
	global_load_lds_dwordx4 v135, s[28:29] offset:3072
	ds_read_b128 v[64:67], v138 offset:0
	ds_read_b128 v[96:99], v142 offset:0
	ds_read_b128 v[100:103], v142 offset:2048
	ds_read_b128 v[104:107], v142 offset:4096
	ds_read_b128 v[108:111], v142 offset:6144
	ds_read_b128 v[68:71], v138 offset:2048
	ds_read_b128 v[72:75], v138 offset:4096
	ds_read_b128 v[76:79], v138 offset:6144
	s_waitcnt lgkmcnt(3)
	v_mfma_f32_16x16x32_bf16 v[0:3], v[64:67], v[96:99], v[0:3]
	v_mfma_f32_16x16x32_bf16 v[4:7], v[64:67], v[100:103], v[4:7]
	ds_read_b128 v[80:83], v139 offset:0
	v_mfma_f32_16x16x32_bf16 v[8:11], v[64:67], v[104:107], v[8:11]
	v_mfma_f32_16x16x32_bf16 v[12:15], v[64:67], v[108:111], v[12:15]
	ds_read_b128 v[112:115], v143 offset:0
	s_waitcnt lgkmcnt(4)
	v_mfma_f32_16x16x32_bf16 v[16:19], v[68:71], v[96:99], v[16:19]
	v_mfma_f32_16x16x32_bf16 v[20:23], v[68:71], v[100:103], v[20:23]
	ds_read_b128 v[116:119], v143 offset:2048
	v_mfma_f32_16x16x32_bf16 v[24:27], v[68:71], v[104:107], v[24:27]
	v_mfma_f32_16x16x32_bf16 v[28:31], v[68:71], v[108:111], v[28:31]
	ds_read_b128 v[120:123], v143 offset:4096
	s_waitcnt lgkmcnt(5)
	v_mfma_f32_16x16x32_bf16 v[32:35], v[72:75], v[96:99], v[32:35]
	v_mfma_f32_16x16x32_bf16 v[36:39], v[72:75], v[100:103], v[36:39]
	ds_read_b128 v[124:127], v143 offset:6144
	v_mfma_f32_16x16x32_bf16 v[40:43], v[72:75], v[104:107], v[40:43]
	v_mfma_f32_16x16x32_bf16 v[44:47], v[72:75], v[108:111], v[44:47]
	ds_read_b128 v[84:87], v139 offset:2048
	s_waitcnt lgkmcnt(6)
	v_mfma_f32_16x16x32_bf16 v[48:51], v[76:79], v[96:99], v[48:51]
	v_mfma_f32_16x16x32_bf16 v[52:55], v[76:79], v[100:103], v[52:55]
	ds_read_b128 v[88:91], v139 offset:4096
	v_mfma_f32_16x16x32_bf16 v[56:59], v[76:79], v[104:107], v[56:59]
	v_mfma_f32_16x16x32_bf16 v[60:63], v[76:79], v[108:111], v[60:63]
	ds_read_b128 v[92:95], v139 offset:6144
	s_waitcnt lgkmcnt(3)
	v_mfma_f32_16x16x32_bf16 v[0:3], v[80:83], v[112:115], v[0:3]
	v_mfma_f32_16x16x32_bf16 v[4:7], v[80:83], v[116:119], v[4:7]
	v_mfma_f32_16x16x32_bf16 v[8:11], v[80:83], v[120:123], v[8:11]
	v_mfma_f32_16x16x32_bf16 v[12:15], v[80:83], v[124:127], v[12:15]
	s_waitcnt lgkmcnt(2)
	v_mfma_f32_16x16x32_bf16 v[16:19], v[84:87], v[112:115], v[16:19]
	v_mfma_f32_16x16x32_bf16 v[20:23], v[84:87], v[116:119], v[20:23]
	v_mfma_f32_16x16x32_bf16 v[24:27], v[84:87], v[120:123], v[24:27]
	v_mfma_f32_16x16x32_bf16 v[28:31], v[84:87], v[124:127], v[28:31]
	s_waitcnt lgkmcnt(1)
	v_mfma_f32_16x16x32_bf16 v[32:35], v[88:91], v[112:115], v[32:35]
	v_mfma_f32_16x16x32_bf16 v[36:39], v[88:91], v[116:119], v[36:39]
	v_mfma_f32_16x16x32_bf16 v[40:43], v[88:91], v[120:123], v[40:43]
	v_mfma_f32_16x16x32_bf16 v[44:47], v[88:91], v[124:127], v[44:47]
	s_waitcnt lgkmcnt(0)
	v_mfma_f32_16x16x32_bf16 v[48:51], v[92:95], v[112:115], v[48:51]
	v_mfma_f32_16x16x32_bf16 v[52:55], v[92:95], v[116:119], v[52:55]
	v_mfma_f32_16x16x32_bf16 v[56:59], v[92:95], v[120:123], v[56:59]
	v_mfma_f32_16x16x32_bf16 v[60:63], v[92:95], v[124:127], v[60:63]
	s_waitcnt vmcnt(0)
	s_barrier
	s_add_u32 s26, s26, 0x80
	s_addc_u32 s27, s27, 0
	s_add_u32 s28, s28, 0x80
	s_addc_u32 s29, s29, 0
	s_mov_b32 m0, s7
	s_nop 0
	global_load_lds_dwordx4 v132, s[26:27] offset:0
	global_load_lds_dwordx4 v133, s[26:27] offset:1024
	global_load_lds_dwordx4 v134, s[26:27] offset:2048
	global_load_lds_dwordx4 v135, s[26:27] offset:3072
	s_mov_b32 m0, s8
	s_nop 0
	global_load_lds_dwordx4 v132, s[28:29] offset:0
	global_load_lds_dwordx4 v133, s[28:29] offset:1024
	global_load_lds_dwordx4 v134, s[28:29] offset:2048
	global_load_lds_dwordx4 v135, s[28:29] offset:3072
	ds_read_b128 v[64:67], v136 offset:0
	ds_read_b128 v[96:99], v140 offset:0
	ds_read_b128 v[100:103], v140 offset:2048
	ds_read_b128 v[104:107], v140 offset:4096
	ds_read_b128 v[108:111], v140 offset:6144
	ds_read_b128 v[68:71], v136 offset:2048
	ds_read_b128 v[72:75], v136 offset:4096
	ds_read_b128 v[76:79], v136 offset:6144
	s_waitcnt lgkmcnt(3)
	v_mfma_f32_16x16x32_bf16 v[0:3], v[64:67], v[96:99], v[0:3]
	v_mfma_f32_16x16x32_bf16 v[4:7], v[64:67], v[100:103], v[4:7]
	ds_read_b128 v[80:83], v137 offset:0
	v_mfma_f32_16x16x32_bf16 v[8:11], v[64:67], v[104:107], v[8:11]
	v_mfma_f32_16x16x32_bf16 v[12:15], v[64:67], v[108:111], v[12:15]
	ds_read_b128 v[112:115], v141 offset:0
	s_waitcnt lgkmcnt(4)
	v_mfma_f32_16x16x32_bf16 v[16:19], v[68:71], v[96:99], v[16:19]
	v_mfma_f32_16x16x32_bf16 v[20:23], v[68:71], v[100:103], v[20:23]
	ds_read_b128 v[116:119], v141 offset:2048
	v_mfma_f32_16x16x32_bf16 v[24:27], v[68:71], v[104:107], v[24:27]
	v_mfma_f32_16x16x32_bf16 v[28:31], v[68:71], v[108:111], v[28:31]
	ds_read_b128 v[120:123], v141 offset:4096
	s_waitcnt lgkmcnt(5)
	v_mfma_f32_16x16x32_bf16 v[32:35], v[72:75], v[96:99], v[32:35]
	v_mfma_f32_16x16x32_bf16 v[36:39], v[72:75], v[100:103], v[36:39]
	ds_read_b128 v[124:127], v141 offset:6144
	v_mfma_f32_16x16x32_bf16 v[40:43], v[72:75], v[104:107], v[40:43]
	v_mfma_f32_16x16x32_bf16 v[44:47], v[72:75], v[108:111], v[44:47]
	ds_read_b128 v[84:87], v137 offset:2048
	s_waitcnt lgkmcnt(6)
	v_mfma_f32_16x16x32_bf16 v[48:51], v[76:79], v[96:99], v[48:51]
	v_mfma_f32_16x16x32_bf16 v[52:55], v[76:79], v[100:103], v[52:55]
	ds_read_b128 v[88:91], v137 offset:4096
	v_mfma_f32_16x16x32_bf16 v[56:59], v[76:79], v[104:107], v[56:59]
	v_mfma_f32_16x16x32_bf16 v[60:63], v[76:79], v[108:111], v[60:63]
	ds_read_b128 v[92:95], v137 offset:6144
	s_waitcnt lgkmcnt(3)
	v_mfma_f32_16x16x32_bf16 v[0:3], v[80:83], v[112:115], v[0:3]
	v_mfma_f32_16x16x32_bf16 v[4:7], v[80:83], v[116:119], v[4:7]
	v_mfma_f32_16x16x32_bf16 v[8:11], v[80:83], v[120:123], v[8:11]
	v_mfma_f32_16x16x32_bf16 v[12:15], v[80:83], v[124:127], v[12:15]
	s_waitcnt lgkmcnt(2)
	v_mfma_f32_16x16x32_bf16 v[16:19], v[84:87], v[112:115], v[16:19]
	v_mfma_f32_16x16x32_bf16 v[20:23], v[84:87], v[116:119], v[20:23]
	v_mfma_f32_16x16x32_bf16 v[24:27], v[84:87], v[120:123], v[24:27]
	v_mfma_f32_16x16x32_bf16 v[28:31], v[84:87], v[124:127], v[28:31]
	s_waitcnt lgkmcnt(1)
	v_mfma_f32_16x16x32_bf16 v[32:35], v[88:91], v[112:115], v[32:35]
	v_mfma_f32_16x16x32_bf16 v[36:39], v[88:91], v[116:119], v[36:39]
	v_mfma_f32_16x16x32_bf16 v[40:43], v[88:91], v[120:123], v[40:43]
	v_mfma_f32_16x16x32_bf16 v[44:47], v[88:91], v[124:127], v[44:47]
	s_waitcnt lgkmcnt(0)
	v_mfma_f32_16x16x32_bf16 v[48:51], v[92:95], v[112:115], v[48:51]
	v_mfma_f32_16x16x32_bf16 v[52:55], v[92:95], v[116:119], v[52:55]
	v_mfma_f32_16x16x32_bf16 v[56:59], v[92:95], v[120:123], v[56:59]
	v_mfma_f32_16x16x32_bf16 v[60:63], v[92:95], v[124:127], v[60:63]
	s_waitcnt vmcnt(0)
	s_barrier
	ds_read_b128 v[64:67], v138 offset:0
	ds_read_b128 v[96:99], v142 offset:0
	ds_read_b128 v[100:103], v142 offset:2048
	ds_read_b128 v[104:107], v142 offset:4096
	ds_read_b128 v[108:111], v142 offset:6144
	ds_read_b128 v[68:71], v138 offset:2048
	ds_read_b128 v[72:75], v138 offset:4096
	ds_read_b128 v[76:79], v138 offset:6144
	s_waitcnt lgkmcnt(3)
	v_mfma_f32_16x16x32_bf16 v[0:3], v[64:67], v[96:99], v[0:3]
	v_mfma_f32_16x16x32_bf16 v[4:7], v[64:67], v[100:103], v[4:7]
	ds_read_b128 v[80:83], v139 offset:0
	v_mfma_f32_16x16x32_bf16 v[8:11], v[64:67], v[104:107], v[8:11]
	v_mfma_f32_16x16x32_bf16 v[12:15], v[64:67], v[108:111], v[12:15]
	ds_read_b128 v[112:115], v143 offset:0
	s_waitcnt lgkmcnt(4)
	v_mfma_f32_16x16x32_bf16 v[16:19], v[68:71], v[96:99], v[16:19]
	v_mfma_f32_16x16x32_bf16 v[20:23], v[68:71], v[100:103], v[20:23]
	ds_read_b128 v[116:119], v143 offset:2048
	v_mfma_f32_16x16x32_bf16 v[24:27], v[68:71], v[104:107], v[24:27]
	v_mfma_f32_16x16x32_bf16 v[28:31], v[68:71], v[108:111], v[28:31]
	ds_read_b128 v[120:123], v143 offset:4096
	s_waitcnt lgkmcnt(5)
	v_mfma_f32_16x16x32_bf16 v[32:35], v[72:75], v[96:99], v[32:35]
	v_mfma_f32_16x16x32_bf16 v[36:39], v[72:75], v[100:103], v[36:39]
	ds_read_b128 v[124:127], v143 offset:6144
	v_mfma_f32_16x16x32_bf16 v[40:43], v[72:75], v[104:107], v[40:43]
	v_mfma_f32_16x16x32_bf16 v[44:47], v[72:75], v[108:111], v[44:47]
	ds_read_b128 v[84:87], v139 offset:2048
	s_waitcnt lgkmcnt(6)
	v_mfma_f32_16x16x32_bf16 v[48:51], v[76:79], v[96:99], v[48:51]
	v_mfma_f32_16x16x32_bf16 v[52:55], v[76:79], v[100:103], v[52:55]
	ds_read_b128 v[88:91], v139 offset:4096
	v_mfma_f32_16x16x32_bf16 v[56:59], v[76:79], v[104:107], v[56:59]
	v_mfma_f32_16x16x32_bf16 v[60:63], v[76:79], v[108:111], v[60:63]
	ds_read_b128 v[92:95], v139 offset:6144
	s_waitcnt lgkmcnt(3)
	v_mfma_f32_16x16x32_bf16 v[0:3], v[80:83], v[112:115], v[0:3]
	v_mfma_f32_16x16x32_bf16 v[4:7], v[80:83], v[116:119], v[4:7]
	v_mfma_f32_16x16x32_bf16 v[8:11], v[80:83], v[120:123], v[8:11]
	v_mfma_f32_16x16x32_bf16 v[12:15], v[80:83], v[124:127], v[12:15]
	s_waitcnt lgkmcnt(2)
	v_mfma_f32_16x16x32_bf16 v[16:19], v[84:87], v[112:115], v[16:19]
	v_mfma_f32_16x16x32_bf16 v[20:23], v[84:87], v[116:119], v[20:23]
	v_mfma_f32_16x16x32_bf16 v[24:27], v[84:87], v[120:123], v[24:27]
	v_mfma_f32_16x16x32_bf16 v[28:31], v[84:87], v[124:127], v[28:31]
	s_waitcnt lgkmcnt(1)
	v_mfma_f32_16x16x32_bf16 v[32:35], v[88:91], v[112:115], v[32:35]
	v_mfma_f32_16x16x32_bf16 v[36:39], v[88:91], v[116:119], v[36:39]
	v_mfma_f32_16x16x32_bf16 v[40:43], v[88:91], v[120:123], v[40:43]
	v_mfma_f32_16x16x32_bf16 v[44:47], v[88:91], v[124:127], v[44:47]
	s_waitcnt lgkmcnt(0)
	v_mfma_f32_16x16x32_bf16 v[48:51], v[92:95], v[112:115], v[48:51]
	v_mfma_f32_16x16x32_bf16 v[52:55], v[92:95], v[116:119], v[52:55]
	v_mfma_f32_16x16x32_bf16 v[56:59], v[92:95], v[120:123], v[56:59]
	v_mfma_f32_16x16x32_bf16 v[60:63], v[92:95], v[124:127], v[60:63]
	s_and_b32 s0, s25, 63
	s_lshr_b32 s1, s25, 6
	v_readlane_b32 s36, v252, 63
	v_readlane_b32 s37, v253, 0
	s_mov_b64 s[40:41], s[36:37]
	s_cmp_lg_u32 s70, 0
	s_cbranch_scc1 .Lgout_xb
	s_mov_b64 s[40:41], s[72:73]
	s_cmpk_lt_u32 s0, 32
	s_cbranch_scc1 .Lgout_xb
	s_sub_u32 s40, s74, 0x1000000
	s_subb_u32 s41, s75, 0
.Lgout_xb:
	s_lshl_b32 s4, s0, 19
	s_lshl_b32 s39, s1, 9
	s_add_u32 s4, s4, s39
	s_add_u32 s40, s40, s4
	s_addc_u32 s41, s41, 0
	s_add_u32 s36, s36, s4
	s_addc_u32 s37, s37, 0
	s_add_i32 s4, s0, -32
	s_lshr_b32 s4, s4, 4
	s_add_i32 s4, s4, 1
	s_cmpk_lt_u32 s0, 32
	s_cselect_b32 s4, 0, s4
	s_mul_i32 s38, s70, 3
	s_add_i32 s4, s4, s38
	s_mul_i32 s4, s4, 0x3000
	s_add_u32 s4, s4, 0x5e02000
	s_add_u32 s4, s4, s39
	s_add_u32 s42, s96, s4
	s_addc_u32 s43, s97, 0
	global_load_dwordx4 v[156:159], v155, s[42:43] offset:0
	global_load_dwordx4 v[160:163], v155, s[42:43] offset:64
	global_load_dwordx4 v[164:167], v155, s[42:43] offset:128
	global_load_dwordx4 v[168:171], v155, s[42:43] offset:192
	global_load_dwordx4 v[64:67], v146, s[40:41] offset:0
	global_load_dwordx4 v[68:71], v146, s[40:41] offset:64
	global_load_dwordx4 v[72:75], v146, s[40:41] offset:128
	global_load_dwordx4 v[76:79], v146, s[40:41] offset:192
	global_load_dwordx4 v[80:83], v147, s[40:41] offset:0
	global_load_dwordx4 v[84:87], v147, s[40:41] offset:64
	global_load_dwordx4 v[88:91], v147, s[40:41] offset:128
	global_load_dwordx4 v[92:95], v147, s[40:41] offset:192
	global_load_dwordx4 v[96:99], v148, s[40:41] offset:0
	global_load_dwordx4 v[100:103], v148, s[40:41] offset:64
	global_load_dwordx4 v[104:107], v148, s[40:41] offset:128
	global_load_dwordx4 v[108:111], v148, s[40:41] offset:192
	global_load_dwordx4 v[112:115], v149, s[40:41] offset:0
	global_load_dwordx4 v[116:119], v149, s[40:41] offset:64
	global_load_dwordx4 v[120:123], v149, s[40:41] offset:128
	global_load_dwordx4 v[124:127], v149, s[40:41] offset:192
	s_waitcnt vmcnt(15)
	v_pk_fma_f32 v[64:65], v[156:157], v[0:1], v[64:65]
	v_pk_fma_f32 v[66:67], v[158:159], v[2:3], v[66:67]
	global_store_dwordx4 v146, v[64:67], s[36:37] offset:0
	s_waitcnt vmcnt(15)
	v_pk_fma_f32 v[68:69], v[160:161], v[16:17], v[68:69]
	v_pk_fma_f32 v[70:71], v[162:163], v[18:19], v[70:71]
	global_store_dwordx4 v146, v[68:71], s[36:37] offset:64
	s_waitcnt vmcnt(15)
	v_pk_fma_f32 v[72:73], v[164:165], v[32:33], v[72:73]
	v_pk_fma_f32 v[74:75], v[166:167], v[34:35], v[74:75]
	global_store_dwordx4 v146, v[72:75], s[36:37] offset:128
	s_waitcnt vmcnt(15)
	v_pk_fma_f32 v[76:77], v[168:169], v[48:49], v[76:77]
	v_pk_fma_f32 v[78:79], v[170:171], v[50:51], v[78:79]
	global_store_dwordx4 v146, v[76:79], s[36:37] offset:192
	s_waitcnt vmcnt(15)
	v_pk_fma_f32 v[80:81], v[156:157], v[4:5], v[80:81]
	v_pk_fma_f32 v[82:83], v[158:159], v[6:7], v[82:83]
	global_store_dwordx4 v147, v[80:83], s[36:37] offset:0
	s_waitcnt vmcnt(15)
	v_pk_fma_f32 v[84:85], v[160:161], v[20:21], v[84:85]
	v_pk_fma_f32 v[86:87], v[162:163], v[22:23], v[86:87]
	global_store_dwordx4 v147, v[84:87], s[36:37] offset:64
	s_waitcnt vmcnt(15)
	v_pk_fma_f32 v[88:89], v[164:165], v[36:37], v[88:89]
	v_pk_fma_f32 v[90:91], v[166:167], v[38:39], v[90:91]
	global_store_dwordx4 v147, v[88:91], s[36:37] offset:128
	s_waitcnt vmcnt(15)
	v_pk_fma_f32 v[92:93], v[168:169], v[52:53], v[92:93]
	v_pk_fma_f32 v[94:95], v[170:171], v[54:55], v[94:95]
	global_store_dwordx4 v147, v[92:95], s[36:37] offset:192
	s_waitcnt vmcnt(15)
	v_pk_fma_f32 v[96:97], v[156:157], v[8:9], v[96:97]
	v_pk_fma_f32 v[98:99], v[158:159], v[10:11], v[98:99]
	global_store_dwordx4 v148, v[96:99], s[36:37] offset:0
	s_waitcnt vmcnt(15)
	v_pk_fma_f32 v[100:101], v[160:161], v[24:25], v[100:101]
	v_pk_fma_f32 v[102:103], v[162:163], v[26:27], v[102:103]
	global_store_dwordx4 v148, v[100:103], s[36:37] offset:64
	s_waitcnt vmcnt(15)
	v_pk_fma_f32 v[104:105], v[164:165], v[40:41], v[104:105]
	v_pk_fma_f32 v[106:107], v[166:167], v[42:43], v[106:107]
	global_store_dwordx4 v148, v[104:107], s[36:37] offset:128
	s_waitcnt vmcnt(15)
	v_pk_fma_f32 v[108:109], v[168:169], v[56:57], v[108:109]
	v_pk_fma_f32 v[110:111], v[170:171], v[58:59], v[110:111]
	global_store_dwordx4 v148, v[108:111], s[36:37] offset:192
	s_waitcnt vmcnt(15)
	v_pk_fma_f32 v[112:113], v[156:157], v[12:13], v[112:113]
	v_pk_fma_f32 v[114:115], v[158:159], v[14:15], v[114:115]
	global_store_dwordx4 v149, v[112:115], s[36:37] offset:0
	s_waitcnt vmcnt(15)
	v_pk_fma_f32 v[116:117], v[160:161], v[28:29], v[116:117]
	v_pk_fma_f32 v[118:119], v[162:163], v[30:31], v[118:119]
	global_store_dwordx4 v149, v[116:119], s[36:37] offset:64
	s_waitcnt vmcnt(15)
	v_pk_fma_f32 v[120:121], v[164:165], v[44:45], v[120:121]
	v_pk_fma_f32 v[122:123], v[166:167], v[46:47], v[122:123]
	global_store_dwordx4 v149, v[120:123], s[36:37] offset:128
	s_waitcnt vmcnt(15)
	v_pk_fma_f32 v[124:125], v[168:169], v[60:61], v[124:125]
	v_pk_fma_f32 v[126:127], v[170:171], v[62:63], v[126:127]
	global_store_dwordx4 v149, v[124:127], s[36:37] offset:192
	v_readlane_b32 s38, v255, 35
	s_add_i32 s25, s25, s38
	s_cmpk_lt_u32 s25, 0x200
	s_cbranch_scc0 .Lgout_done
	s_and_b32 s0, s25, 63
	s_lshr_b32 s1, s25, 6
	s_lshl_b32 s4, s70, 21
	s_lshl_b32 s39, s1, 18
	s_add_u32 s4, s4, s39
	s_add_u32 s4, s4, 0x5600000
	s_add_u32 s26, s96, s4
	s_addc_u32 s27, s97, 0
	s_lshl_b32 s4, s0, 18
	s_add_u32 s4, s4, 0x82a6100
	s_add_u32 s28, s96, s4
	s_addc_u32 s29, s97, 0
	s_mov_b32 m0, s5
	s_nop 0
	global_load_lds_dwordx4 v132, s[26:27] offset:0
	global_load_lds_dwordx4 v133, s[26:27] offset:1024
	global_load_lds_dwordx4 v134, s[26:27] offset:2048
	global_load_lds_dwordx4 v135, s[26:27] offset:3072
	s_mov_b32 m0, s6
	s_nop 0
	global_load_lds_dwordx4 v132, s[28:29] offset:0
	global_load_lds_dwordx4 v133, s[28:29] offset:1024
	global_load_lds_dwordx4 v134, s[28:29] offset:2048
	global_load_lds_dwordx4 v135, s[28:29] offset:3072
	s_branch .Lgout_tile
.Lgout_done:
	v_readlane_b32 s36, v255, 33
	v_readlane_b32 s37, v255, 34
	v_readlane_b32 s38, v255, 35
	v_readlane_b32 s39, v255, 36
